# peeled first K iteration: first two DMA waits leave the previous tile's epilogue stores in flight (counted vmcnt, flag in s32); pre-loop vmcnt(0) drain removed
# speedup vs baseline: 1.0058x; 1.0005x over previous
; #define PG8_STAGE(bufoff, gbase, voff) do { _Pragma("unroll") for (int _i = 0; _i < 2; ++_i) \
;         __builtin_amdgcn_global_load_lds((const unsigned*)((const char*)(gbase) + (voff)[_i]), (PG8_LAS unsigned*)(lds + (bufoff) + ldsw + _i * 8192), 16, 0, 0); } while (0)
; #define PG8_WAIT_V(n) asm volatile("s_waitcnt vmcnt(" #n ")" ::: "memory")
; #define PG8_BAR __builtin_amdgcn_s_barrier()
; template <class Epi, class Sched, bool ALIGN_EPI = false, bool SP2 = false>
; __device__ __forceinline__ void gemm_phase(PG8_LAS unsigned char* lds, const Gemm g, const Sched& S, const Epi& E) {
;     ...
;     const int tid = tid_, wid = __builtin_amdgcn_readfirstlane(tid >> 6), lane = tid & 63, wr = wid >> 2, wc = wid & 3, fr = lane & 15, fq = lane >> 4;
;     const int K = g.K, nt = K / BK;
;     unsigned voffA[2], voffB[2];
; #pragma unroll
;     for (int i = 0; i < 2; ++i) { int R, C; stage_rc(tid * 16 + i * 8192, R, C); const int Rb = Epi::PERM ? ((R & ~31) + perm32(R & 31)) : R;
;         voffA[i] = (unsigned)(R * K + C) * 2u; voffB[i] = (unsigned)(Rb * K + C) * 2u; }
;     const size_t kstep = (size_t)(BK * 2);
;     const size_t hstep = (size_t)HALF * K * 2;
;     const size_t tstep = 2 * hstep;
;     const unsigned ldsw = (unsigned)wid * 1024u;
;     const int aoff = lds_byte(wr * 64 + fr, fq * 8), boff = lds_byte(wc * 32 + fr, fq * 8);
;     ...
;     Unit cur, nxt; int ui = 0;
;     if (!S.next(0, cur)) return;
;     f32x4 acc[2][2][4][2];
; #pragma unroll
;     for (int a = 0; a < 2; ++a)
; #pragma unroll
;         for (int b = 0; b < 2; ++b)
; #pragma unroll
;             for (int m = 0; m < 4; ++m)
; #pragma unroll
;                 for (int n = 0; n < 2; ++n) acc[a][b][m][n] = (f32x4){0.f, 0.f, 0.f, 0.f};
;     bf16x8 At[4][2], B0[2][2], B1[2][2];
;     const char* cA = (const char*)g.A + (size_t)cur.pm * tstep; const char* cB = (const char*)g.Bt + (size_t)cur.pn * tstep;
;     S.a_ready(cur);
;     if constexpr (SP2) {
;         PG8_STAGE(PG8_SB(0, 0), cB, voffB); PG8_STAGE(PG8_SB(0, 1), cB + hstep, voffB); PG8_STAGE(PG8_SA(0, 0), cA, voffA); PG8_STAGE(PG8_SA(0, 1), cA + hstep, voffA);
;         if (wr == 1) PG8_BAR;
;         PG8_WAIT_V(2); PG8_BAR;
;         PG8_STAGE(PG8_SB(1, 0), cB + kstep, voffB); PG8_STAGE(PG8_SA(1, 0), cA + kstep, voffA); PG8_STAGE(PG8_SB(1, 1), cB + hstep + kstep, voffB);
;         PG8_WAIT_V(6); PG8_BAR;
.LBB0_26:
	v_bfe_u32 v18, v8, 4, 2
	v_and_b32_e32 v9, 15, v8
	v_lshlrev_b32_e32 v20, 4, v18
	v_lshlrev_b32_e32 v8, 2, v8
	v_mov_b32_e32 v149, v0
	s_and_b32 s0, s0, 3
	v_lshl_or_b32 v1, s1, 6, v9
	v_lshl_or_b32 v9, v9, 6, v20
	s_lshl_b32 s1, s1, 13
	v_and_b32_e32 v8, 32, v8
	v_lshl_add_u64 v[10:11], s[62:63], 0, v[148:149]
	v_mov_b32_e32 v145, v0
	v_bitop3_b32 v20, v9, s1, v8 bitop3:0xde
	s_lshl_b32 s1, s0, 12
	v_lshl_add_u64 v[12:13], s[62:63], 0, v[144:145]
	v_mov_b32_e32 v151, v0
	v_bitop3_b32 v143, v9, s1, v8 bitop3:0xde
	s_add_i32 m0, s5, 0x18000
	v_lshl_add_u64 v[8:9], v[10:11], 0, s[68:69]
	v_lshl_add_u64 v[14:15], s[18:19], 0, v[150:151]
	v_mov_b32_e32 v147, v0
	s_waitcnt vmcnt(2)
	s_barrier
	global_load_lds_dwordx4 v[8:9], off
	v_lshl_add_u64 v[8:9], v[12:13], 0, s[68:69]
	s_add_i32 m0, s5, 0x1a000
	s_add_i32 s1, s5, 0x8000
	s_add_i32 s60, s5, 0xa000
	v_lshl_add_u64 v[16:17], s[18:19], 0, v[146:147]
	global_load_lds_dwordx4 v[8:9], off
	v_lshl_add_u64 v[8:9], v[14:15], 0, s[68:69]
	s_mov_b32 m0, s1
	s_add_u32 s36, s62, 0x200080
	global_load_lds_dwordx4 v[8:9], off
	v_lshl_add_u64 v[8:9], v[16:17], 0, s[68:69]
	s_mov_b32 m0, s60
	s_addc_u32 s37, s63, 0
	global_load_lds_dwordx4 v[8:9], off
	s_add_i32 m0, s5, 0x1c000
	v_lshl_add_u64 v[8:9], s[36:37], 0, v[148:149]
	global_load_lds_dwordx4 v[8:9], off
	v_lshl_add_u64 v[8:9], s[36:37], 0, v[144:145]
	s_add_i32 m0, s5, 0x1e000
	v_lshlrev_b32_e32 v19, 3, v18
	global_load_lds_dwordx4 v[8:9], off
	v_lshlrev_b32_e32 v8, 17, v6
	v_and_b32_e32 v8, 0xfffc0000, v8
	v_lshl_add_u32 v5, v5, 14, v8
	v_and_b32_e32 v6, 1, v6
	v_lshl_or_b32 v5, v6, 6, v5
	v_lshl_add_u32 v152, v7, 1, v5
	v_lshlrev_b32_e32 v5, 17, v2
	v_and_b32_e32 v5, 0xfffc0000, v5
	s_waitcnt vmcnt(6)
	v_lshl_add_u32 v3, v3, 14, v5
	v_and_b32_e32 v2, 1, v2
	s_cmpk_lt_u32 s12, 0x100
	v_lshl_or_b32 v2, v2, 6, v3
	v_readlane_b32 s36, v254, 2
	v_lshl_or_b32 v162, s0, 5, v19
	s_cselect_b64 s[12:13], -1, 0
	s_mov_b32 s34, 0
	v_cmp_eq_u32_e64 s[40:41], 0, v18
	v_mov_b32_e32 v153, v0
	v_lshl_add_u32 v154, v4, 1, v2
	v_mov_b32_e32 v155, v0
	v_add_u32_e32 v163, 0, v20
	v_readlane_b32 s28, v253, 19
	s_mov_b32 s54, s36
	s_barrier
	v_readlane_b32 s37, v254, 3
	s_mov_b32 s32, 0
	s_branch .LBB0_29

; #define PG8_STAGE(bufoff, gbase, voff) do { _Pragma("unroll") for (int _i = 0; _i < 2; ++_i) \
;         __builtin_amdgcn_global_load_lds((const unsigned*)((const char*)(gbase) + (voff)[_i]), (PG8_LAS unsigned*)(lds + (bufoff) + ldsw + _i * 8192), 16, 0, 0); } while (0)
; #define PG8_LDA(dst, b, h) do { _Pragma("unroll") for (int m = 0; m < 4; ++m) _Pragma("unroll") for (int k = 0; k < 2; ++k) dst[m][k] = *(const PG8_LAS bf16x8*)(lds + PG8_SA(b, h) + aoff + m * 2048 + k * 1024); } while (0)
; #define PG8_LDB(dst, b, h) do { _Pragma("unroll") for (int n = 0; n < 2; ++n) _Pragma("unroll") for (int k = 0; k < 2; ++k) dst[n][k] = *(const PG8_LAS bf16x8*)(lds + PG8_SB(b, h) + boff + n * 2048 + k * 1024); } while (0)
; #define PG8_SCHED __builtin_amdgcn_sched_barrier(0)
; template <class Epi, class Sched, bool ALIGN_EPI = false, bool SP2 = false>
; __device__ __forceinline__ void gemm_phase(PG8_LAS unsigned char* lds, const Gemm g, const Sched& S, const Epi& E) {
;     ...
;         const bool has_next = S.next(ui + 1, nxt);
;         const char* nA = has_next ? (const char*)g.A + (size_t)nxt.pm * tstep : cA; const char* nB = has_next ? (const char*)g.Bt + (size_t)nxt.pn * tstep : cB;
;         for (int t = 0; t < nt; t += 2) {
;             const bool last = (t == nt - 2);
;             const char* a1 = cA + (size_t)(t + 1) * kstep;
;             const char* a2 = last ? nA : cA + (size_t)(t + 2) * kstep; const char* b2 = last ? nB : cB + (size_t)(t + 2) * kstep;
;             const char* a3 = a2 + kstep; const char* b3 = b2 + kstep;
;             if (last && has_next) S.a_ready(nxt);
;             if constexpr (SP2) {
;             PG8_LDB(B0, 0, 0); PG8_LDB(B1, 0, 1); PG8_SCHED; PG8_LDA(At, 0, 0); PG8_STAGE(PG8_SA(1, 1), a1 + hstep, voffA);
.LBB0_35:
	s_ashr_i32 s45, s44, 31
	s_lshl_b64 s[46:47], s[44:45], 22
	s_add_u32 s94, s92, s46
	s_addc_u32 s95, s93, s47
	s_and_b64 s[46:47], s[42:43], exec
	s_cselect_b32 s45, s95, s19
	s_cselect_b32 s73, s94, s18
	s_ashr_i32 s37, s36, 31
	s_lshl_b64 s[46:47], s[36:37], 22
	v_readlane_b32 s58, v254, 47
	v_readlane_b32 s59, v254, 48
	s_add_u32 s96, s58, s46
	s_addc_u32 s97, s59, s47
	s_and_b64 s[46:47], s[42:43], exec
	s_cselect_b32 s37, s97, s63
	s_cselect_b32 s84, s96, s62
	s_add_u32 s58, s18, 0x200080
	s_addc_u32 s59, s19, 0
	s_add_u32 s78, s62, 0x100
	s_addc_u32 s79, s63, 0
	s_mov_b32 s46, -2
	s_waitcnt lgkmcnt(0)
	s_add_u32 s18, s58, 0xffe00080
	s_addc_u32 s19, s59, -1
	s_add_i32 s47, 0, 0x10000
	s_cmpk_eq_i32 s46, 0x7c
	s_cselect_b32 s63, s45, s19
	s_cselect_b32 s62, s73, s18
	v_add_u32_e32 v160, s47, v143
	s_cselect_b32 s19, s37, s79
	s_cselect_b32 s18, s84, s78
	s_add_i32 s80, 0, 0x14000
	ds_read_b128 v[156:159], v160
	ds_read_b128 v[164:167], v160 offset:1024
	ds_read_b128 v[168:171], v160 offset:2048
	ds_read_b128 v[172:175], v160 offset:3072
	v_add_u32_e32 v160, s80, v143
	ds_read_b128 v[176:179], v160
	ds_read_b128 v[180:183], v160 offset:1024
	ds_read_b128 v[184:187], v160 offset:2048
	ds_read_b128 v[204:207], v160 offset:3072
	v_lshl_add_u64 v[160:161], s[58:59], 0, v[152:153]
	s_add_i32 m0, s5, 0xc000
	ds_read_b128 v[208:211], v163
	ds_read_b128 v[212:215], v163 offset:1024
	ds_read_b128 v[216:219], v163 offset:2048
	ds_read_b128 v[220:223], v163 offset:3072
	ds_read_b128 v[224:227], v163 offset:4096
	ds_read_b128 v[228:231], v163 offset:5120
	ds_read_b128 v[232:235], v163 offset:6144
	ds_read_b128 v[236:239], v163 offset:7168
	global_load_lds_dwordx4 v[160:161], off
	v_lshl_add_u64 v[160:161], s[58:59], 0, v[154:155]
	s_add_i32 m0, s5, 0xe000
	s_nop 0
	global_load_lds_dwordx4 v[160:161], off
	s_nop 0
	s_cmp_eq_u32 s32, 0
	s_cbranch_scc1 .Lpw1_f
	s_waitcnt vmcnt(24)
	s_branch .Lpw1_j

; #define PG8_STAGE(bufoff, gbase, voff) do { _Pragma("unroll") for (int _i = 0; _i < 2; ++_i) \
;         __builtin_amdgcn_global_load_lds((const unsigned*)((const char*)(gbase) + (voff)[_i]), (PG8_LAS unsigned*)(lds + (bufoff) + ldsw + _i * 8192), 16, 0, 0); } while (0)
; #define PG8_LDA(dst, b, h) do { _Pragma("unroll") for (int m = 0; m < 4; ++m) _Pragma("unroll") for (int k = 0; k < 2; ++k) dst[m][k] = *(const PG8_LAS bf16x8*)(lds + PG8_SA(b, h) + aoff + m * 2048 + k * 1024); } while (0)
; #define PG8_LDB(dst, b, h) do { _Pragma("unroll") for (int n = 0; n < 2; ++n) _Pragma("unroll") for (int k = 0; k < 2; ++k) dst[n][k] = *(const PG8_LAS bf16x8*)(lds + PG8_SB(b, h) + boff + n * 2048 + k * 1024); } while (0)
; #define PG8_MMA(ai, bj, At, Bt) do { __builtin_amdgcn_s_setprio(1); _Pragma("unroll") for (int m = 0; m < 4; ++m) _Pragma("unroll") for (int n = 0; n < 2; ++n) _Pragma("unroll") for (int k = 0; k < 2; ++k) \
;         acc[ai][bj][m][n] = __builtin_amdgcn_mfma_f32_16x16x32_bf16(Bt[n][k], At[m][k], acc[ai][bj][m][n], 0, 0, 0); __builtin_amdgcn_s_setprio(0); } while (0)
; #define PG8_WAIT_V(n) asm volatile("s_waitcnt vmcnt(" #n ")" ::: "memory")
; #define PG8_WAIT_L(n) asm volatile("s_waitcnt lgkmcnt(" #n ")" ::: "memory")
; #define PG8_BAR __builtin_amdgcn_s_barrier()
; #define PG8_SCHED __builtin_amdgcn_sched_barrier(0)
; template <class Epi, class Sched, bool ALIGN_EPI = false, bool SP2 = false>
; __device__ __forceinline__ void gemm_phase(PG8_LAS unsigned char* lds, const Gemm g, const Sched& S, const Epi& E) {
;     ...
;             PG8_LDB(B0, 0, 0); PG8_LDB(B1, 0, 1); PG8_SCHED; PG8_LDA(At, 0, 0); PG8_STAGE(PG8_SA(1, 1), a1 + hstep, voffA);
;             PG8_WAIT_V(8); PG8_WAIT_L(0); PG8_BAR; PG8_MMA(0, 0, At, B0); PG8_MMA(0, 1, At, B1); PG8_BAR; PG8_SCHED;
;             PG8_LDA(At, 0, 1); PG8_STAGE(PG8_SB(0, 0), b2, voffB); PG8_STAGE(PG8_SB(0, 1), b2 + hstep, voffB); PG8_STAGE(PG8_SA(0, 0), a2, voffA);
;             PG8_WAIT_V(8); PG8_WAIT_L(0); PG8_BAR; PG8_MMA(1, 0, At, B0); PG8_MMA(1, 1, At, B1); PG8_BAR; PG8_SCHED;
.Lpw1_j:
	s_waitcnt lgkmcnt(0)
	s_setprio 1
	s_barrier
	v_mfma_f32_16x16x32_bf16 v[126:129], v[156:159], v[208:211], 0
	v_mfma_f32_16x16x32_bf16 v[122:125], v[168:171], v[208:211], 0
	v_mfma_f32_16x16x32_bf16 v[110:113], v[156:159], v[216:219], 0
	v_mfma_f32_16x16x32_bf16 v[106:109], v[168:171], v[216:219], 0
	v_mfma_f32_16x16x32_bf16 v[94:97], v[156:159], v[224:227], 0
	v_mfma_f32_16x16x32_bf16 v[90:93], v[168:171], v[224:227], 0
	v_mfma_f32_16x16x32_bf16 v[78:81], v[156:159], v[232:235], 0
	v_mfma_f32_16x16x32_bf16 v[74:77], v[168:171], v[232:235], 0
	s_setprio 0
	s_setprio 1
	v_mfma_f32_16x16x32_bf16 v[126:129], v[164:167], v[212:215], v[126:129]
	v_mfma_f32_16x16x32_bf16 v[122:125], v[172:175], v[212:215], v[122:125]
	v_mfma_f32_16x16x32_bf16 v[110:113], v[164:167], v[220:223], v[110:113]
	v_mfma_f32_16x16x32_bf16 v[106:109], v[172:175], v[220:223], v[106:109]
	v_mfma_f32_16x16x32_bf16 v[94:97], v[164:167], v[228:231], v[94:97]
	v_mfma_f32_16x16x32_bf16 v[90:93], v[172:175], v[228:231], v[90:93]
	v_mfma_f32_16x16x32_bf16 v[78:81], v[164:167], v[236:239], v[78:81]
	v_mfma_f32_16x16x32_bf16 v[74:77], v[172:175], v[236:239], v[74:77]
	s_setprio 0
	s_setprio 1
	v_mfma_f32_16x16x32_bf16 v[118:121], v[176:179], v[208:211], 0
	v_mfma_f32_16x16x32_bf16 v[114:117], v[184:187], v[208:211], 0
	v_mfma_f32_16x16x32_bf16 v[102:105], v[176:179], v[216:219], 0
	v_mfma_f32_16x16x32_bf16 v[98:101], v[184:187], v[216:219], 0
	v_mfma_f32_16x16x32_bf16 v[86:89], v[176:179], v[224:227], 0
	v_mfma_f32_16x16x32_bf16 v[82:85], v[184:187], v[224:227], 0
	v_mfma_f32_16x16x32_bf16 v[70:73], v[176:179], v[232:235], 0
	v_mfma_f32_16x16x32_bf16 v[66:69], v[184:187], v[232:235], 0
	s_setprio 0
	s_setprio 1
	v_mfma_f32_16x16x32_bf16 v[118:121], v[180:183], v[212:215], v[118:121]
	v_mfma_f32_16x16x32_bf16 v[114:117], v[204:207], v[212:215], v[114:117]
	v_mfma_f32_16x16x32_bf16 v[102:105], v[180:183], v[220:223], v[102:105]
	v_mfma_f32_16x16x32_bf16 v[98:101], v[204:207], v[220:223], v[98:101]
	v_mfma_f32_16x16x32_bf16 v[86:89], v[180:183], v[228:231], v[86:89]
	v_mfma_f32_16x16x32_bf16 v[82:85], v[204:207], v[228:231], v[82:85]
	v_mfma_f32_16x16x32_bf16 v[70:73], v[180:183], v[236:239], v[70:73]
	v_mfma_f32_16x16x32_bf16 v[66:69], v[204:207], v[236:239], v[66:69]
	s_setprio 0
	s_barrier
	s_add_i32 s47, s47, s4
	v_lshl_add_u64 v[160:161], s[18:19], 0, v[148:149]
	s_mov_b32 m0, s47
	ds_read_b128 v[208:211], v163 offset:16384
	ds_read_b128 v[212:215], v163 offset:17408
	ds_read_b128 v[216:219], v163 offset:18432
	ds_read_b128 v[220:223], v163 offset:19456
	ds_read_b128 v[224:227], v163 offset:20480
	ds_read_b128 v[228:231], v163 offset:21504
	ds_read_b128 v[232:235], v163 offset:22528
	ds_read_b128 v[236:239], v163 offset:23552
	global_load_lds_dwordx4 v[160:161], off
	s_add_i32 m0, s47, 0x2000
	s_add_u32 s76, s18, 0x200000
	v_lshl_add_u64 v[240:241], s[18:19], 0, v[144:145]
	s_addc_u32 s77, s19, 0
	s_add_i32 s47, s80, s4
	global_load_lds_dwordx4 v[240:241], off
	v_lshl_add_u64 v[242:243], s[76:77], 0, v[148:149]
	s_mov_b32 m0, s47
	v_lshl_add_u64 v[244:245], s[62:63], 0, v[146:147]
	global_load_lds_dwordx4 v[242:243], off
	v_lshl_add_u64 v[242:243], s[76:77], 0, v[144:145]
	s_add_i32 m0, s47, 0x2000
	s_nop 0
	global_load_lds_dwordx4 v[242:243], off
	v_lshl_add_u64 v[242:243], s[62:63], 0, v[150:151]
	s_mov_b32 m0, s5
	s_nop 0
	global_load_lds_dwordx4 v[242:243], off
	s_mov_b32 m0, s30
	s_nop 0
	global_load_lds_dwordx4 v[244:245], off
	s_cmp_eq_u32 s32, 0
	s_cbranch_scc1 .Lpw2_f
	s_waitcnt vmcnt(24)
	s_branch .Lpw2_j

; #define PG8_STAGE(bufoff, gbase, voff) do { _Pragma("unroll") for (int _i = 0; _i < 2; ++_i) \
;         __builtin_amdgcn_global_load_lds((const unsigned*)((const char*)(gbase) + (voff)[_i]), (PG8_LAS unsigned*)(lds + (bufoff) + ldsw + _i * 8192), 16, 0, 0); } while (0)
; #define PG8_LDA(dst, b, h) do { _Pragma("unroll") for (int m = 0; m < 4; ++m) _Pragma("unroll") for (int k = 0; k < 2; ++k) dst[m][k] = *(const PG8_LAS bf16x8*)(lds + PG8_SA(b, h) + aoff + m * 2048 + k * 1024); } while (0)
; #define PG8_LDB(dst, b, h) do { _Pragma("unroll") for (int n = 0; n < 2; ++n) _Pragma("unroll") for (int k = 0; k < 2; ++k) dst[n][k] = *(const PG8_LAS bf16x8*)(lds + PG8_SB(b, h) + boff + n * 2048 + k * 1024); } while (0)
; #define PG8_MMA(ai, bj, At, Bt) do { __builtin_amdgcn_s_setprio(1); _Pragma("unroll") for (int m = 0; m < 4; ++m) _Pragma("unroll") for (int n = 0; n < 2; ++n) _Pragma("unroll") for (int k = 0; k < 2; ++k) \
;         acc[ai][bj][m][n] = __builtin_amdgcn_mfma_f32_16x16x32_bf16(Bt[n][k], At[m][k], acc[ai][bj][m][n], 0, 0, 0); __builtin_amdgcn_s_setprio(0); } while (0)
; #define PG8_WAIT_V(n) asm volatile("s_waitcnt vmcnt(" #n ")" ::: "memory")
; #define PG8_WAIT_L(n) asm volatile("s_waitcnt lgkmcnt(" #n ")" ::: "memory")
; #define PG8_BAR __builtin_amdgcn_s_barrier()
; #define PG8_SCHED __builtin_amdgcn_sched_barrier(0)
; template <class Epi, class Sched, bool ALIGN_EPI = false, bool SP2 = false>
; __device__ __forceinline__ void gemm_phase(PG8_LAS unsigned char* lds, const Gemm g, const Sched& S, const Epi& E) {
;     ...
;             PG8_WAIT_V(8); PG8_WAIT_L(0); PG8_BAR; PG8_MMA(1, 0, At, B0); PG8_MMA(1, 1, At, B1); PG8_BAR; PG8_SCHED;
;             PG8_LDB(B0, 1, 0); PG8_LDB(B1, 1, 1); PG8_SCHED; PG8_LDA(At, 1, 0); PG8_STAGE(PG8_SA(0, 1), a2 + hstep, voffA);
;             PG8_WAIT_V(8); PG8_WAIT_L(0); PG8_BAR; PG8_MMA(0, 0, At, B0); PG8_MMA(0, 1, At, B1); PG8_BAR; PG8_SCHED;
.Lpw2_j:
	s_waitcnt lgkmcnt(0)
	s_setprio 1
	s_barrier
	v_mfma_f32_16x16x32_bf16 v[62:65], v[156:159], v[208:211], 0
	v_mfma_f32_16x16x32_bf16 v[58:61], v[168:171], v[208:211], 0
	v_mfma_f32_16x16x32_bf16 v[46:49], v[156:159], v[216:219], 0
	v_mfma_f32_16x16x32_bf16 v[42:45], v[168:171], v[216:219], 0
	v_mfma_f32_16x16x32_bf16 v[30:33], v[156:159], v[224:227], 0
	v_mfma_f32_16x16x32_bf16 v[26:29], v[168:171], v[224:227], 0
	v_mfma_f32_16x16x32_bf16 v[14:17], v[156:159], v[232:235], 0
	v_mfma_f32_16x16x32_bf16 v[10:13], v[168:171], v[232:235], 0
	v_mfma_f32_16x16x32_bf16 v[62:65], v[164:167], v[212:215], v[62:65]
	v_mfma_f32_16x16x32_bf16 v[58:61], v[172:175], v[212:215], v[58:61]
	v_mfma_f32_16x16x32_bf16 v[46:49], v[164:167], v[220:223], v[46:49]
	v_mfma_f32_16x16x32_bf16 v[42:45], v[172:175], v[220:223], v[42:45]
	v_mfma_f32_16x16x32_bf16 v[30:33], v[164:167], v[228:231], v[30:33]
	v_mfma_f32_16x16x32_bf16 v[26:29], v[172:175], v[228:231], v[26:29]
	v_mfma_f32_16x16x32_bf16 v[14:17], v[164:167], v[236:239], v[14:17]
	v_mfma_f32_16x16x32_bf16 v[10:13], v[172:175], v[236:239], v[10:13]
	v_mfma_f32_16x16x32_bf16 v[54:57], v[176:179], v[208:211], 0
	v_mfma_f32_16x16x32_bf16 v[50:53], v[184:187], v[208:211], 0
	v_mfma_f32_16x16x32_bf16 v[38:41], v[176:179], v[216:219], 0
	v_mfma_f32_16x16x32_bf16 v[34:37], v[184:187], v[216:219], 0
	v_mfma_f32_16x16x32_bf16 v[22:25], v[176:179], v[224:227], 0
	v_mfma_f32_16x16x32_bf16 v[18:21], v[184:187], v[224:227], 0
	v_mfma_f32_16x16x32_bf16 v[6:9], v[176:179], v[232:235], 0
	v_mfma_f32_16x16x32_bf16 v[2:5], v[184:187], v[232:235], 0
	v_mfma_f32_16x16x32_bf16 v[54:57], v[180:183], v[212:215], v[54:57]
	v_mfma_f32_16x16x32_bf16 v[50:53], v[204:207], v[212:215], v[50:53]
	v_mfma_f32_16x16x32_bf16 v[38:41], v[180:183], v[220:223], v[38:41]
	v_mfma_f32_16x16x32_bf16 v[34:37], v[204:207], v[220:223], v[34:37]
	v_mfma_f32_16x16x32_bf16 v[22:25], v[180:183], v[228:231], v[22:25]
	v_mfma_f32_16x16x32_bf16 v[18:21], v[204:207], v[228:231], v[18:21]
	v_mfma_f32_16x16x32_bf16 v[6:9], v[180:183], v[236:239], v[6:9]
	v_mfma_f32_16x16x32_bf16 v[2:5], v[204:207], v[236:239], v[2:5]
	s_setprio 0
	s_barrier
	s_add_i32 s47, 0, 0x18000
	s_add_i32 s76, 0, 0x1c000
	v_add_u32_e32 v172, s47, v143
	v_add_u32_e32 v203, s76, v143
	ds_read_b128 v[156:159], v172
	ds_read_b128 v[164:167], v172 offset:1024
	ds_read_b128 v[168:171], v172 offset:2048
	ds_read_b128 v[172:175], v172 offset:3072
	ds_read_b128 v[176:179], v203
	ds_read_b128 v[180:183], v203 offset:1024
	ds_read_b128 v[184:187], v203 offset:2048
	ds_read_b128 v[204:207], v203 offset:3072
	s_add_u32 s62, s62, 0x200000
	s_addc_u32 s63, s63, 0
	s_mov_b32 m0, s57
	v_lshl_add_u64 v[246:247], s[62:63], 0, v[150:151]
	ds_read_b128 v[208:211], v163 offset:32768
	ds_read_b128 v[212:215], v163 offset:33792
	ds_read_b128 v[216:219], v163 offset:34816
	ds_read_b128 v[220:223], v163 offset:35840
	ds_read_b128 v[224:227], v163 offset:36864
	ds_read_b128 v[228:231], v163 offset:37888
	ds_read_b128 v[232:235], v163 offset:38912
	ds_read_b128 v[236:239], v163 offset:39936
	global_load_lds_dwordx4 v[246:247], off
	v_lshl_add_u64 v[246:247], s[62:63], 0, v[146:147]
	s_mov_b32 m0, s67
	s_nop 0
	global_load_lds_dwordx4 v[246:247], off
	s_waitcnt vmcnt(8)
	s_waitcnt lgkmcnt(0)
	s_setprio 1
	s_barrier
	v_mfma_f32_16x16x32_bf16 v[126:129], v[156:159], v[208:211], v[126:129]
	v_mfma_f32_16x16x32_bf16 v[122:125], v[168:171], v[208:211], v[122:125]
	v_mfma_f32_16x16x32_bf16 v[110:113], v[156:159], v[216:219], v[110:113]
	v_mfma_f32_16x16x32_bf16 v[106:109], v[168:171], v[216:219], v[106:109]
	v_mfma_f32_16x16x32_bf16 v[94:97], v[156:159], v[224:227], v[94:97]
	v_mfma_f32_16x16x32_bf16 v[90:93], v[168:171], v[224:227], v[90:93]
	v_mfma_f32_16x16x32_bf16 v[78:81], v[156:159], v[232:235], v[78:81]
	v_mfma_f32_16x16x32_bf16 v[74:77], v[168:171], v[232:235], v[74:77]
	s_setprio 0
	s_setprio 1
	v_mfma_f32_16x16x32_bf16 v[126:129], v[164:167], v[212:215], v[126:129]
	v_mfma_f32_16x16x32_bf16 v[122:125], v[172:175], v[212:215], v[122:125]
	v_mfma_f32_16x16x32_bf16 v[110:113], v[164:167], v[220:223], v[110:113]
	v_mfma_f32_16x16x32_bf16 v[106:109], v[172:175], v[220:223], v[106:109]
	v_mfma_f32_16x16x32_bf16 v[94:97], v[164:167], v[228:231], v[94:97]
	v_mfma_f32_16x16x32_bf16 v[90:93], v[172:175], v[228:231], v[90:93]
	v_mfma_f32_16x16x32_bf16 v[78:81], v[164:167], v[236:239], v[78:81]
	v_mfma_f32_16x16x32_bf16 v[74:77], v[172:175], v[236:239], v[74:77]
	s_setprio 0
	s_setprio 1
	v_mfma_f32_16x16x32_bf16 v[118:121], v[176:179], v[208:211], v[118:121]
	v_mfma_f32_16x16x32_bf16 v[114:117], v[184:187], v[208:211], v[114:117]
	v_mfma_f32_16x16x32_bf16 v[102:105], v[176:179], v[216:219], v[102:105]
	v_mfma_f32_16x16x32_bf16 v[98:101], v[184:187], v[216:219], v[98:101]
	v_mfma_f32_16x16x32_bf16 v[86:89], v[176:179], v[224:227], v[86:89]
	v_mfma_f32_16x16x32_bf16 v[82:85], v[184:187], v[224:227], v[82:85]
	v_mfma_f32_16x16x32_bf16 v[70:73], v[176:179], v[232:235], v[70:73]
	v_mfma_f32_16x16x32_bf16 v[66:69], v[184:187], v[232:235], v[66:69]
	s_setprio 0
	s_setprio 1
	v_mfma_f32_16x16x32_bf16 v[118:121], v[180:183], v[212:215], v[118:121]
	v_mfma_f32_16x16x32_bf16 v[114:117], v[204:207], v[212:215], v[114:117]
	v_mfma_f32_16x16x32_bf16 v[102:105], v[180:183], v[220:223], v[102:105]
	v_mfma_f32_16x16x32_bf16 v[98:101], v[204:207], v[220:223], v[98:101]
	v_mfma_f32_16x16x32_bf16 v[86:89], v[180:183], v[228:231], v[86:89]
	v_mfma_f32_16x16x32_bf16 v[82:85], v[204:207], v[228:231], v[82:85]
	v_mfma_f32_16x16x32_bf16 v[70:73], v[180:183], v[236:239], v[70:73]
	v_mfma_f32_16x16x32_bf16 v[66:69], v[204:207], v[236:239], v[66:69]
	s_setprio 0
	s_barrier
; #define PG8_STAGE(bufoff, gbase, voff) do { _Pragma("unroll") for (int _i = 0; _i < 2; ++_i) \
;         __builtin_amdgcn_global_load_lds((const unsigned*)((const char*)(gbase) + (voff)[_i]), (PG8_LAS unsigned*)(lds + (bufoff) + ldsw + _i * 8192), 16, 0, 0); } while (0)
; #define PG8_LDA(dst, b, h) do { _Pragma("unroll") for (int m = 0; m < 4; ++m) _Pragma("unroll") for (int k = 0; k < 2; ++k) dst[m][k] = *(const PG8_LAS bf16x8*)(lds + PG8_SA(b, h) + aoff + m * 2048 + k * 1024); } while (0)
; #define PG8_LDB(dst, b, h) do { _Pragma("unroll") for (int n = 0; n < 2; ++n) _Pragma("unroll") for (int k = 0; k < 2; ++k) dst[n][k] = *(const PG8_LAS bf16x8*)(lds + PG8_SB(b, h) + boff + n * 2048 + k * 1024); } while (0)
; #define PG8_MMA(ai, bj, At, Bt) do { __builtin_amdgcn_s_setprio(1); _Pragma("unroll") for (int m = 0; m < 4; ++m) _Pragma("unroll") for (int n = 0; n < 2; ++n) _Pragma("unroll") for (int k = 0; k < 2; ++k) \
;         acc[ai][bj][m][n] = __builtin_amdgcn_mfma_f32_16x16x32_bf16(Bt[n][k], At[m][k], acc[ai][bj][m][n], 0, 0, 0); __builtin_amdgcn_s_setprio(0); } while (0)
; #define PG8_WAIT_V(n) asm volatile("s_waitcnt vmcnt(" #n ")" ::: "memory")
; #define PG8_WAIT_L(n) asm volatile("s_waitcnt lgkmcnt(" #n ")" ::: "memory")
; #define PG8_BAR __builtin_amdgcn_s_barrier()
; #define PG8_SCHED __builtin_amdgcn_sched_barrier(0)
; template <class Epi, class Sched, bool ALIGN_EPI = false, bool SP2 = false>
; __device__ __forceinline__ void gemm_phase(PG8_LAS unsigned char* lds, const Gemm g, const Sched& S, const Epi& E) {
;     ...
;             PG8_LDB(B0, 0, 0); PG8_LDB(B1, 0, 1); PG8_SCHED; PG8_LDA(At, 0, 0); PG8_STAGE(PG8_SA(1, 1), a1 + hstep, voffA);
;             PG8_WAIT_V(8); PG8_WAIT_L(0); PG8_BAR; PG8_MMA(0, 0, At, B0); PG8_MMA(0, 1, At, B1); PG8_BAR; PG8_SCHED;
;     ...
;             PG8_LDA(At, 1, 1); PG8_STAGE(PG8_SB(1, 0), b3, voffB); PG8_STAGE(PG8_SB(1, 1), b3 + hstep, voffB); PG8_STAGE(PG8_SA(1, 0), a3, voffA);
;             PG8_WAIT_V(8); PG8_WAIT_L(0); PG8_BAR; PG8_MMA(1, 0, At, B0); PG8_MMA(1, 1, At, B1); PG8_BAR; PG8_SCHED;
	s_add_i32 s47, s47, s4
	v_lshl_add_u64 v[160:161], v[160:161], 0, s[68:69]
	s_mov_b32 m0, s47
	ds_read_b128 v[208:211], v163 offset:49152
	ds_read_b128 v[212:215], v163 offset:50176
	ds_read_b128 v[216:219], v163 offset:51200
	ds_read_b128 v[220:223], v163 offset:52224
	ds_read_b128 v[224:227], v163 offset:53248
	ds_read_b128 v[228:231], v163 offset:54272
	ds_read_b128 v[232:235], v163 offset:55296
	ds_read_b128 v[236:239], v163 offset:56320
	global_load_lds_dwordx4 v[160:161], off
	s_add_i32 m0, s47, 0x2000
	s_add_u32 s18, s18, 0x200080
	v_lshl_add_u64 v[160:161], v[240:241], 0, s[68:69]
	s_addc_u32 s19, s19, 0
	s_add_i32 s47, s76, s4
	global_load_lds_dwordx4 v[160:161], off
	v_lshl_add_u64 v[160:161], s[18:19], 0, v[148:149]
	s_mov_b32 m0, s47
	s_nop 0
	global_load_lds_dwordx4 v[160:161], off
	v_lshl_add_u64 v[160:161], s[18:19], 0, v[144:145]
	s_add_i32 m0, s47, 0x2000
	s_nop 0
	global_load_lds_dwordx4 v[160:161], off
	v_lshl_add_u64 v[160:161], v[242:243], 0, s[68:69]
	s_mov_b32 m0, s1
	s_nop 0
	global_load_lds_dwordx4 v[160:161], off
	v_lshl_add_u64 v[160:161], v[244:245], 0, s[68:69]
	s_mov_b32 m0, s60
	s_nop 0
	global_load_lds_dwordx4 v[160:161], off
	s_nop 0
	s_waitcnt vmcnt(8)
	s_waitcnt lgkmcnt(0)
	s_setprio 1
	s_barrier
	v_mfma_f32_16x16x32_bf16 v[62:65], v[156:159], v[208:211], v[62:65]
	v_mfma_f32_16x16x32_bf16 v[58:61], v[168:171], v[208:211], v[58:61]
	v_mfma_f32_16x16x32_bf16 v[46:49], v[156:159], v[216:219], v[46:49]
	v_mfma_f32_16x16x32_bf16 v[42:45], v[168:171], v[216:219], v[42:45]
	v_mfma_f32_16x16x32_bf16 v[30:33], v[156:159], v[224:227], v[30:33]
	v_mfma_f32_16x16x32_bf16 v[26:29], v[168:171], v[224:227], v[26:29]
	v_mfma_f32_16x16x32_bf16 v[14:17], v[156:159], v[232:235], v[14:17]
	v_mfma_f32_16x16x32_bf16 v[10:13], v[168:171], v[232:235], v[10:13]
	v_mfma_f32_16x16x32_bf16 v[62:65], v[164:167], v[212:215], v[62:65]
	v_mfma_f32_16x16x32_bf16 v[58:61], v[172:175], v[212:215], v[58:61]
	v_mfma_f32_16x16x32_bf16 v[46:49], v[164:167], v[220:223], v[46:49]
	v_mfma_f32_16x16x32_bf16 v[42:45], v[172:175], v[220:223], v[42:45]
	v_mfma_f32_16x16x32_bf16 v[30:33], v[164:167], v[228:231], v[30:33]
	v_mfma_f32_16x16x32_bf16 v[26:29], v[172:175], v[228:231], v[26:29]
	v_mfma_f32_16x16x32_bf16 v[14:17], v[164:167], v[236:239], v[14:17]
	v_mfma_f32_16x16x32_bf16 v[10:13], v[172:175], v[236:239], v[10:13]
	v_mfma_f32_16x16x32_bf16 v[54:57], v[176:179], v[208:211], v[54:57]
	v_mfma_f32_16x16x32_bf16 v[50:53], v[184:187], v[208:211], v[50:53]
	v_mfma_f32_16x16x32_bf16 v[38:41], v[176:179], v[216:219], v[38:41]
	v_mfma_f32_16x16x32_bf16 v[34:37], v[184:187], v[216:219], v[34:37]
	v_mfma_f32_16x16x32_bf16 v[22:25], v[176:179], v[224:227], v[22:25]
	v_mfma_f32_16x16x32_bf16 v[18:21], v[184:187], v[224:227], v[18:21]
	v_mfma_f32_16x16x32_bf16 v[6:9], v[176:179], v[232:235], v[6:9]
	v_mfma_f32_16x16x32_bf16 v[2:5], v[184:187], v[232:235], v[2:5]
	v_mfma_f32_16x16x32_bf16 v[54:57], v[180:183], v[212:215], v[54:57]
	v_mfma_f32_16x16x32_bf16 v[50:53], v[204:207], v[212:215], v[50:53]
	v_mfma_f32_16x16x32_bf16 v[38:41], v[180:183], v[220:223], v[38:41]
	v_mfma_f32_16x16x32_bf16 v[34:37], v[204:207], v[220:223], v[34:37]
	v_mfma_f32_16x16x32_bf16 v[22:25], v[180:183], v[228:231], v[22:25]
	v_mfma_f32_16x16x32_bf16 v[18:21], v[204:207], v[228:231], v[18:21]
	v_mfma_f32_16x16x32_bf16 v[6:9], v[180:183], v[236:239], v[6:9]
	v_mfma_f32_16x16x32_bf16 v[2:5], v[204:207], v[236:239], v[2:5]
	s_setprio 0
	s_barrier
	s_add_i32 s46, s46, 2
	s_add_u32 s58, s58, 0x100
	s_addc_u32 s59, s59, 0
	s_add_u32 s78, s78, 0x100
	s_addc_u32 s79, s79, 0
	s_cmpk_gt_u32 s46, 0x7d
.LBB0_36:
	s_add_u32 s18, s58, 0xffe00080
	s_addc_u32 s19, s59, -1
	s_add_i32 s47, 0, 0x10000
	s_cmpk_eq_i32 s46, 0x7c
	s_cselect_b32 s63, s45, s19
	s_cselect_b32 s62, s73, s18
	v_add_u32_e32 v160, s47, v143
	s_cselect_b32 s19, s37, s79
	s_cselect_b32 s18, s84, s78
	s_add_i32 s80, 0, 0x14000
	ds_read_b128 v[156:159], v160
	ds_read_b128 v[164:167], v160 offset:1024
	ds_read_b128 v[168:171], v160 offset:2048
	ds_read_b128 v[172:175], v160 offset:3072
	v_add_u32_e32 v160, s80, v143
	ds_read_b128 v[176:179], v160
	ds_read_b128 v[180:183], v160 offset:1024
	ds_read_b128 v[184:187], v160 offset:2048
	ds_read_b128 v[204:207], v160 offset:3072
	v_lshl_add_u64 v[160:161], s[58:59], 0, v[152:153]
	s_add_i32 m0, s5, 0xc000
	ds_read_b128 v[208:211], v163
	ds_read_b128 v[212:215], v163 offset:1024
	ds_read_b128 v[216:219], v163 offset:2048
	ds_read_b128 v[220:223], v163 offset:3072
	ds_read_b128 v[224:227], v163 offset:4096
	ds_read_b128 v[228:231], v163 offset:5120
	ds_read_b128 v[232:235], v163 offset:6144
	ds_read_b128 v[236:239], v163 offset:7168
	global_load_lds_dwordx4 v[160:161], off
	v_lshl_add_u64 v[160:161], s[58:59], 0, v[154:155]
	s_add_i32 m0, s5, 0xe000
	s_nop 0
	global_load_lds_dwordx4 v[160:161], off
	s_nop 0
	s_waitcnt vmcnt(8)
	s_waitcnt lgkmcnt(0)
	s_setprio 1
	s_barrier
; #define PG8_STAGE(bufoff, gbase, voff) do { _Pragma("unroll") for (int _i = 0; _i < 2; ++_i) \
;         __builtin_amdgcn_global_load_lds((const unsigned*)((const char*)(gbase) + (voff)[_i]), (PG8_LAS unsigned*)(lds + (bufoff) + ldsw + _i * 8192), 16, 0, 0); } while (0)
; #define PG8_LDA(dst, b, h) do { _Pragma("unroll") for (int m = 0; m < 4; ++m) _Pragma("unroll") for (int k = 0; k < 2; ++k) dst[m][k] = *(const PG8_LAS bf16x8*)(lds + PG8_SA(b, h) + aoff + m * 2048 + k * 1024); } while (0)
; #define PG8_MMA(ai, bj, At, Bt) do { __builtin_amdgcn_s_setprio(1); _Pragma("unroll") for (int m = 0; m < 4; ++m) _Pragma("unroll") for (int n = 0; n < 2; ++n) _Pragma("unroll") for (int k = 0; k < 2; ++k) \
;         acc[ai][bj][m][n] = __builtin_amdgcn_mfma_f32_16x16x32_bf16(Bt[n][k], At[m][k], acc[ai][bj][m][n], 0, 0, 0); __builtin_amdgcn_s_setprio(0); } while (0)
; #define PG8_WAIT_V(n) asm volatile("s_waitcnt vmcnt(" #n ")" ::: "memory")
; #define PG8_WAIT_L(n) asm volatile("s_waitcnt lgkmcnt(" #n ")" ::: "memory")
; #define PG8_BAR __builtin_amdgcn_s_barrier()
; #define PG8_SCHED __builtin_amdgcn_sched_barrier(0)
; template <class Epi, class Sched, bool ALIGN_EPI = false, bool SP2 = false>
; __device__ __forceinline__ void gemm_phase(PG8_LAS unsigned char* lds, const Gemm g, const Sched& S, const Epi& E) {
;     ...
;             PG8_WAIT_V(8); PG8_WAIT_L(0); PG8_BAR; PG8_MMA(0, 0, At, B0); PG8_MMA(0, 1, At, B1); PG8_BAR; PG8_SCHED;
;             PG8_LDA(At, 0, 1); PG8_STAGE(PG8_SB(0, 0), b2, voffB); PG8_STAGE(PG8_SB(0, 1), b2 + hstep, voffB); PG8_STAGE(PG8_SA(0, 0), a2, voffA);
;             PG8_WAIT_V(8); PG8_WAIT_L(0); PG8_BAR; PG8_MMA(1, 0, At, B0); PG8_MMA(1, 1, At, B1); PG8_BAR; PG8_SCHED;
	v_mfma_f32_16x16x32_bf16 v[126:129], v[156:159], v[208:211], v[126:129]
	v_mfma_f32_16x16x32_bf16 v[122:125], v[168:171], v[208:211], v[122:125]
	v_mfma_f32_16x16x32_bf16 v[110:113], v[156:159], v[216:219], v[110:113]
	v_mfma_f32_16x16x32_bf16 v[106:109], v[168:171], v[216:219], v[106:109]
	v_mfma_f32_16x16x32_bf16 v[94:97], v[156:159], v[224:227], v[94:97]
	v_mfma_f32_16x16x32_bf16 v[90:93], v[168:171], v[224:227], v[90:93]
	v_mfma_f32_16x16x32_bf16 v[78:81], v[156:159], v[232:235], v[78:81]
	v_mfma_f32_16x16x32_bf16 v[74:77], v[168:171], v[232:235], v[74:77]
	s_setprio 0
	s_setprio 1
	v_mfma_f32_16x16x32_bf16 v[126:129], v[164:167], v[212:215], v[126:129]
	v_mfma_f32_16x16x32_bf16 v[122:125], v[172:175], v[212:215], v[122:125]
	v_mfma_f32_16x16x32_bf16 v[110:113], v[164:167], v[220:223], v[110:113]
	v_mfma_f32_16x16x32_bf16 v[106:109], v[172:175], v[220:223], v[106:109]
	v_mfma_f32_16x16x32_bf16 v[94:97], v[164:167], v[228:231], v[94:97]
	v_mfma_f32_16x16x32_bf16 v[90:93], v[172:175], v[228:231], v[90:93]
	v_mfma_f32_16x16x32_bf16 v[78:81], v[164:167], v[236:239], v[78:81]
	v_mfma_f32_16x16x32_bf16 v[74:77], v[172:175], v[236:239], v[74:77]
	s_setprio 0
	s_setprio 1
	v_mfma_f32_16x16x32_bf16 v[118:121], v[176:179], v[208:211], v[118:121]
	v_mfma_f32_16x16x32_bf16 v[114:117], v[184:187], v[208:211], v[114:117]
	v_mfma_f32_16x16x32_bf16 v[102:105], v[176:179], v[216:219], v[102:105]
	v_mfma_f32_16x16x32_bf16 v[98:101], v[184:187], v[216:219], v[98:101]
	v_mfma_f32_16x16x32_bf16 v[86:89], v[176:179], v[224:227], v[86:89]
	v_mfma_f32_16x16x32_bf16 v[82:85], v[184:187], v[224:227], v[82:85]
	v_mfma_f32_16x16x32_bf16 v[70:73], v[176:179], v[232:235], v[70:73]
	v_mfma_f32_16x16x32_bf16 v[66:69], v[184:187], v[232:235], v[66:69]
	s_setprio 0
	s_setprio 1
	v_mfma_f32_16x16x32_bf16 v[118:121], v[180:183], v[212:215], v[118:121]
	v_mfma_f32_16x16x32_bf16 v[114:117], v[204:207], v[212:215], v[114:117]
	v_mfma_f32_16x16x32_bf16 v[102:105], v[180:183], v[220:223], v[102:105]
	v_mfma_f32_16x16x32_bf16 v[98:101], v[204:207], v[220:223], v[98:101]
	v_mfma_f32_16x16x32_bf16 v[86:89], v[180:183], v[228:231], v[86:89]
	v_mfma_f32_16x16x32_bf16 v[82:85], v[204:207], v[228:231], v[82:85]
	v_mfma_f32_16x16x32_bf16 v[70:73], v[180:183], v[236:239], v[70:73]
	v_mfma_f32_16x16x32_bf16 v[66:69], v[204:207], v[236:239], v[66:69]
	s_setprio 0
	s_barrier
	s_add_i32 s47, s47, s4
	v_lshl_add_u64 v[160:161], s[18:19], 0, v[148:149]
	s_mov_b32 m0, s47
	ds_read_b128 v[208:211], v163 offset:16384
	ds_read_b128 v[212:215], v163 offset:17408
	ds_read_b128 v[216:219], v163 offset:18432
	ds_read_b128 v[220:223], v163 offset:19456
	ds_read_b128 v[224:227], v163 offset:20480
	ds_read_b128 v[228:231], v163 offset:21504
	ds_read_b128 v[232:235], v163 offset:22528
	ds_read_b128 v[236:239], v163 offset:23552
	global_load_lds_dwordx4 v[160:161], off
	s_add_i32 m0, s47, 0x2000
	s_add_u32 s76, s18, 0x200000
	v_lshl_add_u64 v[240:241], s[18:19], 0, v[144:145]
	s_addc_u32 s77, s19, 0
	s_add_i32 s47, s80, s4
	global_load_lds_dwordx4 v[240:241], off
	v_lshl_add_u64 v[242:243], s[76:77], 0, v[148:149]
	s_mov_b32 m0, s47
	v_lshl_add_u64 v[244:245], s[62:63], 0, v[146:147]
	global_load_lds_dwordx4 v[242:243], off
	v_lshl_add_u64 v[242:243], s[76:77], 0, v[144:145]
	s_add_i32 m0, s47, 0x2000
	s_nop 0
	global_load_lds_dwordx4 v[242:243], off
	v_lshl_add_u64 v[242:243], s[62:63], 0, v[150:151]
	s_mov_b32 m0, s5
	s_nop 0
	global_load_lds_dwordx4 v[242:243], off
	s_mov_b32 m0, s30
	s_nop 0
	global_load_lds_dwordx4 v[244:245], off
	s_waitcnt vmcnt(8)
	s_waitcnt lgkmcnt(0)
	s_setprio 1
	s_barrier
	v_mfma_f32_16x16x32_bf16 v[62:65], v[156:159], v[208:211], v[62:65]
	v_mfma_f32_16x16x32_bf16 v[58:61], v[168:171], v[208:211], v[58:61]
	v_mfma_f32_16x16x32_bf16 v[46:49], v[156:159], v[216:219], v[46:49]
	v_mfma_f32_16x16x32_bf16 v[42:45], v[168:171], v[216:219], v[42:45]
	v_mfma_f32_16x16x32_bf16 v[30:33], v[156:159], v[224:227], v[30:33]
	v_mfma_f32_16x16x32_bf16 v[26:29], v[168:171], v[224:227], v[26:29]
	v_mfma_f32_16x16x32_bf16 v[14:17], v[156:159], v[232:235], v[14:17]
	v_mfma_f32_16x16x32_bf16 v[10:13], v[168:171], v[232:235], v[10:13]
	v_mfma_f32_16x16x32_bf16 v[62:65], v[164:167], v[212:215], v[62:65]
	v_mfma_f32_16x16x32_bf16 v[58:61], v[172:175], v[212:215], v[58:61]
	v_mfma_f32_16x16x32_bf16 v[46:49], v[164:167], v[220:223], v[46:49]
	v_mfma_f32_16x16x32_bf16 v[42:45], v[172:175], v[220:223], v[42:45]
	v_mfma_f32_16x16x32_bf16 v[30:33], v[164:167], v[228:231], v[30:33]
	v_mfma_f32_16x16x32_bf16 v[26:29], v[172:175], v[228:231], v[26:29]
	v_mfma_f32_16x16x32_bf16 v[14:17], v[164:167], v[236:239], v[14:17]
	v_mfma_f32_16x16x32_bf16 v[10:13], v[172:175], v[236:239], v[10:13]
	v_mfma_f32_16x16x32_bf16 v[54:57], v[176:179], v[208:211], v[54:57]
	v_mfma_f32_16x16x32_bf16 v[50:53], v[184:187], v[208:211], v[50:53]
	v_mfma_f32_16x16x32_bf16 v[38:41], v[176:179], v[216:219], v[38:41]
	v_mfma_f32_16x16x32_bf16 v[34:37], v[184:187], v[216:219], v[34:37]
	v_mfma_f32_16x16x32_bf16 v[22:25], v[176:179], v[224:227], v[22:25]
	v_mfma_f32_16x16x32_bf16 v[18:21], v[184:187], v[224:227], v[18:21]
	v_mfma_f32_16x16x32_bf16 v[6:9], v[176:179], v[232:235], v[6:9]
	v_mfma_f32_16x16x32_bf16 v[2:5], v[184:187], v[232:235], v[2:5]
	v_mfma_f32_16x16x32_bf16 v[54:57], v[180:183], v[212:215], v[54:57]
	v_mfma_f32_16x16x32_bf16 v[50:53], v[204:207], v[212:215], v[50:53]
	v_mfma_f32_16x16x32_bf16 v[38:41], v[180:183], v[220:223], v[38:41]
	v_mfma_f32_16x16x32_bf16 v[34:37], v[204:207], v[220:223], v[34:37]
	v_mfma_f32_16x16x32_bf16 v[22:25], v[180:183], v[228:231], v[22:25]
	v_mfma_f32_16x16x32_bf16 v[18:21], v[204:207], v[228:231], v[18:21]
	v_mfma_f32_16x16x32_bf16 v[6:9], v[180:183], v[236:239], v[6:9]
	v_mfma_f32_16x16x32_bf16 v[2:5], v[204:207], v[236:239], v[2:5]
	s_setprio 0
	s_barrier
; #define PG8_STAGE(bufoff, gbase, voff) do { _Pragma("unroll") for (int _i = 0; _i < 2; ++_i) \
;         __builtin_amdgcn_global_load_lds((const unsigned*)((const char*)(gbase) + (voff)[_i]), (PG8_LAS unsigned*)(lds + (bufoff) + ldsw + _i * 8192), 16, 0, 0); } while (0)
; #define PG8_LDA(dst, b, h) do { _Pragma("unroll") for (int m = 0; m < 4; ++m) _Pragma("unroll") for (int k = 0; k < 2; ++k) dst[m][k] = *(const PG8_LAS bf16x8*)(lds + PG8_SA(b, h) + aoff + m * 2048 + k * 1024); } while (0)
; #define PG8_LDB(dst, b, h) do { _Pragma("unroll") for (int n = 0; n < 2; ++n) _Pragma("unroll") for (int k = 0; k < 2; ++k) dst[n][k] = *(const PG8_LAS bf16x8*)(lds + PG8_SB(b, h) + boff + n * 2048 + k * 1024); } while (0)
; #define PG8_MMA(ai, bj, At, Bt) do { __builtin_amdgcn_s_setprio(1); _Pragma("unroll") for (int m = 0; m < 4; ++m) _Pragma("unroll") for (int n = 0; n < 2; ++n) _Pragma("unroll") for (int k = 0; k < 2; ++k) \
;         acc[ai][bj][m][n] = __builtin_amdgcn_mfma_f32_16x16x32_bf16(Bt[n][k], At[m][k], acc[ai][bj][m][n], 0, 0, 0); __builtin_amdgcn_s_setprio(0); } while (0)
; #define PG8_WAIT_V(n) asm volatile("s_waitcnt vmcnt(" #n ")" ::: "memory")
; #define PG8_WAIT_L(n) asm volatile("s_waitcnt lgkmcnt(" #n ")" ::: "memory")
; #define PG8_BAR __builtin_amdgcn_s_barrier()
; #define PG8_SCHED __builtin_amdgcn_sched_barrier(0)
; template <class Epi, class Sched, bool ALIGN_EPI = false, bool SP2 = false>
; __device__ __forceinline__ void gemm_phase(PG8_LAS unsigned char* lds, const Gemm g, const Sched& S, const Epi& E) {
;     ...
;             PG8_LDB(B0, 1, 0); PG8_LDB(B1, 1, 1); PG8_SCHED; PG8_LDA(At, 1, 0); PG8_STAGE(PG8_SA(0, 1), a2 + hstep, voffA);
;             PG8_WAIT_V(8); PG8_WAIT_L(0); PG8_BAR; PG8_MMA(0, 0, At, B0); PG8_MMA(0, 1, At, B1); PG8_BAR; PG8_SCHED;
	s_add_i32 s47, 0, 0x18000
	s_add_i32 s76, 0, 0x1c000
	v_add_u32_e32 v172, s47, v143
	v_add_u32_e32 v203, s76, v143
	ds_read_b128 v[156:159], v172
	ds_read_b128 v[164:167], v172 offset:1024
	ds_read_b128 v[168:171], v172 offset:2048
	ds_read_b128 v[172:175], v172 offset:3072
	ds_read_b128 v[176:179], v203
	ds_read_b128 v[180:183], v203 offset:1024
	ds_read_b128 v[184:187], v203 offset:2048
	ds_read_b128 v[204:207], v203 offset:3072
	s_add_u32 s62, s62, 0x200000
	s_addc_u32 s63, s63, 0
	s_mov_b32 m0, s57
	v_lshl_add_u64 v[246:247], s[62:63], 0, v[150:151]
	ds_read_b128 v[208:211], v163 offset:32768
	ds_read_b128 v[212:215], v163 offset:33792
	ds_read_b128 v[216:219], v163 offset:34816
	ds_read_b128 v[220:223], v163 offset:35840
	ds_read_b128 v[224:227], v163 offset:36864
	ds_read_b128 v[228:231], v163 offset:37888
	ds_read_b128 v[232:235], v163 offset:38912
	ds_read_b128 v[236:239], v163 offset:39936
	global_load_lds_dwordx4 v[246:247], off
	v_lshl_add_u64 v[246:247], s[62:63], 0, v[146:147]
	s_mov_b32 m0, s67
	s_nop 0
	global_load_lds_dwordx4 v[246:247], off
	s_waitcnt vmcnt(8)
	s_waitcnt lgkmcnt(0)
	s_setprio 1
	s_barrier
	v_mfma_f32_16x16x32_bf16 v[126:129], v[156:159], v[208:211], v[126:129]
	v_mfma_f32_16x16x32_bf16 v[122:125], v[168:171], v[208:211], v[122:125]
	v_mfma_f32_16x16x32_bf16 v[110:113], v[156:159], v[216:219], v[110:113]
	v_mfma_f32_16x16x32_bf16 v[106:109], v[168:171], v[216:219], v[106:109]
	v_mfma_f32_16x16x32_bf16 v[94:97], v[156:159], v[224:227], v[94:97]
	v_mfma_f32_16x16x32_bf16 v[90:93], v[168:171], v[224:227], v[90:93]
	v_mfma_f32_16x16x32_bf16 v[78:81], v[156:159], v[232:235], v[78:81]
	v_mfma_f32_16x16x32_bf16 v[74:77], v[168:171], v[232:235], v[74:77]
	s_setprio 0
	s_setprio 1
	v_mfma_f32_16x16x32_bf16 v[126:129], v[164:167], v[212:215], v[126:129]
	v_mfma_f32_16x16x32_bf16 v[122:125], v[172:175], v[212:215], v[122:125]
	v_mfma_f32_16x16x32_bf16 v[110:113], v[164:167], v[220:223], v[110:113]
	v_mfma_f32_16x16x32_bf16 v[106:109], v[172:175], v[220:223], v[106:109]
	v_mfma_f32_16x16x32_bf16 v[94:97], v[164:167], v[228:231], v[94:97]
	v_mfma_f32_16x16x32_bf16 v[90:93], v[172:175], v[228:231], v[90:93]
	v_mfma_f32_16x16x32_bf16 v[78:81], v[164:167], v[236:239], v[78:81]
	v_mfma_f32_16x16x32_bf16 v[74:77], v[172:175], v[236:239], v[74:77]
	s_setprio 0
	s_setprio 1
	v_mfma_f32_16x16x32_bf16 v[118:121], v[176:179], v[208:211], v[118:121]
	v_mfma_f32_16x16x32_bf16 v[114:117], v[184:187], v[208:211], v[114:117]
	v_mfma_f32_16x16x32_bf16 v[102:105], v[176:179], v[216:219], v[102:105]
	v_mfma_f32_16x16x32_bf16 v[98:101], v[184:187], v[216:219], v[98:101]
	v_mfma_f32_16x16x32_bf16 v[86:89], v[176:179], v[224:227], v[86:89]
	v_mfma_f32_16x16x32_bf16 v[82:85], v[184:187], v[224:227], v[82:85]
	v_mfma_f32_16x16x32_bf16 v[70:73], v[176:179], v[232:235], v[70:73]
	v_mfma_f32_16x16x32_bf16 v[66:69], v[184:187], v[232:235], v[66:69]
	s_setprio 0
	s_setprio 1
	v_mfma_f32_16x16x32_bf16 v[118:121], v[180:183], v[212:215], v[118:121]
	v_mfma_f32_16x16x32_bf16 v[114:117], v[204:207], v[212:215], v[114:117]
	v_mfma_f32_16x16x32_bf16 v[102:105], v[180:183], v[220:223], v[102:105]
	v_mfma_f32_16x16x32_bf16 v[98:101], v[204:207], v[220:223], v[98:101]
	v_mfma_f32_16x16x32_bf16 v[86:89], v[180:183], v[228:231], v[86:89]
	v_mfma_f32_16x16x32_bf16 v[82:85], v[204:207], v[228:231], v[82:85]
	v_mfma_f32_16x16x32_bf16 v[70:73], v[180:183], v[236:239], v[70:73]
	v_mfma_f32_16x16x32_bf16 v[66:69], v[204:207], v[236:239], v[66:69]
	s_setprio 0
	s_barrier
; #define PG8_STAGE(bufoff, gbase, voff) do { _Pragma("unroll") for (int _i = 0; _i < 2; ++_i) \
;         __builtin_amdgcn_global_load_lds((const unsigned*)((const char*)(gbase) + (voff)[_i]), (PG8_LAS unsigned*)(lds + (bufoff) + ldsw + _i * 8192), 16, 0, 0); } while (0)
; #define PG8_LDA(dst, b, h) do { _Pragma("unroll") for (int m = 0; m < 4; ++m) _Pragma("unroll") for (int k = 0; k < 2; ++k) dst[m][k] = *(const PG8_LAS bf16x8*)(lds + PG8_SA(b, h) + aoff + m * 2048 + k * 1024); } while (0)
; #define PG8_MMA(ai, bj, At, Bt) do { __builtin_amdgcn_s_setprio(1); _Pragma("unroll") for (int m = 0; m < 4; ++m) _Pragma("unroll") for (int n = 0; n < 2; ++n) _Pragma("unroll") for (int k = 0; k < 2; ++k) \
;         acc[ai][bj][m][n] = __builtin_amdgcn_mfma_f32_16x16x32_bf16(Bt[n][k], At[m][k], acc[ai][bj][m][n], 0, 0, 0); __builtin_amdgcn_s_setprio(0); } while (0)
; #define PG8_WAIT_V(n) asm volatile("s_waitcnt vmcnt(" #n ")" ::: "memory")
; #define PG8_WAIT_L(n) asm volatile("s_waitcnt lgkmcnt(" #n ")" ::: "memory")
; #define PG8_BAR __builtin_amdgcn_s_barrier()
; #define PG8_SCHED __builtin_amdgcn_sched_barrier(0)
; template <class Epi, class Sched, bool ALIGN_EPI = false, bool SP2 = false>
; __device__ __forceinline__ void gemm_phase(PG8_LAS unsigned char* lds, const Gemm g, const Sched& S, const Epi& E) {
;     ...
;             PG8_LDA(At, 1, 1); PG8_STAGE(PG8_SB(1, 0), b3, voffB); PG8_STAGE(PG8_SB(1, 1), b3 + hstep, voffB); PG8_STAGE(PG8_SA(1, 0), a3, voffA);
;             PG8_WAIT_V(8); PG8_WAIT_L(0); PG8_BAR; PG8_MMA(1, 0, At, B0); PG8_MMA(1, 1, At, B1); PG8_BAR; PG8_SCHED;
;     ...
;         if constexpr (ALIGN_EPI) { if (wr == 0) PG8_BAR; }
	s_add_i32 s47, s47, s4
	v_lshl_add_u64 v[160:161], v[160:161], 0, s[68:69]
	s_mov_b32 m0, s47
	ds_read_b128 v[208:211], v163 offset:49152
	ds_read_b128 v[212:215], v163 offset:50176
	ds_read_b128 v[216:219], v163 offset:51200
	ds_read_b128 v[220:223], v163 offset:52224
	ds_read_b128 v[224:227], v163 offset:53248
	ds_read_b128 v[228:231], v163 offset:54272
	ds_read_b128 v[232:235], v163 offset:55296
	ds_read_b128 v[236:239], v163 offset:56320
	global_load_lds_dwordx4 v[160:161], off
	s_add_i32 m0, s47, 0x2000
	s_add_u32 s18, s18, 0x200080
	v_lshl_add_u64 v[160:161], v[240:241], 0, s[68:69]
	s_addc_u32 s19, s19, 0
	s_add_i32 s47, s76, s4
	global_load_lds_dwordx4 v[160:161], off
	v_lshl_add_u64 v[160:161], s[18:19], 0, v[148:149]
	s_mov_b32 m0, s47
	s_nop 0
	global_load_lds_dwordx4 v[160:161], off
	v_lshl_add_u64 v[160:161], s[18:19], 0, v[144:145]
	s_add_i32 m0, s47, 0x2000
	s_nop 0
	global_load_lds_dwordx4 v[160:161], off
	v_lshl_add_u64 v[160:161], v[242:243], 0, s[68:69]
	s_mov_b32 m0, s1
	s_nop 0
	global_load_lds_dwordx4 v[160:161], off
	v_lshl_add_u64 v[160:161], v[244:245], 0, s[68:69]
	s_mov_b32 m0, s60
	s_nop 0
	global_load_lds_dwordx4 v[160:161], off
	s_nop 0
	s_waitcnt vmcnt(8)
	s_waitcnt lgkmcnt(0)
	s_setprio 1
	s_barrier
	v_mfma_f32_16x16x32_bf16 v[62:65], v[156:159], v[208:211], v[62:65]
	v_mfma_f32_16x16x32_bf16 v[58:61], v[168:171], v[208:211], v[58:61]
	v_mfma_f32_16x16x32_bf16 v[46:49], v[156:159], v[216:219], v[46:49]
	v_mfma_f32_16x16x32_bf16 v[42:45], v[168:171], v[216:219], v[42:45]
	v_mfma_f32_16x16x32_bf16 v[30:33], v[156:159], v[224:227], v[30:33]
	v_mfma_f32_16x16x32_bf16 v[26:29], v[168:171], v[224:227], v[26:29]
	v_mfma_f32_16x16x32_bf16 v[14:17], v[156:159], v[232:235], v[14:17]
	v_mfma_f32_16x16x32_bf16 v[10:13], v[168:171], v[232:235], v[10:13]
	v_mfma_f32_16x16x32_bf16 v[62:65], v[164:167], v[212:215], v[62:65]
	v_mfma_f32_16x16x32_bf16 v[58:61], v[172:175], v[212:215], v[58:61]
	v_mfma_f32_16x16x32_bf16 v[46:49], v[164:167], v[220:223], v[46:49]
	v_mfma_f32_16x16x32_bf16 v[42:45], v[172:175], v[220:223], v[42:45]
	v_mfma_f32_16x16x32_bf16 v[30:33], v[164:167], v[228:231], v[30:33]
	v_mfma_f32_16x16x32_bf16 v[26:29], v[172:175], v[228:231], v[26:29]
	v_mfma_f32_16x16x32_bf16 v[14:17], v[164:167], v[236:239], v[14:17]
	v_mfma_f32_16x16x32_bf16 v[10:13], v[172:175], v[236:239], v[10:13]
	v_mfma_f32_16x16x32_bf16 v[54:57], v[176:179], v[208:211], v[54:57]
	v_mfma_f32_16x16x32_bf16 v[50:53], v[184:187], v[208:211], v[50:53]
	v_mfma_f32_16x16x32_bf16 v[38:41], v[176:179], v[216:219], v[38:41]
	v_mfma_f32_16x16x32_bf16 v[34:37], v[184:187], v[216:219], v[34:37]
	v_mfma_f32_16x16x32_bf16 v[22:25], v[176:179], v[224:227], v[22:25]
	v_mfma_f32_16x16x32_bf16 v[18:21], v[184:187], v[224:227], v[18:21]
	v_mfma_f32_16x16x32_bf16 v[6:9], v[176:179], v[232:235], v[6:9]
	v_mfma_f32_16x16x32_bf16 v[2:5], v[184:187], v[232:235], v[2:5]
	v_mfma_f32_16x16x32_bf16 v[54:57], v[180:183], v[212:215], v[54:57]
	v_mfma_f32_16x16x32_bf16 v[50:53], v[204:207], v[212:215], v[50:53]
	v_mfma_f32_16x16x32_bf16 v[38:41], v[180:183], v[220:223], v[38:41]
	v_mfma_f32_16x16x32_bf16 v[34:37], v[204:207], v[220:223], v[34:37]
	v_mfma_f32_16x16x32_bf16 v[22:25], v[180:183], v[228:231], v[22:25]
	v_mfma_f32_16x16x32_bf16 v[18:21], v[204:207], v[228:231], v[18:21]
	v_mfma_f32_16x16x32_bf16 v[6:9], v[180:183], v[236:239], v[6:9]
	v_mfma_f32_16x16x32_bf16 v[2:5], v[204:207], v[236:239], v[2:5]
	s_setprio 0
	s_barrier
	s_add_i32 s46, s46, 2
	s_add_u32 s58, s58, 0x100
	s_addc_u32 s59, s59, 0
	s_add_u32 s78, s78, 0x100
	s_addc_u32 s79, s79, 0
	s_cmpk_gt_u32 s46, 0x7d
	s_cbranch_scc0 .LBB0_36
	s_mov_b32 s32, 1
	s_and_b64 vcc, exec, s[12:13]
	s_cbranch_vccz .LBB0_39
	s_barrier

; #define PG8_STAGE(bufoff, gbase, voff) do { _Pragma("unroll") for (int _i = 0; _i < 2; ++_i) \
;         __builtin_amdgcn_global_load_lds((const unsigned*)((const char*)(gbase) + (voff)[_i]), (PG8_LAS unsigned*)(lds + (bufoff) + ldsw + _i * 8192), 16, 0, 0); } while (0)
; #define PG8_WAIT_V(n) asm volatile("s_waitcnt vmcnt(" #n ")" ::: "memory")
; #define PG8_BAR __builtin_amdgcn_s_barrier()
; template <class Epi, class Sched, bool ALIGN_EPI = false, bool SP2 = false>
; __device__ __forceinline__ void gemm_phase(PG8_LAS unsigned char* lds, const Gemm g, const Sched& S, const Epi& E) {
;     ...
;     const int tid = tid_, wid = __builtin_amdgcn_readfirstlane(tid >> 6), lane = tid & 63, wr = wid >> 2, wc = wid & 3, fr = lane & 15, fq = lane >> 4;
;     const int K = g.K, nt = K / BK;
;     unsigned voffA[2], voffB[2];
; #pragma unroll
;     for (int i = 0; i < 2; ++i) { int R, C; stage_rc(tid * 16 + i * 8192, R, C); const int Rb = Epi::PERM ? ((R & ~31) + perm32(R & 31)) : R;
;         voffA[i] = (unsigned)(R * K + C) * 2u; voffB[i] = (unsigned)(Rb * K + C) * 2u; }
;     const size_t kstep = (size_t)(BK * 2);
;     const size_t hstep = (size_t)HALF * K * 2;
;     const size_t tstep = 2 * hstep;
;     const unsigned ldsw = (unsigned)wid * 1024u;
;     const int aoff = lds_byte(wr * 64 + fr, fq * 8), boff = lds_byte(wc * 32 + fr, fq * 8);
;     ...
;     Unit cur, nxt; int ui = 0;
;     if (!S.next(0, cur)) return;
;     f32x4 acc[2][2][4][2];
; #pragma unroll
;     for (int a = 0; a < 2; ++a)
; #pragma unroll
;         for (int b = 0; b < 2; ++b)
; #pragma unroll
;             for (int m = 0; m < 4; ++m)
; #pragma unroll
;                 for (int n = 0; n < 2; ++n) acc[a][b][m][n] = (f32x4){0.f, 0.f, 0.f, 0.f};
;     bf16x8 At[4][2], B0[2][2], B1[2][2];
;     const char* cA = (const char*)g.A + (size_t)cur.pm * tstep; const char* cB = (const char*)g.Bt + (size_t)cur.pn * tstep;
;     S.a_ready(cur);
;     if constexpr (SP2) {
;         PG8_STAGE(PG8_SB(0, 0), cB, voffB); PG8_STAGE(PG8_SB(0, 1), cB + hstep, voffB); PG8_STAGE(PG8_SA(0, 0), cA, voffA); PG8_STAGE(PG8_SA(0, 1), cA + hstep, voffA);
;         if (wr == 1) PG8_BAR;
;         PG8_WAIT_V(2); PG8_BAR;
;         PG8_STAGE(PG8_SB(1, 0), cB + kstep, voffB); PG8_STAGE(PG8_SA(1, 0), cA + kstep, voffA); PG8_STAGE(PG8_SB(1, 1), cB + hstep + kstep, voffB);
;         PG8_WAIT_V(6); PG8_BAR;
.LBB0_66:
	v_bfe_u32 v18, v16, 4, 2
	v_and_b32_e32 v17, 15, v16
	v_lshlrev_b32_e32 v19, 4, v18
	v_lshlrev_b32_e32 v16, 2, v16
	v_lshl_or_b32 v1, s19, 6, v17
	v_lshl_or_b32 v17, v17, 6, v19
	s_lshl_b32 s19, s19, 13
	v_and_b32_e32 v16, 32, v16
	s_lshl_b32 s5, s5, 5
	v_bitop3_b32 v19, v17, s19, v16 bitop3:0xde
	s_and_b32 s19, s5, 0x60
	s_lshl_b32 s5, s19, 7
	s_add_i32 m0, s62, 0x18000
	v_lshl_add_u64 v[8:9], v[8:9], 0, s[68:69]
	v_bitop3_b32 v143, v17, s5, v16 bitop3:0xde
	s_waitcnt vmcnt(2)
	s_barrier
	global_load_lds_dwordx4 v[8:9], off
	v_lshl_add_u64 v[6:7], v[6:7], 0, s[68:69]
	s_add_i32 m0, s62, 0x1a000
	s_add_i32 s5, s62, 0x8000
	s_add_i32 s57, s62, 0xa000
	global_load_lds_dwordx4 v[6:7], off
	v_lshl_add_u64 v[2:3], v[2:3], 0, s[68:69]
	s_mov_b32 m0, s5
	s_add_u32 s36, s58, 0x80080
	global_load_lds_dwordx4 v[2:3], off
	v_lshl_add_u64 v[2:3], v[4:5], 0, s[68:69]
	s_mov_b32 m0, s57
	s_addc_u32 s37, s59, 0
	global_load_lds_dwordx4 v[2:3], off
	s_add_i32 m0, s62, 0x1c000
	v_lshl_add_u64 v[2:3], s[36:37], 0, v[148:149]
	global_load_lds_dwordx4 v[2:3], off
	v_lshl_add_u64 v[2:3], s[36:37], 0, v[144:145]
	s_add_i32 m0, s62, 0x1e000
	s_cmpk_lt_u32 s18, 0x100
	global_load_lds_dwordx4 v[2:3], off
	v_lshlrev_b32_e32 v2, 5, v18
	v_mov_b32_e32 v3, v0
	v_lshl_add_u64 v[152:153], s[10:11], 0, v[2:3]
	v_lshlrev_b32_e32 v2, 15, v14
	v_and_b32_e32 v2, 0xffff0000, v2
	v_lshl_add_u32 v2, v13, 12, v2
	v_and_b32_e32 v3, 1, v14
	v_lshl_or_b32 v2, v3, 6, v2
	v_lshl_add_u32 v154, v15, 1, v2
	v_lshlrev_b32_e32 v2, 15, v10
	v_and_b32_e32 v2, 0xffff0000, v2
	s_waitcnt vmcnt(6)
	v_lshl_add_u32 v2, v11, 12, v2
	v_and_b32_e32 v3, 1, v10
	v_lshl_or_b32 v160, v18, 3, s19
	v_lshl_or_b32 v2, v3, 6, v2
	v_readlane_b32 s18, v253, 54
	s_cselect_b64 s[42:43], -1, 0
	v_mov_b32_e32 v155, v0
	v_lshl_add_u32 v156, v12, 1, v2
	v_mov_b32_e32 v157, v0
	s_mov_b32 s30, 0
	v_add_u32_e32 v161, 0, v19
	v_readlane_b32 s28, v253, 16
	s_mov_b32 s34, s18
	s_barrier
	v_readlane_b32 s19, v253, 55
	s_mov_b32 s32, 0
	s_branch .LBB0_69

; #define PG8_STAGE(bufoff, gbase, voff) do { _Pragma("unroll") for (int _i = 0; _i < 2; ++_i) \
;         __builtin_amdgcn_global_load_lds((const unsigned*)((const char*)(gbase) + (voff)[_i]), (PG8_LAS unsigned*)(lds + (bufoff) + ldsw + _i * 8192), 16, 0, 0); } while (0)
; #define PG8_LDA(dst, b, h) do { _Pragma("unroll") for (int m = 0; m < 4; ++m) _Pragma("unroll") for (int k = 0; k < 2; ++k) dst[m][k] = *(const PG8_LAS bf16x8*)(lds + PG8_SA(b, h) + aoff + m * 2048 + k * 1024); } while (0)
; #define PG8_LDB(dst, b, h) do { _Pragma("unroll") for (int n = 0; n < 2; ++n) _Pragma("unroll") for (int k = 0; k < 2; ++k) dst[n][k] = *(const PG8_LAS bf16x8*)(lds + PG8_SB(b, h) + boff + n * 2048 + k * 1024); } while (0)
; #define PG8_SCHED __builtin_amdgcn_sched_barrier(0)
; template <class Epi, class Sched, bool ALIGN_EPI = false, bool SP2 = false>
; __device__ __forceinline__ void gemm_phase(PG8_LAS unsigned char* lds, const Gemm g, const Sched& S, const Epi& E) {
;     ...
;         const bool has_next = S.next(ui + 1, nxt);
;         const char* nA = has_next ? (const char*)g.A + (size_t)nxt.pm * tstep : cA; const char* nB = has_next ? (const char*)g.Bt + (size_t)nxt.pn * tstep : cB;
;         for (int t = 0; t < nt; t += 2) {
;             const bool last = (t == nt - 2);
;             const char* a1 = cA + (size_t)(t + 1) * kstep;
;             const char* a2 = last ? nA : cA + (size_t)(t + 2) * kstep; const char* b2 = last ? nB : cB + (size_t)(t + 2) * kstep;
;             const char* a3 = a2 + kstep; const char* b3 = b2 + kstep;
;             if (last && has_next) S.a_ready(nxt);
;             if constexpr (SP2) {
;             PG8_LDB(B0, 0, 0); PG8_LDB(B1, 0, 1); PG8_SCHED; PG8_LDA(At, 0, 0); PG8_STAGE(PG8_SA(1, 1), a1 + hstep, voffA);
.LBB0_75:
	s_ashr_i32 s97, s96, 31
	s_lshl_b64 s[18:19], s[96:97], 20
	s_add_u32 s94, s70, s18
	s_addc_u32 s95, s71, s19
	s_and_b64 s[18:19], s[40:41], exec
	s_cselect_b32 s60, s95, s1
	s_cselect_b32 s73, s94, s0
	s_ashr_i32 s45, s44, 31
	s_lshl_b64 s[18:19], s[44:45], 20
	s_add_u32 s36, s82, s18
	s_addc_u32 s37, s83, s19
	s_and_b64 s[18:19], s[40:41], exec
	s_cselect_b32 s45, s37, s59
	s_cselect_b32 s84, s36, s58
	s_add_u32 s0, s0, 0x80080
	s_addc_u32 s1, s1, 0
	s_add_u32 s78, s58, 0x100
	s_addc_u32 s79, s59, 0
	s_mov_b32 s46, -2
	s_add_u32 s18, s0, 0xfff80080
	s_addc_u32 s19, s1, -1
	s_add_i32 s47, 0, 0x10000
	s_cmp_eq_u32 s46, 28
	s_cselect_b32 s59, s60, s19
	s_cselect_b32 s58, s73, s18
	v_add_u32_e32 v158, s47, v143
	s_cselect_b32 s19, s45, s79
	s_cselect_b32 s18, s84, s78
	s_add_i32 s80, 0, 0x14000
	ds_read_b128 v[162:165], v158
	ds_read_b128 v[166:169], v158 offset:1024
	ds_read_b128 v[170:173], v158 offset:2048
	ds_read_b128 v[174:177], v158 offset:3072
	v_add_u32_e32 v158, s80, v143
	ds_read_b128 v[178:181], v158
	ds_read_b128 v[182:185], v158 offset:1024
	ds_read_b128 v[204:207], v158 offset:2048
	ds_read_b128 v[208:211], v158 offset:3072
	v_lshl_add_u64 v[158:159], s[0:1], 0, v[154:155]
	s_add_i32 m0, s62, 0xc000
	ds_read_b128 v[212:215], v161
	ds_read_b128 v[216:219], v161 offset:1024
	ds_read_b128 v[220:223], v161 offset:2048
	ds_read_b128 v[224:227], v161 offset:3072
	ds_read_b128 v[228:231], v161 offset:4096
	ds_read_b128 v[232:235], v161 offset:5120
	ds_read_b128 v[236:239], v161 offset:6144
	ds_read_b128 v[240:243], v161 offset:7168
	global_load_lds_dwordx4 v[158:159], off
	v_lshl_add_u64 v[158:159], s[0:1], 0, v[156:157]
	s_add_i32 m0, s62, 0xe000
	s_nop 0
	global_load_lds_dwordx4 v[158:159], off
	s_nop 0
	s_cmp_eq_u32 s32, 0
	s_cbranch_scc1 .Lpw3_f
	s_waitcnt vmcnt(24)
	s_branch .Lpw3_j

; #define PG8_STAGE(bufoff, gbase, voff) do { _Pragma("unroll") for (int _i = 0; _i < 2; ++_i) \
;         __builtin_amdgcn_global_load_lds((const unsigned*)((const char*)(gbase) + (voff)[_i]), (PG8_LAS unsigned*)(lds + (bufoff) + ldsw + _i * 8192), 16, 0, 0); } while (0)
; #define PG8_LDA(dst, b, h) do { _Pragma("unroll") for (int m = 0; m < 4; ++m) _Pragma("unroll") for (int k = 0; k < 2; ++k) dst[m][k] = *(const PG8_LAS bf16x8*)(lds + PG8_SA(b, h) + aoff + m * 2048 + k * 1024); } while (0)
; #define PG8_LDB(dst, b, h) do { _Pragma("unroll") for (int n = 0; n < 2; ++n) _Pragma("unroll") for (int k = 0; k < 2; ++k) dst[n][k] = *(const PG8_LAS bf16x8*)(lds + PG8_SB(b, h) + boff + n * 2048 + k * 1024); } while (0)
; #define PG8_MMA(ai, bj, At, Bt) do { __builtin_amdgcn_s_setprio(1); _Pragma("unroll") for (int m = 0; m < 4; ++m) _Pragma("unroll") for (int n = 0; n < 2; ++n) _Pragma("unroll") for (int k = 0; k < 2; ++k) \
;         acc[ai][bj][m][n] = __builtin_amdgcn_mfma_f32_16x16x32_bf16(Bt[n][k], At[m][k], acc[ai][bj][m][n], 0, 0, 0); __builtin_amdgcn_s_setprio(0); } while (0)
; #define PG8_WAIT_V(n) asm volatile("s_waitcnt vmcnt(" #n ")" ::: "memory")
; #define PG8_WAIT_L(n) asm volatile("s_waitcnt lgkmcnt(" #n ")" ::: "memory")
; #define PG8_BAR __builtin_amdgcn_s_barrier()
; #define PG8_SCHED __builtin_amdgcn_sched_barrier(0)
; template <class Epi, class Sched, bool ALIGN_EPI = false, bool SP2 = false>
; __device__ __forceinline__ void gemm_phase(PG8_LAS unsigned char* lds, const Gemm g, const Sched& S, const Epi& E) {
;     ...
;             PG8_LDB(B0, 0, 0); PG8_LDB(B1, 0, 1); PG8_SCHED; PG8_LDA(At, 0, 0); PG8_STAGE(PG8_SA(1, 1), a1 + hstep, voffA);
;             PG8_WAIT_V(8); PG8_WAIT_L(0); PG8_BAR; PG8_MMA(0, 0, At, B0); PG8_MMA(0, 1, At, B1); PG8_BAR; PG8_SCHED;
;             PG8_LDA(At, 0, 1); PG8_STAGE(PG8_SB(0, 0), b2, voffB); PG8_STAGE(PG8_SB(0, 1), b2 + hstep, voffB); PG8_STAGE(PG8_SA(0, 0), a2, voffA);
;             PG8_WAIT_V(8); PG8_WAIT_L(0); PG8_BAR; PG8_MMA(1, 0, At, B0); PG8_MMA(1, 1, At, B1); PG8_BAR; PG8_SCHED;
.Lpw3_j:
	s_nop 0
	s_waitcnt lgkmcnt(0)
	s_setprio 1
	s_barrier
	v_mfma_f32_16x16x32_bf16 v[126:129], v[162:165], v[212:215], 0
	v_mfma_f32_16x16x32_bf16 v[122:125], v[170:173], v[212:215], 0
	v_mfma_f32_16x16x32_bf16 v[110:113], v[162:165], v[220:223], 0
	v_mfma_f32_16x16x32_bf16 v[106:109], v[170:173], v[220:223], 0
	v_mfma_f32_16x16x32_bf16 v[94:97], v[162:165], v[228:231], 0
	v_mfma_f32_16x16x32_bf16 v[90:93], v[170:173], v[228:231], 0
	v_mfma_f32_16x16x32_bf16 v[78:81], v[162:165], v[236:239], 0
	v_mfma_f32_16x16x32_bf16 v[74:77], v[170:173], v[236:239], 0
	s_setprio 0
	s_setprio 1
	v_mfma_f32_16x16x32_bf16 v[126:129], v[166:169], v[216:219], v[126:129]
	v_mfma_f32_16x16x32_bf16 v[122:125], v[174:177], v[216:219], v[122:125]
	v_mfma_f32_16x16x32_bf16 v[110:113], v[166:169], v[224:227], v[110:113]
	v_mfma_f32_16x16x32_bf16 v[106:109], v[174:177], v[224:227], v[106:109]
	v_mfma_f32_16x16x32_bf16 v[94:97], v[166:169], v[232:235], v[94:97]
	v_mfma_f32_16x16x32_bf16 v[90:93], v[174:177], v[232:235], v[90:93]
	v_mfma_f32_16x16x32_bf16 v[78:81], v[166:169], v[240:243], v[78:81]
	v_mfma_f32_16x16x32_bf16 v[74:77], v[174:177], v[240:243], v[74:77]
	s_setprio 0
	s_setprio 1
	v_mfma_f32_16x16x32_bf16 v[118:121], v[178:181], v[212:215], 0
	v_mfma_f32_16x16x32_bf16 v[114:117], v[204:207], v[212:215], 0
	v_mfma_f32_16x16x32_bf16 v[102:105], v[178:181], v[220:223], 0
	v_mfma_f32_16x16x32_bf16 v[98:101], v[204:207], v[220:223], 0
	v_mfma_f32_16x16x32_bf16 v[86:89], v[178:181], v[228:231], 0
	v_mfma_f32_16x16x32_bf16 v[82:85], v[204:207], v[228:231], 0
	v_mfma_f32_16x16x32_bf16 v[70:73], v[178:181], v[236:239], 0
	v_mfma_f32_16x16x32_bf16 v[66:69], v[204:207], v[236:239], 0
	s_setprio 0
	s_setprio 1
	v_mfma_f32_16x16x32_bf16 v[118:121], v[182:185], v[216:219], v[118:121]
	v_mfma_f32_16x16x32_bf16 v[114:117], v[208:211], v[216:219], v[114:117]
	v_mfma_f32_16x16x32_bf16 v[102:105], v[182:185], v[224:227], v[102:105]
	v_mfma_f32_16x16x32_bf16 v[98:101], v[208:211], v[224:227], v[98:101]
	v_mfma_f32_16x16x32_bf16 v[86:89], v[182:185], v[232:235], v[86:89]
	v_mfma_f32_16x16x32_bf16 v[82:85], v[208:211], v[232:235], v[82:85]
	v_mfma_f32_16x16x32_bf16 v[70:73], v[182:185], v[240:243], v[70:73]
	v_mfma_f32_16x16x32_bf16 v[66:69], v[208:211], v[240:243], v[66:69]
	s_setprio 0
	s_barrier
	s_add_i32 s47, s47, s54
	v_lshl_add_u64 v[158:159], s[18:19], 0, v[148:149]
	s_mov_b32 m0, s47
	ds_read_b128 v[212:215], v161 offset:16384
	ds_read_b128 v[216:219], v161 offset:17408
	ds_read_b128 v[220:223], v161 offset:18432
	ds_read_b128 v[224:227], v161 offset:19456
	ds_read_b128 v[228:231], v161 offset:20480
	ds_read_b128 v[232:235], v161 offset:21504
	ds_read_b128 v[236:239], v161 offset:22528
	ds_read_b128 v[240:243], v161 offset:23552
	global_load_lds_dwordx4 v[158:159], off
	s_add_i32 m0, s47, 0x2000
	s_add_u32 s76, s18, 0x80000
	v_lshl_add_u64 v[186:187], s[18:19], 0, v[144:145]
	s_addc_u32 s77, s19, 0
	s_add_i32 s47, s80, s54
	global_load_lds_dwordx4 v[186:187], off
	v_lshl_add_u64 v[244:245], s[76:77], 0, v[148:149]
	s_mov_b32 m0, s47
	v_lshl_add_u64 v[246:247], s[58:59], 0, v[146:147]
	global_load_lds_dwordx4 v[244:245], off
	v_lshl_add_u64 v[244:245], s[76:77], 0, v[144:145]
	s_add_i32 m0, s47, 0x2000
	s_nop 0
	global_load_lds_dwordx4 v[244:245], off
	v_lshl_add_u64 v[244:245], s[58:59], 0, v[150:151]
	s_mov_b32 m0, s62
	s_nop 0
	global_load_lds_dwordx4 v[244:245], off
	s_mov_b32 m0, s63
	s_nop 0
	global_load_lds_dwordx4 v[246:247], off
	s_cmp_eq_u32 s32, 0
	s_cbranch_scc1 .Lpw4_f
	s_waitcnt vmcnt(24)
	s_branch .Lpw4_j

; #define PG8_STAGE(bufoff, gbase, voff) do { _Pragma("unroll") for (int _i = 0; _i < 2; ++_i) \
;         __builtin_amdgcn_global_load_lds((const unsigned*)((const char*)(gbase) + (voff)[_i]), (PG8_LAS unsigned*)(lds + (bufoff) + ldsw + _i * 8192), 16, 0, 0); } while (0)
; #define PG8_LDA(dst, b, h) do { _Pragma("unroll") for (int m = 0; m < 4; ++m) _Pragma("unroll") for (int k = 0; k < 2; ++k) dst[m][k] = *(const PG8_LAS bf16x8*)(lds + PG8_SA(b, h) + aoff + m * 2048 + k * 1024); } while (0)
; #define PG8_LDB(dst, b, h) do { _Pragma("unroll") for (int n = 0; n < 2; ++n) _Pragma("unroll") for (int k = 0; k < 2; ++k) dst[n][k] = *(const PG8_LAS bf16x8*)(lds + PG8_SB(b, h) + boff + n * 2048 + k * 1024); } while (0)
; #define PG8_MMA(ai, bj, At, Bt) do { __builtin_amdgcn_s_setprio(1); _Pragma("unroll") for (int m = 0; m < 4; ++m) _Pragma("unroll") for (int n = 0; n < 2; ++n) _Pragma("unroll") for (int k = 0; k < 2; ++k) \
;         acc[ai][bj][m][n] = __builtin_amdgcn_mfma_f32_16x16x32_bf16(Bt[n][k], At[m][k], acc[ai][bj][m][n], 0, 0, 0); __builtin_amdgcn_s_setprio(0); } while (0)
; #define PG8_WAIT_V(n) asm volatile("s_waitcnt vmcnt(" #n ")" ::: "memory")
; #define PG8_WAIT_L(n) asm volatile("s_waitcnt lgkmcnt(" #n ")" ::: "memory")
; #define PG8_BAR __builtin_amdgcn_s_barrier()
; #define PG8_SCHED __builtin_amdgcn_sched_barrier(0)
; template <class Epi, class Sched, bool ALIGN_EPI = false, bool SP2 = false>
; __device__ __forceinline__ void gemm_phase(PG8_LAS unsigned char* lds, const Gemm g, const Sched& S, const Epi& E) {
;     ...
;             PG8_WAIT_V(8); PG8_WAIT_L(0); PG8_BAR; PG8_MMA(1, 0, At, B0); PG8_MMA(1, 1, At, B1); PG8_BAR; PG8_SCHED;
;             PG8_LDB(B0, 1, 0); PG8_LDB(B1, 1, 1); PG8_SCHED; PG8_LDA(At, 1, 0); PG8_STAGE(PG8_SA(0, 1), a2 + hstep, voffA);
;             PG8_WAIT_V(8); PG8_WAIT_L(0); PG8_BAR; PG8_MMA(0, 0, At, B0); PG8_MMA(0, 1, At, B1); PG8_BAR; PG8_SCHED;
.Lpw4_j:
	s_waitcnt lgkmcnt(0)
	s_setprio 1
	s_barrier
	v_mfma_f32_16x16x32_bf16 v[62:65], v[162:165], v[212:215], 0
	v_mfma_f32_16x16x32_bf16 v[58:61], v[170:173], v[212:215], 0
	v_mfma_f32_16x16x32_bf16 v[46:49], v[162:165], v[220:223], 0
	v_mfma_f32_16x16x32_bf16 v[42:45], v[170:173], v[220:223], 0
	v_mfma_f32_16x16x32_bf16 v[30:33], v[162:165], v[228:231], 0
	v_mfma_f32_16x16x32_bf16 v[26:29], v[170:173], v[228:231], 0
	v_mfma_f32_16x16x32_bf16 v[14:17], v[162:165], v[236:239], 0
	v_mfma_f32_16x16x32_bf16 v[10:13], v[170:173], v[236:239], 0
	v_mfma_f32_16x16x32_bf16 v[62:65], v[166:169], v[216:219], v[62:65]
	v_mfma_f32_16x16x32_bf16 v[58:61], v[174:177], v[216:219], v[58:61]
	v_mfma_f32_16x16x32_bf16 v[46:49], v[166:169], v[224:227], v[46:49]
	v_mfma_f32_16x16x32_bf16 v[42:45], v[174:177], v[224:227], v[42:45]
	v_mfma_f32_16x16x32_bf16 v[30:33], v[166:169], v[232:235], v[30:33]
	v_mfma_f32_16x16x32_bf16 v[26:29], v[174:177], v[232:235], v[26:29]
	v_mfma_f32_16x16x32_bf16 v[14:17], v[166:169], v[240:243], v[14:17]
	v_mfma_f32_16x16x32_bf16 v[10:13], v[174:177], v[240:243], v[10:13]
	v_mfma_f32_16x16x32_bf16 v[54:57], v[178:181], v[212:215], 0
	v_mfma_f32_16x16x32_bf16 v[50:53], v[204:207], v[212:215], 0
	v_mfma_f32_16x16x32_bf16 v[38:41], v[178:181], v[220:223], 0
	v_mfma_f32_16x16x32_bf16 v[34:37], v[204:207], v[220:223], 0
	v_mfma_f32_16x16x32_bf16 v[22:25], v[178:181], v[228:231], 0
	v_mfma_f32_16x16x32_bf16 v[18:21], v[204:207], v[228:231], 0
	v_mfma_f32_16x16x32_bf16 v[6:9], v[178:181], v[236:239], 0
	v_mfma_f32_16x16x32_bf16 v[2:5], v[204:207], v[236:239], 0
	v_mfma_f32_16x16x32_bf16 v[54:57], v[182:185], v[216:219], v[54:57]
	v_mfma_f32_16x16x32_bf16 v[50:53], v[208:211], v[216:219], v[50:53]
	v_mfma_f32_16x16x32_bf16 v[38:41], v[182:185], v[224:227], v[38:41]
	v_mfma_f32_16x16x32_bf16 v[34:37], v[208:211], v[224:227], v[34:37]
	v_mfma_f32_16x16x32_bf16 v[22:25], v[182:185], v[232:235], v[22:25]
	v_mfma_f32_16x16x32_bf16 v[18:21], v[208:211], v[232:235], v[18:21]
	v_mfma_f32_16x16x32_bf16 v[6:9], v[182:185], v[240:243], v[6:9]
	v_mfma_f32_16x16x32_bf16 v[2:5], v[208:211], v[240:243], v[2:5]
	s_setprio 0
	s_barrier
	s_add_i32 s47, 0, 0x18000
	s_add_i32 s76, 0, 0x1c000
	v_add_u32_e32 v174, s47, v143
	v_add_u32_e32 v203, s76, v143
	ds_read_b128 v[162:165], v174
	ds_read_b128 v[166:169], v174 offset:1024
	ds_read_b128 v[170:173], v174 offset:2048
	ds_read_b128 v[174:177], v174 offset:3072
	ds_read_b128 v[178:181], v203
	ds_read_b128 v[182:185], v203 offset:1024
	ds_read_b128 v[204:207], v203 offset:2048
	ds_read_b128 v[208:211], v203 offset:3072
	s_add_u32 s58, s58, 0x80000
	s_addc_u32 s59, s59, 0
	s_mov_b32 m0, s67
	v_lshl_add_u64 v[248:249], s[58:59], 0, v[150:151]
	ds_read_b128 v[212:215], v161 offset:32768
	ds_read_b128 v[216:219], v161 offset:33792
	ds_read_b128 v[220:223], v161 offset:34816
	ds_read_b128 v[224:227], v161 offset:35840
	ds_read_b128 v[228:231], v161 offset:36864
	ds_read_b128 v[232:235], v161 offset:37888
	ds_read_b128 v[236:239], v161 offset:38912
	ds_read_b128 v[240:243], v161 offset:39936
	global_load_lds_dwordx4 v[248:249], off
	v_lshl_add_u64 v[248:249], s[58:59], 0, v[146:147]
	s_mov_b32 m0, s4
	s_nop 0
	global_load_lds_dwordx4 v[248:249], off
	s_waitcnt vmcnt(8)
	s_waitcnt lgkmcnt(0)
	s_setprio 1
	s_barrier
	v_mfma_f32_16x16x32_bf16 v[126:129], v[162:165], v[212:215], v[126:129]
	v_mfma_f32_16x16x32_bf16 v[122:125], v[170:173], v[212:215], v[122:125]
	v_mfma_f32_16x16x32_bf16 v[110:113], v[162:165], v[220:223], v[110:113]
	v_mfma_f32_16x16x32_bf16 v[106:109], v[170:173], v[220:223], v[106:109]
	v_mfma_f32_16x16x32_bf16 v[94:97], v[162:165], v[228:231], v[94:97]
	v_mfma_f32_16x16x32_bf16 v[90:93], v[170:173], v[228:231], v[90:93]
	v_mfma_f32_16x16x32_bf16 v[78:81], v[162:165], v[236:239], v[78:81]
	v_mfma_f32_16x16x32_bf16 v[74:77], v[170:173], v[236:239], v[74:77]
	s_setprio 0
	s_setprio 1
	v_mfma_f32_16x16x32_bf16 v[126:129], v[166:169], v[216:219], v[126:129]
	v_mfma_f32_16x16x32_bf16 v[122:125], v[174:177], v[216:219], v[122:125]
	v_mfma_f32_16x16x32_bf16 v[110:113], v[166:169], v[224:227], v[110:113]
	v_mfma_f32_16x16x32_bf16 v[106:109], v[174:177], v[224:227], v[106:109]
	v_mfma_f32_16x16x32_bf16 v[94:97], v[166:169], v[232:235], v[94:97]
	v_mfma_f32_16x16x32_bf16 v[90:93], v[174:177], v[232:235], v[90:93]
	v_mfma_f32_16x16x32_bf16 v[78:81], v[166:169], v[240:243], v[78:81]
	v_mfma_f32_16x16x32_bf16 v[74:77], v[174:177], v[240:243], v[74:77]
	s_setprio 0
	s_setprio 1
	v_mfma_f32_16x16x32_bf16 v[118:121], v[178:181], v[212:215], v[118:121]
	v_mfma_f32_16x16x32_bf16 v[114:117], v[204:207], v[212:215], v[114:117]
	v_mfma_f32_16x16x32_bf16 v[102:105], v[178:181], v[220:223], v[102:105]
	v_mfma_f32_16x16x32_bf16 v[98:101], v[204:207], v[220:223], v[98:101]
	v_mfma_f32_16x16x32_bf16 v[86:89], v[178:181], v[228:231], v[86:89]
	v_mfma_f32_16x16x32_bf16 v[82:85], v[204:207], v[228:231], v[82:85]
	v_mfma_f32_16x16x32_bf16 v[70:73], v[178:181], v[236:239], v[70:73]
	v_mfma_f32_16x16x32_bf16 v[66:69], v[204:207], v[236:239], v[66:69]
	s_setprio 0
	s_setprio 1
	v_mfma_f32_16x16x32_bf16 v[118:121], v[182:185], v[216:219], v[118:121]
	v_mfma_f32_16x16x32_bf16 v[114:117], v[208:211], v[216:219], v[114:117]
	v_mfma_f32_16x16x32_bf16 v[102:105], v[182:185], v[224:227], v[102:105]
	v_mfma_f32_16x16x32_bf16 v[98:101], v[208:211], v[224:227], v[98:101]
	v_mfma_f32_16x16x32_bf16 v[86:89], v[182:185], v[232:235], v[86:89]
	v_mfma_f32_16x16x32_bf16 v[82:85], v[208:211], v[232:235], v[82:85]
	v_mfma_f32_16x16x32_bf16 v[70:73], v[182:185], v[240:243], v[70:73]
	v_mfma_f32_16x16x32_bf16 v[66:69], v[208:211], v[240:243], v[66:69]
	s_setprio 0
	s_barrier
; #define PG8_STAGE(bufoff, gbase, voff) do { _Pragma("unroll") for (int _i = 0; _i < 2; ++_i) \
;         __builtin_amdgcn_global_load_lds((const unsigned*)((const char*)(gbase) + (voff)[_i]), (PG8_LAS unsigned*)(lds + (bufoff) + ldsw + _i * 8192), 16, 0, 0); } while (0)
; #define PG8_LDA(dst, b, h) do { _Pragma("unroll") for (int m = 0; m < 4; ++m) _Pragma("unroll") for (int k = 0; k < 2; ++k) dst[m][k] = *(const PG8_LAS bf16x8*)(lds + PG8_SA(b, h) + aoff + m * 2048 + k * 1024); } while (0)
; #define PG8_LDB(dst, b, h) do { _Pragma("unroll") for (int n = 0; n < 2; ++n) _Pragma("unroll") for (int k = 0; k < 2; ++k) dst[n][k] = *(const PG8_LAS bf16x8*)(lds + PG8_SB(b, h) + boff + n * 2048 + k * 1024); } while (0)
; #define PG8_MMA(ai, bj, At, Bt) do { __builtin_amdgcn_s_setprio(1); _Pragma("unroll") for (int m = 0; m < 4; ++m) _Pragma("unroll") for (int n = 0; n < 2; ++n) _Pragma("unroll") for (int k = 0; k < 2; ++k) \
;         acc[ai][bj][m][n] = __builtin_amdgcn_mfma_f32_16x16x32_bf16(Bt[n][k], At[m][k], acc[ai][bj][m][n], 0, 0, 0); __builtin_amdgcn_s_setprio(0); } while (0)
; #define PG8_WAIT_V(n) asm volatile("s_waitcnt vmcnt(" #n ")" ::: "memory")
; #define PG8_WAIT_L(n) asm volatile("s_waitcnt lgkmcnt(" #n ")" ::: "memory")
; #define PG8_BAR __builtin_amdgcn_s_barrier()
; #define PG8_SCHED __builtin_amdgcn_sched_barrier(0)
; template <class Epi, class Sched, bool ALIGN_EPI = false, bool SP2 = false>
; __device__ __forceinline__ void gemm_phase(PG8_LAS unsigned char* lds, const Gemm g, const Sched& S, const Epi& E) {
;     ...
;             PG8_LDB(B0, 0, 0); PG8_LDB(B1, 0, 1); PG8_SCHED; PG8_LDA(At, 0, 0); PG8_STAGE(PG8_SA(1, 1), a1 + hstep, voffA);
;             PG8_WAIT_V(8); PG8_WAIT_L(0); PG8_BAR; PG8_MMA(0, 0, At, B0); PG8_MMA(0, 1, At, B1); PG8_BAR; PG8_SCHED;
;     ...
;             PG8_LDA(At, 1, 1); PG8_STAGE(PG8_SB(1, 0), b3, voffB); PG8_STAGE(PG8_SB(1, 1), b3 + hstep, voffB); PG8_STAGE(PG8_SA(1, 0), a3, voffA);
;             PG8_WAIT_V(8); PG8_WAIT_L(0); PG8_BAR; PG8_MMA(1, 0, At, B0); PG8_MMA(1, 1, At, B1); PG8_BAR; PG8_SCHED;
	s_add_i32 s47, s47, s54
	v_lshl_add_u64 v[158:159], v[158:159], 0, s[68:69]
	s_mov_b32 m0, s47
	ds_read_b128 v[212:215], v161 offset:49152
	ds_read_b128 v[216:219], v161 offset:50176
	ds_read_b128 v[220:223], v161 offset:51200
	ds_read_b128 v[224:227], v161 offset:52224
	ds_read_b128 v[228:231], v161 offset:53248
	ds_read_b128 v[232:235], v161 offset:54272
	ds_read_b128 v[236:239], v161 offset:55296
	ds_read_b128 v[240:243], v161 offset:56320
	global_load_lds_dwordx4 v[158:159], off
	s_add_i32 m0, s47, 0x2000
	s_add_u32 s18, s18, 0x80080
	v_lshl_add_u64 v[158:159], v[186:187], 0, s[68:69]
	s_addc_u32 s19, s19, 0
	s_add_i32 s47, s76, s54
	global_load_lds_dwordx4 v[158:159], off
	v_lshl_add_u64 v[158:159], s[18:19], 0, v[148:149]
	s_mov_b32 m0, s47
	s_nop 0
	global_load_lds_dwordx4 v[158:159], off
	v_lshl_add_u64 v[158:159], s[18:19], 0, v[144:145]
	s_add_i32 m0, s47, 0x2000
	s_nop 0
	global_load_lds_dwordx4 v[158:159], off
	v_lshl_add_u64 v[158:159], v[244:245], 0, s[68:69]
	s_mov_b32 m0, s5
	s_nop 0
	global_load_lds_dwordx4 v[158:159], off
	v_lshl_add_u64 v[158:159], v[246:247], 0, s[68:69]
	s_mov_b32 m0, s57
	s_nop 0
	global_load_lds_dwordx4 v[158:159], off
	s_nop 0
	s_waitcnt vmcnt(8)
	s_waitcnt lgkmcnt(0)
	s_setprio 1
	s_barrier
	v_mfma_f32_16x16x32_bf16 v[62:65], v[162:165], v[212:215], v[62:65]
	v_mfma_f32_16x16x32_bf16 v[58:61], v[170:173], v[212:215], v[58:61]
	v_mfma_f32_16x16x32_bf16 v[46:49], v[162:165], v[220:223], v[46:49]
	v_mfma_f32_16x16x32_bf16 v[42:45], v[170:173], v[220:223], v[42:45]
	v_mfma_f32_16x16x32_bf16 v[30:33], v[162:165], v[228:231], v[30:33]
	v_mfma_f32_16x16x32_bf16 v[26:29], v[170:173], v[228:231], v[26:29]
	v_mfma_f32_16x16x32_bf16 v[14:17], v[162:165], v[236:239], v[14:17]
	v_mfma_f32_16x16x32_bf16 v[10:13], v[170:173], v[236:239], v[10:13]
	v_mfma_f32_16x16x32_bf16 v[62:65], v[166:169], v[216:219], v[62:65]
	v_mfma_f32_16x16x32_bf16 v[58:61], v[174:177], v[216:219], v[58:61]
	v_mfma_f32_16x16x32_bf16 v[46:49], v[166:169], v[224:227], v[46:49]
	v_mfma_f32_16x16x32_bf16 v[42:45], v[174:177], v[224:227], v[42:45]
	v_mfma_f32_16x16x32_bf16 v[30:33], v[166:169], v[232:235], v[30:33]
	v_mfma_f32_16x16x32_bf16 v[26:29], v[174:177], v[232:235], v[26:29]
	v_mfma_f32_16x16x32_bf16 v[14:17], v[166:169], v[240:243], v[14:17]
	v_mfma_f32_16x16x32_bf16 v[10:13], v[174:177], v[240:243], v[10:13]
	v_mfma_f32_16x16x32_bf16 v[54:57], v[178:181], v[212:215], v[54:57]
	v_mfma_f32_16x16x32_bf16 v[50:53], v[204:207], v[212:215], v[50:53]
	v_mfma_f32_16x16x32_bf16 v[38:41], v[178:181], v[220:223], v[38:41]
	v_mfma_f32_16x16x32_bf16 v[34:37], v[204:207], v[220:223], v[34:37]
	v_mfma_f32_16x16x32_bf16 v[22:25], v[178:181], v[228:231], v[22:25]
	v_mfma_f32_16x16x32_bf16 v[18:21], v[204:207], v[228:231], v[18:21]
	v_mfma_f32_16x16x32_bf16 v[6:9], v[178:181], v[236:239], v[6:9]
	v_mfma_f32_16x16x32_bf16 v[2:5], v[204:207], v[236:239], v[2:5]
	v_mfma_f32_16x16x32_bf16 v[54:57], v[182:185], v[216:219], v[54:57]
	v_mfma_f32_16x16x32_bf16 v[50:53], v[208:211], v[216:219], v[50:53]
	v_mfma_f32_16x16x32_bf16 v[38:41], v[182:185], v[224:227], v[38:41]
	v_mfma_f32_16x16x32_bf16 v[34:37], v[208:211], v[224:227], v[34:37]
	v_mfma_f32_16x16x32_bf16 v[22:25], v[182:185], v[232:235], v[22:25]
	v_mfma_f32_16x16x32_bf16 v[18:21], v[208:211], v[232:235], v[18:21]
	v_mfma_f32_16x16x32_bf16 v[6:9], v[182:185], v[240:243], v[6:9]
	v_mfma_f32_16x16x32_bf16 v[2:5], v[208:211], v[240:243], v[2:5]
	s_setprio 0
	s_barrier
	s_add_i32 s46, s46, 2
	s_add_u32 s0, s0, 0x100
	s_addc_u32 s1, s1, 0
	s_add_u32 s78, s78, 0x100
	s_addc_u32 s79, s79, 0
	s_cmp_gt_u32 s46, 29
.LBB0_76:
	s_add_u32 s18, s0, 0xfff80080
	s_addc_u32 s19, s1, -1
	s_add_i32 s47, 0, 0x10000
	s_cmp_eq_u32 s46, 28
	s_cselect_b32 s59, s60, s19
	s_cselect_b32 s58, s73, s18
	v_add_u32_e32 v158, s47, v143
	s_cselect_b32 s19, s45, s79
	s_cselect_b32 s18, s84, s78
	s_add_i32 s80, 0, 0x14000
	ds_read_b128 v[162:165], v158
	ds_read_b128 v[166:169], v158 offset:1024
	ds_read_b128 v[170:173], v158 offset:2048
	ds_read_b128 v[174:177], v158 offset:3072
	v_add_u32_e32 v158, s80, v143
	ds_read_b128 v[178:181], v158
	ds_read_b128 v[182:185], v158 offset:1024
	ds_read_b128 v[204:207], v158 offset:2048
	ds_read_b128 v[208:211], v158 offset:3072
	v_lshl_add_u64 v[158:159], s[0:1], 0, v[154:155]
	s_add_i32 m0, s62, 0xc000
	ds_read_b128 v[212:215], v161
	ds_read_b128 v[216:219], v161 offset:1024
	ds_read_b128 v[220:223], v161 offset:2048
	ds_read_b128 v[224:227], v161 offset:3072
	ds_read_b128 v[228:231], v161 offset:4096
	ds_read_b128 v[232:235], v161 offset:5120
	ds_read_b128 v[236:239], v161 offset:6144
	ds_read_b128 v[240:243], v161 offset:7168
	global_load_lds_dwordx4 v[158:159], off
	v_lshl_add_u64 v[158:159], s[0:1], 0, v[156:157]
	s_add_i32 m0, s62, 0xe000
	s_nop 0
	global_load_lds_dwordx4 v[158:159], off
	s_nop 0
	s_waitcnt vmcnt(8)
	s_waitcnt lgkmcnt(0)
	s_setprio 1
	s_barrier
; #define PG8_STAGE(bufoff, gbase, voff) do { _Pragma("unroll") for (int _i = 0; _i < 2; ++_i) \
;         __builtin_amdgcn_global_load_lds((const unsigned*)((const char*)(gbase) + (voff)[_i]), (PG8_LAS unsigned*)(lds + (bufoff) + ldsw + _i * 8192), 16, 0, 0); } while (0)
; #define PG8_LDA(dst, b, h) do { _Pragma("unroll") for (int m = 0; m < 4; ++m) _Pragma("unroll") for (int k = 0; k < 2; ++k) dst[m][k] = *(const PG8_LAS bf16x8*)(lds + PG8_SA(b, h) + aoff + m * 2048 + k * 1024); } while (0)
; #define PG8_MMA(ai, bj, At, Bt) do { __builtin_amdgcn_s_setprio(1); _Pragma("unroll") for (int m = 0; m < 4; ++m) _Pragma("unroll") for (int n = 0; n < 2; ++n) _Pragma("unroll") for (int k = 0; k < 2; ++k) \
;         acc[ai][bj][m][n] = __builtin_amdgcn_mfma_f32_16x16x32_bf16(Bt[n][k], At[m][k], acc[ai][bj][m][n], 0, 0, 0); __builtin_amdgcn_s_setprio(0); } while (0)
; #define PG8_WAIT_V(n) asm volatile("s_waitcnt vmcnt(" #n ")" ::: "memory")
; #define PG8_WAIT_L(n) asm volatile("s_waitcnt lgkmcnt(" #n ")" ::: "memory")
; #define PG8_BAR __builtin_amdgcn_s_barrier()
; #define PG8_SCHED __builtin_amdgcn_sched_barrier(0)
; template <class Epi, class Sched, bool ALIGN_EPI = false, bool SP2 = false>
; __device__ __forceinline__ void gemm_phase(PG8_LAS unsigned char* lds, const Gemm g, const Sched& S, const Epi& E) {
;     ...
;             PG8_WAIT_V(8); PG8_WAIT_L(0); PG8_BAR; PG8_MMA(0, 0, At, B0); PG8_MMA(0, 1, At, B1); PG8_BAR; PG8_SCHED;
;             PG8_LDA(At, 0, 1); PG8_STAGE(PG8_SB(0, 0), b2, voffB); PG8_STAGE(PG8_SB(0, 1), b2 + hstep, voffB); PG8_STAGE(PG8_SA(0, 0), a2, voffA);
;             PG8_WAIT_V(8); PG8_WAIT_L(0); PG8_BAR; PG8_MMA(1, 0, At, B0); PG8_MMA(1, 1, At, B1); PG8_BAR; PG8_SCHED;
	v_mfma_f32_16x16x32_bf16 v[126:129], v[162:165], v[212:215], v[126:129]
	v_mfma_f32_16x16x32_bf16 v[122:125], v[170:173], v[212:215], v[122:125]
	v_mfma_f32_16x16x32_bf16 v[110:113], v[162:165], v[220:223], v[110:113]
	v_mfma_f32_16x16x32_bf16 v[106:109], v[170:173], v[220:223], v[106:109]
	v_mfma_f32_16x16x32_bf16 v[94:97], v[162:165], v[228:231], v[94:97]
	v_mfma_f32_16x16x32_bf16 v[90:93], v[170:173], v[228:231], v[90:93]
	v_mfma_f32_16x16x32_bf16 v[78:81], v[162:165], v[236:239], v[78:81]
	v_mfma_f32_16x16x32_bf16 v[74:77], v[170:173], v[236:239], v[74:77]
	s_setprio 0
	s_setprio 1
	v_mfma_f32_16x16x32_bf16 v[126:129], v[166:169], v[216:219], v[126:129]
	v_mfma_f32_16x16x32_bf16 v[122:125], v[174:177], v[216:219], v[122:125]
	v_mfma_f32_16x16x32_bf16 v[110:113], v[166:169], v[224:227], v[110:113]
	v_mfma_f32_16x16x32_bf16 v[106:109], v[174:177], v[224:227], v[106:109]
	v_mfma_f32_16x16x32_bf16 v[94:97], v[166:169], v[232:235], v[94:97]
	v_mfma_f32_16x16x32_bf16 v[90:93], v[174:177], v[232:235], v[90:93]
	v_mfma_f32_16x16x32_bf16 v[78:81], v[166:169], v[240:243], v[78:81]
	v_mfma_f32_16x16x32_bf16 v[74:77], v[174:177], v[240:243], v[74:77]
	s_setprio 0
	s_setprio 1
	v_mfma_f32_16x16x32_bf16 v[118:121], v[178:181], v[212:215], v[118:121]
	v_mfma_f32_16x16x32_bf16 v[114:117], v[204:207], v[212:215], v[114:117]
	v_mfma_f32_16x16x32_bf16 v[102:105], v[178:181], v[220:223], v[102:105]
	v_mfma_f32_16x16x32_bf16 v[98:101], v[204:207], v[220:223], v[98:101]
	v_mfma_f32_16x16x32_bf16 v[86:89], v[178:181], v[228:231], v[86:89]
	v_mfma_f32_16x16x32_bf16 v[82:85], v[204:207], v[228:231], v[82:85]
	v_mfma_f32_16x16x32_bf16 v[70:73], v[178:181], v[236:239], v[70:73]
	v_mfma_f32_16x16x32_bf16 v[66:69], v[204:207], v[236:239], v[66:69]
	s_setprio 0
	s_setprio 1
	v_mfma_f32_16x16x32_bf16 v[118:121], v[182:185], v[216:219], v[118:121]
	v_mfma_f32_16x16x32_bf16 v[114:117], v[208:211], v[216:219], v[114:117]
	v_mfma_f32_16x16x32_bf16 v[102:105], v[182:185], v[224:227], v[102:105]
	v_mfma_f32_16x16x32_bf16 v[98:101], v[208:211], v[224:227], v[98:101]
	v_mfma_f32_16x16x32_bf16 v[86:89], v[182:185], v[232:235], v[86:89]
	v_mfma_f32_16x16x32_bf16 v[82:85], v[208:211], v[232:235], v[82:85]
	v_mfma_f32_16x16x32_bf16 v[70:73], v[182:185], v[240:243], v[70:73]
	v_mfma_f32_16x16x32_bf16 v[66:69], v[208:211], v[240:243], v[66:69]
	s_setprio 0
	s_barrier
	s_add_i32 s47, s47, s54
	v_lshl_add_u64 v[158:159], s[18:19], 0, v[148:149]
	s_mov_b32 m0, s47
	ds_read_b128 v[212:215], v161 offset:16384
	ds_read_b128 v[216:219], v161 offset:17408
	ds_read_b128 v[220:223], v161 offset:18432
	ds_read_b128 v[224:227], v161 offset:19456
	ds_read_b128 v[228:231], v161 offset:20480
	ds_read_b128 v[232:235], v161 offset:21504
	ds_read_b128 v[236:239], v161 offset:22528
	ds_read_b128 v[240:243], v161 offset:23552
	global_load_lds_dwordx4 v[158:159], off
	s_add_i32 m0, s47, 0x2000
	s_add_u32 s76, s18, 0x80000
	v_lshl_add_u64 v[186:187], s[18:19], 0, v[144:145]
	s_addc_u32 s77, s19, 0
	s_add_i32 s47, s80, s54
	global_load_lds_dwordx4 v[186:187], off
	v_lshl_add_u64 v[244:245], s[76:77], 0, v[148:149]
	s_mov_b32 m0, s47
	v_lshl_add_u64 v[246:247], s[58:59], 0, v[146:147]
	global_load_lds_dwordx4 v[244:245], off
	v_lshl_add_u64 v[244:245], s[76:77], 0, v[144:145]
	s_add_i32 m0, s47, 0x2000
	s_nop 0
	global_load_lds_dwordx4 v[244:245], off
	v_lshl_add_u64 v[244:245], s[58:59], 0, v[150:151]
	s_mov_b32 m0, s62
	s_nop 0
	global_load_lds_dwordx4 v[244:245], off
	s_mov_b32 m0, s63
	s_nop 0
	global_load_lds_dwordx4 v[246:247], off
	s_waitcnt vmcnt(8)
	s_waitcnt lgkmcnt(0)
	s_setprio 1
	s_barrier
	v_mfma_f32_16x16x32_bf16 v[62:65], v[162:165], v[212:215], v[62:65]
	v_mfma_f32_16x16x32_bf16 v[58:61], v[170:173], v[212:215], v[58:61]
	v_mfma_f32_16x16x32_bf16 v[46:49], v[162:165], v[220:223], v[46:49]
	v_mfma_f32_16x16x32_bf16 v[42:45], v[170:173], v[220:223], v[42:45]
	v_mfma_f32_16x16x32_bf16 v[30:33], v[162:165], v[228:231], v[30:33]
	v_mfma_f32_16x16x32_bf16 v[26:29], v[170:173], v[228:231], v[26:29]
	v_mfma_f32_16x16x32_bf16 v[14:17], v[162:165], v[236:239], v[14:17]
	v_mfma_f32_16x16x32_bf16 v[10:13], v[170:173], v[236:239], v[10:13]
	v_mfma_f32_16x16x32_bf16 v[62:65], v[166:169], v[216:219], v[62:65]
	v_mfma_f32_16x16x32_bf16 v[58:61], v[174:177], v[216:219], v[58:61]
	v_mfma_f32_16x16x32_bf16 v[46:49], v[166:169], v[224:227], v[46:49]
	v_mfma_f32_16x16x32_bf16 v[42:45], v[174:177], v[224:227], v[42:45]
	v_mfma_f32_16x16x32_bf16 v[30:33], v[166:169], v[232:235], v[30:33]
	v_mfma_f32_16x16x32_bf16 v[26:29], v[174:177], v[232:235], v[26:29]
	v_mfma_f32_16x16x32_bf16 v[14:17], v[166:169], v[240:243], v[14:17]
	v_mfma_f32_16x16x32_bf16 v[10:13], v[174:177], v[240:243], v[10:13]
	v_mfma_f32_16x16x32_bf16 v[54:57], v[178:181], v[212:215], v[54:57]
	v_mfma_f32_16x16x32_bf16 v[50:53], v[204:207], v[212:215], v[50:53]
	v_mfma_f32_16x16x32_bf16 v[38:41], v[178:181], v[220:223], v[38:41]
	v_mfma_f32_16x16x32_bf16 v[34:37], v[204:207], v[220:223], v[34:37]
	v_mfma_f32_16x16x32_bf16 v[22:25], v[178:181], v[228:231], v[22:25]
	v_mfma_f32_16x16x32_bf16 v[18:21], v[204:207], v[228:231], v[18:21]
	v_mfma_f32_16x16x32_bf16 v[6:9], v[178:181], v[236:239], v[6:9]
	v_mfma_f32_16x16x32_bf16 v[2:5], v[204:207], v[236:239], v[2:5]
	v_mfma_f32_16x16x32_bf16 v[54:57], v[182:185], v[216:219], v[54:57]
	v_mfma_f32_16x16x32_bf16 v[50:53], v[208:211], v[216:219], v[50:53]
	v_mfma_f32_16x16x32_bf16 v[38:41], v[182:185], v[224:227], v[38:41]
	v_mfma_f32_16x16x32_bf16 v[34:37], v[208:211], v[224:227], v[34:37]
	v_mfma_f32_16x16x32_bf16 v[22:25], v[182:185], v[232:235], v[22:25]
	v_mfma_f32_16x16x32_bf16 v[18:21], v[208:211], v[232:235], v[18:21]
	v_mfma_f32_16x16x32_bf16 v[6:9], v[182:185], v[240:243], v[6:9]
	v_mfma_f32_16x16x32_bf16 v[2:5], v[208:211], v[240:243], v[2:5]
	s_setprio 0
	s_barrier
; #define PG8_STAGE(bufoff, gbase, voff) do { _Pragma("unroll") for (int _i = 0; _i < 2; ++_i) \
;         __builtin_amdgcn_global_load_lds((const unsigned*)((const char*)(gbase) + (voff)[_i]), (PG8_LAS unsigned*)(lds + (bufoff) + ldsw + _i * 8192), 16, 0, 0); } while (0)
; #define PG8_LDA(dst, b, h) do { _Pragma("unroll") for (int m = 0; m < 4; ++m) _Pragma("unroll") for (int k = 0; k < 2; ++k) dst[m][k] = *(const PG8_LAS bf16x8*)(lds + PG8_SA(b, h) + aoff + m * 2048 + k * 1024); } while (0)
; #define PG8_LDB(dst, b, h) do { _Pragma("unroll") for (int n = 0; n < 2; ++n) _Pragma("unroll") for (int k = 0; k < 2; ++k) dst[n][k] = *(const PG8_LAS bf16x8*)(lds + PG8_SB(b, h) + boff + n * 2048 + k * 1024); } while (0)
; #define PG8_MMA(ai, bj, At, Bt) do { __builtin_amdgcn_s_setprio(1); _Pragma("unroll") for (int m = 0; m < 4; ++m) _Pragma("unroll") for (int n = 0; n < 2; ++n) _Pragma("unroll") for (int k = 0; k < 2; ++k) \
;         acc[ai][bj][m][n] = __builtin_amdgcn_mfma_f32_16x16x32_bf16(Bt[n][k], At[m][k], acc[ai][bj][m][n], 0, 0, 0); __builtin_amdgcn_s_setprio(0); } while (0)
; #define PG8_WAIT_V(n) asm volatile("s_waitcnt vmcnt(" #n ")" ::: "memory")
; #define PG8_WAIT_L(n) asm volatile("s_waitcnt lgkmcnt(" #n ")" ::: "memory")
; #define PG8_BAR __builtin_amdgcn_s_barrier()
; #define PG8_SCHED __builtin_amdgcn_sched_barrier(0)
; template <class Epi, class Sched, bool ALIGN_EPI = false, bool SP2 = false>
; __device__ __forceinline__ void gemm_phase(PG8_LAS unsigned char* lds, const Gemm g, const Sched& S, const Epi& E) {
;     ...
;             PG8_LDB(B0, 1, 0); PG8_LDB(B1, 1, 1); PG8_SCHED; PG8_LDA(At, 1, 0); PG8_STAGE(PG8_SA(0, 1), a2 + hstep, voffA);
;             PG8_WAIT_V(8); PG8_WAIT_L(0); PG8_BAR; PG8_MMA(0, 0, At, B0); PG8_MMA(0, 1, At, B1); PG8_BAR; PG8_SCHED;
	s_add_i32 s47, 0, 0x18000
	s_add_i32 s76, 0, 0x1c000
	v_add_u32_e32 v174, s47, v143
	v_add_u32_e32 v203, s76, v143
	ds_read_b128 v[162:165], v174
	ds_read_b128 v[166:169], v174 offset:1024
	ds_read_b128 v[170:173], v174 offset:2048
	ds_read_b128 v[174:177], v174 offset:3072
	ds_read_b128 v[178:181], v203
	ds_read_b128 v[182:185], v203 offset:1024
	ds_read_b128 v[204:207], v203 offset:2048
	ds_read_b128 v[208:211], v203 offset:3072
	s_add_u32 s58, s58, 0x80000
	s_addc_u32 s59, s59, 0
	s_mov_b32 m0, s67
	v_lshl_add_u64 v[248:249], s[58:59], 0, v[150:151]
	ds_read_b128 v[212:215], v161 offset:32768
	ds_read_b128 v[216:219], v161 offset:33792
	ds_read_b128 v[220:223], v161 offset:34816
	ds_read_b128 v[224:227], v161 offset:35840
	ds_read_b128 v[228:231], v161 offset:36864
	ds_read_b128 v[232:235], v161 offset:37888
	ds_read_b128 v[236:239], v161 offset:38912
	ds_read_b128 v[240:243], v161 offset:39936
	global_load_lds_dwordx4 v[248:249], off
	v_lshl_add_u64 v[248:249], s[58:59], 0, v[146:147]
	s_mov_b32 m0, s4
	s_nop 0
	global_load_lds_dwordx4 v[248:249], off
	s_waitcnt vmcnt(8)
	s_waitcnt lgkmcnt(0)
	s_setprio 1
	s_barrier
	v_mfma_f32_16x16x32_bf16 v[126:129], v[162:165], v[212:215], v[126:129]
	v_mfma_f32_16x16x32_bf16 v[122:125], v[170:173], v[212:215], v[122:125]
	v_mfma_f32_16x16x32_bf16 v[110:113], v[162:165], v[220:223], v[110:113]
	v_mfma_f32_16x16x32_bf16 v[106:109], v[170:173], v[220:223], v[106:109]
	v_mfma_f32_16x16x32_bf16 v[94:97], v[162:165], v[228:231], v[94:97]
	v_mfma_f32_16x16x32_bf16 v[90:93], v[170:173], v[228:231], v[90:93]
	v_mfma_f32_16x16x32_bf16 v[78:81], v[162:165], v[236:239], v[78:81]
	v_mfma_f32_16x16x32_bf16 v[74:77], v[170:173], v[236:239], v[74:77]
	s_setprio 0
	s_setprio 1
	v_mfma_f32_16x16x32_bf16 v[126:129], v[166:169], v[216:219], v[126:129]
	v_mfma_f32_16x16x32_bf16 v[122:125], v[174:177], v[216:219], v[122:125]
	v_mfma_f32_16x16x32_bf16 v[110:113], v[166:169], v[224:227], v[110:113]
	v_mfma_f32_16x16x32_bf16 v[106:109], v[174:177], v[224:227], v[106:109]
	v_mfma_f32_16x16x32_bf16 v[94:97], v[166:169], v[232:235], v[94:97]
	v_mfma_f32_16x16x32_bf16 v[90:93], v[174:177], v[232:235], v[90:93]
	v_mfma_f32_16x16x32_bf16 v[78:81], v[166:169], v[240:243], v[78:81]
	v_mfma_f32_16x16x32_bf16 v[74:77], v[174:177], v[240:243], v[74:77]
	s_setprio 0
	s_setprio 1
	v_mfma_f32_16x16x32_bf16 v[118:121], v[178:181], v[212:215], v[118:121]
	v_mfma_f32_16x16x32_bf16 v[114:117], v[204:207], v[212:215], v[114:117]
	v_mfma_f32_16x16x32_bf16 v[102:105], v[178:181], v[220:223], v[102:105]
	v_mfma_f32_16x16x32_bf16 v[98:101], v[204:207], v[220:223], v[98:101]
	v_mfma_f32_16x16x32_bf16 v[86:89], v[178:181], v[228:231], v[86:89]
	v_mfma_f32_16x16x32_bf16 v[82:85], v[204:207], v[228:231], v[82:85]
	v_mfma_f32_16x16x32_bf16 v[70:73], v[178:181], v[236:239], v[70:73]
	v_mfma_f32_16x16x32_bf16 v[66:69], v[204:207], v[236:239], v[66:69]
	s_setprio 0
	s_setprio 1
	v_mfma_f32_16x16x32_bf16 v[118:121], v[182:185], v[216:219], v[118:121]
	v_mfma_f32_16x16x32_bf16 v[114:117], v[208:211], v[216:219], v[114:117]
	v_mfma_f32_16x16x32_bf16 v[102:105], v[182:185], v[224:227], v[102:105]
	v_mfma_f32_16x16x32_bf16 v[98:101], v[208:211], v[224:227], v[98:101]
	v_mfma_f32_16x16x32_bf16 v[86:89], v[182:185], v[232:235], v[86:89]
	v_mfma_f32_16x16x32_bf16 v[82:85], v[208:211], v[232:235], v[82:85]
	v_mfma_f32_16x16x32_bf16 v[70:73], v[182:185], v[240:243], v[70:73]
	v_mfma_f32_16x16x32_bf16 v[66:69], v[208:211], v[240:243], v[66:69]
	s_setprio 0
	s_barrier
; #define PG8_STAGE(bufoff, gbase, voff) do { _Pragma("unroll") for (int _i = 0; _i < 2; ++_i) \
;         __builtin_amdgcn_global_load_lds((const unsigned*)((const char*)(gbase) + (voff)[_i]), (PG8_LAS unsigned*)(lds + (bufoff) + ldsw + _i * 8192), 16, 0, 0); } while (0)
; #define PG8_LDA(dst, b, h) do { _Pragma("unroll") for (int m = 0; m < 4; ++m) _Pragma("unroll") for (int k = 0; k < 2; ++k) dst[m][k] = *(const PG8_LAS bf16x8*)(lds + PG8_SA(b, h) + aoff + m * 2048 + k * 1024); } while (0)
; #define PG8_MMA(ai, bj, At, Bt) do { __builtin_amdgcn_s_setprio(1); _Pragma("unroll") for (int m = 0; m < 4; ++m) _Pragma("unroll") for (int n = 0; n < 2; ++n) _Pragma("unroll") for (int k = 0; k < 2; ++k) \
;         acc[ai][bj][m][n] = __builtin_amdgcn_mfma_f32_16x16x32_bf16(Bt[n][k], At[m][k], acc[ai][bj][m][n], 0, 0, 0); __builtin_amdgcn_s_setprio(0); } while (0)
; #define PG8_WAIT_V(n) asm volatile("s_waitcnt vmcnt(" #n ")" ::: "memory")
; #define PG8_WAIT_L(n) asm volatile("s_waitcnt lgkmcnt(" #n ")" ::: "memory")
; #define PG8_BAR __builtin_amdgcn_s_barrier()
; #define PG8_SCHED __builtin_amdgcn_sched_barrier(0)
; template <class Epi, class Sched, bool ALIGN_EPI = false, bool SP2 = false>
; __device__ __forceinline__ void gemm_phase(PG8_LAS unsigned char* lds, const Gemm g, const Sched& S, const Epi& E) {
;     ...
;             PG8_LDA(At, 1, 1); PG8_STAGE(PG8_SB(1, 0), b3, voffB); PG8_STAGE(PG8_SB(1, 1), b3 + hstep, voffB); PG8_STAGE(PG8_SA(1, 0), a3, voffA);
;             PG8_WAIT_V(8); PG8_WAIT_L(0); PG8_BAR; PG8_MMA(1, 0, At, B0); PG8_MMA(1, 1, At, B1); PG8_BAR; PG8_SCHED;
;     ...
;         if constexpr (ALIGN_EPI) { if (wr == 0) PG8_BAR; }
	s_add_i32 s47, s47, s54
	v_lshl_add_u64 v[158:159], v[158:159], 0, s[68:69]
	s_mov_b32 m0, s47
	ds_read_b128 v[212:215], v161 offset:49152
	ds_read_b128 v[216:219], v161 offset:50176
	ds_read_b128 v[220:223], v161 offset:51200
	ds_read_b128 v[224:227], v161 offset:52224
	ds_read_b128 v[228:231], v161 offset:53248
	ds_read_b128 v[232:235], v161 offset:54272
	ds_read_b128 v[236:239], v161 offset:55296
	ds_read_b128 v[240:243], v161 offset:56320
	global_load_lds_dwordx4 v[158:159], off
	s_add_i32 m0, s47, 0x2000
	s_add_u32 s18, s18, 0x80080
	v_lshl_add_u64 v[158:159], v[186:187], 0, s[68:69]
	s_addc_u32 s19, s19, 0
	s_add_i32 s47, s76, s54
	global_load_lds_dwordx4 v[158:159], off
	v_lshl_add_u64 v[158:159], s[18:19], 0, v[148:149]
	s_mov_b32 m0, s47
	s_nop 0
	global_load_lds_dwordx4 v[158:159], off
	v_lshl_add_u64 v[158:159], s[18:19], 0, v[144:145]
	s_add_i32 m0, s47, 0x2000
	s_nop 0
	global_load_lds_dwordx4 v[158:159], off
	v_lshl_add_u64 v[158:159], v[244:245], 0, s[68:69]
	s_mov_b32 m0, s5
	s_nop 0
	global_load_lds_dwordx4 v[158:159], off
	v_lshl_add_u64 v[158:159], v[246:247], 0, s[68:69]
	s_mov_b32 m0, s57
	s_nop 0
	global_load_lds_dwordx4 v[158:159], off
	s_nop 0
	s_waitcnt vmcnt(8)
	s_waitcnt lgkmcnt(0)
	s_setprio 1
	s_barrier
	v_mfma_f32_16x16x32_bf16 v[62:65], v[162:165], v[212:215], v[62:65]
	v_mfma_f32_16x16x32_bf16 v[58:61], v[170:173], v[212:215], v[58:61]
	v_mfma_f32_16x16x32_bf16 v[46:49], v[162:165], v[220:223], v[46:49]
	v_mfma_f32_16x16x32_bf16 v[42:45], v[170:173], v[220:223], v[42:45]
	v_mfma_f32_16x16x32_bf16 v[30:33], v[162:165], v[228:231], v[30:33]
	v_mfma_f32_16x16x32_bf16 v[26:29], v[170:173], v[228:231], v[26:29]
	v_mfma_f32_16x16x32_bf16 v[14:17], v[162:165], v[236:239], v[14:17]
	v_mfma_f32_16x16x32_bf16 v[10:13], v[170:173], v[236:239], v[10:13]
	v_mfma_f32_16x16x32_bf16 v[62:65], v[166:169], v[216:219], v[62:65]
	v_mfma_f32_16x16x32_bf16 v[58:61], v[174:177], v[216:219], v[58:61]
	v_mfma_f32_16x16x32_bf16 v[46:49], v[166:169], v[224:227], v[46:49]
	v_mfma_f32_16x16x32_bf16 v[42:45], v[174:177], v[224:227], v[42:45]
	v_mfma_f32_16x16x32_bf16 v[30:33], v[166:169], v[232:235], v[30:33]
	v_mfma_f32_16x16x32_bf16 v[26:29], v[174:177], v[232:235], v[26:29]
	v_mfma_f32_16x16x32_bf16 v[14:17], v[166:169], v[240:243], v[14:17]
	v_mfma_f32_16x16x32_bf16 v[10:13], v[174:177], v[240:243], v[10:13]
	v_mfma_f32_16x16x32_bf16 v[54:57], v[178:181], v[212:215], v[54:57]
	v_mfma_f32_16x16x32_bf16 v[50:53], v[204:207], v[212:215], v[50:53]
	v_mfma_f32_16x16x32_bf16 v[38:41], v[178:181], v[220:223], v[38:41]
	v_mfma_f32_16x16x32_bf16 v[34:37], v[204:207], v[220:223], v[34:37]
	v_mfma_f32_16x16x32_bf16 v[22:25], v[178:181], v[228:231], v[22:25]
	v_mfma_f32_16x16x32_bf16 v[18:21], v[204:207], v[228:231], v[18:21]
	v_mfma_f32_16x16x32_bf16 v[6:9], v[178:181], v[236:239], v[6:9]
	v_mfma_f32_16x16x32_bf16 v[2:5], v[204:207], v[236:239], v[2:5]
	v_mfma_f32_16x16x32_bf16 v[54:57], v[182:185], v[216:219], v[54:57]
	v_mfma_f32_16x16x32_bf16 v[50:53], v[208:211], v[216:219], v[50:53]
	v_mfma_f32_16x16x32_bf16 v[38:41], v[182:185], v[224:227], v[38:41]
	v_mfma_f32_16x16x32_bf16 v[34:37], v[208:211], v[224:227], v[34:37]
	v_mfma_f32_16x16x32_bf16 v[22:25], v[182:185], v[232:235], v[22:25]
	v_mfma_f32_16x16x32_bf16 v[18:21], v[208:211], v[232:235], v[18:21]
	v_mfma_f32_16x16x32_bf16 v[6:9], v[182:185], v[240:243], v[6:9]
	v_mfma_f32_16x16x32_bf16 v[2:5], v[208:211], v[240:243], v[2:5]
	s_setprio 0
	s_barrier
	s_add_i32 s46, s46, 2
	s_add_u32 s0, s0, 0x100
	s_addc_u32 s1, s1, 0
	s_add_u32 s78, s78, 0x100
	s_addc_u32 s79, s79, 0
	s_cmp_gt_u32 s46, 29
	s_cbranch_scc0 .LBB0_76
	s_mov_b32 s32, 1
	s_and_b64 vcc, exec, s[42:43]
	s_cbranch_vccz .LBB0_79
	s_barrier

; #define PG8_STAGE(bufoff, gbase, voff) do { _Pragma("unroll") for (int _i = 0; _i < 2; ++_i) \
;         __builtin_amdgcn_global_load_lds((const unsigned*)((const char*)(gbase) + (voff)[_i]), (PG8_LAS unsigned*)(lds + (bufoff) + ldsw + _i * 8192), 16, 0, 0); } while (0)
; #define PG8_WAIT_V(n) asm volatile("s_waitcnt vmcnt(" #n ")" ::: "memory")
; #define PG8_BAR __builtin_amdgcn_s_barrier()
; template <class Epi, class Sched, bool ALIGN_EPI = false, bool SP2 = false>
; __device__ __forceinline__ void gemm_phase(PG8_LAS unsigned char* lds, const Gemm g, const Sched& S, const Epi& E) {
;     ...
;     const int tid = tid_, wid = __builtin_amdgcn_readfirstlane(tid >> 6), lane = tid & 63, wr = wid >> 2, wc = wid & 3, fr = lane & 15, fq = lane >> 4;
;     const int K = g.K, nt = K / BK;
;     unsigned voffA[2], voffB[2];
; #pragma unroll
;     for (int i = 0; i < 2; ++i) { int R, C; stage_rc(tid * 16 + i * 8192, R, C); const int Rb = Epi::PERM ? ((R & ~31) + perm32(R & 31)) : R;
;         voffA[i] = (unsigned)(R * K + C) * 2u; voffB[i] = (unsigned)(Rb * K + C) * 2u; }
;     const size_t kstep = (size_t)(BK * 2);
;     const size_t hstep = (size_t)HALF * K * 2;
;     const size_t tstep = 2 * hstep;
;     const unsigned ldsw = (unsigned)wid * 1024u;
;     const int aoff = lds_byte(wr * 64 + fr, fq * 8), boff = lds_byte(wc * 32 + fr, fq * 8);
;     ...
;     Unit cur, nxt; int ui = 0;
;     if (!S.next(0, cur)) return;
;     f32x4 acc[2][2][4][2];
; #pragma unroll
;     for (int a = 0; a < 2; ++a)
; #pragma unroll
;         for (int b = 0; b < 2; ++b)
; #pragma unroll
;             for (int m = 0; m < 4; ++m)
; #pragma unroll
;                 for (int n = 0; n < 2; ++n) acc[a][b][m][n] = (f32x4){0.f, 0.f, 0.f, 0.f};
;     bf16x8 At[4][2], B0[2][2], B1[2][2];
;     const char* cA = (const char*)g.A + (size_t)cur.pm * tstep; const char* cB = (const char*)g.Bt + (size_t)cur.pn * tstep;
;     S.a_ready(cur);
;     if constexpr (SP2) {
;         PG8_STAGE(PG8_SB(0, 0), cB, voffB); PG8_STAGE(PG8_SB(0, 1), cB + hstep, voffB); PG8_STAGE(PG8_SA(0, 0), cA, voffA); PG8_STAGE(PG8_SA(0, 1), cA + hstep, voffA);
;         if (wr == 1) PG8_BAR;
;         PG8_WAIT_V(2); PG8_BAR;
;         PG8_STAGE(PG8_SB(1, 0), cB + kstep, voffB); PG8_STAGE(PG8_SA(1, 0), cA + kstep, voffA); PG8_STAGE(PG8_SB(1, 1), cB + hstep + kstep, voffB);
;         PG8_WAIT_V(6); PG8_BAR;
.LBB0_88:
	v_bfe_u32 v18, v8, 4, 2
	v_and_b32_e32 v9, 15, v8
	v_lshlrev_b32_e32 v20, 4, v18
	v_lshlrev_b32_e32 v8, 2, v8
	v_mov_b32_e32 v149, v0
	s_and_b32 s60, s28, 3
	v_lshl_or_b32 v1, s19, 6, v9
	v_lshl_or_b32 v9, v9, 6, v20
	s_lshl_b32 s19, s19, 13
	v_and_b32_e32 v8, 32, v8
	v_lshl_add_u64 v[10:11], s[58:59], 0, v[148:149]
	v_mov_b32_e32 v145, v0
	v_bitop3_b32 v20, v9, s19, v8 bitop3:0xde
	s_lshl_b32 s19, s60, 12
	v_lshl_add_u64 v[12:13], s[58:59], 0, v[144:145]
	v_mov_b32_e32 v151, v0
	v_bitop3_b32 v143, v9, s19, v8 bitop3:0xde
	s_add_i32 m0, s5, 0x18000
	v_lshl_add_u64 v[8:9], v[10:11], 0, s[68:69]
	v_lshl_add_u64 v[14:15], s[40:41], 0, v[150:151]
	v_mov_b32_e32 v147, v0
	s_waitcnt vmcnt(2)
	s_barrier
	global_load_lds_dwordx4 v[8:9], off
	v_lshl_add_u64 v[8:9], v[12:13], 0, s[68:69]
	s_add_i32 m0, s5, 0x1a000
	s_add_i32 s67, s5, 0x8000
	s_add_i32 s28, s5, 0xa000
	v_lshl_add_u64 v[16:17], s[40:41], 0, v[146:147]
	global_load_lds_dwordx4 v[8:9], off
	v_lshl_add_u64 v[8:9], v[14:15], 0, s[68:69]
	s_mov_b32 m0, s67
	s_add_u32 s36, s58, 0x80080
	global_load_lds_dwordx4 v[8:9], off
	v_lshl_add_u64 v[8:9], v[16:17], 0, s[68:69]
	s_mov_b32 m0, s28
	s_addc_u32 s37, s59, 0
	global_load_lds_dwordx4 v[8:9], off
	s_add_i32 m0, s5, 0x1c000
	v_lshl_add_u64 v[8:9], s[36:37], 0, v[148:149]
	global_load_lds_dwordx4 v[8:9], off
	v_lshl_add_u64 v[8:9], s[36:37], 0, v[144:145]
	s_add_i32 m0, s5, 0x1e000
	v_lshlrev_b32_e32 v19, 3, v18
	global_load_lds_dwordx4 v[8:9], off
	v_lshlrev_b32_e32 v8, 15, v6
	v_and_b32_e32 v8, 0xffff0000, v8
	v_lshl_add_u32 v5, v5, 12, v8
	v_and_b32_e32 v6, 1, v6
	v_lshl_or_b32 v5, v6, 6, v5
	v_lshl_add_u32 v152, v7, 1, v5
	v_lshlrev_b32_e32 v5, 15, v2
	v_and_b32_e32 v5, 0xffff0000, v5
	s_waitcnt vmcnt(6)
	v_lshl_add_u32 v3, v3, 12, v5
	v_and_b32_e32 v2, 1, v2
	s_cmpk_lt_u32 s18, 0x100
	v_lshl_or_b32 v2, v2, 6, v3
	v_readlane_b32 s18, v254, 2
	v_lshl_or_b32 v160, s60, 5, v19
	s_cselect_b64 s[36:37], -1, 0
	s_mov_b32 s86, 0
	v_cmp_eq_u32_e64 s[42:43], 0, v18
	v_mov_b32_e32 v153, v0
	v_lshl_add_u32 v154, v4, 1, v2
	v_mov_b32_e32 v155, v0
	v_add_u32_e32 v161, 0, v20
	v_readlane_b32 s54, v253, 19
	s_mov_b32 s73, s18
	s_barrier
	v_readlane_b32 s19, v254, 3
	s_mov_b32 s32, 0
	s_branch .LBB0_91

; #define PG8_STAGE(bufoff, gbase, voff) do { _Pragma("unroll") for (int _i = 0; _i < 2; ++_i) \
;         __builtin_amdgcn_global_load_lds((const unsigned*)((const char*)(gbase) + (voff)[_i]), (PG8_LAS unsigned*)(lds + (bufoff) + ldsw + _i * 8192), 16, 0, 0); } while (0)
; #define PG8_LDA(dst, b, h) do { _Pragma("unroll") for (int m = 0; m < 4; ++m) _Pragma("unroll") for (int k = 0; k < 2; ++k) dst[m][k] = *(const PG8_LAS bf16x8*)(lds + PG8_SA(b, h) + aoff + m * 2048 + k * 1024); } while (0)
; #define PG8_LDB(dst, b, h) do { _Pragma("unroll") for (int n = 0; n < 2; ++n) _Pragma("unroll") for (int k = 0; k < 2; ++k) dst[n][k] = *(const PG8_LAS bf16x8*)(lds + PG8_SB(b, h) + boff + n * 2048 + k * 1024); } while (0)
; #define PG8_SCHED __builtin_amdgcn_sched_barrier(0)
; template <class Epi, class Sched, bool ALIGN_EPI = false, bool SP2 = false>
; __device__ __forceinline__ void gemm_phase(PG8_LAS unsigned char* lds, const Gemm g, const Sched& S, const Epi& E) {
;     ...
;         const bool has_next = S.next(ui + 1, nxt);
;         const char* nA = has_next ? (const char*)g.A + (size_t)nxt.pm * tstep : cA; const char* nB = has_next ? (const char*)g.Bt + (size_t)nxt.pn * tstep : cB;
;         for (int t = 0; t < nt; t += 2) {
;             const bool last = (t == nt - 2);
;             const char* a1 = cA + (size_t)(t + 1) * kstep;
;             const char* a2 = last ? nA : cA + (size_t)(t + 2) * kstep; const char* b2 = last ? nB : cB + (size_t)(t + 2) * kstep;
;             const char* a3 = a2 + kstep; const char* b3 = b2 + kstep;
;             if (last && has_next) S.a_ready(nxt);
;             if constexpr (SP2) {
;             PG8_LDB(B0, 0, 0); PG8_LDB(B1, 0, 1); PG8_SCHED; PG8_LDA(At, 0, 0); PG8_STAGE(PG8_SA(1, 1), a1 + hstep, voffA);
.LBB0_97:
	s_ashr_i32 s97, s96, 31
	s_lshl_b64 s[18:19], s[96:97], 20
	s_add_u32 s18, s12, s18
	s_addc_u32 s19, s13, s19
	s_and_b64 s[46:47], s[44:45], exec
	s_cselect_b32 s97, s19, s41
	s_cselect_b32 s84, s18, s40
	s_ashr_i32 s95, s94, 31
	s_lshl_b64 s[46:47], s[94:95], 20
	v_readlane_b32 s62, v254, 45
	v_readlane_b32 s63, v254, 46
	s_add_u32 s62, s62, s46
	s_addc_u32 s63, s63, s47
	s_and_b64 s[46:47], s[44:45], exec
	s_cselect_b32 s85, s63, s59
	s_cselect_b32 s95, s62, s58
	s_add_u32 vcc_lo, s40, 0x80080
	s_addc_u32 vcc_hi, s41, 0
	s_add_u32 s78, s58, 0x100
	s_addc_u32 s79, s59, 0
	s_mov_b32 s46, -2
	s_waitcnt lgkmcnt(0)
	s_add_u32 s40, vcc_lo, 0xfff80080
	s_addc_u32 s41, vcc_hi, -1
	s_add_i32 s47, 0, 0x10000
	s_cmp_eq_u32 s46, 28
	s_cselect_b32 s59, s97, s41
	s_cselect_b32 s58, s84, s40
	s_cselect_b32 s41, s85, s79
	s_cselect_b32 s40, s95, s78
	s_add_i32 s80, 0, 0x14000
	v_add_u32_e32 v170, s47, v143
	v_add_u32_e32 v186, s80, v143
	ds_read_b128 v[156:159], v170
	ds_read_b128 v[162:165], v170 offset:1024
	ds_read_b128 v[166:169], v170 offset:2048
	ds_read_b128 v[170:173], v170 offset:3072
	ds_read_b128 v[174:177], v186
	ds_read_b128 v[178:181], v186 offset:1024
	ds_read_b128 v[182:185], v186 offset:2048
	ds_read_b128 v[204:207], v186 offset:3072
	v_lshl_add_u64 v[186:187], vcc, 0, v[152:153]
	s_add_i32 m0, s5, 0xc000
	ds_read_b128 v[208:211], v161
	ds_read_b128 v[212:215], v161 offset:1024
	ds_read_b128 v[216:219], v161 offset:2048
	ds_read_b128 v[220:223], v161 offset:3072
	ds_read_b128 v[224:227], v161 offset:4096
	ds_read_b128 v[228:231], v161 offset:5120
	ds_read_b128 v[232:235], v161 offset:6144
	ds_read_b128 v[236:239], v161 offset:7168
	global_load_lds_dwordx4 v[186:187], off
	v_lshl_add_u64 v[186:187], vcc, 0, v[154:155]
	s_add_i32 m0, s5, 0xe000
	s_nop 0
	global_load_lds_dwordx4 v[186:187], off
	s_cmp_eq_u32 s32, 0
	s_cbranch_scc1 .Lpw5_f
	s_waitcnt vmcnt(24)
	s_branch .Lpw5_j

; #define PG8_STAGE(bufoff, gbase, voff) do { _Pragma("unroll") for (int _i = 0; _i < 2; ++_i) \
;         __builtin_amdgcn_global_load_lds((const unsigned*)((const char*)(gbase) + (voff)[_i]), (PG8_LAS unsigned*)(lds + (bufoff) + ldsw + _i * 8192), 16, 0, 0); } while (0)
; #define PG8_LDA(dst, b, h) do { _Pragma("unroll") for (int m = 0; m < 4; ++m) _Pragma("unroll") for (int k = 0; k < 2; ++k) dst[m][k] = *(const PG8_LAS bf16x8*)(lds + PG8_SA(b, h) + aoff + m * 2048 + k * 1024); } while (0)
; #define PG8_LDB(dst, b, h) do { _Pragma("unroll") for (int n = 0; n < 2; ++n) _Pragma("unroll") for (int k = 0; k < 2; ++k) dst[n][k] = *(const PG8_LAS bf16x8*)(lds + PG8_SB(b, h) + boff + n * 2048 + k * 1024); } while (0)
; #define PG8_MMA(ai, bj, At, Bt) do { __builtin_amdgcn_s_setprio(1); _Pragma("unroll") for (int m = 0; m < 4; ++m) _Pragma("unroll") for (int n = 0; n < 2; ++n) _Pragma("unroll") for (int k = 0; k < 2; ++k) \
;         acc[ai][bj][m][n] = __builtin_amdgcn_mfma_f32_16x16x32_bf16(Bt[n][k], At[m][k], acc[ai][bj][m][n], 0, 0, 0); __builtin_amdgcn_s_setprio(0); } while (0)
; #define PG8_WAIT_V(n) asm volatile("s_waitcnt vmcnt(" #n ")" ::: "memory")
; #define PG8_WAIT_L(n) asm volatile("s_waitcnt lgkmcnt(" #n ")" ::: "memory")
; #define PG8_BAR __builtin_amdgcn_s_barrier()
; #define PG8_SCHED __builtin_amdgcn_sched_barrier(0)
; template <class Epi, class Sched, bool ALIGN_EPI = false, bool SP2 = false>
; __device__ __forceinline__ void gemm_phase(PG8_LAS unsigned char* lds, const Gemm g, const Sched& S, const Epi& E) {
;     ...
;             PG8_LDB(B0, 0, 0); PG8_LDB(B1, 0, 1); PG8_SCHED; PG8_LDA(At, 0, 0); PG8_STAGE(PG8_SA(1, 1), a1 + hstep, voffA);
;             PG8_WAIT_V(8); PG8_WAIT_L(0); PG8_BAR; PG8_MMA(0, 0, At, B0); PG8_MMA(0, 1, At, B1); PG8_BAR; PG8_SCHED;
;             PG8_LDA(At, 0, 1); PG8_STAGE(PG8_SB(0, 0), b2, voffB); PG8_STAGE(PG8_SB(0, 1), b2 + hstep, voffB); PG8_STAGE(PG8_SA(0, 0), a2, voffA);
;             PG8_WAIT_V(8); PG8_WAIT_L(0); PG8_BAR; PG8_MMA(1, 0, At, B0); PG8_MMA(1, 1, At, B1); PG8_BAR; PG8_SCHED;
.Lpw5_j:
	s_nop 0
	s_waitcnt lgkmcnt(0)
	s_setprio 1
	s_barrier
	v_mfma_f32_16x16x32_bf16 v[126:129], v[156:159], v[208:211], 0
	v_mfma_f32_16x16x32_bf16 v[122:125], v[166:169], v[208:211], 0
	v_mfma_f32_16x16x32_bf16 v[110:113], v[156:159], v[216:219], 0
	v_mfma_f32_16x16x32_bf16 v[106:109], v[166:169], v[216:219], 0
	v_mfma_f32_16x16x32_bf16 v[94:97], v[156:159], v[224:227], 0
	v_mfma_f32_16x16x32_bf16 v[90:93], v[166:169], v[224:227], 0
	v_mfma_f32_16x16x32_bf16 v[78:81], v[156:159], v[232:235], 0
	v_mfma_f32_16x16x32_bf16 v[74:77], v[166:169], v[232:235], 0
	s_setprio 0
	s_setprio 1
	v_mfma_f32_16x16x32_bf16 v[126:129], v[162:165], v[212:215], v[126:129]
	v_mfma_f32_16x16x32_bf16 v[122:125], v[170:173], v[212:215], v[122:125]
	v_mfma_f32_16x16x32_bf16 v[110:113], v[162:165], v[220:223], v[110:113]
	v_mfma_f32_16x16x32_bf16 v[106:109], v[170:173], v[220:223], v[106:109]
	v_mfma_f32_16x16x32_bf16 v[94:97], v[162:165], v[228:231], v[94:97]
	v_mfma_f32_16x16x32_bf16 v[90:93], v[170:173], v[228:231], v[90:93]
	v_mfma_f32_16x16x32_bf16 v[78:81], v[162:165], v[236:239], v[78:81]
	v_mfma_f32_16x16x32_bf16 v[74:77], v[170:173], v[236:239], v[74:77]
	s_setprio 0
	s_setprio 1
	v_mfma_f32_16x16x32_bf16 v[118:121], v[174:177], v[208:211], 0
	v_mfma_f32_16x16x32_bf16 v[114:117], v[182:185], v[208:211], 0
	v_mfma_f32_16x16x32_bf16 v[102:105], v[174:177], v[216:219], 0
	v_mfma_f32_16x16x32_bf16 v[98:101], v[182:185], v[216:219], 0
	v_mfma_f32_16x16x32_bf16 v[86:89], v[174:177], v[224:227], 0
	v_mfma_f32_16x16x32_bf16 v[82:85], v[182:185], v[224:227], 0
	v_mfma_f32_16x16x32_bf16 v[70:73], v[174:177], v[232:235], 0
	v_mfma_f32_16x16x32_bf16 v[66:69], v[182:185], v[232:235], 0
	s_setprio 0
	s_setprio 1
	v_mfma_f32_16x16x32_bf16 v[118:121], v[178:181], v[212:215], v[118:121]
	v_mfma_f32_16x16x32_bf16 v[114:117], v[204:207], v[212:215], v[114:117]
	v_mfma_f32_16x16x32_bf16 v[102:105], v[178:181], v[220:223], v[102:105]
	v_mfma_f32_16x16x32_bf16 v[98:101], v[204:207], v[220:223], v[98:101]
	v_mfma_f32_16x16x32_bf16 v[86:89], v[178:181], v[228:231], v[86:89]
	v_mfma_f32_16x16x32_bf16 v[82:85], v[204:207], v[228:231], v[82:85]
	v_mfma_f32_16x16x32_bf16 v[70:73], v[178:181], v[236:239], v[70:73]
	v_mfma_f32_16x16x32_bf16 v[66:69], v[204:207], v[236:239], v[66:69]
	s_setprio 0
	s_barrier
	s_add_i32 s47, s47, s4
	v_lshl_add_u64 v[186:187], s[40:41], 0, v[148:149]
	s_mov_b32 m0, s47
	ds_read_b128 v[208:211], v161 offset:16384
	ds_read_b128 v[212:215], v161 offset:17408
	ds_read_b128 v[216:219], v161 offset:18432
	ds_read_b128 v[220:223], v161 offset:19456
	ds_read_b128 v[224:227], v161 offset:20480
	ds_read_b128 v[228:231], v161 offset:21504
	ds_read_b128 v[232:235], v161 offset:22528
	ds_read_b128 v[236:239], v161 offset:23552
	global_load_lds_dwordx4 v[186:187], off
	s_add_i32 m0, s47, 0x2000
	s_add_u32 s76, s40, 0x80000
	v_lshl_add_u64 v[240:241], s[40:41], 0, v[144:145]
	s_addc_u32 s77, s41, 0
	s_add_i32 s47, s80, s4
	global_load_lds_dwordx4 v[240:241], off
	v_lshl_add_u64 v[242:243], s[76:77], 0, v[148:149]
	s_mov_b32 m0, s47
	v_lshl_add_u64 v[244:245], s[58:59], 0, v[146:147]
	global_load_lds_dwordx4 v[242:243], off
	v_lshl_add_u64 v[242:243], s[76:77], 0, v[144:145]
	s_add_i32 m0, s47, 0x2000
	s_nop 0
	global_load_lds_dwordx4 v[242:243], off
	v_lshl_add_u64 v[242:243], s[58:59], 0, v[150:151]
	s_mov_b32 m0, s5
	s_nop 0
	global_load_lds_dwordx4 v[242:243], off
	s_mov_b32 m0, s30
	s_nop 0
	global_load_lds_dwordx4 v[244:245], off
	s_cmp_eq_u32 s32, 0
	s_cbranch_scc1 .Lpw6_f
	s_waitcnt vmcnt(24)
	s_branch .Lpw6_j

; #define PG8_STAGE(bufoff, gbase, voff) do { _Pragma("unroll") for (int _i = 0; _i < 2; ++_i) \
;         __builtin_amdgcn_global_load_lds((const unsigned*)((const char*)(gbase) + (voff)[_i]), (PG8_LAS unsigned*)(lds + (bufoff) + ldsw + _i * 8192), 16, 0, 0); } while (0)
; #define PG8_LDA(dst, b, h) do { _Pragma("unroll") for (int m = 0; m < 4; ++m) _Pragma("unroll") for (int k = 0; k < 2; ++k) dst[m][k] = *(const PG8_LAS bf16x8*)(lds + PG8_SA(b, h) + aoff + m * 2048 + k * 1024); } while (0)
; #define PG8_LDB(dst, b, h) do { _Pragma("unroll") for (int n = 0; n < 2; ++n) _Pragma("unroll") for (int k = 0; k < 2; ++k) dst[n][k] = *(const PG8_LAS bf16x8*)(lds + PG8_SB(b, h) + boff + n * 2048 + k * 1024); } while (0)
; #define PG8_MMA(ai, bj, At, Bt) do { __builtin_amdgcn_s_setprio(1); _Pragma("unroll") for (int m = 0; m < 4; ++m) _Pragma("unroll") for (int n = 0; n < 2; ++n) _Pragma("unroll") for (int k = 0; k < 2; ++k) \
;         acc[ai][bj][m][n] = __builtin_amdgcn_mfma_f32_16x16x32_bf16(Bt[n][k], At[m][k], acc[ai][bj][m][n], 0, 0, 0); __builtin_amdgcn_s_setprio(0); } while (0)
; #define PG8_WAIT_V(n) asm volatile("s_waitcnt vmcnt(" #n ")" ::: "memory")
; #define PG8_WAIT_L(n) asm volatile("s_waitcnt lgkmcnt(" #n ")" ::: "memory")
; #define PG8_BAR __builtin_amdgcn_s_barrier()
; #define PG8_SCHED __builtin_amdgcn_sched_barrier(0)
; template <class Epi, class Sched, bool ALIGN_EPI = false, bool SP2 = false>
; __device__ __forceinline__ void gemm_phase(PG8_LAS unsigned char* lds, const Gemm g, const Sched& S, const Epi& E) {
;     ...
;             PG8_WAIT_V(8); PG8_WAIT_L(0); PG8_BAR; PG8_MMA(1, 0, At, B0); PG8_MMA(1, 1, At, B1); PG8_BAR; PG8_SCHED;
;             PG8_LDB(B0, 1, 0); PG8_LDB(B1, 1, 1); PG8_SCHED; PG8_LDA(At, 1, 0); PG8_STAGE(PG8_SA(0, 1), a2 + hstep, voffA);
;             PG8_WAIT_V(8); PG8_WAIT_L(0); PG8_BAR; PG8_MMA(0, 0, At, B0); PG8_MMA(0, 1, At, B1); PG8_BAR; PG8_SCHED;
.Lpw6_j:
	s_waitcnt lgkmcnt(0)
	s_setprio 1
	s_barrier
	v_mfma_f32_16x16x32_bf16 v[62:65], v[156:159], v[208:211], 0
	v_mfma_f32_16x16x32_bf16 v[58:61], v[166:169], v[208:211], 0
	v_mfma_f32_16x16x32_bf16 v[46:49], v[156:159], v[216:219], 0
	v_mfma_f32_16x16x32_bf16 v[42:45], v[166:169], v[216:219], 0
	v_mfma_f32_16x16x32_bf16 v[30:33], v[156:159], v[224:227], 0
	v_mfma_f32_16x16x32_bf16 v[26:29], v[166:169], v[224:227], 0
	v_mfma_f32_16x16x32_bf16 v[14:17], v[156:159], v[232:235], 0
	v_mfma_f32_16x16x32_bf16 v[10:13], v[166:169], v[232:235], 0
	v_mfma_f32_16x16x32_bf16 v[62:65], v[162:165], v[212:215], v[62:65]
	v_mfma_f32_16x16x32_bf16 v[58:61], v[170:173], v[212:215], v[58:61]
	v_mfma_f32_16x16x32_bf16 v[46:49], v[162:165], v[220:223], v[46:49]
	v_mfma_f32_16x16x32_bf16 v[42:45], v[170:173], v[220:223], v[42:45]
	v_mfma_f32_16x16x32_bf16 v[30:33], v[162:165], v[228:231], v[30:33]
	v_mfma_f32_16x16x32_bf16 v[26:29], v[170:173], v[228:231], v[26:29]
	v_mfma_f32_16x16x32_bf16 v[14:17], v[162:165], v[236:239], v[14:17]
	v_mfma_f32_16x16x32_bf16 v[10:13], v[170:173], v[236:239], v[10:13]
	v_mfma_f32_16x16x32_bf16 v[54:57], v[174:177], v[208:211], 0
	v_mfma_f32_16x16x32_bf16 v[50:53], v[182:185], v[208:211], 0
	v_mfma_f32_16x16x32_bf16 v[38:41], v[174:177], v[216:219], 0
	v_mfma_f32_16x16x32_bf16 v[34:37], v[182:185], v[216:219], 0
	v_mfma_f32_16x16x32_bf16 v[22:25], v[174:177], v[224:227], 0
	v_mfma_f32_16x16x32_bf16 v[18:21], v[182:185], v[224:227], 0
	v_mfma_f32_16x16x32_bf16 v[6:9], v[174:177], v[232:235], 0
	v_mfma_f32_16x16x32_bf16 v[2:5], v[182:185], v[232:235], 0
	v_mfma_f32_16x16x32_bf16 v[54:57], v[178:181], v[212:215], v[54:57]
	v_mfma_f32_16x16x32_bf16 v[50:53], v[204:207], v[212:215], v[50:53]
	v_mfma_f32_16x16x32_bf16 v[38:41], v[178:181], v[220:223], v[38:41]
	v_mfma_f32_16x16x32_bf16 v[34:37], v[204:207], v[220:223], v[34:37]
	v_mfma_f32_16x16x32_bf16 v[22:25], v[178:181], v[228:231], v[22:25]
	v_mfma_f32_16x16x32_bf16 v[18:21], v[204:207], v[228:231], v[18:21]
	v_mfma_f32_16x16x32_bf16 v[6:9], v[178:181], v[236:239], v[6:9]
	v_mfma_f32_16x16x32_bf16 v[2:5], v[204:207], v[236:239], v[2:5]
	s_setprio 0
	s_barrier
	s_add_i32 s47, 0, 0x18000
	s_add_i32 s76, 0, 0x1c000
	v_add_u32_e32 v170, s47, v143
	v_add_u32_e32 v203, s76, v143
	ds_read_b128 v[156:159], v170
	ds_read_b128 v[162:165], v170 offset:1024
	ds_read_b128 v[166:169], v170 offset:2048
	ds_read_b128 v[170:173], v170 offset:3072
	ds_read_b128 v[174:177], v203
	ds_read_b128 v[178:181], v203 offset:1024
	ds_read_b128 v[182:185], v203 offset:2048
	ds_read_b128 v[204:207], v203 offset:3072
	s_add_u32 s58, s58, 0x80000
	s_addc_u32 s59, s59, 0
	s_mov_b32 m0, s34
	v_lshl_add_u64 v[246:247], s[58:59], 0, v[150:151]
	ds_read_b128 v[208:211], v161 offset:32768
	ds_read_b128 v[212:215], v161 offset:33792
	ds_read_b128 v[216:219], v161 offset:34816
	ds_read_b128 v[220:223], v161 offset:35840
	ds_read_b128 v[224:227], v161 offset:36864
	ds_read_b128 v[228:231], v161 offset:37888
	ds_read_b128 v[232:235], v161 offset:38912
	ds_read_b128 v[236:239], v161 offset:39936
	global_load_lds_dwordx4 v[246:247], off
	v_lshl_add_u64 v[246:247], s[58:59], 0, v[146:147]
	s_mov_b32 m0, s57
	s_nop 0
	global_load_lds_dwordx4 v[246:247], off
	s_waitcnt vmcnt(8)
	s_waitcnt lgkmcnt(0)
	s_setprio 1
	s_barrier
	v_mfma_f32_16x16x32_bf16 v[126:129], v[156:159], v[208:211], v[126:129]
	v_mfma_f32_16x16x32_bf16 v[122:125], v[166:169], v[208:211], v[122:125]
	v_mfma_f32_16x16x32_bf16 v[110:113], v[156:159], v[216:219], v[110:113]
	v_mfma_f32_16x16x32_bf16 v[106:109], v[166:169], v[216:219], v[106:109]
	v_mfma_f32_16x16x32_bf16 v[94:97], v[156:159], v[224:227], v[94:97]
	v_mfma_f32_16x16x32_bf16 v[90:93], v[166:169], v[224:227], v[90:93]
	v_mfma_f32_16x16x32_bf16 v[78:81], v[156:159], v[232:235], v[78:81]
	v_mfma_f32_16x16x32_bf16 v[74:77], v[166:169], v[232:235], v[74:77]
	s_setprio 0
	s_setprio 1
	v_mfma_f32_16x16x32_bf16 v[126:129], v[162:165], v[212:215], v[126:129]
	v_mfma_f32_16x16x32_bf16 v[122:125], v[170:173], v[212:215], v[122:125]
	v_mfma_f32_16x16x32_bf16 v[110:113], v[162:165], v[220:223], v[110:113]
	v_mfma_f32_16x16x32_bf16 v[106:109], v[170:173], v[220:223], v[106:109]
	v_mfma_f32_16x16x32_bf16 v[94:97], v[162:165], v[228:231], v[94:97]
	v_mfma_f32_16x16x32_bf16 v[90:93], v[170:173], v[228:231], v[90:93]
	v_mfma_f32_16x16x32_bf16 v[78:81], v[162:165], v[236:239], v[78:81]
	v_mfma_f32_16x16x32_bf16 v[74:77], v[170:173], v[236:239], v[74:77]
	s_setprio 0
	s_setprio 1
	v_mfma_f32_16x16x32_bf16 v[118:121], v[174:177], v[208:211], v[118:121]
	v_mfma_f32_16x16x32_bf16 v[114:117], v[182:185], v[208:211], v[114:117]
	v_mfma_f32_16x16x32_bf16 v[102:105], v[174:177], v[216:219], v[102:105]
	v_mfma_f32_16x16x32_bf16 v[98:101], v[182:185], v[216:219], v[98:101]
	v_mfma_f32_16x16x32_bf16 v[86:89], v[174:177], v[224:227], v[86:89]
	v_mfma_f32_16x16x32_bf16 v[82:85], v[182:185], v[224:227], v[82:85]
	v_mfma_f32_16x16x32_bf16 v[70:73], v[174:177], v[232:235], v[70:73]
	v_mfma_f32_16x16x32_bf16 v[66:69], v[182:185], v[232:235], v[66:69]
	s_setprio 0
	s_setprio 1
	v_mfma_f32_16x16x32_bf16 v[118:121], v[178:181], v[212:215], v[118:121]
	v_mfma_f32_16x16x32_bf16 v[114:117], v[204:207], v[212:215], v[114:117]
	v_mfma_f32_16x16x32_bf16 v[102:105], v[178:181], v[220:223], v[102:105]
	v_mfma_f32_16x16x32_bf16 v[98:101], v[204:207], v[220:223], v[98:101]
	v_mfma_f32_16x16x32_bf16 v[86:89], v[178:181], v[228:231], v[86:89]
	v_mfma_f32_16x16x32_bf16 v[82:85], v[204:207], v[228:231], v[82:85]
	v_mfma_f32_16x16x32_bf16 v[70:73], v[178:181], v[236:239], v[70:73]
	v_mfma_f32_16x16x32_bf16 v[66:69], v[204:207], v[236:239], v[66:69]
	s_setprio 0
	s_barrier
; #define PG8_STAGE(bufoff, gbase, voff) do { _Pragma("unroll") for (int _i = 0; _i < 2; ++_i) \
;         __builtin_amdgcn_global_load_lds((const unsigned*)((const char*)(gbase) + (voff)[_i]), (PG8_LAS unsigned*)(lds + (bufoff) + ldsw + _i * 8192), 16, 0, 0); } while (0)
; #define PG8_LDA(dst, b, h) do { _Pragma("unroll") for (int m = 0; m < 4; ++m) _Pragma("unroll") for (int k = 0; k < 2; ++k) dst[m][k] = *(const PG8_LAS bf16x8*)(lds + PG8_SA(b, h) + aoff + m * 2048 + k * 1024); } while (0)
; #define PG8_LDB(dst, b, h) do { _Pragma("unroll") for (int n = 0; n < 2; ++n) _Pragma("unroll") for (int k = 0; k < 2; ++k) dst[n][k] = *(const PG8_LAS bf16x8*)(lds + PG8_SB(b, h) + boff + n * 2048 + k * 1024); } while (0)
; #define PG8_MMA(ai, bj, At, Bt) do { __builtin_amdgcn_s_setprio(1); _Pragma("unroll") for (int m = 0; m < 4; ++m) _Pragma("unroll") for (int n = 0; n < 2; ++n) _Pragma("unroll") for (int k = 0; k < 2; ++k) \
;         acc[ai][bj][m][n] = __builtin_amdgcn_mfma_f32_16x16x32_bf16(Bt[n][k], At[m][k], acc[ai][bj][m][n], 0, 0, 0); __builtin_amdgcn_s_setprio(0); } while (0)
; #define PG8_WAIT_V(n) asm volatile("s_waitcnt vmcnt(" #n ")" ::: "memory")
; #define PG8_WAIT_L(n) asm volatile("s_waitcnt lgkmcnt(" #n ")" ::: "memory")
; #define PG8_BAR __builtin_amdgcn_s_barrier()
; #define PG8_SCHED __builtin_amdgcn_sched_barrier(0)
; template <class Epi, class Sched, bool ALIGN_EPI = false, bool SP2 = false>
; __device__ __forceinline__ void gemm_phase(PG8_LAS unsigned char* lds, const Gemm g, const Sched& S, const Epi& E) {
;     ...
;             PG8_LDB(B0, 0, 0); PG8_LDB(B1, 0, 1); PG8_SCHED; PG8_LDA(At, 0, 0); PG8_STAGE(PG8_SA(1, 1), a1 + hstep, voffA);
;             PG8_WAIT_V(8); PG8_WAIT_L(0); PG8_BAR; PG8_MMA(0, 0, At, B0); PG8_MMA(0, 1, At, B1); PG8_BAR; PG8_SCHED;
;     ...
;             PG8_LDA(At, 1, 1); PG8_STAGE(PG8_SB(1, 0), b3, voffB); PG8_STAGE(PG8_SB(1, 1), b3 + hstep, voffB); PG8_STAGE(PG8_SA(1, 0), a3, voffA);
;             PG8_WAIT_V(8); PG8_WAIT_L(0); PG8_BAR; PG8_MMA(1, 0, At, B0); PG8_MMA(1, 1, At, B1); PG8_BAR; PG8_SCHED;
	s_add_i32 s47, s47, s4
	v_lshl_add_u64 v[186:187], v[186:187], 0, s[68:69]
	s_mov_b32 m0, s47
	ds_read_b128 v[208:211], v161 offset:49152
	ds_read_b128 v[212:215], v161 offset:50176
	ds_read_b128 v[216:219], v161 offset:51200
	ds_read_b128 v[220:223], v161 offset:52224
	ds_read_b128 v[224:227], v161 offset:53248
	ds_read_b128 v[228:231], v161 offset:54272
	ds_read_b128 v[232:235], v161 offset:55296
	ds_read_b128 v[236:239], v161 offset:56320
	global_load_lds_dwordx4 v[186:187], off
	s_add_i32 m0, s47, 0x2000
	s_add_u32 s40, s40, 0x80080
	v_lshl_add_u64 v[186:187], v[240:241], 0, s[68:69]
	s_addc_u32 s41, s41, 0
	s_add_i32 s47, s76, s4
	global_load_lds_dwordx4 v[186:187], off
	v_lshl_add_u64 v[186:187], s[40:41], 0, v[148:149]
	s_mov_b32 m0, s47
	s_nop 0
	global_load_lds_dwordx4 v[186:187], off
	v_lshl_add_u64 v[186:187], s[40:41], 0, v[144:145]
	s_add_i32 m0, s47, 0x2000
	s_nop 0
	global_load_lds_dwordx4 v[186:187], off
	v_lshl_add_u64 v[186:187], v[242:243], 0, s[68:69]
	s_mov_b32 m0, s67
	s_nop 0
	global_load_lds_dwordx4 v[186:187], off
	v_lshl_add_u64 v[186:187], v[244:245], 0, s[68:69]
	s_mov_b32 m0, s28
	s_nop 0
	global_load_lds_dwordx4 v[186:187], off
	s_nop 0
	s_waitcnt vmcnt(8)
	s_waitcnt lgkmcnt(0)
	s_setprio 1
	s_barrier
	v_mfma_f32_16x16x32_bf16 v[62:65], v[156:159], v[208:211], v[62:65]
	v_mfma_f32_16x16x32_bf16 v[58:61], v[166:169], v[208:211], v[58:61]
	v_mfma_f32_16x16x32_bf16 v[46:49], v[156:159], v[216:219], v[46:49]
	v_mfma_f32_16x16x32_bf16 v[42:45], v[166:169], v[216:219], v[42:45]
	v_mfma_f32_16x16x32_bf16 v[30:33], v[156:159], v[224:227], v[30:33]
	v_mfma_f32_16x16x32_bf16 v[26:29], v[166:169], v[224:227], v[26:29]
	v_mfma_f32_16x16x32_bf16 v[14:17], v[156:159], v[232:235], v[14:17]
	v_mfma_f32_16x16x32_bf16 v[10:13], v[166:169], v[232:235], v[10:13]
	v_mfma_f32_16x16x32_bf16 v[62:65], v[162:165], v[212:215], v[62:65]
	v_mfma_f32_16x16x32_bf16 v[58:61], v[170:173], v[212:215], v[58:61]
	v_mfma_f32_16x16x32_bf16 v[46:49], v[162:165], v[220:223], v[46:49]
	v_mfma_f32_16x16x32_bf16 v[42:45], v[170:173], v[220:223], v[42:45]
	v_mfma_f32_16x16x32_bf16 v[30:33], v[162:165], v[228:231], v[30:33]
	v_mfma_f32_16x16x32_bf16 v[26:29], v[170:173], v[228:231], v[26:29]
	v_mfma_f32_16x16x32_bf16 v[14:17], v[162:165], v[236:239], v[14:17]
	v_mfma_f32_16x16x32_bf16 v[10:13], v[170:173], v[236:239], v[10:13]
	v_mfma_f32_16x16x32_bf16 v[54:57], v[174:177], v[208:211], v[54:57]
	v_mfma_f32_16x16x32_bf16 v[50:53], v[182:185], v[208:211], v[50:53]
	v_mfma_f32_16x16x32_bf16 v[38:41], v[174:177], v[216:219], v[38:41]
	v_mfma_f32_16x16x32_bf16 v[34:37], v[182:185], v[216:219], v[34:37]
	v_mfma_f32_16x16x32_bf16 v[22:25], v[174:177], v[224:227], v[22:25]
	v_mfma_f32_16x16x32_bf16 v[18:21], v[182:185], v[224:227], v[18:21]
	v_mfma_f32_16x16x32_bf16 v[6:9], v[174:177], v[232:235], v[6:9]
	v_mfma_f32_16x16x32_bf16 v[2:5], v[182:185], v[232:235], v[2:5]
	v_mfma_f32_16x16x32_bf16 v[54:57], v[178:181], v[212:215], v[54:57]
	v_mfma_f32_16x16x32_bf16 v[50:53], v[204:207], v[212:215], v[50:53]
	v_mfma_f32_16x16x32_bf16 v[38:41], v[178:181], v[220:223], v[38:41]
	v_mfma_f32_16x16x32_bf16 v[34:37], v[204:207], v[220:223], v[34:37]
	v_mfma_f32_16x16x32_bf16 v[22:25], v[178:181], v[228:231], v[22:25]
	v_mfma_f32_16x16x32_bf16 v[18:21], v[204:207], v[228:231], v[18:21]
	v_mfma_f32_16x16x32_bf16 v[6:9], v[178:181], v[236:239], v[6:9]
	v_mfma_f32_16x16x32_bf16 v[2:5], v[204:207], v[236:239], v[2:5]
	s_setprio 0
	s_barrier
	s_add_i32 s46, s46, 2
	s_add_u32 vcc_lo, vcc_lo, 0x100
	s_addc_u32 vcc_hi, vcc_hi, 0
	s_add_u32 s78, s78, 0x100
	s_addc_u32 s79, s79, 0
	s_cmp_gt_u32 s46, 29
.LBB0_98:
	s_add_u32 s40, vcc_lo, 0xfff80080
	s_addc_u32 s41, vcc_hi, -1
	s_add_i32 s47, 0, 0x10000
	s_cmp_eq_u32 s46, 28
	s_cselect_b32 s59, s97, s41
	s_cselect_b32 s58, s84, s40
	s_cselect_b32 s41, s85, s79
	s_cselect_b32 s40, s95, s78
	s_add_i32 s80, 0, 0x14000
	v_add_u32_e32 v170, s47, v143
	v_add_u32_e32 v186, s80, v143
	ds_read_b128 v[156:159], v170
	ds_read_b128 v[162:165], v170 offset:1024
	ds_read_b128 v[166:169], v170 offset:2048
	ds_read_b128 v[170:173], v170 offset:3072
	ds_read_b128 v[174:177], v186
	ds_read_b128 v[178:181], v186 offset:1024
	ds_read_b128 v[182:185], v186 offset:2048
	ds_read_b128 v[204:207], v186 offset:3072
	v_lshl_add_u64 v[186:187], vcc, 0, v[152:153]
	s_add_i32 m0, s5, 0xc000
	ds_read_b128 v[208:211], v161
	ds_read_b128 v[212:215], v161 offset:1024
	ds_read_b128 v[216:219], v161 offset:2048
	ds_read_b128 v[220:223], v161 offset:3072
	ds_read_b128 v[224:227], v161 offset:4096
	ds_read_b128 v[228:231], v161 offset:5120
	ds_read_b128 v[232:235], v161 offset:6144
	ds_read_b128 v[236:239], v161 offset:7168
	global_load_lds_dwordx4 v[186:187], off
	v_lshl_add_u64 v[186:187], vcc, 0, v[154:155]
	s_add_i32 m0, s5, 0xe000
	s_nop 0
	global_load_lds_dwordx4 v[186:187], off
	s_nop 0
	s_waitcnt vmcnt(8)
	s_waitcnt lgkmcnt(0)
	s_setprio 1
	s_barrier
; #define PG8_STAGE(bufoff, gbase, voff) do { _Pragma("unroll") for (int _i = 0; _i < 2; ++_i) \
;         __builtin_amdgcn_global_load_lds((const unsigned*)((const char*)(gbase) + (voff)[_i]), (PG8_LAS unsigned*)(lds + (bufoff) + ldsw + _i * 8192), 16, 0, 0); } while (0)
; #define PG8_LDA(dst, b, h) do { _Pragma("unroll") for (int m = 0; m < 4; ++m) _Pragma("unroll") for (int k = 0; k < 2; ++k) dst[m][k] = *(const PG8_LAS bf16x8*)(lds + PG8_SA(b, h) + aoff + m * 2048 + k * 1024); } while (0)
; #define PG8_MMA(ai, bj, At, Bt) do { __builtin_amdgcn_s_setprio(1); _Pragma("unroll") for (int m = 0; m < 4; ++m) _Pragma("unroll") for (int n = 0; n < 2; ++n) _Pragma("unroll") for (int k = 0; k < 2; ++k) \
;         acc[ai][bj][m][n] = __builtin_amdgcn_mfma_f32_16x16x32_bf16(Bt[n][k], At[m][k], acc[ai][bj][m][n], 0, 0, 0); __builtin_amdgcn_s_setprio(0); } while (0)
; #define PG8_WAIT_V(n) asm volatile("s_waitcnt vmcnt(" #n ")" ::: "memory")
; #define PG8_WAIT_L(n) asm volatile("s_waitcnt lgkmcnt(" #n ")" ::: "memory")
; #define PG8_BAR __builtin_amdgcn_s_barrier()
; #define PG8_SCHED __builtin_amdgcn_sched_barrier(0)
; template <class Epi, class Sched, bool ALIGN_EPI = false, bool SP2 = false>
; __device__ __forceinline__ void gemm_phase(PG8_LAS unsigned char* lds, const Gemm g, const Sched& S, const Epi& E) {
;     ...
;             PG8_WAIT_V(8); PG8_WAIT_L(0); PG8_BAR; PG8_MMA(0, 0, At, B0); PG8_MMA(0, 1, At, B1); PG8_BAR; PG8_SCHED;
;             PG8_LDA(At, 0, 1); PG8_STAGE(PG8_SB(0, 0), b2, voffB); PG8_STAGE(PG8_SB(0, 1), b2 + hstep, voffB); PG8_STAGE(PG8_SA(0, 0), a2, voffA);
;             PG8_WAIT_V(8); PG8_WAIT_L(0); PG8_BAR; PG8_MMA(1, 0, At, B0); PG8_MMA(1, 1, At, B1); PG8_BAR; PG8_SCHED;
	v_mfma_f32_16x16x32_bf16 v[126:129], v[156:159], v[208:211], v[126:129]
	v_mfma_f32_16x16x32_bf16 v[122:125], v[166:169], v[208:211], v[122:125]
	v_mfma_f32_16x16x32_bf16 v[110:113], v[156:159], v[216:219], v[110:113]
	v_mfma_f32_16x16x32_bf16 v[106:109], v[166:169], v[216:219], v[106:109]
	v_mfma_f32_16x16x32_bf16 v[94:97], v[156:159], v[224:227], v[94:97]
	v_mfma_f32_16x16x32_bf16 v[90:93], v[166:169], v[224:227], v[90:93]
	v_mfma_f32_16x16x32_bf16 v[78:81], v[156:159], v[232:235], v[78:81]
	v_mfma_f32_16x16x32_bf16 v[74:77], v[166:169], v[232:235], v[74:77]
	s_setprio 0
	s_setprio 1
	v_mfma_f32_16x16x32_bf16 v[126:129], v[162:165], v[212:215], v[126:129]
	v_mfma_f32_16x16x32_bf16 v[122:125], v[170:173], v[212:215], v[122:125]
	v_mfma_f32_16x16x32_bf16 v[110:113], v[162:165], v[220:223], v[110:113]
	v_mfma_f32_16x16x32_bf16 v[106:109], v[170:173], v[220:223], v[106:109]
	v_mfma_f32_16x16x32_bf16 v[94:97], v[162:165], v[228:231], v[94:97]
	v_mfma_f32_16x16x32_bf16 v[90:93], v[170:173], v[228:231], v[90:93]
	v_mfma_f32_16x16x32_bf16 v[78:81], v[162:165], v[236:239], v[78:81]
	v_mfma_f32_16x16x32_bf16 v[74:77], v[170:173], v[236:239], v[74:77]
	s_setprio 0
	s_setprio 1
	v_mfma_f32_16x16x32_bf16 v[118:121], v[174:177], v[208:211], v[118:121]
	v_mfma_f32_16x16x32_bf16 v[114:117], v[182:185], v[208:211], v[114:117]
	v_mfma_f32_16x16x32_bf16 v[102:105], v[174:177], v[216:219], v[102:105]
	v_mfma_f32_16x16x32_bf16 v[98:101], v[182:185], v[216:219], v[98:101]
	v_mfma_f32_16x16x32_bf16 v[86:89], v[174:177], v[224:227], v[86:89]
	v_mfma_f32_16x16x32_bf16 v[82:85], v[182:185], v[224:227], v[82:85]
	v_mfma_f32_16x16x32_bf16 v[70:73], v[174:177], v[232:235], v[70:73]
	v_mfma_f32_16x16x32_bf16 v[66:69], v[182:185], v[232:235], v[66:69]
	s_setprio 0
	s_setprio 1
	v_mfma_f32_16x16x32_bf16 v[118:121], v[178:181], v[212:215], v[118:121]
	v_mfma_f32_16x16x32_bf16 v[114:117], v[204:207], v[212:215], v[114:117]
	v_mfma_f32_16x16x32_bf16 v[102:105], v[178:181], v[220:223], v[102:105]
	v_mfma_f32_16x16x32_bf16 v[98:101], v[204:207], v[220:223], v[98:101]
	v_mfma_f32_16x16x32_bf16 v[86:89], v[178:181], v[228:231], v[86:89]
	v_mfma_f32_16x16x32_bf16 v[82:85], v[204:207], v[228:231], v[82:85]
	v_mfma_f32_16x16x32_bf16 v[70:73], v[178:181], v[236:239], v[70:73]
	v_mfma_f32_16x16x32_bf16 v[66:69], v[204:207], v[236:239], v[66:69]
	s_setprio 0
	s_barrier
	s_add_i32 s47, s47, s4
	v_lshl_add_u64 v[186:187], s[40:41], 0, v[148:149]
	s_mov_b32 m0, s47
	ds_read_b128 v[208:211], v161 offset:16384
	ds_read_b128 v[212:215], v161 offset:17408
	ds_read_b128 v[216:219], v161 offset:18432
	ds_read_b128 v[220:223], v161 offset:19456
	ds_read_b128 v[224:227], v161 offset:20480
	ds_read_b128 v[228:231], v161 offset:21504
	ds_read_b128 v[232:235], v161 offset:22528
	ds_read_b128 v[236:239], v161 offset:23552
	global_load_lds_dwordx4 v[186:187], off
	s_add_i32 m0, s47, 0x2000
	s_add_u32 s76, s40, 0x80000
	v_lshl_add_u64 v[240:241], s[40:41], 0, v[144:145]
	s_addc_u32 s77, s41, 0
	s_add_i32 s47, s80, s4
	global_load_lds_dwordx4 v[240:241], off
	v_lshl_add_u64 v[242:243], s[76:77], 0, v[148:149]
	s_mov_b32 m0, s47
	v_lshl_add_u64 v[244:245], s[58:59], 0, v[146:147]
	global_load_lds_dwordx4 v[242:243], off
	v_lshl_add_u64 v[242:243], s[76:77], 0, v[144:145]
	s_add_i32 m0, s47, 0x2000
	s_nop 0
	global_load_lds_dwordx4 v[242:243], off
	v_lshl_add_u64 v[242:243], s[58:59], 0, v[150:151]
	s_mov_b32 m0, s5
	s_nop 0
	global_load_lds_dwordx4 v[242:243], off
	s_mov_b32 m0, s30
	s_nop 0
	global_load_lds_dwordx4 v[244:245], off
	s_waitcnt vmcnt(8)
	s_waitcnt lgkmcnt(0)
	s_setprio 1
	s_barrier
	v_mfma_f32_16x16x32_bf16 v[62:65], v[156:159], v[208:211], v[62:65]
	v_mfma_f32_16x16x32_bf16 v[58:61], v[166:169], v[208:211], v[58:61]
	v_mfma_f32_16x16x32_bf16 v[46:49], v[156:159], v[216:219], v[46:49]
	v_mfma_f32_16x16x32_bf16 v[42:45], v[166:169], v[216:219], v[42:45]
	v_mfma_f32_16x16x32_bf16 v[30:33], v[156:159], v[224:227], v[30:33]
	v_mfma_f32_16x16x32_bf16 v[26:29], v[166:169], v[224:227], v[26:29]
	v_mfma_f32_16x16x32_bf16 v[14:17], v[156:159], v[232:235], v[14:17]
	v_mfma_f32_16x16x32_bf16 v[10:13], v[166:169], v[232:235], v[10:13]
	v_mfma_f32_16x16x32_bf16 v[62:65], v[162:165], v[212:215], v[62:65]
	v_mfma_f32_16x16x32_bf16 v[58:61], v[170:173], v[212:215], v[58:61]
	v_mfma_f32_16x16x32_bf16 v[46:49], v[162:165], v[220:223], v[46:49]
	v_mfma_f32_16x16x32_bf16 v[42:45], v[170:173], v[220:223], v[42:45]
	v_mfma_f32_16x16x32_bf16 v[30:33], v[162:165], v[228:231], v[30:33]
	v_mfma_f32_16x16x32_bf16 v[26:29], v[170:173], v[228:231], v[26:29]
	v_mfma_f32_16x16x32_bf16 v[14:17], v[162:165], v[236:239], v[14:17]
	v_mfma_f32_16x16x32_bf16 v[10:13], v[170:173], v[236:239], v[10:13]
	v_mfma_f32_16x16x32_bf16 v[54:57], v[174:177], v[208:211], v[54:57]
	v_mfma_f32_16x16x32_bf16 v[50:53], v[182:185], v[208:211], v[50:53]
	v_mfma_f32_16x16x32_bf16 v[38:41], v[174:177], v[216:219], v[38:41]
	v_mfma_f32_16x16x32_bf16 v[34:37], v[182:185], v[216:219], v[34:37]
	v_mfma_f32_16x16x32_bf16 v[22:25], v[174:177], v[224:227], v[22:25]
	v_mfma_f32_16x16x32_bf16 v[18:21], v[182:185], v[224:227], v[18:21]
	v_mfma_f32_16x16x32_bf16 v[6:9], v[174:177], v[232:235], v[6:9]
	v_mfma_f32_16x16x32_bf16 v[2:5], v[182:185], v[232:235], v[2:5]
	v_mfma_f32_16x16x32_bf16 v[54:57], v[178:181], v[212:215], v[54:57]
	v_mfma_f32_16x16x32_bf16 v[50:53], v[204:207], v[212:215], v[50:53]
	v_mfma_f32_16x16x32_bf16 v[38:41], v[178:181], v[220:223], v[38:41]
	v_mfma_f32_16x16x32_bf16 v[34:37], v[204:207], v[220:223], v[34:37]
	v_mfma_f32_16x16x32_bf16 v[22:25], v[178:181], v[228:231], v[22:25]
	v_mfma_f32_16x16x32_bf16 v[18:21], v[204:207], v[228:231], v[18:21]
	v_mfma_f32_16x16x32_bf16 v[6:9], v[178:181], v[236:239], v[6:9]
	v_mfma_f32_16x16x32_bf16 v[2:5], v[204:207], v[236:239], v[2:5]
	s_setprio 0
	s_barrier
; #define PG8_STAGE(bufoff, gbase, voff) do { _Pragma("unroll") for (int _i = 0; _i < 2; ++_i) \
;         __builtin_amdgcn_global_load_lds((const unsigned*)((const char*)(gbase) + (voff)[_i]), (PG8_LAS unsigned*)(lds + (bufoff) + ldsw + _i * 8192), 16, 0, 0); } while (0)
; #define PG8_LDA(dst, b, h) do { _Pragma("unroll") for (int m = 0; m < 4; ++m) _Pragma("unroll") for (int k = 0; k < 2; ++k) dst[m][k] = *(const PG8_LAS bf16x8*)(lds + PG8_SA(b, h) + aoff + m * 2048 + k * 1024); } while (0)
; #define PG8_LDB(dst, b, h) do { _Pragma("unroll") for (int n = 0; n < 2; ++n) _Pragma("unroll") for (int k = 0; k < 2; ++k) dst[n][k] = *(const PG8_LAS bf16x8*)(lds + PG8_SB(b, h) + boff + n * 2048 + k * 1024); } while (0)
; #define PG8_MMA(ai, bj, At, Bt) do { __builtin_amdgcn_s_setprio(1); _Pragma("unroll") for (int m = 0; m < 4; ++m) _Pragma("unroll") for (int n = 0; n < 2; ++n) _Pragma("unroll") for (int k = 0; k < 2; ++k) \
;         acc[ai][bj][m][n] = __builtin_amdgcn_mfma_f32_16x16x32_bf16(Bt[n][k], At[m][k], acc[ai][bj][m][n], 0, 0, 0); __builtin_amdgcn_s_setprio(0); } while (0)
; #define PG8_WAIT_V(n) asm volatile("s_waitcnt vmcnt(" #n ")" ::: "memory")
; #define PG8_WAIT_L(n) asm volatile("s_waitcnt lgkmcnt(" #n ")" ::: "memory")
; #define PG8_BAR __builtin_amdgcn_s_barrier()
; #define PG8_SCHED __builtin_amdgcn_sched_barrier(0)
; template <class Epi, class Sched, bool ALIGN_EPI = false, bool SP2 = false>
; __device__ __forceinline__ void gemm_phase(PG8_LAS unsigned char* lds, const Gemm g, const Sched& S, const Epi& E) {
;     ...
;             PG8_LDB(B0, 1, 0); PG8_LDB(B1, 1, 1); PG8_SCHED; PG8_LDA(At, 1, 0); PG8_STAGE(PG8_SA(0, 1), a2 + hstep, voffA);
;             PG8_WAIT_V(8); PG8_WAIT_L(0); PG8_BAR; PG8_MMA(0, 0, At, B0); PG8_MMA(0, 1, At, B1); PG8_BAR; PG8_SCHED;
;             PG8_LDA(At, 1, 1); PG8_STAGE(PG8_SB(1, 0), b3, voffB); PG8_STAGE(PG8_SB(1, 1), b3 + hstep, voffB); PG8_STAGE(PG8_SA(1, 0), a3, voffA);
;             PG8_WAIT_V(8); PG8_WAIT_L(0); PG8_BAR; PG8_MMA(1, 0, At, B0); PG8_MMA(1, 1, At, B1); PG8_BAR; PG8_SCHED;
	s_add_i32 s47, 0, 0x18000
	s_add_i32 s76, 0, 0x1c000
	v_add_u32_e32 v170, s47, v143
	v_add_u32_e32 v203, s76, v143
	ds_read_b128 v[156:159], v170
	ds_read_b128 v[162:165], v170 offset:1024
	ds_read_b128 v[166:169], v170 offset:2048
	ds_read_b128 v[170:173], v170 offset:3072
	ds_read_b128 v[174:177], v203
	ds_read_b128 v[178:181], v203 offset:1024
	ds_read_b128 v[182:185], v203 offset:2048
	ds_read_b128 v[204:207], v203 offset:3072
	s_add_u32 s58, s58, 0x80000
	s_addc_u32 s59, s59, 0
	s_mov_b32 m0, s34
	v_lshl_add_u64 v[246:247], s[58:59], 0, v[150:151]
	ds_read_b128 v[208:211], v161 offset:32768
	ds_read_b128 v[212:215], v161 offset:33792
	ds_read_b128 v[216:219], v161 offset:34816
	ds_read_b128 v[220:223], v161 offset:35840
	ds_read_b128 v[224:227], v161 offset:36864
	ds_read_b128 v[228:231], v161 offset:37888
	ds_read_b128 v[232:235], v161 offset:38912
	ds_read_b128 v[236:239], v161 offset:39936
	global_load_lds_dwordx4 v[246:247], off
	v_lshl_add_u64 v[246:247], s[58:59], 0, v[146:147]
	s_mov_b32 m0, s57
	s_nop 0
	global_load_lds_dwordx4 v[246:247], off
	s_waitcnt vmcnt(8)
	s_waitcnt lgkmcnt(0)
	s_setprio 1
	s_barrier
	v_mfma_f32_16x16x32_bf16 v[126:129], v[156:159], v[208:211], v[126:129]
	v_mfma_f32_16x16x32_bf16 v[122:125], v[166:169], v[208:211], v[122:125]
	v_mfma_f32_16x16x32_bf16 v[110:113], v[156:159], v[216:219], v[110:113]
	v_mfma_f32_16x16x32_bf16 v[106:109], v[166:169], v[216:219], v[106:109]
	v_mfma_f32_16x16x32_bf16 v[94:97], v[156:159], v[224:227], v[94:97]
	v_mfma_f32_16x16x32_bf16 v[90:93], v[166:169], v[224:227], v[90:93]
	v_mfma_f32_16x16x32_bf16 v[78:81], v[156:159], v[232:235], v[78:81]
	v_mfma_f32_16x16x32_bf16 v[74:77], v[166:169], v[232:235], v[74:77]
	s_setprio 0
	s_setprio 1
	v_mfma_f32_16x16x32_bf16 v[126:129], v[162:165], v[212:215], v[126:129]
	v_mfma_f32_16x16x32_bf16 v[122:125], v[170:173], v[212:215], v[122:125]
	v_mfma_f32_16x16x32_bf16 v[110:113], v[162:165], v[220:223], v[110:113]
	v_mfma_f32_16x16x32_bf16 v[106:109], v[170:173], v[220:223], v[106:109]
	v_mfma_f32_16x16x32_bf16 v[94:97], v[162:165], v[228:231], v[94:97]
	v_mfma_f32_16x16x32_bf16 v[90:93], v[170:173], v[228:231], v[90:93]
	v_mfma_f32_16x16x32_bf16 v[78:81], v[162:165], v[236:239], v[78:81]
	v_mfma_f32_16x16x32_bf16 v[74:77], v[170:173], v[236:239], v[74:77]
	s_setprio 0
	s_setprio 1
	v_mfma_f32_16x16x32_bf16 v[118:121], v[174:177], v[208:211], v[118:121]
	v_mfma_f32_16x16x32_bf16 v[114:117], v[182:185], v[208:211], v[114:117]
	v_mfma_f32_16x16x32_bf16 v[102:105], v[174:177], v[216:219], v[102:105]
	v_mfma_f32_16x16x32_bf16 v[98:101], v[182:185], v[216:219], v[98:101]
	v_mfma_f32_16x16x32_bf16 v[86:89], v[174:177], v[224:227], v[86:89]
	v_mfma_f32_16x16x32_bf16 v[82:85], v[182:185], v[224:227], v[82:85]
	v_mfma_f32_16x16x32_bf16 v[70:73], v[174:177], v[232:235], v[70:73]
	v_mfma_f32_16x16x32_bf16 v[66:69], v[182:185], v[232:235], v[66:69]
	s_setprio 0
	s_setprio 1
	v_mfma_f32_16x16x32_bf16 v[118:121], v[178:181], v[212:215], v[118:121]
	v_mfma_f32_16x16x32_bf16 v[114:117], v[204:207], v[212:215], v[114:117]
	v_mfma_f32_16x16x32_bf16 v[102:105], v[178:181], v[220:223], v[102:105]
	v_mfma_f32_16x16x32_bf16 v[98:101], v[204:207], v[220:223], v[98:101]
	v_mfma_f32_16x16x32_bf16 v[86:89], v[178:181], v[228:231], v[86:89]
	v_mfma_f32_16x16x32_bf16 v[82:85], v[204:207], v[228:231], v[82:85]
	v_mfma_f32_16x16x32_bf16 v[70:73], v[178:181], v[236:239], v[70:73]
	v_mfma_f32_16x16x32_bf16 v[66:69], v[204:207], v[236:239], v[66:69]
	s_setprio 0
	s_barrier
	s_add_i32 s47, s47, s4
	v_lshl_add_u64 v[186:187], v[186:187], 0, s[68:69]
	s_mov_b32 m0, s47
	ds_read_b128 v[208:211], v161 offset:49152
	ds_read_b128 v[212:215], v161 offset:50176
	ds_read_b128 v[216:219], v161 offset:51200
	ds_read_b128 v[220:223], v161 offset:52224
	ds_read_b128 v[224:227], v161 offset:53248
	ds_read_b128 v[228:231], v161 offset:54272
	ds_read_b128 v[232:235], v161 offset:55296
	ds_read_b128 v[236:239], v161 offset:56320
	global_load_lds_dwordx4 v[186:187], off
	s_add_i32 m0, s47, 0x2000
	s_add_u32 s40, s40, 0x80080
	v_lshl_add_u64 v[186:187], v[240:241], 0, s[68:69]
	s_addc_u32 s41, s41, 0
	s_add_i32 s47, s76, s4
	global_load_lds_dwordx4 v[186:187], off
	v_lshl_add_u64 v[186:187], s[40:41], 0, v[148:149]
	s_mov_b32 m0, s47
	s_nop 0
	global_load_lds_dwordx4 v[186:187], off
	v_lshl_add_u64 v[186:187], s[40:41], 0, v[144:145]
	s_add_i32 m0, s47, 0x2000
	s_nop 0
	global_load_lds_dwordx4 v[186:187], off
	v_lshl_add_u64 v[186:187], v[242:243], 0, s[68:69]
	s_mov_b32 m0, s67
	s_nop 0
	global_load_lds_dwordx4 v[186:187], off
	v_lshl_add_u64 v[186:187], v[244:245], 0, s[68:69]
	s_mov_b32 m0, s28
	s_nop 0
	global_load_lds_dwordx4 v[186:187], off
	s_nop 0
	s_waitcnt vmcnt(8)
	s_waitcnt lgkmcnt(0)
	s_setprio 1
	s_barrier
; #define PG8_STAGE(bufoff, gbase, voff) do { _Pragma("unroll") for (int _i = 0; _i < 2; ++_i) \
;         __builtin_amdgcn_global_load_lds((const unsigned*)((const char*)(gbase) + (voff)[_i]), (PG8_LAS unsigned*)(lds + (bufoff) + ldsw + _i * 8192), 16, 0, 0); } while (0)
; #define PG8_LDA(dst, b, h) do { _Pragma("unroll") for (int m = 0; m < 4; ++m) _Pragma("unroll") for (int k = 0; k < 2; ++k) dst[m][k] = *(const PG8_LAS bf16x8*)(lds + PG8_SA(b, h) + aoff + m * 2048 + k * 1024); } while (0)
; #define PG8_MMA(ai, bj, At, Bt) do { __builtin_amdgcn_s_setprio(1); _Pragma("unroll") for (int m = 0; m < 4; ++m) _Pragma("unroll") for (int n = 0; n < 2; ++n) _Pragma("unroll") for (int k = 0; k < 2; ++k) \
;         acc[ai][bj][m][n] = __builtin_amdgcn_mfma_f32_16x16x32_bf16(Bt[n][k], At[m][k], acc[ai][bj][m][n], 0, 0, 0); __builtin_amdgcn_s_setprio(0); } while (0)
; #define PG8_WAIT_V(n) asm volatile("s_waitcnt vmcnt(" #n ")" ::: "memory")
; #define PG8_WAIT_L(n) asm volatile("s_waitcnt lgkmcnt(" #n ")" ::: "memory")
; #define PG8_BAR __builtin_amdgcn_s_barrier()
; #define PG8_SCHED __builtin_amdgcn_sched_barrier(0)
;     __device__ __forceinline__ void operator()(const f32x4 (&acc)[2][2][4][2], const Unit& u, int wr, int wc, int fr, int fq) const {
;         const int row0 = u.pm * BM + wr * 64 + fr, col0 = u.pn * BM + wc * 32 + 8 * fq;
; #pragma unroll
;         for (int ai = 0; ai < 2; ++ai)
; #pragma unroll
;             for (int m = 0; m < 4; ++m) { const size_t row = (size_t)(row0 + ai * HALF + m * 16); float ss = 0.f;
; #pragma unroll
;                 for (int bj = 0; bj < 2; ++bj) { const size_t off = row * DM + col0 + bj * HALF;
;                     f32x4 v0 = acc[ai][bj][m][0] + *(const f32x4*)(base + off), v1 = acc[ai][bj][m][1] + *(const f32x4*)(base + off + 4);
; template <class Epi, class Sched, bool ALIGN_EPI = false, bool SP2 = false>
; __device__ __forceinline__ void gemm_phase(PG8_LAS unsigned char* lds, const Gemm g, const Sched& S, const Epi& E) {
;     ...
;             PG8_LDA(At, 1, 1); PG8_STAGE(PG8_SB(1, 0), b3, voffB); PG8_STAGE(PG8_SB(1, 1), b3 + hstep, voffB); PG8_STAGE(PG8_SA(1, 0), a3, voffA);
;             PG8_WAIT_V(8); PG8_WAIT_L(0); PG8_BAR; PG8_MMA(1, 0, At, B0); PG8_MMA(1, 1, At, B1); PG8_BAR; PG8_SCHED;
	v_mfma_f32_16x16x32_bf16 v[62:65], v[156:159], v[208:211], v[62:65]
	v_mfma_f32_16x16x32_bf16 v[58:61], v[166:169], v[208:211], v[58:61]
	v_mfma_f32_16x16x32_bf16 v[46:49], v[156:159], v[216:219], v[46:49]
	v_mfma_f32_16x16x32_bf16 v[42:45], v[166:169], v[216:219], v[42:45]
	v_mfma_f32_16x16x32_bf16 v[30:33], v[156:159], v[224:227], v[30:33]
	v_mfma_f32_16x16x32_bf16 v[26:29], v[166:169], v[224:227], v[26:29]
	v_mfma_f32_16x16x32_bf16 v[14:17], v[156:159], v[232:235], v[14:17]
	v_mfma_f32_16x16x32_bf16 v[10:13], v[166:169], v[232:235], v[10:13]
	v_mfma_f32_16x16x32_bf16 v[62:65], v[162:165], v[212:215], v[62:65]
	v_mfma_f32_16x16x32_bf16 v[58:61], v[170:173], v[212:215], v[58:61]
	v_mfma_f32_16x16x32_bf16 v[46:49], v[162:165], v[220:223], v[46:49]
	v_mfma_f32_16x16x32_bf16 v[42:45], v[170:173], v[220:223], v[42:45]
	v_mfma_f32_16x16x32_bf16 v[30:33], v[162:165], v[228:231], v[30:33]
	v_mfma_f32_16x16x32_bf16 v[26:29], v[170:173], v[228:231], v[26:29]
	v_mfma_f32_16x16x32_bf16 v[14:17], v[162:165], v[236:239], v[14:17]
	v_mfma_f32_16x16x32_bf16 v[10:13], v[170:173], v[236:239], v[10:13]
	v_mfma_f32_16x16x32_bf16 v[54:57], v[174:177], v[208:211], v[54:57]
	v_mfma_f32_16x16x32_bf16 v[50:53], v[182:185], v[208:211], v[50:53]
	v_mfma_f32_16x16x32_bf16 v[38:41], v[174:177], v[216:219], v[38:41]
	v_mfma_f32_16x16x32_bf16 v[34:37], v[182:185], v[216:219], v[34:37]
	v_mfma_f32_16x16x32_bf16 v[22:25], v[174:177], v[224:227], v[22:25]
	v_mfma_f32_16x16x32_bf16 v[18:21], v[182:185], v[224:227], v[18:21]
	v_mfma_f32_16x16x32_bf16 v[6:9], v[174:177], v[232:235], v[6:9]
	v_mfma_f32_16x16x32_bf16 v[2:5], v[182:185], v[232:235], v[2:5]
	v_mfma_f32_16x16x32_bf16 v[54:57], v[178:181], v[212:215], v[54:57]
	v_mfma_f32_16x16x32_bf16 v[50:53], v[204:207], v[212:215], v[50:53]
	v_mfma_f32_16x16x32_bf16 v[38:41], v[178:181], v[220:223], v[38:41]
	v_mfma_f32_16x16x32_bf16 v[34:37], v[204:207], v[220:223], v[34:37]
	v_mfma_f32_16x16x32_bf16 v[22:25], v[178:181], v[228:231], v[22:25]
	v_mfma_f32_16x16x32_bf16 v[18:21], v[204:207], v[228:231], v[18:21]
	v_mfma_f32_16x16x32_bf16 v[6:9], v[178:181], v[236:239], v[6:9]
	v_mfma_f32_16x16x32_bf16 v[2:5], v[204:207], v[236:239], v[2:5]
	s_setprio 0
	s_barrier
	s_add_i32 s46, s46, 2
	s_add_u32 vcc_lo, vcc_lo, 0x100
	s_addc_u32 vcc_hi, vcc_hi, 0
	s_add_u32 s78, s78, 0x100
	s_addc_u32 s79, s79, 0
	s_cmp_gt_u32 s46, 29
	s_cbranch_scc0 .LBB0_98
	s_mov_b32 s32, 1
	v_lshl_add_u32 v156, s73, 8, v1
	v_lshl_or_b32 v157, s54, 8, v160
	v_lshl_add_u32 v157, v156, 11, v157
	v_mov_b32_e32 v247, 0
	v_lshlrev_b32_e32 v246, 2, v157
	v_lshl_add_u64 v[162:163], s[8:9], 0, v[246:247]
	v_lshlrev_b32_e32 v246, 1, v157
	v_lshl_add_u64 v[244:245], s[70:71], 0, v[246:247]
	s_mov_b32 s41, 0
	global_load_dwordx4 v[164:167], v[162:163], off
	global_load_dwordx4 v[168:171], v[162:163], off offset:16
	global_load_dwordx4 v[172:175], v[162:163], off offset:512
	global_load_dwordx4 v[176:179], v[162:163], off offset:528
	s_mov_b32 s40, 0x20000
	v_lshl_add_u64 v[246:247], v[162:163], 0, s[40:41]
	global_load_dwordx4 v[180:183], v[246:247], off
	global_load_dwordx4 v[184:187], v[246:247], off offset:16
	global_load_dwordx4 v[204:207], v[246:247], off offset:512
	global_load_dwordx4 v[208:211], v[246:247], off offset:528
	s_mov_b32 s40, 0x40000
	v_lshl_add_u64 v[246:247], v[162:163], 0, s[40:41]
	global_load_dwordx4 v[212:215], v[246:247], off
	global_load_dwordx4 v[216:219], v[246:247], off offset:16
	global_load_dwordx4 v[220:223], v[246:247], off offset:512
	global_load_dwordx4 v[224:227], v[246:247], off offset:528
	s_mov_b32 s40, 0x60000
	v_lshl_add_u64 v[246:247], v[162:163], 0, s[40:41]
	global_load_dwordx4 v[228:231], v[246:247], off
	global_load_dwordx4 v[232:235], v[246:247], off offset:16
	global_load_dwordx4 v[236:239], v[246:247], off offset:512
	global_load_dwordx4 v[240:243], v[246:247], off offset:528
	s_and_b64 vcc, exec, s[36:37]
	s_cbranch_vccz .Lx1_nobar
	s_barrier

; #define PG8_STAGE(bufoff, gbase, voff) do { _Pragma("unroll") for (int _i = 0; _i < 2; ++_i) \
;         __builtin_amdgcn_global_load_lds((const unsigned*)((const char*)(gbase) + (voff)[_i]), (PG8_LAS unsigned*)(lds + (bufoff) + ldsw + _i * 8192), 16, 0, 0); } while (0)
; #define PG8_WAIT_V(n) asm volatile("s_waitcnt vmcnt(" #n ")" ::: "memory")
; #define PG8_BAR __builtin_amdgcn_s_barrier()
; template <class Epi, class Sched, bool ALIGN_EPI = false, bool SP2 = false>
; __device__ __forceinline__ void gemm_phase(PG8_LAS unsigned char* lds, const Gemm g, const Sched& S, const Epi& E) {
;     ...
;     const int tid = tid_, wid = __builtin_amdgcn_readfirstlane(tid >> 6), lane = tid & 63, wr = wid >> 2, wc = wid & 3, fr = lane & 15, fq = lane >> 4;
;     const int K = g.K, nt = K / BK;
;     unsigned voffA[2], voffB[2];
; #pragma unroll
;     for (int i = 0; i < 2; ++i) { int R, C; stage_rc(tid * 16 + i * 8192, R, C); const int Rb = Epi::PERM ? ((R & ~31) + perm32(R & 31)) : R;
;         voffA[i] = (unsigned)(R * K + C) * 2u; voffB[i] = (unsigned)(Rb * K + C) * 2u; }
;     const size_t kstep = (size_t)(BK * 2);
;     const size_t hstep = (size_t)HALF * K * 2;
;     const size_t tstep = 2 * hstep;
;     const unsigned ldsw = (unsigned)wid * 1024u;
;     const int aoff = lds_byte(wr * 64 + fr, fq * 8), boff = lds_byte(wc * 32 + fr, fq * 8);
;     ...
;     Unit cur, nxt; int ui = 0;
;     if (!S.next(0, cur)) return;
;     f32x4 acc[2][2][4][2];
; #pragma unroll
;     for (int a = 0; a < 2; ++a)
; #pragma unroll
;         for (int b = 0; b < 2; ++b)
; #pragma unroll
;             for (int m = 0; m < 4; ++m)
; #pragma unroll
;                 for (int n = 0; n < 2; ++n) acc[a][b][m][n] = (f32x4){0.f, 0.f, 0.f, 0.f};
;     bf16x8 At[4][2], B0[2][2], B1[2][2];
;     const char* cA = (const char*)g.A + (size_t)cur.pm * tstep; const char* cB = (const char*)g.Bt + (size_t)cur.pn * tstep;
;     S.a_ready(cur);
;     if constexpr (SP2) {
;         PG8_STAGE(PG8_SB(0, 0), cB, voffB); PG8_STAGE(PG8_SB(0, 1), cB + hstep, voffB); PG8_STAGE(PG8_SA(0, 0), cA, voffA); PG8_STAGE(PG8_SA(0, 1), cA + hstep, voffA);
;         if (wr == 1) PG8_BAR;
;         PG8_WAIT_V(2); PG8_BAR;
;         PG8_STAGE(PG8_SB(1, 0), cB + kstep, voffB); PG8_STAGE(PG8_SA(1, 0), cA + kstep, voffA); PG8_STAGE(PG8_SB(1, 1), cB + hstep + kstep, voffB);
;         PG8_WAIT_V(6); PG8_BAR;
.LBB0_126:
	v_and_b32_e32 v16, 15, v1
	v_and_b32_e32 v17, 48, v1
	v_lshlrev_b32_e32 v1, 2, v1
	s_and_b32 s11, s9, 3
	v_lshl_or_b32 v18, v16, 6, v17
	s_lshl_b32 s8, s8, 13
	v_and_b32_e32 v1, 32, v1
	s_add_i32 m0, s5, 0x18000
	v_lshl_add_u64 v[8:9], v[8:9], 0, s[68:69]
	v_bitop3_b32 v19, v18, s8, v1 bitop3:0xde
	s_lshl_b32 s8, s11, 12
	s_waitcnt vmcnt(2)
	s_barrier
	global_load_lds_dwordx4 v[8:9], off
	v_lshl_add_u64 v[6:7], v[6:7], 0, s[68:69]
	s_add_i32 m0, s5, 0x1a000
	s_add_i32 s54, s5, 0x8000
	s_add_i32 s57, s5, 0xa000
	v_bitop3_b32 v1, v18, s8, v1 bitop3:0xde
	global_load_lds_dwordx4 v[6:7], off
	v_lshl_add_u64 v[2:3], v[2:3], 0, s[68:69]
	s_mov_b32 m0, s54
	s_add_u32 s8, s62, 0x20080
	global_load_lds_dwordx4 v[2:3], off
	v_lshl_add_u64 v[2:3], v[4:5], 0, s[68:69]
	s_mov_b32 m0, s57
	s_addc_u32 s9, s63, 0
	global_load_lds_dwordx4 v[2:3], off
	s_add_i32 m0, s5, 0x1c000
	v_lshl_add_u64 v[2:3], s[8:9], 0, v[148:149]
	global_load_lds_dwordx4 v[2:3], off
	v_lshl_add_u64 v[2:3], s[8:9], 0, v[144:145]
	s_add_i32 m0, s5, 0x1e000
	s_cmpk_lt_u32 s10, 0x100
	global_load_lds_dwordx4 v[2:3], off
	s_cselect_b64 s[8:9], -1, 0
	s_and_b32 s10, s10, 0xffffff00
	s_lshl_b32 s11, s11, 6
	s_or_b32 s10, s11, s10
	v_or3_b32 v2, s10, v17, v16
	v_ashrrev_i32_e32 v3, 31, v2
	v_readlane_b32 s10, v254, 61
	v_lshlrev_b64 v[2:3], 4, v[2:3]
	v_readlane_b32 s11, v254, 62
	v_lshl_add_u64 v[154:155], s[6:7], 0, v[2:3]
	s_waitcnt vmcnt(6)
	v_mov_b32_e32 v157, v0
	v_lshl_add_u64 v[152:153], s[10:11], 0, v[2:3]
	v_lshlrev_b32_e32 v2, 13, v14
	v_and_b32_e32 v2, 0xffffc000, v2
	v_lshl_add_u32 v2, v13, 10, v2
	v_and_b32_e32 v3, 1, v14
	v_lshl_or_b32 v2, v3, 6, v2
	v_lshl_add_u32 v156, v15, 1, v2
	v_lshlrev_b32_e32 v2, 13, v10
	v_and_b32_e32 v2, 0xffffc000, v2
	v_lshl_add_u32 v2, v11, 10, v2
	v_and_b32_e32 v3, 1, v10
	v_lshl_or_b32 v2, v3, 6, v2
	v_readlane_b32 s10, v254, 2
	v_lshl_add_u32 v158, v12, 1, v2
	v_mov_b32_e32 v159, v0
	s_mov_b32 s60, 0
	v_add_u32_e32 v143, 0, v19
	v_readlane_b32 s86, v253, 19
	s_mov_b32 s67, s10
	s_barrier
	v_readlane_b32 s11, v254, 3
	s_mov_b32 s32, 0
	s_branch .LBB0_129

; #define PG8_STAGE(bufoff, gbase, voff) do { _Pragma("unroll") for (int _i = 0; _i < 2; ++_i) \
;         __builtin_amdgcn_global_load_lds((const unsigned*)((const char*)(gbase) + (voff)[_i]), (PG8_LAS unsigned*)(lds + (bufoff) + ldsw + _i * 8192), 16, 0, 0); } while (0)
; #define PG8_LDA(dst, b, h) do { _Pragma("unroll") for (int m = 0; m < 4; ++m) _Pragma("unroll") for (int k = 0; k < 2; ++k) dst[m][k] = *(const PG8_LAS bf16x8*)(lds + PG8_SA(b, h) + aoff + m * 2048 + k * 1024); } while (0)
; #define PG8_LDB(dst, b, h) do { _Pragma("unroll") for (int n = 0; n < 2; ++n) _Pragma("unroll") for (int k = 0; k < 2; ++k) dst[n][k] = *(const PG8_LAS bf16x8*)(lds + PG8_SB(b, h) + boff + n * 2048 + k * 1024); } while (0)
; #define PG8_SCHED __builtin_amdgcn_sched_barrier(0)
; template <class Epi, class Sched, bool ALIGN_EPI = false, bool SP2 = false>
; __device__ __forceinline__ void gemm_phase(PG8_LAS unsigned char* lds, const Gemm g, const Sched& S, const Epi& E) {
;     ...
;         const bool has_next = S.next(ui + 1, nxt);
;         const char* nA = has_next ? (const char*)g.A + (size_t)nxt.pm * tstep : cA; const char* nB = has_next ? (const char*)g.Bt + (size_t)nxt.pn * tstep : cB;
;         for (int t = 0; t < nt; t += 2) {
;             const bool last = (t == nt - 2);
;             const char* a1 = cA + (size_t)(t + 1) * kstep;
;             const char* a2 = last ? nA : cA + (size_t)(t + 2) * kstep; const char* b2 = last ? nB : cB + (size_t)(t + 2) * kstep;
;             const char* a3 = a2 + kstep; const char* b3 = b2 + kstep;
;             if (last && has_next) S.a_ready(nxt);
;             if constexpr (SP2) {
;             PG8_LDB(B0, 0, 0); PG8_LDB(B1, 0, 1); PG8_SCHED; PG8_LDA(At, 0, 0); PG8_STAGE(PG8_SA(1, 1), a1 + hstep, voffA);
.LBB0_135:
	s_ashr_i32 s37, s36, 31
	s_lshl_b64 s[40:41], s[36:37], 18
	v_readlane_b32 s44, v254, 59
	v_readlane_b32 s45, v254, 60
	s_add_u32 s40, s44, s40
	s_addc_u32 s41, s45, s41
	s_and_b64 s[44:45], s[42:43], exec
	s_cselect_b32 s37, s41, s19
	s_cselect_b32 s73, s40, s18
	s_ashr_i32 s11, s10, 31
	s_lshl_b64 s[44:45], s[10:11], 18
	v_readlane_b32 s46, v254, 41
	v_readlane_b32 s47, v254, 42
	s_add_u32 s44, s46, s44
	s_addc_u32 s45, s47, s45
	s_and_b64 s[46:47], s[42:43], exec
	s_cselect_b32 s11, s45, s63
	s_cselect_b32 s84, s44, s62
	s_add_u32 s58, s18, 0x20080
	s_addc_u32 s59, s19, 0
	s_add_u32 s85, s62, 0x100
	s_addc_u32 s78, s63, 0
	s_mov_b32 s79, -2
	s_add_u32 s18, s58, 0xfffe0080
	s_addc_u32 s19, s59, -1
	s_add_i32 s46, 0, 0x10000
	s_cmp_eq_u32 s79, 4
	s_cselect_b32 s63, s37, s19
	s_cselect_b32 s62, s73, s18
	s_cselect_b32 s19, s11, s78
	s_cselect_b32 s18, s84, s85
	s_add_i32 s76, 0, 0x14000
	v_add_u32_e32 v172, s46, v1
	v_add_u32_e32 v203, s76, v1
	ds_read_b128 v[160:163], v172
	ds_read_b128 v[164:167], v172 offset:1024
	ds_read_b128 v[168:171], v172 offset:2048
	ds_read_b128 v[172:175], v172 offset:3072
	ds_read_b128 v[176:179], v203
	ds_read_b128 v[180:183], v203 offset:1024
	ds_read_b128 v[184:187], v203 offset:2048
	ds_read_b128 v[204:207], v203 offset:3072
	v_lshl_add_u64 v[240:241], s[58:59], 0, v[156:157]
	s_add_i32 m0, s5, 0xc000
	ds_read_b128 v[208:211], v143
	ds_read_b128 v[212:215], v143 offset:1024
	ds_read_b128 v[216:219], v143 offset:2048
	ds_read_b128 v[220:223], v143 offset:3072
	ds_read_b128 v[224:227], v143 offset:4096
	ds_read_b128 v[228:231], v143 offset:5120
	ds_read_b128 v[232:235], v143 offset:6144
	ds_read_b128 v[236:239], v143 offset:7168
	global_load_lds_dwordx4 v[240:241], off
	v_lshl_add_u64 v[240:241], s[58:59], 0, v[158:159]
	s_add_i32 m0, s5, 0xe000
	s_nop 0
	global_load_lds_dwordx4 v[240:241], off
	s_nop 0
	s_cmp_eq_u32 s32, 0
	s_cbranch_scc1 .Lpw7_f
	s_waitcnt vmcnt(24)
	s_branch .Lpw7_j

; #define PG8_STAGE(bufoff, gbase, voff) do { _Pragma("unroll") for (int _i = 0; _i < 2; ++_i) \
;         __builtin_amdgcn_global_load_lds((const unsigned*)((const char*)(gbase) + (voff)[_i]), (PG8_LAS unsigned*)(lds + (bufoff) + ldsw + _i * 8192), 16, 0, 0); } while (0)
; #define PG8_LDA(dst, b, h) do { _Pragma("unroll") for (int m = 0; m < 4; ++m) _Pragma("unroll") for (int k = 0; k < 2; ++k) dst[m][k] = *(const PG8_LAS bf16x8*)(lds + PG8_SA(b, h) + aoff + m * 2048 + k * 1024); } while (0)
; #define PG8_LDB(dst, b, h) do { _Pragma("unroll") for (int n = 0; n < 2; ++n) _Pragma("unroll") for (int k = 0; k < 2; ++k) dst[n][k] = *(const PG8_LAS bf16x8*)(lds + PG8_SB(b, h) + boff + n * 2048 + k * 1024); } while (0)
; #define PG8_MMA(ai, bj, At, Bt) do { __builtin_amdgcn_s_setprio(1); _Pragma("unroll") for (int m = 0; m < 4; ++m) _Pragma("unroll") for (int n = 0; n < 2; ++n) _Pragma("unroll") for (int k = 0; k < 2; ++k) \
;         acc[ai][bj][m][n] = __builtin_amdgcn_mfma_f32_16x16x32_bf16(Bt[n][k], At[m][k], acc[ai][bj][m][n], 0, 0, 0); __builtin_amdgcn_s_setprio(0); } while (0)
; #define PG8_WAIT_V(n) asm volatile("s_waitcnt vmcnt(" #n ")" ::: "memory")
; #define PG8_WAIT_L(n) asm volatile("s_waitcnt lgkmcnt(" #n ")" ::: "memory")
; #define PG8_BAR __builtin_amdgcn_s_barrier()
; #define PG8_SCHED __builtin_amdgcn_sched_barrier(0)
; template <class Epi, class Sched, bool ALIGN_EPI = false, bool SP2 = false>
; __device__ __forceinline__ void gemm_phase(PG8_LAS unsigned char* lds, const Gemm g, const Sched& S, const Epi& E) {
;     ...
;             PG8_LDB(B0, 0, 0); PG8_LDB(B1, 0, 1); PG8_SCHED; PG8_LDA(At, 0, 0); PG8_STAGE(PG8_SA(1, 1), a1 + hstep, voffA);
;             PG8_WAIT_V(8); PG8_WAIT_L(0); PG8_BAR; PG8_MMA(0, 0, At, B0); PG8_MMA(0, 1, At, B1); PG8_BAR; PG8_SCHED;
;             PG8_LDA(At, 0, 1); PG8_STAGE(PG8_SB(0, 0), b2, voffB); PG8_STAGE(PG8_SB(0, 1), b2 + hstep, voffB); PG8_STAGE(PG8_SA(0, 0), a2, voffA);
;             PG8_WAIT_V(8); PG8_WAIT_L(0); PG8_BAR; PG8_MMA(1, 0, At, B0); PG8_MMA(1, 1, At, B1); PG8_BAR; PG8_SCHED;
.Lpw7_j:
	s_nop 0
	s_waitcnt lgkmcnt(0)
	s_setprio 1
	s_barrier
	v_mfma_f32_16x16x32_bf16 v[126:129], v[160:163], v[208:211], 0
	v_mfma_f32_16x16x32_bf16 v[122:125], v[168:171], v[208:211], 0
	v_mfma_f32_16x16x32_bf16 v[110:113], v[160:163], v[216:219], 0
	v_mfma_f32_16x16x32_bf16 v[106:109], v[168:171], v[216:219], 0
	v_mfma_f32_16x16x32_bf16 v[94:97], v[160:163], v[224:227], 0
	v_mfma_f32_16x16x32_bf16 v[90:93], v[168:171], v[224:227], 0
	v_mfma_f32_16x16x32_bf16 v[78:81], v[160:163], v[232:235], 0
	v_mfma_f32_16x16x32_bf16 v[74:77], v[168:171], v[232:235], 0
	s_setprio 0
	s_setprio 1
	v_mfma_f32_16x16x32_bf16 v[126:129], v[164:167], v[212:215], v[126:129]
	v_mfma_f32_16x16x32_bf16 v[122:125], v[172:175], v[212:215], v[122:125]
	v_mfma_f32_16x16x32_bf16 v[110:113], v[164:167], v[220:223], v[110:113]
	v_mfma_f32_16x16x32_bf16 v[106:109], v[172:175], v[220:223], v[106:109]
	v_mfma_f32_16x16x32_bf16 v[94:97], v[164:167], v[228:231], v[94:97]
	v_mfma_f32_16x16x32_bf16 v[90:93], v[172:175], v[228:231], v[90:93]
	v_mfma_f32_16x16x32_bf16 v[78:81], v[164:167], v[236:239], v[78:81]
	v_mfma_f32_16x16x32_bf16 v[74:77], v[172:175], v[236:239], v[74:77]
	s_setprio 0
	s_setprio 1
	v_mfma_f32_16x16x32_bf16 v[118:121], v[176:179], v[208:211], 0
	v_mfma_f32_16x16x32_bf16 v[114:117], v[184:187], v[208:211], 0
	v_mfma_f32_16x16x32_bf16 v[102:105], v[176:179], v[216:219], 0
	v_mfma_f32_16x16x32_bf16 v[98:101], v[184:187], v[216:219], 0
	v_mfma_f32_16x16x32_bf16 v[86:89], v[176:179], v[224:227], 0
	v_mfma_f32_16x16x32_bf16 v[82:85], v[184:187], v[224:227], 0
	v_mfma_f32_16x16x32_bf16 v[70:73], v[176:179], v[232:235], 0
	v_mfma_f32_16x16x32_bf16 v[66:69], v[184:187], v[232:235], 0
	s_setprio 0
	s_setprio 1
	v_mfma_f32_16x16x32_bf16 v[118:121], v[180:183], v[212:215], v[118:121]
	v_mfma_f32_16x16x32_bf16 v[114:117], v[204:207], v[212:215], v[114:117]
	v_mfma_f32_16x16x32_bf16 v[102:105], v[180:183], v[220:223], v[102:105]
	v_mfma_f32_16x16x32_bf16 v[98:101], v[204:207], v[220:223], v[98:101]
	v_mfma_f32_16x16x32_bf16 v[86:89], v[180:183], v[228:231], v[86:89]
	v_mfma_f32_16x16x32_bf16 v[82:85], v[204:207], v[228:231], v[82:85]
	v_mfma_f32_16x16x32_bf16 v[70:73], v[180:183], v[236:239], v[70:73]
	v_mfma_f32_16x16x32_bf16 v[66:69], v[204:207], v[236:239], v[66:69]
	s_setprio 0
	s_barrier
	s_add_i32 s46, s46, s4
	v_lshl_add_u64 v[240:241], s[18:19], 0, v[148:149]
	s_mov_b32 m0, s46
	ds_read_b128 v[208:211], v143 offset:16384
	ds_read_b128 v[212:215], v143 offset:17408
	ds_read_b128 v[216:219], v143 offset:18432
	ds_read_b128 v[220:223], v143 offset:19456
	ds_read_b128 v[224:227], v143 offset:20480
	ds_read_b128 v[228:231], v143 offset:21504
	ds_read_b128 v[232:235], v143 offset:22528
	ds_read_b128 v[236:239], v143 offset:23552
	global_load_lds_dwordx4 v[240:241], off
	s_add_i32 m0, s46, 0x2000
	s_add_u32 s46, s18, 0x20000
	v_lshl_add_u64 v[242:243], s[18:19], 0, v[144:145]
	s_addc_u32 s47, s19, 0
	s_add_i32 s76, s76, s4
	global_load_lds_dwordx4 v[242:243], off
	v_lshl_add_u64 v[244:245], s[46:47], 0, v[148:149]
	s_mov_b32 m0, s76
	v_lshl_add_u64 v[246:247], s[62:63], 0, v[146:147]
	global_load_lds_dwordx4 v[244:245], off
	v_lshl_add_u64 v[244:245], s[46:47], 0, v[144:145]
	s_add_i32 m0, s76, 0x2000
	s_nop 0
	global_load_lds_dwordx4 v[244:245], off
	v_lshl_add_u64 v[244:245], s[62:63], 0, v[150:151]
	s_mov_b32 m0, s5
	s_nop 0
	global_load_lds_dwordx4 v[244:245], off
	s_mov_b32 m0, s28
	s_nop 0
	global_load_lds_dwordx4 v[246:247], off
	s_cmp_eq_u32 s32, 0
	s_cbranch_scc1 .Lpw8_f
	s_waitcnt vmcnt(24)
	s_branch .Lpw8_j

; #define PG8_STAGE(bufoff, gbase, voff) do { _Pragma("unroll") for (int _i = 0; _i < 2; ++_i) \
;         __builtin_amdgcn_global_load_lds((const unsigned*)((const char*)(gbase) + (voff)[_i]), (PG8_LAS unsigned*)(lds + (bufoff) + ldsw + _i * 8192), 16, 0, 0); } while (0)
; #define PG8_LDA(dst, b, h) do { _Pragma("unroll") for (int m = 0; m < 4; ++m) _Pragma("unroll") for (int k = 0; k < 2; ++k) dst[m][k] = *(const PG8_LAS bf16x8*)(lds + PG8_SA(b, h) + aoff + m * 2048 + k * 1024); } while (0)
; #define PG8_LDB(dst, b, h) do { _Pragma("unroll") for (int n = 0; n < 2; ++n) _Pragma("unroll") for (int k = 0; k < 2; ++k) dst[n][k] = *(const PG8_LAS bf16x8*)(lds + PG8_SB(b, h) + boff + n * 2048 + k * 1024); } while (0)
; #define PG8_MMA(ai, bj, At, Bt) do { __builtin_amdgcn_s_setprio(1); _Pragma("unroll") for (int m = 0; m < 4; ++m) _Pragma("unroll") for (int n = 0; n < 2; ++n) _Pragma("unroll") for (int k = 0; k < 2; ++k) \
;         acc[ai][bj][m][n] = __builtin_amdgcn_mfma_f32_16x16x32_bf16(Bt[n][k], At[m][k], acc[ai][bj][m][n], 0, 0, 0); __builtin_amdgcn_s_setprio(0); } while (0)
; #define PG8_WAIT_V(n) asm volatile("s_waitcnt vmcnt(" #n ")" ::: "memory")
; #define PG8_WAIT_L(n) asm volatile("s_waitcnt lgkmcnt(" #n ")" ::: "memory")
; #define PG8_BAR __builtin_amdgcn_s_barrier()
; #define PG8_SCHED __builtin_amdgcn_sched_barrier(0)
; template <class Epi, class Sched, bool ALIGN_EPI = false, bool SP2 = false>
; __device__ __forceinline__ void gemm_phase(PG8_LAS unsigned char* lds, const Gemm g, const Sched& S, const Epi& E) {
;     ...
;             PG8_WAIT_V(8); PG8_WAIT_L(0); PG8_BAR; PG8_MMA(1, 0, At, B0); PG8_MMA(1, 1, At, B1); PG8_BAR; PG8_SCHED;
;             PG8_LDB(B0, 1, 0); PG8_LDB(B1, 1, 1); PG8_SCHED; PG8_LDA(At, 1, 0); PG8_STAGE(PG8_SA(0, 1), a2 + hstep, voffA);
;             PG8_WAIT_V(8); PG8_WAIT_L(0); PG8_BAR; PG8_MMA(0, 0, At, B0); PG8_MMA(0, 1, At, B1); PG8_BAR; PG8_SCHED;
.Lpw8_j:
	s_waitcnt lgkmcnt(0)
	s_setprio 1
	s_barrier
	v_mfma_f32_16x16x32_bf16 v[62:65], v[160:163], v[208:211], 0
	v_mfma_f32_16x16x32_bf16 v[58:61], v[168:171], v[208:211], 0
	v_mfma_f32_16x16x32_bf16 v[46:49], v[160:163], v[216:219], 0
	v_mfma_f32_16x16x32_bf16 v[42:45], v[168:171], v[216:219], 0
	v_mfma_f32_16x16x32_bf16 v[30:33], v[160:163], v[224:227], 0
	v_mfma_f32_16x16x32_bf16 v[26:29], v[168:171], v[224:227], 0
	v_mfma_f32_16x16x32_bf16 v[14:17], v[160:163], v[232:235], 0
	v_mfma_f32_16x16x32_bf16 v[10:13], v[168:171], v[232:235], 0
	v_mfma_f32_16x16x32_bf16 v[62:65], v[164:167], v[212:215], v[62:65]
	v_mfma_f32_16x16x32_bf16 v[58:61], v[172:175], v[212:215], v[58:61]
	v_mfma_f32_16x16x32_bf16 v[46:49], v[164:167], v[220:223], v[46:49]
	v_mfma_f32_16x16x32_bf16 v[42:45], v[172:175], v[220:223], v[42:45]
	v_mfma_f32_16x16x32_bf16 v[30:33], v[164:167], v[228:231], v[30:33]
	v_mfma_f32_16x16x32_bf16 v[26:29], v[172:175], v[228:231], v[26:29]
	v_mfma_f32_16x16x32_bf16 v[14:17], v[164:167], v[236:239], v[14:17]
	v_mfma_f32_16x16x32_bf16 v[10:13], v[172:175], v[236:239], v[10:13]
	v_mfma_f32_16x16x32_bf16 v[54:57], v[176:179], v[208:211], 0
	v_mfma_f32_16x16x32_bf16 v[50:53], v[184:187], v[208:211], 0
	v_mfma_f32_16x16x32_bf16 v[38:41], v[176:179], v[216:219], 0
	v_mfma_f32_16x16x32_bf16 v[34:37], v[184:187], v[216:219], 0
	v_mfma_f32_16x16x32_bf16 v[22:25], v[176:179], v[224:227], 0
	v_mfma_f32_16x16x32_bf16 v[18:21], v[184:187], v[224:227], 0
	v_mfma_f32_16x16x32_bf16 v[6:9], v[176:179], v[232:235], 0
	v_mfma_f32_16x16x32_bf16 v[2:5], v[184:187], v[232:235], 0
	v_mfma_f32_16x16x32_bf16 v[54:57], v[180:183], v[212:215], v[54:57]
	v_mfma_f32_16x16x32_bf16 v[50:53], v[204:207], v[212:215], v[50:53]
	v_mfma_f32_16x16x32_bf16 v[38:41], v[180:183], v[220:223], v[38:41]
	v_mfma_f32_16x16x32_bf16 v[34:37], v[204:207], v[220:223], v[34:37]
	v_mfma_f32_16x16x32_bf16 v[22:25], v[180:183], v[228:231], v[22:25]
	v_mfma_f32_16x16x32_bf16 v[18:21], v[204:207], v[228:231], v[18:21]
	v_mfma_f32_16x16x32_bf16 v[6:9], v[180:183], v[236:239], v[6:9]
	v_mfma_f32_16x16x32_bf16 v[2:5], v[204:207], v[236:239], v[2:5]
	s_setprio 0
	s_barrier
	s_add_i32 s76, 0, 0x18000
	s_add_i32 s77, 0, 0x1c000
	v_add_u32_e32 v172, s76, v1
	v_add_u32_e32 v203, s77, v1
	ds_read_b128 v[160:163], v172
	ds_read_b128 v[164:167], v172 offset:1024
	ds_read_b128 v[168:171], v172 offset:2048
	ds_read_b128 v[172:175], v172 offset:3072
	ds_read_b128 v[176:179], v203
	ds_read_b128 v[180:183], v203 offset:1024
	ds_read_b128 v[184:187], v203 offset:2048
	ds_read_b128 v[204:207], v203 offset:3072
	s_add_u32 s46, s62, 0x20000
	s_addc_u32 s47, s63, 0
	s_mov_b32 m0, s30
	v_lshl_add_u64 v[248:249], s[46:47], 0, v[150:151]
	ds_read_b128 v[208:211], v143 offset:32768
	ds_read_b128 v[212:215], v143 offset:33792
	ds_read_b128 v[216:219], v143 offset:34816
	ds_read_b128 v[220:223], v143 offset:35840
	ds_read_b128 v[224:227], v143 offset:36864
	ds_read_b128 v[228:231], v143 offset:37888
	ds_read_b128 v[232:235], v143 offset:38912
	ds_read_b128 v[236:239], v143 offset:39936
	global_load_lds_dwordx4 v[248:249], off
	v_lshl_add_u64 v[248:249], s[46:47], 0, v[146:147]
	s_mov_b32 m0, s34
	s_nop 0
	global_load_lds_dwordx4 v[248:249], off
	s_waitcnt vmcnt(8)
	s_waitcnt lgkmcnt(0)
	s_setprio 1
	s_barrier
	v_mfma_f32_16x16x32_bf16 v[126:129], v[160:163], v[208:211], v[126:129]
	v_mfma_f32_16x16x32_bf16 v[122:125], v[168:171], v[208:211], v[122:125]
	v_mfma_f32_16x16x32_bf16 v[110:113], v[160:163], v[216:219], v[110:113]
	v_mfma_f32_16x16x32_bf16 v[106:109], v[168:171], v[216:219], v[106:109]
	v_mfma_f32_16x16x32_bf16 v[94:97], v[160:163], v[224:227], v[94:97]
	v_mfma_f32_16x16x32_bf16 v[90:93], v[168:171], v[224:227], v[90:93]
	v_mfma_f32_16x16x32_bf16 v[78:81], v[160:163], v[232:235], v[78:81]
	v_mfma_f32_16x16x32_bf16 v[74:77], v[168:171], v[232:235], v[74:77]
	s_setprio 0
	s_setprio 1
	v_mfma_f32_16x16x32_bf16 v[126:129], v[164:167], v[212:215], v[126:129]
	v_mfma_f32_16x16x32_bf16 v[122:125], v[172:175], v[212:215], v[122:125]
	v_mfma_f32_16x16x32_bf16 v[110:113], v[164:167], v[220:223], v[110:113]
	v_mfma_f32_16x16x32_bf16 v[106:109], v[172:175], v[220:223], v[106:109]
	v_mfma_f32_16x16x32_bf16 v[94:97], v[164:167], v[228:231], v[94:97]
	v_mfma_f32_16x16x32_bf16 v[90:93], v[172:175], v[228:231], v[90:93]
	v_mfma_f32_16x16x32_bf16 v[78:81], v[164:167], v[236:239], v[78:81]
	v_mfma_f32_16x16x32_bf16 v[74:77], v[172:175], v[236:239], v[74:77]
	s_setprio 0
	s_setprio 1
	v_mfma_f32_16x16x32_bf16 v[118:121], v[176:179], v[208:211], v[118:121]
	v_mfma_f32_16x16x32_bf16 v[114:117], v[184:187], v[208:211], v[114:117]
	v_mfma_f32_16x16x32_bf16 v[102:105], v[176:179], v[216:219], v[102:105]
	v_mfma_f32_16x16x32_bf16 v[98:101], v[184:187], v[216:219], v[98:101]
	v_mfma_f32_16x16x32_bf16 v[86:89], v[176:179], v[224:227], v[86:89]
	v_mfma_f32_16x16x32_bf16 v[82:85], v[184:187], v[224:227], v[82:85]
	v_mfma_f32_16x16x32_bf16 v[70:73], v[176:179], v[232:235], v[70:73]
	v_mfma_f32_16x16x32_bf16 v[66:69], v[184:187], v[232:235], v[66:69]
	s_setprio 0
	s_setprio 1
	v_mfma_f32_16x16x32_bf16 v[118:121], v[180:183], v[212:215], v[118:121]
	v_mfma_f32_16x16x32_bf16 v[114:117], v[204:207], v[212:215], v[114:117]
	v_mfma_f32_16x16x32_bf16 v[102:105], v[180:183], v[220:223], v[102:105]
	v_mfma_f32_16x16x32_bf16 v[98:101], v[204:207], v[220:223], v[98:101]
	v_mfma_f32_16x16x32_bf16 v[86:89], v[180:183], v[228:231], v[86:89]
	v_mfma_f32_16x16x32_bf16 v[82:85], v[204:207], v[228:231], v[82:85]
	v_mfma_f32_16x16x32_bf16 v[70:73], v[180:183], v[236:239], v[70:73]
	v_mfma_f32_16x16x32_bf16 v[66:69], v[204:207], v[236:239], v[66:69]
	s_setprio 0
	s_barrier
; #define PG8_STAGE(bufoff, gbase, voff) do { _Pragma("unroll") for (int _i = 0; _i < 2; ++_i) \
;         __builtin_amdgcn_global_load_lds((const unsigned*)((const char*)(gbase) + (voff)[_i]), (PG8_LAS unsigned*)(lds + (bufoff) + ldsw + _i * 8192), 16, 0, 0); } while (0)
; #define PG8_LDA(dst, b, h) do { _Pragma("unroll") for (int m = 0; m < 4; ++m) _Pragma("unroll") for (int k = 0; k < 2; ++k) dst[m][k] = *(const PG8_LAS bf16x8*)(lds + PG8_SA(b, h) + aoff + m * 2048 + k * 1024); } while (0)
; #define PG8_LDB(dst, b, h) do { _Pragma("unroll") for (int n = 0; n < 2; ++n) _Pragma("unroll") for (int k = 0; k < 2; ++k) dst[n][k] = *(const PG8_LAS bf16x8*)(lds + PG8_SB(b, h) + boff + n * 2048 + k * 1024); } while (0)
; #define PG8_MMA(ai, bj, At, Bt) do { __builtin_amdgcn_s_setprio(1); _Pragma("unroll") for (int m = 0; m < 4; ++m) _Pragma("unroll") for (int n = 0; n < 2; ++n) _Pragma("unroll") for (int k = 0; k < 2; ++k) \
;         acc[ai][bj][m][n] = __builtin_amdgcn_mfma_f32_16x16x32_bf16(Bt[n][k], At[m][k], acc[ai][bj][m][n], 0, 0, 0); __builtin_amdgcn_s_setprio(0); } while (0)
; #define PG8_WAIT_V(n) asm volatile("s_waitcnt vmcnt(" #n ")" ::: "memory")
; #define PG8_WAIT_L(n) asm volatile("s_waitcnt lgkmcnt(" #n ")" ::: "memory")
; #define PG8_BAR __builtin_amdgcn_s_barrier()
; #define PG8_SCHED __builtin_amdgcn_sched_barrier(0)
; template <class Epi, class Sched, bool ALIGN_EPI = false, bool SP2 = false>
; __device__ __forceinline__ void gemm_phase(PG8_LAS unsigned char* lds, const Gemm g, const Sched& S, const Epi& E) {
;     ...
;             PG8_LDB(B0, 0, 0); PG8_LDB(B1, 0, 1); PG8_SCHED; PG8_LDA(At, 0, 0); PG8_STAGE(PG8_SA(1, 1), a1 + hstep, voffA);
;             PG8_WAIT_V(8); PG8_WAIT_L(0); PG8_BAR; PG8_MMA(0, 0, At, B0); PG8_MMA(0, 1, At, B1); PG8_BAR; PG8_SCHED;
;     ...
;             PG8_LDA(At, 1, 1); PG8_STAGE(PG8_SB(1, 0), b3, voffB); PG8_STAGE(PG8_SB(1, 1), b3 + hstep, voffB); PG8_STAGE(PG8_SA(1, 0), a3, voffA);
;             PG8_WAIT_V(8); PG8_WAIT_L(0); PG8_BAR; PG8_MMA(1, 0, At, B0); PG8_MMA(1, 1, At, B1); PG8_BAR; PG8_SCHED;
	s_add_i32 s46, s76, s4
	v_lshl_add_u64 v[240:241], v[240:241], 0, s[68:69]
	s_mov_b32 m0, s46
	ds_read_b128 v[208:211], v143 offset:49152
	ds_read_b128 v[212:215], v143 offset:50176
	ds_read_b128 v[216:219], v143 offset:51200
	ds_read_b128 v[220:223], v143 offset:52224
	ds_read_b128 v[224:227], v143 offset:53248
	ds_read_b128 v[228:231], v143 offset:54272
	ds_read_b128 v[232:235], v143 offset:55296
	ds_read_b128 v[236:239], v143 offset:56320
	global_load_lds_dwordx4 v[240:241], off
	s_add_i32 m0, s46, 0x2000
	s_add_u32 s18, s18, 0x20080
	v_lshl_add_u64 v[240:241], v[242:243], 0, s[68:69]
	s_addc_u32 s19, s19, 0
	s_add_i32 s46, s77, s4
	global_load_lds_dwordx4 v[240:241], off
	v_lshl_add_u64 v[240:241], s[18:19], 0, v[148:149]
	s_mov_b32 m0, s46
	s_nop 0
	global_load_lds_dwordx4 v[240:241], off
	v_lshl_add_u64 v[240:241], s[18:19], 0, v[144:145]
	s_add_i32 m0, s46, 0x2000
	s_nop 0
	global_load_lds_dwordx4 v[240:241], off
	v_lshl_add_u64 v[240:241], v[244:245], 0, s[68:69]
	s_mov_b32 m0, s54
	s_nop 0
	global_load_lds_dwordx4 v[240:241], off
	v_lshl_add_u64 v[240:241], v[246:247], 0, s[68:69]
	s_mov_b32 m0, s57
	s_nop 0
	global_load_lds_dwordx4 v[240:241], off
	s_nop 0
	s_waitcnt vmcnt(8)
	s_waitcnt lgkmcnt(0)
	s_setprio 1
	s_barrier
	v_mfma_f32_16x16x32_bf16 v[62:65], v[160:163], v[208:211], v[62:65]
	v_mfma_f32_16x16x32_bf16 v[58:61], v[168:171], v[208:211], v[58:61]
	v_mfma_f32_16x16x32_bf16 v[46:49], v[160:163], v[216:219], v[46:49]
	v_mfma_f32_16x16x32_bf16 v[42:45], v[168:171], v[216:219], v[42:45]
	v_mfma_f32_16x16x32_bf16 v[30:33], v[160:163], v[224:227], v[30:33]
	v_mfma_f32_16x16x32_bf16 v[26:29], v[168:171], v[224:227], v[26:29]
	v_mfma_f32_16x16x32_bf16 v[14:17], v[160:163], v[232:235], v[14:17]
	v_mfma_f32_16x16x32_bf16 v[10:13], v[168:171], v[232:235], v[10:13]
	v_mfma_f32_16x16x32_bf16 v[62:65], v[164:167], v[212:215], v[62:65]
	v_mfma_f32_16x16x32_bf16 v[58:61], v[172:175], v[212:215], v[58:61]
	v_mfma_f32_16x16x32_bf16 v[46:49], v[164:167], v[220:223], v[46:49]
	v_mfma_f32_16x16x32_bf16 v[42:45], v[172:175], v[220:223], v[42:45]
	v_mfma_f32_16x16x32_bf16 v[30:33], v[164:167], v[228:231], v[30:33]
	v_mfma_f32_16x16x32_bf16 v[26:29], v[172:175], v[228:231], v[26:29]
	v_mfma_f32_16x16x32_bf16 v[14:17], v[164:167], v[236:239], v[14:17]
	v_mfma_f32_16x16x32_bf16 v[10:13], v[172:175], v[236:239], v[10:13]
	v_mfma_f32_16x16x32_bf16 v[54:57], v[176:179], v[208:211], v[54:57]
	v_mfma_f32_16x16x32_bf16 v[50:53], v[184:187], v[208:211], v[50:53]
	v_mfma_f32_16x16x32_bf16 v[38:41], v[176:179], v[216:219], v[38:41]
	v_mfma_f32_16x16x32_bf16 v[34:37], v[184:187], v[216:219], v[34:37]
	v_mfma_f32_16x16x32_bf16 v[22:25], v[176:179], v[224:227], v[22:25]
	v_mfma_f32_16x16x32_bf16 v[18:21], v[184:187], v[224:227], v[18:21]
	v_mfma_f32_16x16x32_bf16 v[6:9], v[176:179], v[232:235], v[6:9]
	v_mfma_f32_16x16x32_bf16 v[2:5], v[184:187], v[232:235], v[2:5]
	v_mfma_f32_16x16x32_bf16 v[54:57], v[180:183], v[212:215], v[54:57]
	v_mfma_f32_16x16x32_bf16 v[50:53], v[204:207], v[212:215], v[50:53]
	v_mfma_f32_16x16x32_bf16 v[38:41], v[180:183], v[220:223], v[38:41]
	v_mfma_f32_16x16x32_bf16 v[34:37], v[204:207], v[220:223], v[34:37]
	v_mfma_f32_16x16x32_bf16 v[22:25], v[180:183], v[228:231], v[22:25]
	v_mfma_f32_16x16x32_bf16 v[18:21], v[204:207], v[228:231], v[18:21]
	v_mfma_f32_16x16x32_bf16 v[6:9], v[180:183], v[236:239], v[6:9]
	v_mfma_f32_16x16x32_bf16 v[2:5], v[204:207], v[236:239], v[2:5]
	s_setprio 0
	s_barrier
	s_add_i32 s79, s79, 2
	s_add_u32 s58, s58, 0x100
	s_addc_u32 s59, s59, 0
	s_add_u32 s85, s85, 0x100
	s_addc_u32 s78, s78, 0
	s_cmp_gt_u32 s79, 5
.LBB0_136:
	s_add_u32 s18, s58, 0xfffe0080
	s_addc_u32 s19, s59, -1
	s_add_i32 s46, 0, 0x10000
	s_cmp_eq_u32 s79, 4
	s_cselect_b32 s63, s37, s19
	s_cselect_b32 s62, s73, s18
	s_cselect_b32 s19, s11, s78
	s_cselect_b32 s18, s84, s85
	s_add_i32 s76, 0, 0x14000
	v_add_u32_e32 v172, s46, v1
	v_add_u32_e32 v203, s76, v1
	ds_read_b128 v[160:163], v172
	ds_read_b128 v[164:167], v172 offset:1024
	ds_read_b128 v[168:171], v172 offset:2048
	ds_read_b128 v[172:175], v172 offset:3072
	ds_read_b128 v[176:179], v203
	ds_read_b128 v[180:183], v203 offset:1024
	ds_read_b128 v[184:187], v203 offset:2048
	ds_read_b128 v[204:207], v203 offset:3072
	v_lshl_add_u64 v[240:241], s[58:59], 0, v[156:157]
	s_add_i32 m0, s5, 0xc000
	ds_read_b128 v[208:211], v143
	ds_read_b128 v[212:215], v143 offset:1024
	ds_read_b128 v[216:219], v143 offset:2048
	ds_read_b128 v[220:223], v143 offset:3072
	ds_read_b128 v[224:227], v143 offset:4096
	ds_read_b128 v[228:231], v143 offset:5120
	ds_read_b128 v[232:235], v143 offset:6144
	ds_read_b128 v[236:239], v143 offset:7168
	global_load_lds_dwordx4 v[240:241], off
	v_lshl_add_u64 v[240:241], s[58:59], 0, v[158:159]
	s_add_i32 m0, s5, 0xe000
	s_nop 0
	global_load_lds_dwordx4 v[240:241], off
	s_nop 0
	s_waitcnt vmcnt(8)
	s_waitcnt lgkmcnt(0)
	s_setprio 1
	s_barrier
; #define PG8_STAGE(bufoff, gbase, voff) do { _Pragma("unroll") for (int _i = 0; _i < 2; ++_i) \
;         __builtin_amdgcn_global_load_lds((const unsigned*)((const char*)(gbase) + (voff)[_i]), (PG8_LAS unsigned*)(lds + (bufoff) + ldsw + _i * 8192), 16, 0, 0); } while (0)
; #define PG8_LDA(dst, b, h) do { _Pragma("unroll") for (int m = 0; m < 4; ++m) _Pragma("unroll") for (int k = 0; k < 2; ++k) dst[m][k] = *(const PG8_LAS bf16x8*)(lds + PG8_SA(b, h) + aoff + m * 2048 + k * 1024); } while (0)
; #define PG8_MMA(ai, bj, At, Bt) do { __builtin_amdgcn_s_setprio(1); _Pragma("unroll") for (int m = 0; m < 4; ++m) _Pragma("unroll") for (int n = 0; n < 2; ++n) _Pragma("unroll") for (int k = 0; k < 2; ++k) \
;         acc[ai][bj][m][n] = __builtin_amdgcn_mfma_f32_16x16x32_bf16(Bt[n][k], At[m][k], acc[ai][bj][m][n], 0, 0, 0); __builtin_amdgcn_s_setprio(0); } while (0)
; #define PG8_WAIT_V(n) asm volatile("s_waitcnt vmcnt(" #n ")" ::: "memory")
; #define PG8_WAIT_L(n) asm volatile("s_waitcnt lgkmcnt(" #n ")" ::: "memory")
; #define PG8_BAR __builtin_amdgcn_s_barrier()
; #define PG8_SCHED __builtin_amdgcn_sched_barrier(0)
; template <class Epi, class Sched, bool ALIGN_EPI = false, bool SP2 = false>
; __device__ __forceinline__ void gemm_phase(PG8_LAS unsigned char* lds, const Gemm g, const Sched& S, const Epi& E) {
;     ...
;             PG8_WAIT_V(8); PG8_WAIT_L(0); PG8_BAR; PG8_MMA(0, 0, At, B0); PG8_MMA(0, 1, At, B1); PG8_BAR; PG8_SCHED;
;             PG8_LDA(At, 0, 1); PG8_STAGE(PG8_SB(0, 0), b2, voffB); PG8_STAGE(PG8_SB(0, 1), b2 + hstep, voffB); PG8_STAGE(PG8_SA(0, 0), a2, voffA);
;             PG8_WAIT_V(8); PG8_WAIT_L(0); PG8_BAR; PG8_MMA(1, 0, At, B0); PG8_MMA(1, 1, At, B1); PG8_BAR; PG8_SCHED;
	v_mfma_f32_16x16x32_bf16 v[126:129], v[160:163], v[208:211], v[126:129]
	v_mfma_f32_16x16x32_bf16 v[122:125], v[168:171], v[208:211], v[122:125]
	v_mfma_f32_16x16x32_bf16 v[110:113], v[160:163], v[216:219], v[110:113]
	v_mfma_f32_16x16x32_bf16 v[106:109], v[168:171], v[216:219], v[106:109]
	v_mfma_f32_16x16x32_bf16 v[94:97], v[160:163], v[224:227], v[94:97]
	v_mfma_f32_16x16x32_bf16 v[90:93], v[168:171], v[224:227], v[90:93]
	v_mfma_f32_16x16x32_bf16 v[78:81], v[160:163], v[232:235], v[78:81]
	v_mfma_f32_16x16x32_bf16 v[74:77], v[168:171], v[232:235], v[74:77]
	s_setprio 0
	s_setprio 1
	v_mfma_f32_16x16x32_bf16 v[126:129], v[164:167], v[212:215], v[126:129]
	v_mfma_f32_16x16x32_bf16 v[122:125], v[172:175], v[212:215], v[122:125]
	v_mfma_f32_16x16x32_bf16 v[110:113], v[164:167], v[220:223], v[110:113]
	v_mfma_f32_16x16x32_bf16 v[106:109], v[172:175], v[220:223], v[106:109]
	v_mfma_f32_16x16x32_bf16 v[94:97], v[164:167], v[228:231], v[94:97]
	v_mfma_f32_16x16x32_bf16 v[90:93], v[172:175], v[228:231], v[90:93]
	v_mfma_f32_16x16x32_bf16 v[78:81], v[164:167], v[236:239], v[78:81]
	v_mfma_f32_16x16x32_bf16 v[74:77], v[172:175], v[236:239], v[74:77]
	s_setprio 0
	s_setprio 1
	v_mfma_f32_16x16x32_bf16 v[118:121], v[176:179], v[208:211], v[118:121]
	v_mfma_f32_16x16x32_bf16 v[114:117], v[184:187], v[208:211], v[114:117]
	v_mfma_f32_16x16x32_bf16 v[102:105], v[176:179], v[216:219], v[102:105]
	v_mfma_f32_16x16x32_bf16 v[98:101], v[184:187], v[216:219], v[98:101]
	v_mfma_f32_16x16x32_bf16 v[86:89], v[176:179], v[224:227], v[86:89]
	v_mfma_f32_16x16x32_bf16 v[82:85], v[184:187], v[224:227], v[82:85]
	v_mfma_f32_16x16x32_bf16 v[70:73], v[176:179], v[232:235], v[70:73]
	v_mfma_f32_16x16x32_bf16 v[66:69], v[184:187], v[232:235], v[66:69]
	s_setprio 0
	s_setprio 1
	v_mfma_f32_16x16x32_bf16 v[118:121], v[180:183], v[212:215], v[118:121]
	v_mfma_f32_16x16x32_bf16 v[114:117], v[204:207], v[212:215], v[114:117]
	v_mfma_f32_16x16x32_bf16 v[102:105], v[180:183], v[220:223], v[102:105]
	v_mfma_f32_16x16x32_bf16 v[98:101], v[204:207], v[220:223], v[98:101]
	v_mfma_f32_16x16x32_bf16 v[86:89], v[180:183], v[228:231], v[86:89]
	v_mfma_f32_16x16x32_bf16 v[82:85], v[204:207], v[228:231], v[82:85]
	v_mfma_f32_16x16x32_bf16 v[70:73], v[180:183], v[236:239], v[70:73]
	v_mfma_f32_16x16x32_bf16 v[66:69], v[204:207], v[236:239], v[66:69]
	s_setprio 0
	s_barrier
	s_add_i32 s46, s46, s4
	v_lshl_add_u64 v[240:241], s[18:19], 0, v[148:149]
	s_mov_b32 m0, s46
	ds_read_b128 v[208:211], v143 offset:16384
	ds_read_b128 v[212:215], v143 offset:17408
	ds_read_b128 v[216:219], v143 offset:18432
	ds_read_b128 v[220:223], v143 offset:19456
	ds_read_b128 v[224:227], v143 offset:20480
	ds_read_b128 v[228:231], v143 offset:21504
	ds_read_b128 v[232:235], v143 offset:22528
	ds_read_b128 v[236:239], v143 offset:23552
	global_load_lds_dwordx4 v[240:241], off
	s_add_i32 m0, s46, 0x2000
	s_add_u32 s46, s18, 0x20000
	v_lshl_add_u64 v[242:243], s[18:19], 0, v[144:145]
	s_addc_u32 s47, s19, 0
	s_add_i32 s76, s76, s4
	global_load_lds_dwordx4 v[242:243], off
	v_lshl_add_u64 v[244:245], s[46:47], 0, v[148:149]
	s_mov_b32 m0, s76
	v_lshl_add_u64 v[246:247], s[62:63], 0, v[146:147]
	global_load_lds_dwordx4 v[244:245], off
	v_lshl_add_u64 v[244:245], s[46:47], 0, v[144:145]
	s_add_i32 m0, s76, 0x2000
	s_nop 0
	global_load_lds_dwordx4 v[244:245], off
	v_lshl_add_u64 v[244:245], s[62:63], 0, v[150:151]
	s_mov_b32 m0, s5
	s_nop 0
	global_load_lds_dwordx4 v[244:245], off
	s_mov_b32 m0, s28
	s_nop 0
	global_load_lds_dwordx4 v[246:247], off
	s_waitcnt vmcnt(8)
	s_waitcnt lgkmcnt(0)
	s_setprio 1
	s_barrier
	v_mfma_f32_16x16x32_bf16 v[62:65], v[160:163], v[208:211], v[62:65]
	v_mfma_f32_16x16x32_bf16 v[58:61], v[168:171], v[208:211], v[58:61]
	v_mfma_f32_16x16x32_bf16 v[46:49], v[160:163], v[216:219], v[46:49]
	v_mfma_f32_16x16x32_bf16 v[42:45], v[168:171], v[216:219], v[42:45]
	v_mfma_f32_16x16x32_bf16 v[30:33], v[160:163], v[224:227], v[30:33]
	v_mfma_f32_16x16x32_bf16 v[26:29], v[168:171], v[224:227], v[26:29]
	v_mfma_f32_16x16x32_bf16 v[14:17], v[160:163], v[232:235], v[14:17]
	v_mfma_f32_16x16x32_bf16 v[10:13], v[168:171], v[232:235], v[10:13]
	v_mfma_f32_16x16x32_bf16 v[62:65], v[164:167], v[212:215], v[62:65]
	v_mfma_f32_16x16x32_bf16 v[58:61], v[172:175], v[212:215], v[58:61]
	v_mfma_f32_16x16x32_bf16 v[46:49], v[164:167], v[220:223], v[46:49]
	v_mfma_f32_16x16x32_bf16 v[42:45], v[172:175], v[220:223], v[42:45]
	v_mfma_f32_16x16x32_bf16 v[30:33], v[164:167], v[228:231], v[30:33]
	v_mfma_f32_16x16x32_bf16 v[26:29], v[172:175], v[228:231], v[26:29]
	v_mfma_f32_16x16x32_bf16 v[14:17], v[164:167], v[236:239], v[14:17]
	v_mfma_f32_16x16x32_bf16 v[10:13], v[172:175], v[236:239], v[10:13]
	v_mfma_f32_16x16x32_bf16 v[54:57], v[176:179], v[208:211], v[54:57]
	v_mfma_f32_16x16x32_bf16 v[50:53], v[184:187], v[208:211], v[50:53]
	v_mfma_f32_16x16x32_bf16 v[38:41], v[176:179], v[216:219], v[38:41]
	v_mfma_f32_16x16x32_bf16 v[34:37], v[184:187], v[216:219], v[34:37]
	v_mfma_f32_16x16x32_bf16 v[22:25], v[176:179], v[224:227], v[22:25]
	v_mfma_f32_16x16x32_bf16 v[18:21], v[184:187], v[224:227], v[18:21]
	v_mfma_f32_16x16x32_bf16 v[6:9], v[176:179], v[232:235], v[6:9]
	v_mfma_f32_16x16x32_bf16 v[2:5], v[184:187], v[232:235], v[2:5]
	v_mfma_f32_16x16x32_bf16 v[54:57], v[180:183], v[212:215], v[54:57]
	v_mfma_f32_16x16x32_bf16 v[50:53], v[204:207], v[212:215], v[50:53]
	v_mfma_f32_16x16x32_bf16 v[38:41], v[180:183], v[220:223], v[38:41]
	v_mfma_f32_16x16x32_bf16 v[34:37], v[204:207], v[220:223], v[34:37]
	v_mfma_f32_16x16x32_bf16 v[22:25], v[180:183], v[228:231], v[22:25]
	v_mfma_f32_16x16x32_bf16 v[18:21], v[204:207], v[228:231], v[18:21]
	v_mfma_f32_16x16x32_bf16 v[6:9], v[180:183], v[236:239], v[6:9]
	v_mfma_f32_16x16x32_bf16 v[2:5], v[204:207], v[236:239], v[2:5]
	s_setprio 0
	s_barrier
; #define PG8_STAGE(bufoff, gbase, voff) do { _Pragma("unroll") for (int _i = 0; _i < 2; ++_i) \
;         __builtin_amdgcn_global_load_lds((const unsigned*)((const char*)(gbase) + (voff)[_i]), (PG8_LAS unsigned*)(lds + (bufoff) + ldsw + _i * 8192), 16, 0, 0); } while (0)
; #define PG8_LDA(dst, b, h) do { _Pragma("unroll") for (int m = 0; m < 4; ++m) _Pragma("unroll") for (int k = 0; k < 2; ++k) dst[m][k] = *(const PG8_LAS bf16x8*)(lds + PG8_SA(b, h) + aoff + m * 2048 + k * 1024); } while (0)
; #define PG8_LDB(dst, b, h) do { _Pragma("unroll") for (int n = 0; n < 2; ++n) _Pragma("unroll") for (int k = 0; k < 2; ++k) dst[n][k] = *(const PG8_LAS bf16x8*)(lds + PG8_SB(b, h) + boff + n * 2048 + k * 1024); } while (0)
; #define PG8_MMA(ai, bj, At, Bt) do { __builtin_amdgcn_s_setprio(1); _Pragma("unroll") for (int m = 0; m < 4; ++m) _Pragma("unroll") for (int n = 0; n < 2; ++n) _Pragma("unroll") for (int k = 0; k < 2; ++k) \
;         acc[ai][bj][m][n] = __builtin_amdgcn_mfma_f32_16x16x32_bf16(Bt[n][k], At[m][k], acc[ai][bj][m][n], 0, 0, 0); __builtin_amdgcn_s_setprio(0); } while (0)
; #define PG8_WAIT_V(n) asm volatile("s_waitcnt vmcnt(" #n ")" ::: "memory")
; #define PG8_WAIT_L(n) asm volatile("s_waitcnt lgkmcnt(" #n ")" ::: "memory")
; #define PG8_BAR __builtin_amdgcn_s_barrier()
; #define PG8_SCHED __builtin_amdgcn_sched_barrier(0)
; template <class Epi, class Sched, bool ALIGN_EPI = false, bool SP2 = false>
; __device__ __forceinline__ void gemm_phase(PG8_LAS unsigned char* lds, const Gemm g, const Sched& S, const Epi& E) {
;     ...
;             PG8_LDB(B0, 1, 0); PG8_LDB(B1, 1, 1); PG8_SCHED; PG8_LDA(At, 1, 0); PG8_STAGE(PG8_SA(0, 1), a2 + hstep, voffA);
;             PG8_WAIT_V(8); PG8_WAIT_L(0); PG8_BAR; PG8_MMA(0, 0, At, B0); PG8_MMA(0, 1, At, B1); PG8_BAR; PG8_SCHED;
;             PG8_LDA(At, 1, 1); PG8_STAGE(PG8_SB(1, 0), b3, voffB); PG8_STAGE(PG8_SB(1, 1), b3 + hstep, voffB); PG8_STAGE(PG8_SA(1, 0), a3, voffA);
;             PG8_WAIT_V(8); PG8_WAIT_L(0); PG8_BAR; PG8_MMA(1, 0, At, B0); PG8_MMA(1, 1, At, B1); PG8_BAR; PG8_SCHED;
	s_add_i32 s76, 0, 0x18000
	s_add_i32 s77, 0, 0x1c000
	v_add_u32_e32 v172, s76, v1
	v_add_u32_e32 v203, s77, v1
	ds_read_b128 v[160:163], v172
	ds_read_b128 v[164:167], v172 offset:1024
	ds_read_b128 v[168:171], v172 offset:2048
	ds_read_b128 v[172:175], v172 offset:3072
	ds_read_b128 v[176:179], v203
	ds_read_b128 v[180:183], v203 offset:1024
	ds_read_b128 v[184:187], v203 offset:2048
	ds_read_b128 v[204:207], v203 offset:3072
	s_add_u32 s46, s62, 0x20000
	s_addc_u32 s47, s63, 0
	s_mov_b32 m0, s30
	v_lshl_add_u64 v[248:249], s[46:47], 0, v[150:151]
	ds_read_b128 v[208:211], v143 offset:32768
	ds_read_b128 v[212:215], v143 offset:33792
	ds_read_b128 v[216:219], v143 offset:34816
	ds_read_b128 v[220:223], v143 offset:35840
	ds_read_b128 v[224:227], v143 offset:36864
	ds_read_b128 v[228:231], v143 offset:37888
	ds_read_b128 v[232:235], v143 offset:38912
	ds_read_b128 v[236:239], v143 offset:39936
	global_load_lds_dwordx4 v[248:249], off
	v_lshl_add_u64 v[248:249], s[46:47], 0, v[146:147]
	s_mov_b32 m0, s34
	s_nop 0
	global_load_lds_dwordx4 v[248:249], off
	s_waitcnt vmcnt(8)
	s_waitcnt lgkmcnt(0)
	s_setprio 1
	s_barrier
	v_mfma_f32_16x16x32_bf16 v[126:129], v[160:163], v[208:211], v[126:129]
	v_mfma_f32_16x16x32_bf16 v[122:125], v[168:171], v[208:211], v[122:125]
	v_mfma_f32_16x16x32_bf16 v[110:113], v[160:163], v[216:219], v[110:113]
	v_mfma_f32_16x16x32_bf16 v[106:109], v[168:171], v[216:219], v[106:109]
	v_mfma_f32_16x16x32_bf16 v[94:97], v[160:163], v[224:227], v[94:97]
	v_mfma_f32_16x16x32_bf16 v[90:93], v[168:171], v[224:227], v[90:93]
	v_mfma_f32_16x16x32_bf16 v[78:81], v[160:163], v[232:235], v[78:81]
	v_mfma_f32_16x16x32_bf16 v[74:77], v[168:171], v[232:235], v[74:77]
	s_setprio 0
	s_setprio 1
	v_mfma_f32_16x16x32_bf16 v[126:129], v[164:167], v[212:215], v[126:129]
	v_mfma_f32_16x16x32_bf16 v[122:125], v[172:175], v[212:215], v[122:125]
	v_mfma_f32_16x16x32_bf16 v[110:113], v[164:167], v[220:223], v[110:113]
	v_mfma_f32_16x16x32_bf16 v[106:109], v[172:175], v[220:223], v[106:109]
	v_mfma_f32_16x16x32_bf16 v[94:97], v[164:167], v[228:231], v[94:97]
	v_mfma_f32_16x16x32_bf16 v[90:93], v[172:175], v[228:231], v[90:93]
	v_mfma_f32_16x16x32_bf16 v[78:81], v[164:167], v[236:239], v[78:81]
	v_mfma_f32_16x16x32_bf16 v[74:77], v[172:175], v[236:239], v[74:77]
	s_setprio 0
	s_setprio 1
	v_mfma_f32_16x16x32_bf16 v[118:121], v[176:179], v[208:211], v[118:121]
	v_mfma_f32_16x16x32_bf16 v[114:117], v[184:187], v[208:211], v[114:117]
	v_mfma_f32_16x16x32_bf16 v[102:105], v[176:179], v[216:219], v[102:105]
	v_mfma_f32_16x16x32_bf16 v[98:101], v[184:187], v[216:219], v[98:101]
	v_mfma_f32_16x16x32_bf16 v[86:89], v[176:179], v[224:227], v[86:89]
	v_mfma_f32_16x16x32_bf16 v[82:85], v[184:187], v[224:227], v[82:85]
	v_mfma_f32_16x16x32_bf16 v[70:73], v[176:179], v[232:235], v[70:73]
	v_mfma_f32_16x16x32_bf16 v[66:69], v[184:187], v[232:235], v[66:69]
	s_setprio 0
	s_setprio 1
	v_mfma_f32_16x16x32_bf16 v[118:121], v[180:183], v[212:215], v[118:121]
	v_mfma_f32_16x16x32_bf16 v[114:117], v[204:207], v[212:215], v[114:117]
	v_mfma_f32_16x16x32_bf16 v[102:105], v[180:183], v[220:223], v[102:105]
	v_mfma_f32_16x16x32_bf16 v[98:101], v[204:207], v[220:223], v[98:101]
	v_mfma_f32_16x16x32_bf16 v[86:89], v[180:183], v[228:231], v[86:89]
	v_mfma_f32_16x16x32_bf16 v[82:85], v[204:207], v[228:231], v[82:85]
	v_mfma_f32_16x16x32_bf16 v[70:73], v[180:183], v[236:239], v[70:73]
	v_mfma_f32_16x16x32_bf16 v[66:69], v[204:207], v[236:239], v[66:69]
	s_setprio 0
	s_barrier
	s_add_i32 s46, s76, s4
	v_lshl_add_u64 v[240:241], v[240:241], 0, s[68:69]
	s_mov_b32 m0, s46
	ds_read_b128 v[208:211], v143 offset:49152
	ds_read_b128 v[212:215], v143 offset:50176
	ds_read_b128 v[216:219], v143 offset:51200
	ds_read_b128 v[220:223], v143 offset:52224
	ds_read_b128 v[224:227], v143 offset:53248
	ds_read_b128 v[228:231], v143 offset:54272
	ds_read_b128 v[232:235], v143 offset:55296
	ds_read_b128 v[236:239], v143 offset:56320
	global_load_lds_dwordx4 v[240:241], off
	s_add_i32 m0, s46, 0x2000
	s_add_u32 s18, s18, 0x20080
	v_lshl_add_u64 v[240:241], v[242:243], 0, s[68:69]
	s_addc_u32 s19, s19, 0
	s_add_i32 s46, s77, s4
	global_load_lds_dwordx4 v[240:241], off
	v_lshl_add_u64 v[240:241], s[18:19], 0, v[148:149]
	s_mov_b32 m0, s46
	s_nop 0
	global_load_lds_dwordx4 v[240:241], off
	v_lshl_add_u64 v[240:241], s[18:19], 0, v[144:145]
	s_add_i32 m0, s46, 0x2000
	s_nop 0
	global_load_lds_dwordx4 v[240:241], off
	v_lshl_add_u64 v[240:241], v[244:245], 0, s[68:69]
	s_mov_b32 m0, s54
	s_nop 0
	global_load_lds_dwordx4 v[240:241], off
	v_lshl_add_u64 v[240:241], v[246:247], 0, s[68:69]
	s_mov_b32 m0, s57
	s_nop 0
	global_load_lds_dwordx4 v[240:241], off
	s_nop 0
	s_waitcnt vmcnt(8)
	s_waitcnt lgkmcnt(0)
	s_setprio 1
	s_barrier
; #define PG8_BAR __builtin_amdgcn_s_barrier()
;     __device__ __forceinline__ void operator()(const f32x4 (&acc)[2][2][4][2], const Unit& u, int wr, int wc, int fr, int fq) const {
;         const int row0 = u.pm * BM + wr * 64 + fr, col0 = u.pn * BM + wc * 32 + 8 * fq;
;         const int tidn = (wr * 4 + wc) * 64 + fq * 16 + fr;
;         const u32x4* gp = (const u32x4*)G8 + (size_t)(u.pm * 16 + gsel + u.pn) * 8 * 512 + tidn;
;         u32x4* mp = M1 + (size_t)(u.pm * 8 + u.pn) * 16 * 512 + tidn;
;         constexpr float K255 = 1.0f / 255.0f;
; #pragma unroll
;         for (int ai = 0; ai < 2; ++ai)
; #pragma unroll
;             for (int m = 0; m < 4; ++m) { const size_t row = (size_t)(row0 + ai * HALF + m * 16);
; template <class Epi, class Sched, bool ALIGN_EPI = false, bool SP2 = false>
; __device__ __forceinline__ void gemm_phase(PG8_LAS unsigned char* lds, const Gemm g, const Sched& S, const Epi& E) {
;     ...
;             PG8_WAIT_V(8); PG8_WAIT_L(0); PG8_BAR; PG8_MMA(1, 0, At, B0); PG8_MMA(1, 1, At, B1); PG8_BAR; PG8_SCHED;
;             } else {
;             PG8_LDB(B0, 0, 0); PG8_SCHED; PG8_LDA(At, 0, 0); PG8_STAGE(PG8_SA(1, 1), a1 + hstep, voffA);
;             PG8_WAIT_L(8); PG8_BAR; PG8_WAIT_L(0); PG8_MMA(0, 0, At, B0); PG8_BAR; PG8_SCHED;
;             PG8_LDB(B1, 0, 1); PG8_STAGE(PG8_SB(0, 0), b2, voffB);
;             PG8_BAR; PG8_WAIT_L(0); PG8_MMA(0, 1, At, B1); PG8_BAR;
;             PG8_LDA(At, 0, 1); PG8_STAGE(PG8_SA(0, 0), a2, voffA);
;             PG8_BAR; PG8_WAIT_L(0); PG8_MMA(1, 0, At, B0); PG8_BAR; PG8_SCHED;
;             PG8_STAGE(PG8_SB(0, 1), b2 + hstep, voffB);
;             PG8_WAIT_V(6); PG8_BAR; PG8_MMA(1, 1, At, B1); PG8_BAR;
;             PG8_LDB(B0, 1, 0); PG8_SCHED; PG8_LDA(At, 1, 0); PG8_STAGE(PG8_SA(0, 1), a2 + hstep, voffA);
;             PG8_WAIT_L(8); PG8_BAR; PG8_WAIT_L(0); PG8_MMA(0, 0, At, B0); PG8_BAR; PG8_SCHED;
;             PG8_LDB(B1, 1, 1); PG8_STAGE(PG8_SB(1, 0), b3, voffB);
;             PG8_BAR; PG8_WAIT_L(0); PG8_MMA(0, 1, At, B1); PG8_BAR;
;             PG8_LDA(At, 1, 1); PG8_STAGE(PG8_SA(1, 0), a3, voffA);
;             PG8_BAR; PG8_WAIT_L(0); PG8_MMA(1, 0, At, B0); PG8_BAR; PG8_SCHED;
;             PG8_STAGE(PG8_SB(1, 1), b3 + hstep, voffB);
;             PG8_WAIT_V(6); PG8_BAR; PG8_MMA(1, 1, At, B1); PG8_BAR;
;             }
;         }
;         if constexpr (ALIGN_EPI) { if (wr == 0) PG8_BAR; }
	v_mfma_f32_16x16x32_bf16 v[62:65], v[160:163], v[208:211], v[62:65]
	v_mfma_f32_16x16x32_bf16 v[58:61], v[168:171], v[208:211], v[58:61]
	v_mfma_f32_16x16x32_bf16 v[46:49], v[160:163], v[216:219], v[46:49]
	v_mfma_f32_16x16x32_bf16 v[42:45], v[168:171], v[216:219], v[42:45]
	v_mfma_f32_16x16x32_bf16 v[30:33], v[160:163], v[224:227], v[30:33]
	v_mfma_f32_16x16x32_bf16 v[26:29], v[168:171], v[224:227], v[26:29]
	v_mfma_f32_16x16x32_bf16 v[14:17], v[160:163], v[232:235], v[14:17]
	v_mfma_f32_16x16x32_bf16 v[10:13], v[168:171], v[232:235], v[10:13]
	v_mfma_f32_16x16x32_bf16 v[62:65], v[164:167], v[212:215], v[62:65]
	v_mfma_f32_16x16x32_bf16 v[58:61], v[172:175], v[212:215], v[58:61]
	v_mfma_f32_16x16x32_bf16 v[46:49], v[164:167], v[220:223], v[46:49]
	v_mfma_f32_16x16x32_bf16 v[42:45], v[172:175], v[220:223], v[42:45]
	v_mfma_f32_16x16x32_bf16 v[30:33], v[164:167], v[228:231], v[30:33]
	v_mfma_f32_16x16x32_bf16 v[26:29], v[172:175], v[228:231], v[26:29]
	v_mfma_f32_16x16x32_bf16 v[14:17], v[164:167], v[236:239], v[14:17]
	v_mfma_f32_16x16x32_bf16 v[10:13], v[172:175], v[236:239], v[10:13]
	v_mfma_f32_16x16x32_bf16 v[54:57], v[176:179], v[208:211], v[54:57]
	v_mfma_f32_16x16x32_bf16 v[50:53], v[184:187], v[208:211], v[50:53]
	v_mfma_f32_16x16x32_bf16 v[38:41], v[176:179], v[216:219], v[38:41]
	v_mfma_f32_16x16x32_bf16 v[34:37], v[184:187], v[216:219], v[34:37]
	v_mfma_f32_16x16x32_bf16 v[22:25], v[176:179], v[224:227], v[22:25]
	v_mfma_f32_16x16x32_bf16 v[18:21], v[184:187], v[224:227], v[18:21]
	v_mfma_f32_16x16x32_bf16 v[6:9], v[176:179], v[232:235], v[6:9]
	v_mfma_f32_16x16x32_bf16 v[2:5], v[184:187], v[232:235], v[2:5]
	v_mfma_f32_16x16x32_bf16 v[54:57], v[180:183], v[212:215], v[54:57]
	v_mfma_f32_16x16x32_bf16 v[50:53], v[204:207], v[212:215], v[50:53]
	v_mfma_f32_16x16x32_bf16 v[38:41], v[180:183], v[220:223], v[38:41]
	v_mfma_f32_16x16x32_bf16 v[34:37], v[204:207], v[220:223], v[34:37]
	v_mfma_f32_16x16x32_bf16 v[22:25], v[180:183], v[228:231], v[22:25]
	v_mfma_f32_16x16x32_bf16 v[18:21], v[204:207], v[228:231], v[18:21]
	v_mfma_f32_16x16x32_bf16 v[6:9], v[180:183], v[236:239], v[6:9]
	v_mfma_f32_16x16x32_bf16 v[2:5], v[204:207], v[236:239], v[2:5]
	s_setprio 0
	s_barrier
	s_add_i32 s79, s79, 2
	s_add_u32 s58, s58, 0x100
	s_addc_u32 s59, s59, 0
	s_add_u32 s85, s85, 0x100
	s_addc_u32 s78, s78, 0
	s_cmp_gt_u32 s79, 5
	s_cbranch_scc0 .LBB0_136
	s_mov_b32 s32, 1
	s_lshl_b32 s11, s67, 4
	s_add_i32 s18, s11, s86
	s_ashr_i32 s19, s18, 31
	s_lshl_b64 s[46:47], s[18:19], 16
	v_lshl_add_u64 v[162:163], v[152:153], 0, s[46:47]
	s_lshl_b32 s11, s67, 3
	s_sub_i32 s18, s18, s11
	s_ashr_i32 s19, s18, 31
	s_lshl_b64 s[18:19], s[18:19], 17
	v_lshl_add_u64 v[160:161], v[154:155], 0, s[18:19]
	s_mov_b32 s47, 0
	global_load_dwordx4 v[168:171], v[162:163], off
	s_mov_b32 s46, 0x2000
	v_lshl_add_u64 v[164:165], v[162:163], 0, s[46:47]
	global_load_dwordx4 v[172:175], v[164:165], off
	s_mov_b32 s46, 0x4000
	v_lshl_add_u64 v[164:165], v[162:163], 0, s[46:47]
	global_load_dwordx4 v[176:179], v[164:165], off
	s_mov_b32 s46, 0x6000
	v_lshl_add_u64 v[164:165], v[162:163], 0, s[46:47]
	global_load_dwordx4 v[180:183], v[164:165], off
	s_mov_b32 s46, 0x8000
	v_lshl_add_u64 v[164:165], v[162:163], 0, s[46:47]
	global_load_dwordx4 v[184:187], v[164:165], off
	s_mov_b32 s46, 0xa000
	v_lshl_add_u64 v[164:165], v[162:163], 0, s[46:47]
	global_load_dwordx4 v[204:207], v[164:165], off
	s_mov_b32 s46, 0xc000
	v_lshl_add_u64 v[164:165], v[162:163], 0, s[46:47]
	global_load_dwordx4 v[208:211], v[164:165], off
	s_mov_b32 s46, 0xe000
	v_lshl_add_u64 v[164:165], v[162:163], 0, s[46:47]
	global_load_dwordx4 v[212:215], v[164:165], off
	s_and_b64 vcc, exec, s[8:9]
	s_cbranch_vccz .Lg0_nobar
	s_barrier

; #define PG8_STAGE(bufoff, gbase, voff) do { _Pragma("unroll") for (int _i = 0; _i < 2; ++_i) \
;         __builtin_amdgcn_global_load_lds((const unsigned*)((const char*)(gbase) + (voff)[_i]), (PG8_LAS unsigned*)(lds + (bufoff) + ldsw + _i * 8192), 16, 0, 0); } while (0)
; #define PG8_WAIT_V(n) asm volatile("s_waitcnt vmcnt(" #n ")" ::: "memory")
; #define PG8_BAR __builtin_amdgcn_s_barrier()
; template <class Epi, class Sched, bool ALIGN_EPI = false, bool SP2 = false>
; __device__ __forceinline__ void gemm_phase(PG8_LAS unsigned char* lds, const Gemm g, const Sched& S, const Epi& E) {
;     ...
;     for (int i = 0; i < 2; ++i) { int R, C; stage_rc(tid * 16 + i * 8192, R, C); const int Rb = Epi::PERM ? ((R & ~31) + perm32(R & 31)) : R;
;         voffA[i] = (unsigned)(R * K + C) * 2u; voffB[i] = (unsigned)(Rb * K + C) * 2u; }
;     const size_t kstep = (size_t)(BK * 2);
;     const size_t hstep = (size_t)HALF * K * 2;
;     const size_t tstep = 2 * hstep;
;     const unsigned ldsw = (unsigned)wid * 1024u;
;     const int aoff = lds_byte(wr * 64 + fr, fq * 8), boff = lds_byte(wc * 32 + fr, fq * 8);
;     ...
;         PG8_STAGE(PG8_SB(0, 0), cB, voffB); PG8_STAGE(PG8_SB(0, 1), cB + hstep, voffB); PG8_STAGE(PG8_SA(0, 0), cA, voffA); PG8_STAGE(PG8_SA(0, 1), cA + hstep, voffA);
;         if (wr == 1) PG8_BAR;
;         PG8_WAIT_V(2); PG8_BAR;
;         PG8_STAGE(PG8_SB(1, 0), cB + kstep, voffB); PG8_STAGE(PG8_SA(1, 0), cA + kstep, voffA); PG8_STAGE(PG8_SB(1, 1), cB + hstep + kstep, voffB);
;         PG8_WAIT_V(6); PG8_BAR;
.LBB0_146:
	v_bfe_u32 v20, v18, 4, 2
	v_and_b32_e32 v19, 15, v18
	v_lshlrev_b32_e32 v21, 3, v20
	v_lshlrev_b32_e32 v20, 4, v20
	v_lshlrev_b32_e32 v18, 2, v18
	s_and_b32 s18, s10, 3
	v_lshl_or_b32 v1, s1, 6, v19
	v_lshl_or_b32 v22, v19, 6, v20
	s_lshl_b32 s1, s1, 13
	v_and_b32_e32 v18, 32, v18
	s_add_i32 m0, s54, 0x18000
	v_lshl_add_u64 v[8:9], v[8:9], 0, s[68:69]
	v_bitop3_b32 v23, v22, s1, v18 bitop3:0xde
	s_lshl_b32 s1, s18, 12
	s_waitcnt vmcnt(2)
	s_barrier
	global_load_lds_dwordx4 v[8:9], off
	v_lshl_add_u64 v[6:7], v[6:7], 0, s[68:69]
	s_add_i32 m0, s54, 0x1a000
	s_add_i32 s62, s54, 0x8000
	s_add_i32 s63, s54, 0xa000
	global_load_lds_dwordx4 v[6:7], off
	v_lshl_add_u64 v[2:3], v[2:3], 0, s[68:69]
	s_mov_b32 m0, s62
	s_add_u32 s10, s42, 0x60080
	global_load_lds_dwordx4 v[2:3], off
	v_lshl_add_u64 v[2:3], v[4:5], 0, s[68:69]
	s_mov_b32 m0, s63
	s_addc_u32 s11, s43, 0
	global_load_lds_dwordx4 v[2:3], off
	s_add_i32 m0, s54, 0x1c000
	v_lshl_add_u64 v[2:3], s[10:11], 0, v[148:149]
	global_load_lds_dwordx4 v[2:3], off
	v_lshl_add_u64 v[2:3], s[10:11], 0, v[144:145]
	s_add_i32 m0, s54, 0x1e000
	s_cmpk_lt_u32 s0, 0x100
	global_load_lds_dwordx4 v[2:3], off
	v_bitop3_b32 v143, v22, s1, v18 bitop3:0xde
	s_cselect_b64 s[10:11], -1, 0
	s_and_b32 s0, s0, 0xffffff00
	s_lshl_b32 s1, s18, 6
	s_or_b32 s0, s1, s0
	v_or3_b32 v2, s0, v20, v19
	v_ashrrev_i32_e32 v3, 31, v2
	v_readlane_b32 s0, v254, 61
	v_lshlrev_b64 v[2:3], 4, v[2:3]
	v_readlane_b32 s1, v254, 62
	v_lshl_add_u64 v[154:155], s[6:7], 0, v[2:3]
	s_movk_i32 s6, 0x6000
	v_lshl_add_u64 v[152:153], s[0:1], 0, v[2:3]
	v_lshrrev_b32_e32 v3, 1, v15
	v_mul_lo_u32 v2, v14, s3
	v_mad_u64_u32 v[2:3], s[0:1], v3, s6, v[2:3]
	v_or_b32_e32 v2, v2, v16
	v_lshl_or_b32 v168, s18, 5, v21
	v_add_lshl_u32 v2, v2, v17, 1
	v_mov_b32_e32 v3, v0
	s_mov_b64 s[18:19], 0x60080
	v_lshl_add_u64 v[156:157], v[2:3], 0, s[18:19]
	v_lshrrev_b32_e32 v3, 1, v10
	v_mul_lo_u32 v2, v11, s3
	v_mad_u64_u32 v[2:3], s[0:1], v3, s6, v[2:3]
	s_waitcnt vmcnt(6)
	v_or_b32_e32 v2, v2, v12
	v_add_lshl_u32 v2, v2, v13, 1
	v_mov_b32_e32 v3, v0
	v_readlane_b32 s0, v254, 2
	v_lshl_add_u64 v[158:159], v[2:3], 0, s[18:19]
	s_mov_b32 s67, 0
	v_add_u32_e32 v169, 0, v23
	v_readlane_b32 s28, v253, 19
	s_mov_b32 s34, s0
	s_barrier
	v_readlane_b32 s1, v254, 3
	s_mov_b32 s32, 0
	s_branch .LBB0_149

; #define PG8_STAGE(bufoff, gbase, voff) do { _Pragma("unroll") for (int _i = 0; _i < 2; ++_i) \
;         __builtin_amdgcn_global_load_lds((const unsigned*)((const char*)(gbase) + (voff)[_i]), (PG8_LAS unsigned*)(lds + (bufoff) + ldsw + _i * 8192), 16, 0, 0); } while (0)
; #define PG8_LDA(dst, b, h) do { _Pragma("unroll") for (int m = 0; m < 4; ++m) _Pragma("unroll") for (int k = 0; k < 2; ++k) dst[m][k] = *(const PG8_LAS bf16x8*)(lds + PG8_SA(b, h) + aoff + m * 2048 + k * 1024); } while (0)
; #define PG8_LDB(dst, b, h) do { _Pragma("unroll") for (int n = 0; n < 2; ++n) _Pragma("unroll") for (int k = 0; k < 2; ++k) dst[n][k] = *(const PG8_LAS bf16x8*)(lds + PG8_SB(b, h) + boff + n * 2048 + k * 1024); } while (0)
; #define PG8_SCHED __builtin_amdgcn_sched_barrier(0)
; template <class Epi, class Sched, bool ALIGN_EPI = false, bool SP2 = false>
; __device__ __forceinline__ void gemm_phase(PG8_LAS unsigned char* lds, const Gemm g, const Sched& S, const Epi& E) {
;     ...
;         const char* nA = has_next ? (const char*)g.A + (size_t)nxt.pm * tstep : cA; const char* nB = has_next ? (const char*)g.Bt + (size_t)nxt.pn * tstep : cB;
;         for (int t = 0; t < nt; t += 2) {
;             const bool last = (t == nt - 2);
;             const char* a1 = cA + (size_t)(t + 1) * kstep;
;             const char* a2 = last ? nA : cA + (size_t)(t + 2) * kstep; const char* b2 = last ? nB : cB + (size_t)(t + 2) * kstep;
;             const char* a3 = a2 + kstep; const char* b3 = b2 + kstep;
;             if (last && has_next) S.a_ready(nxt);
;             if constexpr (SP2) {
;             PG8_LDB(B0, 0, 0); PG8_LDB(B1, 0, 1); PG8_SCHED; PG8_LDA(At, 0, 0); PG8_STAGE(PG8_SA(1, 1), a1 + hstep, voffA);
.LBB0_159:
	s_add_u32 s60, s42, 0x100
	s_addc_u32 s73, s43, 0
	s_mov_b32 s46, -2
	s_add_u32 s42, s36, 0x100
	s_addc_u32 s43, s37, 0
	s_add_i32 s47, 0, 0x10000
	s_cmp_eq_u32 s46, 20
	s_cselect_b32 s45, s1, s43
	s_cselect_b32 s44, s0, s42
	s_cselect_b32 s19, s7, s73
	s_cselect_b32 s18, s6, s60
	s_add_i32 s76, 0, 0x14000
	v_add_u32_e32 v174, s47, v143
	v_add_u32_e32 v186, s76, v143
	ds_read_b128 v[160:163], v174
	ds_read_b128 v[164:167], v174 offset:1024
	ds_read_b128 v[170:173], v174 offset:2048
	ds_read_b128 v[174:177], v174 offset:3072
	ds_read_b128 v[178:181], v186
	ds_read_b128 v[182:185], v186 offset:1024
	ds_read_b128 v[204:207], v186 offset:2048
	ds_read_b128 v[208:211], v186 offset:3072
	v_lshl_add_u64 v[186:187], s[36:37], 0, v[156:157]
	s_add_i32 m0, s54, 0xc000
	ds_read_b128 v[212:215], v169
	ds_read_b128 v[216:219], v169 offset:1024
	ds_read_b128 v[220:223], v169 offset:2048
	ds_read_b128 v[224:227], v169 offset:3072
	ds_read_b128 v[228:231], v169 offset:4096
	ds_read_b128 v[232:235], v169 offset:5120
	ds_read_b128 v[236:239], v169 offset:6144
	ds_read_b128 v[240:243], v169 offset:7168
	global_load_lds_dwordx4 v[186:187], off
	v_lshl_add_u64 v[186:187], s[36:37], 0, v[158:159]
	s_add_i32 m0, s54, 0xe000
	s_nop 0
	global_load_lds_dwordx4 v[186:187], off
	s_cmp_eq_u32 s32, 0
	s_cbranch_scc1 .Lpw9_f
	s_waitcnt vmcnt(24)
	s_branch .Lpw9_j

; #define PG8_STAGE(bufoff, gbase, voff) do { _Pragma("unroll") for (int _i = 0; _i < 2; ++_i) \
;         __builtin_amdgcn_global_load_lds((const unsigned*)((const char*)(gbase) + (voff)[_i]), (PG8_LAS unsigned*)(lds + (bufoff) + ldsw + _i * 8192), 16, 0, 0); } while (0)
; #define PG8_LDA(dst, b, h) do { _Pragma("unroll") for (int m = 0; m < 4; ++m) _Pragma("unroll") for (int k = 0; k < 2; ++k) dst[m][k] = *(const PG8_LAS bf16x8*)(lds + PG8_SA(b, h) + aoff + m * 2048 + k * 1024); } while (0)
; #define PG8_LDB(dst, b, h) do { _Pragma("unroll") for (int n = 0; n < 2; ++n) _Pragma("unroll") for (int k = 0; k < 2; ++k) dst[n][k] = *(const PG8_LAS bf16x8*)(lds + PG8_SB(b, h) + boff + n * 2048 + k * 1024); } while (0)
; #define PG8_MMA(ai, bj, At, Bt) do { __builtin_amdgcn_s_setprio(1); _Pragma("unroll") for (int m = 0; m < 4; ++m) _Pragma("unroll") for (int n = 0; n < 2; ++n) _Pragma("unroll") for (int k = 0; k < 2; ++k) \
;         acc[ai][bj][m][n] = __builtin_amdgcn_mfma_f32_16x16x32_bf16(Bt[n][k], At[m][k], acc[ai][bj][m][n], 0, 0, 0); __builtin_amdgcn_s_setprio(0); } while (0)
; #define PG8_WAIT_V(n) asm volatile("s_waitcnt vmcnt(" #n ")" ::: "memory")
; #define PG8_WAIT_L(n) asm volatile("s_waitcnt lgkmcnt(" #n ")" ::: "memory")
; #define PG8_BAR __builtin_amdgcn_s_barrier()
; #define PG8_SCHED __builtin_amdgcn_sched_barrier(0)
; template <class Epi, class Sched, bool ALIGN_EPI = false, bool SP2 = false>
; __device__ __forceinline__ void gemm_phase(PG8_LAS unsigned char* lds, const Gemm g, const Sched& S, const Epi& E) {
;     ...
;             PG8_LDB(B0, 0, 0); PG8_LDB(B1, 0, 1); PG8_SCHED; PG8_LDA(At, 0, 0); PG8_STAGE(PG8_SA(1, 1), a1 + hstep, voffA);
;             PG8_WAIT_V(8); PG8_WAIT_L(0); PG8_BAR; PG8_MMA(0, 0, At, B0); PG8_MMA(0, 1, At, B1); PG8_BAR; PG8_SCHED;
;             PG8_LDA(At, 0, 1); PG8_STAGE(PG8_SB(0, 0), b2, voffB); PG8_STAGE(PG8_SB(0, 1), b2 + hstep, voffB); PG8_STAGE(PG8_SA(0, 0), a2, voffA);
;             PG8_WAIT_V(8); PG8_WAIT_L(0); PG8_BAR; PG8_MMA(1, 0, At, B0); PG8_MMA(1, 1, At, B1); PG8_BAR; PG8_SCHED;
.Lpw9_j:
	s_nop 0
	s_waitcnt lgkmcnt(0)
	s_setprio 1
	s_barrier
	v_mfma_f32_16x16x32_bf16 v[126:129], v[160:163], v[212:215], 0
	v_mfma_f32_16x16x32_bf16 v[122:125], v[170:173], v[212:215], 0
	v_mfma_f32_16x16x32_bf16 v[110:113], v[160:163], v[220:223], 0
	v_mfma_f32_16x16x32_bf16 v[106:109], v[170:173], v[220:223], 0
	v_mfma_f32_16x16x32_bf16 v[94:97], v[160:163], v[228:231], 0
	v_mfma_f32_16x16x32_bf16 v[90:93], v[170:173], v[228:231], 0
	v_mfma_f32_16x16x32_bf16 v[78:81], v[160:163], v[236:239], 0
	v_mfma_f32_16x16x32_bf16 v[74:77], v[170:173], v[236:239], 0
	s_setprio 0
	s_setprio 1
	v_mfma_f32_16x16x32_bf16 v[126:129], v[164:167], v[216:219], v[126:129]
	v_mfma_f32_16x16x32_bf16 v[122:125], v[174:177], v[216:219], v[122:125]
	v_mfma_f32_16x16x32_bf16 v[110:113], v[164:167], v[224:227], v[110:113]
	v_mfma_f32_16x16x32_bf16 v[106:109], v[174:177], v[224:227], v[106:109]
	v_mfma_f32_16x16x32_bf16 v[94:97], v[164:167], v[232:235], v[94:97]
	v_mfma_f32_16x16x32_bf16 v[90:93], v[174:177], v[232:235], v[90:93]
	v_mfma_f32_16x16x32_bf16 v[78:81], v[164:167], v[240:243], v[78:81]
	v_mfma_f32_16x16x32_bf16 v[74:77], v[174:177], v[240:243], v[74:77]
	s_setprio 0
	s_setprio 1
	v_mfma_f32_16x16x32_bf16 v[118:121], v[178:181], v[212:215], 0
	v_mfma_f32_16x16x32_bf16 v[114:117], v[204:207], v[212:215], 0
	v_mfma_f32_16x16x32_bf16 v[102:105], v[178:181], v[220:223], 0
	v_mfma_f32_16x16x32_bf16 v[98:101], v[204:207], v[220:223], 0
	v_mfma_f32_16x16x32_bf16 v[86:89], v[178:181], v[228:231], 0
	v_mfma_f32_16x16x32_bf16 v[82:85], v[204:207], v[228:231], 0
	v_mfma_f32_16x16x32_bf16 v[70:73], v[178:181], v[236:239], 0
	v_mfma_f32_16x16x32_bf16 v[66:69], v[204:207], v[236:239], 0
	s_setprio 0
	s_setprio 1
	v_mfma_f32_16x16x32_bf16 v[118:121], v[182:185], v[216:219], v[118:121]
	v_mfma_f32_16x16x32_bf16 v[114:117], v[208:211], v[216:219], v[114:117]
	v_mfma_f32_16x16x32_bf16 v[102:105], v[182:185], v[224:227], v[102:105]
	v_mfma_f32_16x16x32_bf16 v[98:101], v[208:211], v[224:227], v[98:101]
	v_mfma_f32_16x16x32_bf16 v[86:89], v[182:185], v[232:235], v[86:89]
	v_mfma_f32_16x16x32_bf16 v[82:85], v[208:211], v[232:235], v[82:85]
	v_mfma_f32_16x16x32_bf16 v[70:73], v[182:185], v[240:243], v[70:73]
	v_mfma_f32_16x16x32_bf16 v[66:69], v[208:211], v[240:243], v[66:69]
	s_setprio 0
	s_barrier
	s_add_i32 s36, s47, s4
	v_lshl_add_u64 v[186:187], s[18:19], 0, v[148:149]
	s_mov_b32 m0, s36
	ds_read_b128 v[212:215], v169 offset:16384
	ds_read_b128 v[216:219], v169 offset:17408
	ds_read_b128 v[220:223], v169 offset:18432
	ds_read_b128 v[224:227], v169 offset:19456
	ds_read_b128 v[228:231], v169 offset:20480
	ds_read_b128 v[232:235], v169 offset:21504
	ds_read_b128 v[236:239], v169 offset:22528
	ds_read_b128 v[240:243], v169 offset:23552
	global_load_lds_dwordx4 v[186:187], off
	s_add_i32 m0, s36, 0x2000
	s_add_u32 s36, s18, 0x60000
	v_lshl_add_u64 v[244:245], s[18:19], 0, v[144:145]
	s_addc_u32 s37, s19, 0
	s_add_i32 s47, s76, s4
	global_load_lds_dwordx4 v[244:245], off
	v_lshl_add_u64 v[246:247], s[36:37], 0, v[148:149]
	s_mov_b32 m0, s47
	v_lshl_add_u64 v[248:249], s[44:45], 0, v[146:147]
	global_load_lds_dwordx4 v[246:247], off
	v_lshl_add_u64 v[246:247], s[36:37], 0, v[144:145]
	s_add_i32 m0, s47, 0x2000
	s_nop 0
	global_load_lds_dwordx4 v[246:247], off
	v_lshl_add_u64 v[246:247], s[44:45], 0, v[150:151]
	s_mov_b32 m0, s54
	s_nop 0
	global_load_lds_dwordx4 v[246:247], off
	s_mov_b32 m0, s57
	s_nop 0
	global_load_lds_dwordx4 v[248:249], off
	s_cmp_eq_u32 s32, 0
	s_cbranch_scc1 .Lpw10_f
	s_waitcnt vmcnt(24)
	s_branch .Lpw10_j

; #define PG8_STAGE(bufoff, gbase, voff) do { _Pragma("unroll") for (int _i = 0; _i < 2; ++_i) \
;         __builtin_amdgcn_global_load_lds((const unsigned*)((const char*)(gbase) + (voff)[_i]), (PG8_LAS unsigned*)(lds + (bufoff) + ldsw + _i * 8192), 16, 0, 0); } while (0)
; #define PG8_LDA(dst, b, h) do { _Pragma("unroll") for (int m = 0; m < 4; ++m) _Pragma("unroll") for (int k = 0; k < 2; ++k) dst[m][k] = *(const PG8_LAS bf16x8*)(lds + PG8_SA(b, h) + aoff + m * 2048 + k * 1024); } while (0)
; #define PG8_LDB(dst, b, h) do { _Pragma("unroll") for (int n = 0; n < 2; ++n) _Pragma("unroll") for (int k = 0; k < 2; ++k) dst[n][k] = *(const PG8_LAS bf16x8*)(lds + PG8_SB(b, h) + boff + n * 2048 + k * 1024); } while (0)
; #define PG8_MMA(ai, bj, At, Bt) do { __builtin_amdgcn_s_setprio(1); _Pragma("unroll") for (int m = 0; m < 4; ++m) _Pragma("unroll") for (int n = 0; n < 2; ++n) _Pragma("unroll") for (int k = 0; k < 2; ++k) \
;         acc[ai][bj][m][n] = __builtin_amdgcn_mfma_f32_16x16x32_bf16(Bt[n][k], At[m][k], acc[ai][bj][m][n], 0, 0, 0); __builtin_amdgcn_s_setprio(0); } while (0)
; #define PG8_WAIT_V(n) asm volatile("s_waitcnt vmcnt(" #n ")" ::: "memory")
; #define PG8_WAIT_L(n) asm volatile("s_waitcnt lgkmcnt(" #n ")" ::: "memory")
; #define PG8_BAR __builtin_amdgcn_s_barrier()
; #define PG8_SCHED __builtin_amdgcn_sched_barrier(0)
; template <class Epi, class Sched, bool ALIGN_EPI = false, bool SP2 = false>
; __device__ __forceinline__ void gemm_phase(PG8_LAS unsigned char* lds, const Gemm g, const Sched& S, const Epi& E) {
;     ...
;             PG8_WAIT_V(8); PG8_WAIT_L(0); PG8_BAR; PG8_MMA(1, 0, At, B0); PG8_MMA(1, 1, At, B1); PG8_BAR; PG8_SCHED;
;             PG8_LDB(B0, 1, 0); PG8_LDB(B1, 1, 1); PG8_SCHED; PG8_LDA(At, 1, 0); PG8_STAGE(PG8_SA(0, 1), a2 + hstep, voffA);
;             PG8_WAIT_V(8); PG8_WAIT_L(0); PG8_BAR; PG8_MMA(0, 0, At, B0); PG8_MMA(0, 1, At, B1); PG8_BAR; PG8_SCHED;
.Lpw10_j:
	s_waitcnt lgkmcnt(0)
	s_setprio 1
	s_barrier
	v_mfma_f32_16x16x32_bf16 v[62:65], v[160:163], v[212:215], 0
	v_mfma_f32_16x16x32_bf16 v[58:61], v[170:173], v[212:215], 0
	v_mfma_f32_16x16x32_bf16 v[46:49], v[160:163], v[220:223], 0
	v_mfma_f32_16x16x32_bf16 v[42:45], v[170:173], v[220:223], 0
	v_mfma_f32_16x16x32_bf16 v[30:33], v[160:163], v[228:231], 0
	v_mfma_f32_16x16x32_bf16 v[26:29], v[170:173], v[228:231], 0
	v_mfma_f32_16x16x32_bf16 v[14:17], v[160:163], v[236:239], 0
	v_mfma_f32_16x16x32_bf16 v[10:13], v[170:173], v[236:239], 0
	v_mfma_f32_16x16x32_bf16 v[62:65], v[164:167], v[216:219], v[62:65]
	v_mfma_f32_16x16x32_bf16 v[58:61], v[174:177], v[216:219], v[58:61]
	v_mfma_f32_16x16x32_bf16 v[46:49], v[164:167], v[224:227], v[46:49]
	v_mfma_f32_16x16x32_bf16 v[42:45], v[174:177], v[224:227], v[42:45]
	v_mfma_f32_16x16x32_bf16 v[30:33], v[164:167], v[232:235], v[30:33]
	v_mfma_f32_16x16x32_bf16 v[26:29], v[174:177], v[232:235], v[26:29]
	v_mfma_f32_16x16x32_bf16 v[14:17], v[164:167], v[240:243], v[14:17]
	v_mfma_f32_16x16x32_bf16 v[10:13], v[174:177], v[240:243], v[10:13]
	v_mfma_f32_16x16x32_bf16 v[54:57], v[178:181], v[212:215], 0
	v_mfma_f32_16x16x32_bf16 v[50:53], v[204:207], v[212:215], 0
	v_mfma_f32_16x16x32_bf16 v[38:41], v[178:181], v[220:223], 0
	v_mfma_f32_16x16x32_bf16 v[34:37], v[204:207], v[220:223], 0
	v_mfma_f32_16x16x32_bf16 v[22:25], v[178:181], v[228:231], 0
	v_mfma_f32_16x16x32_bf16 v[18:21], v[204:207], v[228:231], 0
	v_mfma_f32_16x16x32_bf16 v[6:9], v[178:181], v[236:239], 0
	v_mfma_f32_16x16x32_bf16 v[2:5], v[204:207], v[236:239], 0
	v_mfma_f32_16x16x32_bf16 v[54:57], v[182:185], v[216:219], v[54:57]
	v_mfma_f32_16x16x32_bf16 v[50:53], v[208:211], v[216:219], v[50:53]
	v_mfma_f32_16x16x32_bf16 v[38:41], v[182:185], v[224:227], v[38:41]
	v_mfma_f32_16x16x32_bf16 v[34:37], v[208:211], v[224:227], v[34:37]
	v_mfma_f32_16x16x32_bf16 v[22:25], v[182:185], v[232:235], v[22:25]
	v_mfma_f32_16x16x32_bf16 v[18:21], v[208:211], v[232:235], v[18:21]
	v_mfma_f32_16x16x32_bf16 v[6:9], v[182:185], v[240:243], v[6:9]
	v_mfma_f32_16x16x32_bf16 v[2:5], v[208:211], v[240:243], v[2:5]
	s_setprio 0
	s_barrier
	s_add_i32 s47, 0, 0x18000
	s_add_i32 s76, 0, 0x1c000
	v_add_u32_e32 v174, s47, v143
	v_add_u32_e32 v203, s76, v143
	ds_read_b128 v[160:163], v174
	ds_read_b128 v[164:167], v174 offset:1024
	ds_read_b128 v[170:173], v174 offset:2048
	ds_read_b128 v[174:177], v174 offset:3072
	ds_read_b128 v[178:181], v203
	ds_read_b128 v[182:185], v203 offset:1024
	ds_read_b128 v[204:207], v203 offset:2048
	ds_read_b128 v[208:211], v203 offset:3072
	s_add_u32 s36, s44, 0x60000
	s_addc_u32 s37, s45, 0
	s_mov_b32 m0, s58
	v_lshl_add_u64 v[250:251], s[36:37], 0, v[150:151]
	ds_read_b128 v[212:215], v169 offset:32768
	ds_read_b128 v[216:219], v169 offset:33792
	ds_read_b128 v[220:223], v169 offset:34816
	ds_read_b128 v[224:227], v169 offset:35840
	ds_read_b128 v[228:231], v169 offset:36864
	ds_read_b128 v[232:235], v169 offset:37888
	ds_read_b128 v[236:239], v169 offset:38912
	ds_read_b128 v[240:243], v169 offset:39936
	global_load_lds_dwordx4 v[250:251], off
	v_lshl_add_u64 v[250:251], s[36:37], 0, v[146:147]
	s_mov_b32 m0, s59
	s_nop 0
	global_load_lds_dwordx4 v[250:251], off
	s_waitcnt vmcnt(8)
	s_waitcnt lgkmcnt(0)
	s_setprio 1
	s_barrier
	v_mfma_f32_16x16x32_bf16 v[126:129], v[160:163], v[212:215], v[126:129]
	v_mfma_f32_16x16x32_bf16 v[122:125], v[170:173], v[212:215], v[122:125]
	v_mfma_f32_16x16x32_bf16 v[110:113], v[160:163], v[220:223], v[110:113]
	v_mfma_f32_16x16x32_bf16 v[106:109], v[170:173], v[220:223], v[106:109]
	v_mfma_f32_16x16x32_bf16 v[94:97], v[160:163], v[228:231], v[94:97]
	v_mfma_f32_16x16x32_bf16 v[90:93], v[170:173], v[228:231], v[90:93]
	v_mfma_f32_16x16x32_bf16 v[78:81], v[160:163], v[236:239], v[78:81]
	v_mfma_f32_16x16x32_bf16 v[74:77], v[170:173], v[236:239], v[74:77]
	s_setprio 0
	s_setprio 1
	v_mfma_f32_16x16x32_bf16 v[126:129], v[164:167], v[216:219], v[126:129]
	v_mfma_f32_16x16x32_bf16 v[122:125], v[174:177], v[216:219], v[122:125]
	v_mfma_f32_16x16x32_bf16 v[110:113], v[164:167], v[224:227], v[110:113]
	v_mfma_f32_16x16x32_bf16 v[106:109], v[174:177], v[224:227], v[106:109]
	v_mfma_f32_16x16x32_bf16 v[94:97], v[164:167], v[232:235], v[94:97]
	v_mfma_f32_16x16x32_bf16 v[90:93], v[174:177], v[232:235], v[90:93]
	v_mfma_f32_16x16x32_bf16 v[78:81], v[164:167], v[240:243], v[78:81]
	v_mfma_f32_16x16x32_bf16 v[74:77], v[174:177], v[240:243], v[74:77]
	s_setprio 0
	s_setprio 1
	v_mfma_f32_16x16x32_bf16 v[118:121], v[178:181], v[212:215], v[118:121]
	v_mfma_f32_16x16x32_bf16 v[114:117], v[204:207], v[212:215], v[114:117]
	v_mfma_f32_16x16x32_bf16 v[102:105], v[178:181], v[220:223], v[102:105]
	v_mfma_f32_16x16x32_bf16 v[98:101], v[204:207], v[220:223], v[98:101]
	v_mfma_f32_16x16x32_bf16 v[86:89], v[178:181], v[228:231], v[86:89]
	v_mfma_f32_16x16x32_bf16 v[82:85], v[204:207], v[228:231], v[82:85]
	v_mfma_f32_16x16x32_bf16 v[70:73], v[178:181], v[236:239], v[70:73]
	v_mfma_f32_16x16x32_bf16 v[66:69], v[204:207], v[236:239], v[66:69]
	s_setprio 0
	s_setprio 1
	v_mfma_f32_16x16x32_bf16 v[118:121], v[182:185], v[216:219], v[118:121]
	v_mfma_f32_16x16x32_bf16 v[114:117], v[208:211], v[216:219], v[114:117]
	v_mfma_f32_16x16x32_bf16 v[102:105], v[182:185], v[224:227], v[102:105]
	v_mfma_f32_16x16x32_bf16 v[98:101], v[208:211], v[224:227], v[98:101]
	v_mfma_f32_16x16x32_bf16 v[86:89], v[182:185], v[232:235], v[86:89]
	v_mfma_f32_16x16x32_bf16 v[82:85], v[208:211], v[232:235], v[82:85]
	v_mfma_f32_16x16x32_bf16 v[70:73], v[182:185], v[240:243], v[70:73]
	v_mfma_f32_16x16x32_bf16 v[66:69], v[208:211], v[240:243], v[66:69]
	s_setprio 0
	s_barrier
; #define PG8_STAGE(bufoff, gbase, voff) do { _Pragma("unroll") for (int _i = 0; _i < 2; ++_i) \
;         __builtin_amdgcn_global_load_lds((const unsigned*)((const char*)(gbase) + (voff)[_i]), (PG8_LAS unsigned*)(lds + (bufoff) + ldsw + _i * 8192), 16, 0, 0); } while (0)
; #define PG8_LDA(dst, b, h) do { _Pragma("unroll") for (int m = 0; m < 4; ++m) _Pragma("unroll") for (int k = 0; k < 2; ++k) dst[m][k] = *(const PG8_LAS bf16x8*)(lds + PG8_SA(b, h) + aoff + m * 2048 + k * 1024); } while (0)
; #define PG8_LDB(dst, b, h) do { _Pragma("unroll") for (int n = 0; n < 2; ++n) _Pragma("unroll") for (int k = 0; k < 2; ++k) dst[n][k] = *(const PG8_LAS bf16x8*)(lds + PG8_SB(b, h) + boff + n * 2048 + k * 1024); } while (0)
; #define PG8_MMA(ai, bj, At, Bt) do { __builtin_amdgcn_s_setprio(1); _Pragma("unroll") for (int m = 0; m < 4; ++m) _Pragma("unroll") for (int n = 0; n < 2; ++n) _Pragma("unroll") for (int k = 0; k < 2; ++k) \
;         acc[ai][bj][m][n] = __builtin_amdgcn_mfma_f32_16x16x32_bf16(Bt[n][k], At[m][k], acc[ai][bj][m][n], 0, 0, 0); __builtin_amdgcn_s_setprio(0); } while (0)
; #define PG8_WAIT_V(n) asm volatile("s_waitcnt vmcnt(" #n ")" ::: "memory")
; #define PG8_BAR __builtin_amdgcn_s_barrier()
; template <class Epi, class Sched, bool ALIGN_EPI = false, bool SP2 = false>
; __device__ __forceinline__ void gemm_phase(PG8_LAS unsigned char* lds, const Gemm g, const Sched& S, const Epi& E) {
;     ...
;         for (int t = 0; t < nt; t += 2) {
;             const bool last = (t == nt - 2);
;             const char* a1 = cA + (size_t)(t + 1) * kstep;
;             const char* a2 = last ? nA : cA + (size_t)(t + 2) * kstep; const char* b2 = last ? nB : cB + (size_t)(t + 2) * kstep;
;             const char* a3 = a2 + kstep; const char* b3 = b2 + kstep;
;             if (last && has_next) S.a_ready(nxt);
;             if constexpr (SP2) {
;             PG8_LDB(B0, 0, 0); PG8_LDB(B1, 0, 1); PG8_SCHED; PG8_LDA(At, 0, 0); PG8_STAGE(PG8_SA(1, 1), a1 + hstep, voffA);
;             PG8_WAIT_V(8); PG8_WAIT_L(0); PG8_BAR; PG8_MMA(0, 0, At, B0); PG8_MMA(0, 1, At, B1); PG8_BAR; PG8_SCHED;
;     ...
;             PG8_LDA(At, 1, 1); PG8_STAGE(PG8_SB(1, 0), b3, voffB); PG8_STAGE(PG8_SB(1, 1), b3 + hstep, voffB); PG8_STAGE(PG8_SA(1, 0), a3, voffA);
;             PG8_WAIT_V(8); PG8_WAIT_L(0); PG8_BAR; PG8_MMA(1, 0, At, B0); PG8_MMA(1, 1, At, B1); PG8_BAR; PG8_SCHED;
	s_add_i32 s36, s47, s4
	v_lshl_add_u64 v[186:187], v[186:187], 0, s[68:69]
	s_mov_b32 m0, s36
	ds_read_b128 v[212:215], v169 offset:49152
	ds_read_b128 v[216:219], v169 offset:50176
	ds_read_b128 v[220:223], v169 offset:51200
	ds_read_b128 v[224:227], v169 offset:52224
	ds_read_b128 v[228:231], v169 offset:53248
	ds_read_b128 v[232:235], v169 offset:54272
	ds_read_b128 v[236:239], v169 offset:55296
	ds_read_b128 v[240:243], v169 offset:56320
	global_load_lds_dwordx4 v[186:187], off
	s_add_i32 m0, s36, 0x2000
	s_add_u32 s18, s18, 0x60080
	v_lshl_add_u64 v[186:187], v[244:245], 0, s[68:69]
	s_addc_u32 s19, s19, 0
	s_add_i32 s36, s76, s4
	global_load_lds_dwordx4 v[186:187], off
	v_lshl_add_u64 v[186:187], s[18:19], 0, v[148:149]
	s_mov_b32 m0, s36
	s_nop 0
	global_load_lds_dwordx4 v[186:187], off
	v_lshl_add_u64 v[186:187], s[18:19], 0, v[144:145]
	s_add_i32 m0, s36, 0x2000
	s_nop 0
	global_load_lds_dwordx4 v[186:187], off
	v_lshl_add_u64 v[186:187], v[246:247], 0, s[68:69]
	s_mov_b32 m0, s62
	s_nop 0
	global_load_lds_dwordx4 v[186:187], off
	v_lshl_add_u64 v[186:187], v[248:249], 0, s[68:69]
	s_mov_b32 m0, s63
	s_nop 0
	global_load_lds_dwordx4 v[186:187], off
	s_nop 0
	s_waitcnt vmcnt(8)
	s_waitcnt lgkmcnt(0)
	s_setprio 1
	s_barrier
	v_mfma_f32_16x16x32_bf16 v[62:65], v[160:163], v[212:215], v[62:65]
	v_mfma_f32_16x16x32_bf16 v[58:61], v[170:173], v[212:215], v[58:61]
	v_mfma_f32_16x16x32_bf16 v[46:49], v[160:163], v[220:223], v[46:49]
	v_mfma_f32_16x16x32_bf16 v[42:45], v[170:173], v[220:223], v[42:45]
	v_mfma_f32_16x16x32_bf16 v[30:33], v[160:163], v[228:231], v[30:33]
	v_mfma_f32_16x16x32_bf16 v[26:29], v[170:173], v[228:231], v[26:29]
	v_mfma_f32_16x16x32_bf16 v[14:17], v[160:163], v[236:239], v[14:17]
	v_mfma_f32_16x16x32_bf16 v[10:13], v[170:173], v[236:239], v[10:13]
	v_mfma_f32_16x16x32_bf16 v[62:65], v[164:167], v[216:219], v[62:65]
	v_mfma_f32_16x16x32_bf16 v[58:61], v[174:177], v[216:219], v[58:61]
	v_mfma_f32_16x16x32_bf16 v[46:49], v[164:167], v[224:227], v[46:49]
	v_mfma_f32_16x16x32_bf16 v[42:45], v[174:177], v[224:227], v[42:45]
	v_mfma_f32_16x16x32_bf16 v[30:33], v[164:167], v[232:235], v[30:33]
	v_mfma_f32_16x16x32_bf16 v[26:29], v[174:177], v[232:235], v[26:29]
	v_mfma_f32_16x16x32_bf16 v[14:17], v[164:167], v[240:243], v[14:17]
	v_mfma_f32_16x16x32_bf16 v[10:13], v[174:177], v[240:243], v[10:13]
	v_mfma_f32_16x16x32_bf16 v[54:57], v[178:181], v[212:215], v[54:57]
	v_mfma_f32_16x16x32_bf16 v[50:53], v[204:207], v[212:215], v[50:53]
	v_mfma_f32_16x16x32_bf16 v[38:41], v[178:181], v[220:223], v[38:41]
	v_mfma_f32_16x16x32_bf16 v[34:37], v[204:207], v[220:223], v[34:37]
	v_mfma_f32_16x16x32_bf16 v[22:25], v[178:181], v[228:231], v[22:25]
	v_mfma_f32_16x16x32_bf16 v[18:21], v[204:207], v[228:231], v[18:21]
	v_mfma_f32_16x16x32_bf16 v[6:9], v[178:181], v[236:239], v[6:9]
	v_mfma_f32_16x16x32_bf16 v[2:5], v[204:207], v[236:239], v[2:5]
	v_mfma_f32_16x16x32_bf16 v[54:57], v[182:185], v[216:219], v[54:57]
	v_mfma_f32_16x16x32_bf16 v[50:53], v[208:211], v[216:219], v[50:53]
	v_mfma_f32_16x16x32_bf16 v[38:41], v[182:185], v[224:227], v[38:41]
	v_mfma_f32_16x16x32_bf16 v[34:37], v[208:211], v[224:227], v[34:37]
	v_mfma_f32_16x16x32_bf16 v[22:25], v[182:185], v[232:235], v[22:25]
	v_mfma_f32_16x16x32_bf16 v[18:21], v[208:211], v[232:235], v[18:21]
	v_mfma_f32_16x16x32_bf16 v[6:9], v[182:185], v[240:243], v[6:9]
	v_mfma_f32_16x16x32_bf16 v[2:5], v[208:211], v[240:243], v[2:5]
	s_setprio 0
	s_barrier
	s_add_i32 s46, s46, 2
	s_add_u32 s60, s60, 0x100
	s_addc_u32 s73, s73, 0
	s_cmp_gt_u32 s46, 21
	s_mov_b64 s[36:37], s[42:43]
.LBB0_160:
	s_add_u32 s42, s36, 0x100
	s_addc_u32 s43, s37, 0
	s_add_i32 s47, 0, 0x10000
	s_cmp_eq_u32 s46, 20
	s_cselect_b32 s45, s1, s43
	s_cselect_b32 s44, s0, s42
	s_cselect_b32 s19, s7, s73
	s_cselect_b32 s18, s6, s60
	s_add_i32 s76, 0, 0x14000
	v_add_u32_e32 v174, s47, v143
	v_add_u32_e32 v186, s76, v143
	ds_read_b128 v[160:163], v174
	ds_read_b128 v[164:167], v174 offset:1024
	ds_read_b128 v[170:173], v174 offset:2048
	ds_read_b128 v[174:177], v174 offset:3072
	ds_read_b128 v[178:181], v186
	ds_read_b128 v[182:185], v186 offset:1024
	ds_read_b128 v[204:207], v186 offset:2048
	ds_read_b128 v[208:211], v186 offset:3072
	v_lshl_add_u64 v[186:187], s[36:37], 0, v[156:157]
	s_add_i32 m0, s54, 0xc000
	ds_read_b128 v[212:215], v169
	ds_read_b128 v[216:219], v169 offset:1024
	ds_read_b128 v[220:223], v169 offset:2048
	ds_read_b128 v[224:227], v169 offset:3072
	ds_read_b128 v[228:231], v169 offset:4096
	ds_read_b128 v[232:235], v169 offset:5120
	ds_read_b128 v[236:239], v169 offset:6144
	ds_read_b128 v[240:243], v169 offset:7168
	global_load_lds_dwordx4 v[186:187], off
	v_lshl_add_u64 v[186:187], s[36:37], 0, v[158:159]
	s_add_i32 m0, s54, 0xe000
	s_nop 0
	global_load_lds_dwordx4 v[186:187], off
	s_nop 0
	s_waitcnt vmcnt(8)
	s_waitcnt lgkmcnt(0)
	s_setprio 1
	s_barrier
; #define PG8_STAGE(bufoff, gbase, voff) do { _Pragma("unroll") for (int _i = 0; _i < 2; ++_i) \
;         __builtin_amdgcn_global_load_lds((const unsigned*)((const char*)(gbase) + (voff)[_i]), (PG8_LAS unsigned*)(lds + (bufoff) + ldsw + _i * 8192), 16, 0, 0); } while (0)
; #define PG8_LDA(dst, b, h) do { _Pragma("unroll") for (int m = 0; m < 4; ++m) _Pragma("unroll") for (int k = 0; k < 2; ++k) dst[m][k] = *(const PG8_LAS bf16x8*)(lds + PG8_SA(b, h) + aoff + m * 2048 + k * 1024); } while (0)
; #define PG8_MMA(ai, bj, At, Bt) do { __builtin_amdgcn_s_setprio(1); _Pragma("unroll") for (int m = 0; m < 4; ++m) _Pragma("unroll") for (int n = 0; n < 2; ++n) _Pragma("unroll") for (int k = 0; k < 2; ++k) \
;         acc[ai][bj][m][n] = __builtin_amdgcn_mfma_f32_16x16x32_bf16(Bt[n][k], At[m][k], acc[ai][bj][m][n], 0, 0, 0); __builtin_amdgcn_s_setprio(0); } while (0)
; #define PG8_WAIT_V(n) asm volatile("s_waitcnt vmcnt(" #n ")" ::: "memory")
; #define PG8_WAIT_L(n) asm volatile("s_waitcnt lgkmcnt(" #n ")" ::: "memory")
; #define PG8_BAR __builtin_amdgcn_s_barrier()
; #define PG8_SCHED __builtin_amdgcn_sched_barrier(0)
; template <class Epi, class Sched, bool ALIGN_EPI = false, bool SP2 = false>
; __device__ __forceinline__ void gemm_phase(PG8_LAS unsigned char* lds, const Gemm g, const Sched& S, const Epi& E) {
;     ...
;             PG8_WAIT_V(8); PG8_WAIT_L(0); PG8_BAR; PG8_MMA(0, 0, At, B0); PG8_MMA(0, 1, At, B1); PG8_BAR; PG8_SCHED;
;             PG8_LDA(At, 0, 1); PG8_STAGE(PG8_SB(0, 0), b2, voffB); PG8_STAGE(PG8_SB(0, 1), b2 + hstep, voffB); PG8_STAGE(PG8_SA(0, 0), a2, voffA);
;             PG8_WAIT_V(8); PG8_WAIT_L(0); PG8_BAR; PG8_MMA(1, 0, At, B0); PG8_MMA(1, 1, At, B1); PG8_BAR; PG8_SCHED;
	v_mfma_f32_16x16x32_bf16 v[126:129], v[160:163], v[212:215], v[126:129]
	v_mfma_f32_16x16x32_bf16 v[122:125], v[170:173], v[212:215], v[122:125]
	v_mfma_f32_16x16x32_bf16 v[110:113], v[160:163], v[220:223], v[110:113]
	v_mfma_f32_16x16x32_bf16 v[106:109], v[170:173], v[220:223], v[106:109]
	v_mfma_f32_16x16x32_bf16 v[94:97], v[160:163], v[228:231], v[94:97]
	v_mfma_f32_16x16x32_bf16 v[90:93], v[170:173], v[228:231], v[90:93]
	v_mfma_f32_16x16x32_bf16 v[78:81], v[160:163], v[236:239], v[78:81]
	v_mfma_f32_16x16x32_bf16 v[74:77], v[170:173], v[236:239], v[74:77]
	s_setprio 0
	s_setprio 1
	v_mfma_f32_16x16x32_bf16 v[126:129], v[164:167], v[216:219], v[126:129]
	v_mfma_f32_16x16x32_bf16 v[122:125], v[174:177], v[216:219], v[122:125]
	v_mfma_f32_16x16x32_bf16 v[110:113], v[164:167], v[224:227], v[110:113]
	v_mfma_f32_16x16x32_bf16 v[106:109], v[174:177], v[224:227], v[106:109]
	v_mfma_f32_16x16x32_bf16 v[94:97], v[164:167], v[232:235], v[94:97]
	v_mfma_f32_16x16x32_bf16 v[90:93], v[174:177], v[232:235], v[90:93]
	v_mfma_f32_16x16x32_bf16 v[78:81], v[164:167], v[240:243], v[78:81]
	v_mfma_f32_16x16x32_bf16 v[74:77], v[174:177], v[240:243], v[74:77]
	s_setprio 0
	s_setprio 1
	v_mfma_f32_16x16x32_bf16 v[118:121], v[178:181], v[212:215], v[118:121]
	v_mfma_f32_16x16x32_bf16 v[114:117], v[204:207], v[212:215], v[114:117]
	v_mfma_f32_16x16x32_bf16 v[102:105], v[178:181], v[220:223], v[102:105]
	v_mfma_f32_16x16x32_bf16 v[98:101], v[204:207], v[220:223], v[98:101]
	v_mfma_f32_16x16x32_bf16 v[86:89], v[178:181], v[228:231], v[86:89]
	v_mfma_f32_16x16x32_bf16 v[82:85], v[204:207], v[228:231], v[82:85]
	v_mfma_f32_16x16x32_bf16 v[70:73], v[178:181], v[236:239], v[70:73]
	v_mfma_f32_16x16x32_bf16 v[66:69], v[204:207], v[236:239], v[66:69]
	s_setprio 0
	s_setprio 1
	v_mfma_f32_16x16x32_bf16 v[118:121], v[182:185], v[216:219], v[118:121]
	v_mfma_f32_16x16x32_bf16 v[114:117], v[208:211], v[216:219], v[114:117]
	v_mfma_f32_16x16x32_bf16 v[102:105], v[182:185], v[224:227], v[102:105]
	v_mfma_f32_16x16x32_bf16 v[98:101], v[208:211], v[224:227], v[98:101]
	v_mfma_f32_16x16x32_bf16 v[86:89], v[182:185], v[232:235], v[86:89]
	v_mfma_f32_16x16x32_bf16 v[82:85], v[208:211], v[232:235], v[82:85]
	v_mfma_f32_16x16x32_bf16 v[70:73], v[182:185], v[240:243], v[70:73]
	v_mfma_f32_16x16x32_bf16 v[66:69], v[208:211], v[240:243], v[66:69]
	s_setprio 0
	s_barrier
	s_add_i32 s36, s47, s4
	v_lshl_add_u64 v[186:187], s[18:19], 0, v[148:149]
	s_mov_b32 m0, s36
	ds_read_b128 v[212:215], v169 offset:16384
	ds_read_b128 v[216:219], v169 offset:17408
	ds_read_b128 v[220:223], v169 offset:18432
	ds_read_b128 v[224:227], v169 offset:19456
	ds_read_b128 v[228:231], v169 offset:20480
	ds_read_b128 v[232:235], v169 offset:21504
	ds_read_b128 v[236:239], v169 offset:22528
	ds_read_b128 v[240:243], v169 offset:23552
	global_load_lds_dwordx4 v[186:187], off
	s_add_i32 m0, s36, 0x2000
	s_add_u32 s36, s18, 0x60000
	v_lshl_add_u64 v[244:245], s[18:19], 0, v[144:145]
	s_addc_u32 s37, s19, 0
	s_add_i32 s47, s76, s4
	global_load_lds_dwordx4 v[244:245], off
	v_lshl_add_u64 v[246:247], s[36:37], 0, v[148:149]
	s_mov_b32 m0, s47
	v_lshl_add_u64 v[248:249], s[44:45], 0, v[146:147]
	global_load_lds_dwordx4 v[246:247], off
	v_lshl_add_u64 v[246:247], s[36:37], 0, v[144:145]
	s_add_i32 m0, s47, 0x2000
	s_nop 0
	global_load_lds_dwordx4 v[246:247], off
	v_lshl_add_u64 v[246:247], s[44:45], 0, v[150:151]
	s_mov_b32 m0, s54
	s_nop 0
	global_load_lds_dwordx4 v[246:247], off
	s_mov_b32 m0, s57
	s_nop 0
	global_load_lds_dwordx4 v[248:249], off
	s_waitcnt vmcnt(8)
	s_waitcnt lgkmcnt(0)
	s_setprio 1
	s_barrier
	v_mfma_f32_16x16x32_bf16 v[62:65], v[160:163], v[212:215], v[62:65]
	v_mfma_f32_16x16x32_bf16 v[58:61], v[170:173], v[212:215], v[58:61]
	v_mfma_f32_16x16x32_bf16 v[46:49], v[160:163], v[220:223], v[46:49]
	v_mfma_f32_16x16x32_bf16 v[42:45], v[170:173], v[220:223], v[42:45]
	v_mfma_f32_16x16x32_bf16 v[30:33], v[160:163], v[228:231], v[30:33]
	v_mfma_f32_16x16x32_bf16 v[26:29], v[170:173], v[228:231], v[26:29]
	v_mfma_f32_16x16x32_bf16 v[14:17], v[160:163], v[236:239], v[14:17]
	v_mfma_f32_16x16x32_bf16 v[10:13], v[170:173], v[236:239], v[10:13]
	v_mfma_f32_16x16x32_bf16 v[62:65], v[164:167], v[216:219], v[62:65]
	v_mfma_f32_16x16x32_bf16 v[58:61], v[174:177], v[216:219], v[58:61]
	v_mfma_f32_16x16x32_bf16 v[46:49], v[164:167], v[224:227], v[46:49]
	v_mfma_f32_16x16x32_bf16 v[42:45], v[174:177], v[224:227], v[42:45]
	v_mfma_f32_16x16x32_bf16 v[30:33], v[164:167], v[232:235], v[30:33]
	v_mfma_f32_16x16x32_bf16 v[26:29], v[174:177], v[232:235], v[26:29]
	v_mfma_f32_16x16x32_bf16 v[14:17], v[164:167], v[240:243], v[14:17]
	v_mfma_f32_16x16x32_bf16 v[10:13], v[174:177], v[240:243], v[10:13]
	v_mfma_f32_16x16x32_bf16 v[54:57], v[178:181], v[212:215], v[54:57]
	v_mfma_f32_16x16x32_bf16 v[50:53], v[204:207], v[212:215], v[50:53]
	v_mfma_f32_16x16x32_bf16 v[38:41], v[178:181], v[220:223], v[38:41]
	v_mfma_f32_16x16x32_bf16 v[34:37], v[204:207], v[220:223], v[34:37]
	v_mfma_f32_16x16x32_bf16 v[22:25], v[178:181], v[228:231], v[22:25]
	v_mfma_f32_16x16x32_bf16 v[18:21], v[204:207], v[228:231], v[18:21]
	v_mfma_f32_16x16x32_bf16 v[6:9], v[178:181], v[236:239], v[6:9]
	v_mfma_f32_16x16x32_bf16 v[2:5], v[204:207], v[236:239], v[2:5]
	v_mfma_f32_16x16x32_bf16 v[54:57], v[182:185], v[216:219], v[54:57]
	v_mfma_f32_16x16x32_bf16 v[50:53], v[208:211], v[216:219], v[50:53]
	v_mfma_f32_16x16x32_bf16 v[38:41], v[182:185], v[224:227], v[38:41]
	v_mfma_f32_16x16x32_bf16 v[34:37], v[208:211], v[224:227], v[34:37]
	v_mfma_f32_16x16x32_bf16 v[22:25], v[182:185], v[232:235], v[22:25]
	v_mfma_f32_16x16x32_bf16 v[18:21], v[208:211], v[232:235], v[18:21]
	v_mfma_f32_16x16x32_bf16 v[6:9], v[182:185], v[240:243], v[6:9]
	v_mfma_f32_16x16x32_bf16 v[2:5], v[208:211], v[240:243], v[2:5]
	s_setprio 0
	s_barrier
; #define PG8_STAGE(bufoff, gbase, voff) do { _Pragma("unroll") for (int _i = 0; _i < 2; ++_i) \
;         __builtin_amdgcn_global_load_lds((const unsigned*)((const char*)(gbase) + (voff)[_i]), (PG8_LAS unsigned*)(lds + (bufoff) + ldsw + _i * 8192), 16, 0, 0); } while (0)
; #define PG8_LDA(dst, b, h) do { _Pragma("unroll") for (int m = 0; m < 4; ++m) _Pragma("unroll") for (int k = 0; k < 2; ++k) dst[m][k] = *(const PG8_LAS bf16x8*)(lds + PG8_SA(b, h) + aoff + m * 2048 + k * 1024); } while (0)
; #define PG8_LDB(dst, b, h) do { _Pragma("unroll") for (int n = 0; n < 2; ++n) _Pragma("unroll") for (int k = 0; k < 2; ++k) dst[n][k] = *(const PG8_LAS bf16x8*)(lds + PG8_SB(b, h) + boff + n * 2048 + k * 1024); } while (0)
; #define PG8_MMA(ai, bj, At, Bt) do { __builtin_amdgcn_s_setprio(1); _Pragma("unroll") for (int m = 0; m < 4; ++m) _Pragma("unroll") for (int n = 0; n < 2; ++n) _Pragma("unroll") for (int k = 0; k < 2; ++k) \
;         acc[ai][bj][m][n] = __builtin_amdgcn_mfma_f32_16x16x32_bf16(Bt[n][k], At[m][k], acc[ai][bj][m][n], 0, 0, 0); __builtin_amdgcn_s_setprio(0); } while (0)
; #define PG8_WAIT_V(n) asm volatile("s_waitcnt vmcnt(" #n ")" ::: "memory")
; #define PG8_WAIT_L(n) asm volatile("s_waitcnt lgkmcnt(" #n ")" ::: "memory")
; #define PG8_BAR __builtin_amdgcn_s_barrier()
; #define PG8_SCHED __builtin_amdgcn_sched_barrier(0)
; template <class Epi, class Sched, bool ALIGN_EPI = false, bool SP2 = false>
; __device__ __forceinline__ void gemm_phase(PG8_LAS unsigned char* lds, const Gemm g, const Sched& S, const Epi& E) {
;     ...
;             PG8_LDB(B0, 1, 0); PG8_LDB(B1, 1, 1); PG8_SCHED; PG8_LDA(At, 1, 0); PG8_STAGE(PG8_SA(0, 1), a2 + hstep, voffA);
;             PG8_WAIT_V(8); PG8_WAIT_L(0); PG8_BAR; PG8_MMA(0, 0, At, B0); PG8_MMA(0, 1, At, B1); PG8_BAR; PG8_SCHED;
	s_add_i32 s47, 0, 0x18000
	s_add_i32 s76, 0, 0x1c000
	v_add_u32_e32 v174, s47, v143
	v_add_u32_e32 v203, s76, v143
	ds_read_b128 v[160:163], v174
	ds_read_b128 v[164:167], v174 offset:1024
	ds_read_b128 v[170:173], v174 offset:2048
	ds_read_b128 v[174:177], v174 offset:3072
	ds_read_b128 v[178:181], v203
	ds_read_b128 v[182:185], v203 offset:1024
	ds_read_b128 v[204:207], v203 offset:2048
	ds_read_b128 v[208:211], v203 offset:3072
	s_add_u32 s36, s44, 0x60000
	s_addc_u32 s37, s45, 0
	s_mov_b32 m0, s58
	v_lshl_add_u64 v[250:251], s[36:37], 0, v[150:151]
	ds_read_b128 v[212:215], v169 offset:32768
	ds_read_b128 v[216:219], v169 offset:33792
	ds_read_b128 v[220:223], v169 offset:34816
	ds_read_b128 v[224:227], v169 offset:35840
	ds_read_b128 v[228:231], v169 offset:36864
	ds_read_b128 v[232:235], v169 offset:37888
	ds_read_b128 v[236:239], v169 offset:38912
	ds_read_b128 v[240:243], v169 offset:39936
	global_load_lds_dwordx4 v[250:251], off
	v_lshl_add_u64 v[250:251], s[36:37], 0, v[146:147]
	s_mov_b32 m0, s59
	s_nop 0
	global_load_lds_dwordx4 v[250:251], off
	s_waitcnt vmcnt(8)
	s_waitcnt lgkmcnt(0)
	s_setprio 1
	s_barrier
	v_mfma_f32_16x16x32_bf16 v[126:129], v[160:163], v[212:215], v[126:129]
	v_mfma_f32_16x16x32_bf16 v[122:125], v[170:173], v[212:215], v[122:125]
	v_mfma_f32_16x16x32_bf16 v[110:113], v[160:163], v[220:223], v[110:113]
	v_mfma_f32_16x16x32_bf16 v[106:109], v[170:173], v[220:223], v[106:109]
	v_mfma_f32_16x16x32_bf16 v[94:97], v[160:163], v[228:231], v[94:97]
	v_mfma_f32_16x16x32_bf16 v[90:93], v[170:173], v[228:231], v[90:93]
	v_mfma_f32_16x16x32_bf16 v[78:81], v[160:163], v[236:239], v[78:81]
	v_mfma_f32_16x16x32_bf16 v[74:77], v[170:173], v[236:239], v[74:77]
	s_setprio 0
	s_setprio 1
	v_mfma_f32_16x16x32_bf16 v[126:129], v[164:167], v[216:219], v[126:129]
	v_mfma_f32_16x16x32_bf16 v[122:125], v[174:177], v[216:219], v[122:125]
	v_mfma_f32_16x16x32_bf16 v[110:113], v[164:167], v[224:227], v[110:113]
	v_mfma_f32_16x16x32_bf16 v[106:109], v[174:177], v[224:227], v[106:109]
	v_mfma_f32_16x16x32_bf16 v[94:97], v[164:167], v[232:235], v[94:97]
	v_mfma_f32_16x16x32_bf16 v[90:93], v[174:177], v[232:235], v[90:93]
	v_mfma_f32_16x16x32_bf16 v[78:81], v[164:167], v[240:243], v[78:81]
	v_mfma_f32_16x16x32_bf16 v[74:77], v[174:177], v[240:243], v[74:77]
	s_setprio 0
	s_setprio 1
	v_mfma_f32_16x16x32_bf16 v[118:121], v[178:181], v[212:215], v[118:121]
	v_mfma_f32_16x16x32_bf16 v[114:117], v[204:207], v[212:215], v[114:117]
	v_mfma_f32_16x16x32_bf16 v[102:105], v[178:181], v[220:223], v[102:105]
	v_mfma_f32_16x16x32_bf16 v[98:101], v[204:207], v[220:223], v[98:101]
	v_mfma_f32_16x16x32_bf16 v[86:89], v[178:181], v[228:231], v[86:89]
	v_mfma_f32_16x16x32_bf16 v[82:85], v[204:207], v[228:231], v[82:85]
	v_mfma_f32_16x16x32_bf16 v[70:73], v[178:181], v[236:239], v[70:73]
	v_mfma_f32_16x16x32_bf16 v[66:69], v[204:207], v[236:239], v[66:69]
	s_setprio 0
	s_setprio 1
	v_mfma_f32_16x16x32_bf16 v[118:121], v[182:185], v[216:219], v[118:121]
	v_mfma_f32_16x16x32_bf16 v[114:117], v[208:211], v[216:219], v[114:117]
	v_mfma_f32_16x16x32_bf16 v[102:105], v[182:185], v[224:227], v[102:105]
	v_mfma_f32_16x16x32_bf16 v[98:101], v[208:211], v[224:227], v[98:101]
	v_mfma_f32_16x16x32_bf16 v[86:89], v[182:185], v[232:235], v[86:89]
	v_mfma_f32_16x16x32_bf16 v[82:85], v[208:211], v[232:235], v[82:85]
	v_mfma_f32_16x16x32_bf16 v[70:73], v[182:185], v[240:243], v[70:73]
	v_mfma_f32_16x16x32_bf16 v[66:69], v[208:211], v[240:243], v[66:69]
	s_setprio 0
	s_barrier
; #define PG8_STAGE(bufoff, gbase, voff) do { _Pragma("unroll") for (int _i = 0; _i < 2; ++_i) \
;         __builtin_amdgcn_global_load_lds((const unsigned*)((const char*)(gbase) + (voff)[_i]), (PG8_LAS unsigned*)(lds + (bufoff) + ldsw + _i * 8192), 16, 0, 0); } while (0)
; #define PG8_LDA(dst, b, h) do { _Pragma("unroll") for (int m = 0; m < 4; ++m) _Pragma("unroll") for (int k = 0; k < 2; ++k) dst[m][k] = *(const PG8_LAS bf16x8*)(lds + PG8_SA(b, h) + aoff + m * 2048 + k * 1024); } while (0)
; #define PG8_MMA(ai, bj, At, Bt) do { __builtin_amdgcn_s_setprio(1); _Pragma("unroll") for (int m = 0; m < 4; ++m) _Pragma("unroll") for (int n = 0; n < 2; ++n) _Pragma("unroll") for (int k = 0; k < 2; ++k) \
;         acc[ai][bj][m][n] = __builtin_amdgcn_mfma_f32_16x16x32_bf16(Bt[n][k], At[m][k], acc[ai][bj][m][n], 0, 0, 0); __builtin_amdgcn_s_setprio(0); } while (0)
; #define PG8_WAIT_V(n) asm volatile("s_waitcnt vmcnt(" #n ")" ::: "memory")
; #define PG8_WAIT_L(n) asm volatile("s_waitcnt lgkmcnt(" #n ")" ::: "memory")
; #define PG8_BAR __builtin_amdgcn_s_barrier()
; #define PG8_SCHED __builtin_amdgcn_sched_barrier(0)
; template <class Epi, class Sched, bool ALIGN_EPI = false, bool SP2 = false>
; __device__ __forceinline__ void gemm_phase(PG8_LAS unsigned char* lds, const Gemm g, const Sched& S, const Epi& E) {
;     ...
;             PG8_LDA(At, 1, 1); PG8_STAGE(PG8_SB(1, 0), b3, voffB); PG8_STAGE(PG8_SB(1, 1), b3 + hstep, voffB); PG8_STAGE(PG8_SA(1, 0), a3, voffA);
;             PG8_WAIT_V(8); PG8_WAIT_L(0); PG8_BAR; PG8_MMA(1, 0, At, B0); PG8_MMA(1, 1, At, B1); PG8_BAR; PG8_SCHED;
;     ...
;         if constexpr (ALIGN_EPI) { if (wr == 0) PG8_BAR; }
	s_add_i32 s36, s47, s4
	v_lshl_add_u64 v[186:187], v[186:187], 0, s[68:69]
	s_mov_b32 m0, s36
	ds_read_b128 v[212:215], v169 offset:49152
	ds_read_b128 v[216:219], v169 offset:50176
	ds_read_b128 v[220:223], v169 offset:51200
	ds_read_b128 v[224:227], v169 offset:52224
	ds_read_b128 v[228:231], v169 offset:53248
	ds_read_b128 v[232:235], v169 offset:54272
	ds_read_b128 v[236:239], v169 offset:55296
	ds_read_b128 v[240:243], v169 offset:56320
	global_load_lds_dwordx4 v[186:187], off
	s_add_i32 m0, s36, 0x2000
	s_add_u32 s18, s18, 0x60080
	v_lshl_add_u64 v[186:187], v[244:245], 0, s[68:69]
	s_addc_u32 s19, s19, 0
	s_add_i32 s36, s76, s4
	global_load_lds_dwordx4 v[186:187], off
	v_lshl_add_u64 v[186:187], s[18:19], 0, v[148:149]
	s_mov_b32 m0, s36
	s_nop 0
	global_load_lds_dwordx4 v[186:187], off
	v_lshl_add_u64 v[186:187], s[18:19], 0, v[144:145]
	s_add_i32 m0, s36, 0x2000
	s_nop 0
	global_load_lds_dwordx4 v[186:187], off
	v_lshl_add_u64 v[186:187], v[246:247], 0, s[68:69]
	s_mov_b32 m0, s62
	s_nop 0
	global_load_lds_dwordx4 v[186:187], off
	v_lshl_add_u64 v[186:187], v[248:249], 0, s[68:69]
	s_mov_b32 m0, s63
	s_nop 0
	global_load_lds_dwordx4 v[186:187], off
	s_nop 0
	s_waitcnt vmcnt(8)
	s_waitcnt lgkmcnt(0)
	s_setprio 1
	s_barrier
	v_mfma_f32_16x16x32_bf16 v[62:65], v[160:163], v[212:215], v[62:65]
	v_mfma_f32_16x16x32_bf16 v[58:61], v[170:173], v[212:215], v[58:61]
	v_mfma_f32_16x16x32_bf16 v[46:49], v[160:163], v[220:223], v[46:49]
	v_mfma_f32_16x16x32_bf16 v[42:45], v[170:173], v[220:223], v[42:45]
	v_mfma_f32_16x16x32_bf16 v[30:33], v[160:163], v[228:231], v[30:33]
	v_mfma_f32_16x16x32_bf16 v[26:29], v[170:173], v[228:231], v[26:29]
	v_mfma_f32_16x16x32_bf16 v[14:17], v[160:163], v[236:239], v[14:17]
	v_mfma_f32_16x16x32_bf16 v[10:13], v[170:173], v[236:239], v[10:13]
	v_mfma_f32_16x16x32_bf16 v[62:65], v[164:167], v[216:219], v[62:65]
	v_mfma_f32_16x16x32_bf16 v[58:61], v[174:177], v[216:219], v[58:61]
	v_mfma_f32_16x16x32_bf16 v[46:49], v[164:167], v[224:227], v[46:49]
	v_mfma_f32_16x16x32_bf16 v[42:45], v[174:177], v[224:227], v[42:45]
	v_mfma_f32_16x16x32_bf16 v[30:33], v[164:167], v[232:235], v[30:33]
	v_mfma_f32_16x16x32_bf16 v[26:29], v[174:177], v[232:235], v[26:29]
	v_mfma_f32_16x16x32_bf16 v[14:17], v[164:167], v[240:243], v[14:17]
	v_mfma_f32_16x16x32_bf16 v[10:13], v[174:177], v[240:243], v[10:13]
	v_mfma_f32_16x16x32_bf16 v[54:57], v[178:181], v[212:215], v[54:57]
	v_mfma_f32_16x16x32_bf16 v[50:53], v[204:207], v[212:215], v[50:53]
	v_mfma_f32_16x16x32_bf16 v[38:41], v[178:181], v[220:223], v[38:41]
	v_mfma_f32_16x16x32_bf16 v[34:37], v[204:207], v[220:223], v[34:37]
	v_mfma_f32_16x16x32_bf16 v[22:25], v[178:181], v[228:231], v[22:25]
	v_mfma_f32_16x16x32_bf16 v[18:21], v[204:207], v[228:231], v[18:21]
	v_mfma_f32_16x16x32_bf16 v[6:9], v[178:181], v[236:239], v[6:9]
	v_mfma_f32_16x16x32_bf16 v[2:5], v[204:207], v[236:239], v[2:5]
	v_mfma_f32_16x16x32_bf16 v[54:57], v[182:185], v[216:219], v[54:57]
	v_mfma_f32_16x16x32_bf16 v[50:53], v[208:211], v[216:219], v[50:53]
	v_mfma_f32_16x16x32_bf16 v[38:41], v[182:185], v[224:227], v[38:41]
	v_mfma_f32_16x16x32_bf16 v[34:37], v[208:211], v[224:227], v[34:37]
	v_mfma_f32_16x16x32_bf16 v[22:25], v[182:185], v[232:235], v[22:25]
	v_mfma_f32_16x16x32_bf16 v[18:21], v[208:211], v[232:235], v[18:21]
	v_mfma_f32_16x16x32_bf16 v[6:9], v[182:185], v[240:243], v[6:9]
	v_mfma_f32_16x16x32_bf16 v[2:5], v[208:211], v[240:243], v[2:5]
	s_setprio 0
	s_barrier
	s_add_i32 s46, s46, 2
	s_add_u32 s60, s60, 0x100
	s_addc_u32 s73, s73, 0
	s_cmp_gt_u32 s46, 21
	s_mov_b64 s[36:37], s[42:43]
	s_cbranch_scc0 .LBB0_160
	s_mov_b32 s32, 1
	s_and_b64 vcc, exec, s[10:11]
	s_cbranch_vccz .LBB0_163
	s_barrier

; #define PG8_STAGE(bufoff, gbase, voff) do { _Pragma("unroll") for (int _i = 0; _i < 2; ++_i) \
;         __builtin_amdgcn_global_load_lds((const unsigned*)((const char*)(gbase) + (voff)[_i]), (PG8_LAS unsigned*)(lds + (bufoff) + ldsw + _i * 8192), 16, 0, 0); } while (0)
; #define PG8_WAIT_V(n) asm volatile("s_waitcnt vmcnt(" #n ")" ::: "memory")
; #define PG8_BAR __builtin_amdgcn_s_barrier()
; template <class Epi, class Sched, bool ALIGN_EPI = false, bool SP2 = false>
; __device__ __forceinline__ void gemm_phase(PG8_LAS unsigned char* lds, const Gemm g, const Sched& S, const Epi& E) {
;     ...
;     for (int i = 0; i < 2; ++i) { int R, C; stage_rc(tid * 16 + i * 8192, R, C); const int Rb = Epi::PERM ? ((R & ~31) + perm32(R & 31)) : R;
;         voffA[i] = (unsigned)(R * K + C) * 2u; voffB[i] = (unsigned)(Rb * K + C) * 2u; }
;     const size_t kstep = (size_t)(BK * 2);
;     const size_t hstep = (size_t)HALF * K * 2;
;     const size_t tstep = 2 * hstep;
;     const unsigned ldsw = (unsigned)wid * 1024u;
;     const int aoff = lds_byte(wr * 64 + fr, fq * 8), boff = lds_byte(wc * 32 + fr, fq * 8);
;     ...
;         PG8_STAGE(PG8_SB(0, 0), cB, voffB); PG8_STAGE(PG8_SB(0, 1), cB + hstep, voffB); PG8_STAGE(PG8_SA(0, 0), cA, voffA); PG8_STAGE(PG8_SA(0, 1), cA + hstep, voffA);
;         if (wr == 1) PG8_BAR;
;         PG8_WAIT_V(2); PG8_BAR;
;         PG8_STAGE(PG8_SB(1, 0), cB + kstep, voffB); PG8_STAGE(PG8_SA(1, 0), cA + kstep, voffA); PG8_STAGE(PG8_SB(1, 1), cB + hstep + kstep, voffB);
;         PG8_WAIT_V(6); PG8_BAR;
.LBB0_275:
	s_and_b32 s7, s5, 3
	s_add_i32 m0, s30, 0x18000
	v_lshl_add_u64 v[8:9], v[8:9], 0, s[68:69]
	s_lshl_b32 s5, s4, 13
	s_lshl_b32 s10, s7, 12
	s_waitcnt vmcnt(2)
	s_barrier
	global_load_lds_dwordx4 v[8:9], off
	v_lshl_add_u64 v[6:7], v[6:7], 0, s[68:69]
	s_add_i32 m0, s30, 0x1a000
	s_add_i32 s46, s30, 0x8000
	s_add_i32 s47, s30, 0xa000
	global_load_lds_dwordx4 v[6:7], off
	v_lshl_add_u64 v[2:3], v[2:3], 0, s[68:69]
	s_mov_b32 m0, s46
	s_add_u32 s8, s18, 0x80080
	global_load_lds_dwordx4 v[2:3], off
	v_lshl_add_u64 v[2:3], v[4:5], 0, s[68:69]
	s_mov_b32 m0, s47
	s_addc_u32 s9, s19, 0
	global_load_lds_dwordx4 v[2:3], off
	s_add_i32 m0, s30, 0x1c000
	v_lshl_add_u64 v[2:3], s[8:9], 0, v[146:147]
	global_load_lds_dwordx4 v[2:3], off
	v_lshl_add_u64 v[2:3], s[8:9], 0, v[142:143]
	s_add_i32 m0, s30, 0x1e000
	v_lshlrev_b32_e32 v6, 2, v12
	global_load_lds_dwordx4 v[2:3], off
	v_bfe_u32 v3, v12, 4, 2
	v_and_b32_e32 v2, 15, v12
	v_lshlrev_b32_e32 v4, 3, v3
	v_lshlrev_b32_e32 v3, 4, v3
	v_lshl_or_b32 v5, v2, 6, v3
	v_and_b32_e32 v6, 32, v6
	s_cmpk_lt_u32 s6, 0x100
	v_lshl_or_b32 v1, s4, 6, v2
	v_bitop3_b32 v7, v5, s5, v6 bitop3:0xde
	v_lshl_or_b32 v161, s7, 5, v4
	s_cselect_b64 s[4:5], -1, 0
	s_and_b32 s6, s6, 0xffffff00
	s_lshl_b32 s7, s7, 6
	s_or_b32 s6, s7, s6
	v_or3_b32 v2, s6, v3, v2
	v_readlane_b32 s6, v254, 61
	v_ashrrev_i32_e32 v3, 31, v2
	v_readlane_b32 s7, v254, 62
	s_waitcnt vmcnt(6)
	v_bitop3_b32 v160, v5, s10, v6 bitop3:0xde
	v_mov_b32_e32 v153, v0
	v_lshl_add_u64 v[150:151], v[2:3], 4, s[6:7]
	v_lshlrev_b32_e32 v2, 15, v15
	v_and_b32_e32 v2, 0xffff0000, v2
	v_lshl_add_u32 v2, v14, 12, v2
	v_and_b32_e32 v3, 1, v15
	v_lshl_or_b32 v2, v3, 6, v2
	v_lshl_add_u32 v152, v16, 1, v2
	v_lshlrev_b32_e32 v2, 15, v10
	v_and_b32_e32 v2, 0xffff0000, v2
	v_lshl_add_u32 v2, v11, 12, v2
	v_and_b32_e32 v3, 1, v10
	v_lshl_or_b32 v2, v3, 6, v2
	v_readlane_b32 s6, v253, 60
	v_lshl_add_u32 v154, v13, 1, v2
	v_mov_b32_e32 v155, v0
	s_mov_b32 s54, 0
	v_add_u32_e32 v162, 0, v7
	v_readlane_b32 s57, v253, 20
	s_mov_b32 s58, s6
	s_barrier
	v_readlane_b32 s7, v253, 61
	s_waitcnt vmcnt(0)
	s_mov_b32 s32, 0
	s_branch .LBB0_278

; #define PG8_STAGE(bufoff, gbase, voff) do { _Pragma("unroll") for (int _i = 0; _i < 2; ++_i) \
;         __builtin_amdgcn_global_load_lds((const unsigned*)((const char*)(gbase) + (voff)[_i]), (PG8_LAS unsigned*)(lds + (bufoff) + ldsw + _i * 8192), 16, 0, 0); } while (0)
; #define PG8_LDA(dst, b, h) do { _Pragma("unroll") for (int m = 0; m < 4; ++m) _Pragma("unroll") for (int k = 0; k < 2; ++k) dst[m][k] = *(const PG8_LAS bf16x8*)(lds + PG8_SA(b, h) + aoff + m * 2048 + k * 1024); } while (0)
; #define PG8_LDB(dst, b, h) do { _Pragma("unroll") for (int n = 0; n < 2; ++n) _Pragma("unroll") for (int k = 0; k < 2; ++k) dst[n][k] = *(const PG8_LAS bf16x8*)(lds + PG8_SB(b, h) + boff + n * 2048 + k * 1024); } while (0)
; #define PG8_SCHED __builtin_amdgcn_sched_barrier(0)
; template <class Epi, class Sched, bool ALIGN_EPI = false, bool SP2 = false>
; __device__ __forceinline__ void gemm_phase(PG8_LAS unsigned char* lds, const Gemm g, const Sched& S, const Epi& E) {
;     ...
;         const char* nA = has_next ? (const char*)g.A + (size_t)nxt.pm * tstep : cA; const char* nB = has_next ? (const char*)g.Bt + (size_t)nxt.pn * tstep : cB;
;         for (int t = 0; t < nt; t += 2) {
;             const bool last = (t == nt - 2);
;             const char* a1 = cA + (size_t)(t + 1) * kstep;
;             const char* a2 = last ? nA : cA + (size_t)(t + 2) * kstep; const char* b2 = last ? nB : cB + (size_t)(t + 2) * kstep;
;             const char* a3 = a2 + kstep; const char* b3 = b2 + kstep;
;             if (last && has_next) S.a_ready(nxt);
;             if constexpr (SP2) {
;             PG8_LDB(B0, 0, 0); PG8_LDB(B1, 0, 1); PG8_SCHED; PG8_LDA(At, 0, 0); PG8_STAGE(PG8_SA(1, 1), a1 + hstep, voffA);
.LBB0_280:
	s_ashr_i32 s9, s8, 31
	s_lshl_b64 s[10:11], s[8:9], 20
	s_add_u32 s10, s70, s10
	s_addc_u32 s11, s71, s11
	s_and_b64 s[12:13], s[40:41], exec
	s_cselect_b32 s9, s11, s37
	s_cselect_b32 s59, s10, s36
	s_ashr_i32 s7, s6, 31
	s_lshl_b64 s[12:13], s[6:7], 20
	s_add_u32 s12, s74, s12
	s_addc_u32 s13, s75, s13
	s_and_b64 s[42:43], s[40:41], exec
	s_cselect_b32 s7, s13, s19
	s_cselect_b32 s60, s12, s18
	s_add_u32 s36, s36, 0x80080
	s_addc_u32 s37, s37, 0
	s_add_u32 s62, s18, 0x100
	s_addc_u32 s63, s19, 0
	s_mov_b32 s67, -2
	s_add_u32 s18, s36, 0xfff80080
	s_addc_u32 s19, s37, -1
	s_add_i32 s73, 0, 0x10000
	s_cmp_eq_u32 s67, 28
	s_cselect_b32 s43, s9, s19
	s_cselect_b32 s42, s59, s18
	v_add_u32_e32 v163, s73, v160
	s_cselect_b32 s19, s7, s63
	s_cselect_b32 s18, s60, s62
	s_add_i32 s76, 0, 0x14000
	ds_read_b128 v[156:159], v163
	ds_read_b128 v[164:167], v163 offset:1024
	ds_read_b128 v[168:171], v163 offset:2048
	ds_read_b128 v[172:175], v163 offset:3072
	v_add_u32_e32 v163, s76, v160
	ds_read_b128 v[176:179], v163
	ds_read_b128 v[180:183], v163 offset:1024
	ds_read_b128 v[184:187], v163 offset:2048
	ds_read_b128 v[204:207], v163 offset:3072
	v_lshl_add_u64 v[240:241], s[36:37], 0, v[152:153]
	s_add_i32 m0, s30, 0xc000
	ds_read_b128 v[208:211], v162
	ds_read_b128 v[212:215], v162 offset:1024
	ds_read_b128 v[216:219], v162 offset:2048
	ds_read_b128 v[220:223], v162 offset:3072
	ds_read_b128 v[224:227], v162 offset:4096
	ds_read_b128 v[228:231], v162 offset:5120
	ds_read_b128 v[232:235], v162 offset:6144
	ds_read_b128 v[236:239], v162 offset:7168
	global_load_lds_dwordx4 v[240:241], off
	v_lshl_add_u64 v[240:241], s[36:37], 0, v[154:155]
	s_add_i32 m0, s30, 0xe000
	s_nop 0
	global_load_lds_dwordx4 v[240:241], off
	s_nop 0
	s_nop 0
	s_cmp_eq_u32 s32, 0
	s_cbranch_scc1 .Lpw11_f
	s_waitcnt vmcnt(16)
	s_branch .Lpw11_j

; #define PG8_STAGE(bufoff, gbase, voff) do { _Pragma("unroll") for (int _i = 0; _i < 2; ++_i) \
;         __builtin_amdgcn_global_load_lds((const unsigned*)((const char*)(gbase) + (voff)[_i]), (PG8_LAS unsigned*)(lds + (bufoff) + ldsw + _i * 8192), 16, 0, 0); } while (0)
; #define PG8_LDA(dst, b, h) do { _Pragma("unroll") for (int m = 0; m < 4; ++m) _Pragma("unroll") for (int k = 0; k < 2; ++k) dst[m][k] = *(const PG8_LAS bf16x8*)(lds + PG8_SA(b, h) + aoff + m * 2048 + k * 1024); } while (0)
; #define PG8_LDB(dst, b, h) do { _Pragma("unroll") for (int n = 0; n < 2; ++n) _Pragma("unroll") for (int k = 0; k < 2; ++k) dst[n][k] = *(const PG8_LAS bf16x8*)(lds + PG8_SB(b, h) + boff + n * 2048 + k * 1024); } while (0)
; #define PG8_MMA(ai, bj, At, Bt) do { __builtin_amdgcn_s_setprio(1); _Pragma("unroll") for (int m = 0; m < 4; ++m) _Pragma("unroll") for (int n = 0; n < 2; ++n) _Pragma("unroll") for (int k = 0; k < 2; ++k) \
;         acc[ai][bj][m][n] = __builtin_amdgcn_mfma_f32_16x16x32_bf16(Bt[n][k], At[m][k], acc[ai][bj][m][n], 0, 0, 0); __builtin_amdgcn_s_setprio(0); } while (0)
; #define PG8_WAIT_V(n) asm volatile("s_waitcnt vmcnt(" #n ")" ::: "memory")
; #define PG8_WAIT_L(n) asm volatile("s_waitcnt lgkmcnt(" #n ")" ::: "memory")
; #define PG8_BAR __builtin_amdgcn_s_barrier()
; #define PG8_SCHED __builtin_amdgcn_sched_barrier(0)
; template <class Epi, class Sched, bool ALIGN_EPI = false, bool SP2 = false>
; __device__ __forceinline__ void gemm_phase(PG8_LAS unsigned char* lds, const Gemm g, const Sched& S, const Epi& E) {
;     ...
;             PG8_LDB(B0, 0, 0); PG8_LDB(B1, 0, 1); PG8_SCHED; PG8_LDA(At, 0, 0); PG8_STAGE(PG8_SA(1, 1), a1 + hstep, voffA);
;             PG8_WAIT_V(8); PG8_WAIT_L(0); PG8_BAR; PG8_MMA(0, 0, At, B0); PG8_MMA(0, 1, At, B1); PG8_BAR; PG8_SCHED;
;             PG8_LDA(At, 0, 1); PG8_STAGE(PG8_SB(0, 0), b2, voffB); PG8_STAGE(PG8_SB(0, 1), b2 + hstep, voffB); PG8_STAGE(PG8_SA(0, 0), a2, voffA);
;             PG8_WAIT_V(8); PG8_WAIT_L(0); PG8_BAR; PG8_MMA(1, 0, At, B0); PG8_MMA(1, 1, At, B1); PG8_BAR; PG8_SCHED;
.Lpw11_j:
	s_waitcnt lgkmcnt(0)
	s_setprio 1
	s_barrier
	v_mfma_f32_16x16x32_bf16 v[126:129], v[156:159], v[208:211], 0
	v_mfma_f32_16x16x32_bf16 v[122:125], v[168:171], v[208:211], 0
	v_mfma_f32_16x16x32_bf16 v[110:113], v[156:159], v[216:219], 0
	v_mfma_f32_16x16x32_bf16 v[106:109], v[168:171], v[216:219], 0
	v_mfma_f32_16x16x32_bf16 v[94:97], v[156:159], v[224:227], 0
	v_mfma_f32_16x16x32_bf16 v[90:93], v[168:171], v[224:227], 0
	v_mfma_f32_16x16x32_bf16 v[78:81], v[156:159], v[232:235], 0
	v_mfma_f32_16x16x32_bf16 v[74:77], v[168:171], v[232:235], 0
	s_setprio 0
	s_setprio 1
	v_mfma_f32_16x16x32_bf16 v[126:129], v[164:167], v[212:215], v[126:129]
	v_mfma_f32_16x16x32_bf16 v[122:125], v[172:175], v[212:215], v[122:125]
	v_mfma_f32_16x16x32_bf16 v[110:113], v[164:167], v[220:223], v[110:113]
	v_mfma_f32_16x16x32_bf16 v[106:109], v[172:175], v[220:223], v[106:109]
	v_mfma_f32_16x16x32_bf16 v[94:97], v[164:167], v[228:231], v[94:97]
	v_mfma_f32_16x16x32_bf16 v[90:93], v[172:175], v[228:231], v[90:93]
	v_mfma_f32_16x16x32_bf16 v[78:81], v[164:167], v[236:239], v[78:81]
	v_mfma_f32_16x16x32_bf16 v[74:77], v[172:175], v[236:239], v[74:77]
	s_setprio 0
	s_setprio 1
	v_mfma_f32_16x16x32_bf16 v[118:121], v[176:179], v[208:211], 0
	v_mfma_f32_16x16x32_bf16 v[114:117], v[184:187], v[208:211], 0
	v_mfma_f32_16x16x32_bf16 v[102:105], v[176:179], v[216:219], 0
	v_mfma_f32_16x16x32_bf16 v[98:101], v[184:187], v[216:219], 0
	v_mfma_f32_16x16x32_bf16 v[86:89], v[176:179], v[224:227], 0
	v_mfma_f32_16x16x32_bf16 v[82:85], v[184:187], v[224:227], 0
	v_mfma_f32_16x16x32_bf16 v[70:73], v[176:179], v[232:235], 0
	v_mfma_f32_16x16x32_bf16 v[66:69], v[184:187], v[232:235], 0
	s_setprio 0
	s_setprio 1
	v_mfma_f32_16x16x32_bf16 v[118:121], v[180:183], v[212:215], v[118:121]
	v_mfma_f32_16x16x32_bf16 v[114:117], v[204:207], v[212:215], v[114:117]
	v_mfma_f32_16x16x32_bf16 v[102:105], v[180:183], v[220:223], v[102:105]
	v_mfma_f32_16x16x32_bf16 v[98:101], v[204:207], v[220:223], v[98:101]
	v_mfma_f32_16x16x32_bf16 v[86:89], v[180:183], v[228:231], v[86:89]
	v_mfma_f32_16x16x32_bf16 v[82:85], v[204:207], v[228:231], v[82:85]
	v_mfma_f32_16x16x32_bf16 v[70:73], v[180:183], v[236:239], v[70:73]
	v_mfma_f32_16x16x32_bf16 v[66:69], v[204:207], v[236:239], v[66:69]
	s_setprio 0
	s_barrier
	s_add_i32 s73, s73, s28
	v_lshl_add_u64 v[240:241], s[18:19], 0, v[146:147]
	s_mov_b32 m0, s73
	ds_read_b128 v[208:211], v162 offset:16384
	ds_read_b128 v[212:215], v162 offset:17408
	ds_read_b128 v[216:219], v162 offset:18432
	ds_read_b128 v[220:223], v162 offset:19456
	ds_read_b128 v[224:227], v162 offset:20480
	ds_read_b128 v[228:231], v162 offset:21504
	ds_read_b128 v[232:235], v162 offset:22528
	ds_read_b128 v[236:239], v162 offset:23552
	global_load_lds_dwordx4 v[240:241], off
	s_add_i32 m0, s73, 0x2000
	s_add_u32 s78, s18, 0x80000
	v_lshl_add_u64 v[242:243], s[18:19], 0, v[142:143]
	s_addc_u32 s79, s19, 0
	s_add_i32 s73, s76, s28
	global_load_lds_dwordx4 v[242:243], off
	v_lshl_add_u64 v[244:245], s[78:79], 0, v[146:147]
	s_mov_b32 m0, s73
	v_lshl_add_u64 v[246:247], s[42:43], 0, v[144:145]
	global_load_lds_dwordx4 v[244:245], off
	v_lshl_add_u64 v[244:245], s[78:79], 0, v[142:143]
	s_add_i32 m0, s73, 0x2000
	s_nop 0
	global_load_lds_dwordx4 v[244:245], off
	v_lshl_add_u64 v[244:245], s[42:43], 0, v[148:149]
	s_mov_b32 m0, s30
	s_nop 0
	global_load_lds_dwordx4 v[244:245], off
	s_mov_b32 m0, s34
	s_nop 0
	global_load_lds_dwordx4 v[246:247], off
	s_cmp_eq_u32 s32, 0
	s_cbranch_scc1 .Lpw12_f
	s_waitcnt vmcnt(16)
	s_branch .Lpw12_j

; #define PG8_STAGE(bufoff, gbase, voff) do { _Pragma("unroll") for (int _i = 0; _i < 2; ++_i) \
;         __builtin_amdgcn_global_load_lds((const unsigned*)((const char*)(gbase) + (voff)[_i]), (PG8_LAS unsigned*)(lds + (bufoff) + ldsw + _i * 8192), 16, 0, 0); } while (0)
; #define PG8_LDA(dst, b, h) do { _Pragma("unroll") for (int m = 0; m < 4; ++m) _Pragma("unroll") for (int k = 0; k < 2; ++k) dst[m][k] = *(const PG8_LAS bf16x8*)(lds + PG8_SA(b, h) + aoff + m * 2048 + k * 1024); } while (0)
; #define PG8_LDB(dst, b, h) do { _Pragma("unroll") for (int n = 0; n < 2; ++n) _Pragma("unroll") for (int k = 0; k < 2; ++k) dst[n][k] = *(const PG8_LAS bf16x8*)(lds + PG8_SB(b, h) + boff + n * 2048 + k * 1024); } while (0)
; #define PG8_MMA(ai, bj, At, Bt) do { __builtin_amdgcn_s_setprio(1); _Pragma("unroll") for (int m = 0; m < 4; ++m) _Pragma("unroll") for (int n = 0; n < 2; ++n) _Pragma("unroll") for (int k = 0; k < 2; ++k) \
;         acc[ai][bj][m][n] = __builtin_amdgcn_mfma_f32_16x16x32_bf16(Bt[n][k], At[m][k], acc[ai][bj][m][n], 0, 0, 0); __builtin_amdgcn_s_setprio(0); } while (0)
; #define PG8_WAIT_V(n) asm volatile("s_waitcnt vmcnt(" #n ")" ::: "memory")
; #define PG8_WAIT_L(n) asm volatile("s_waitcnt lgkmcnt(" #n ")" ::: "memory")
; #define PG8_BAR __builtin_amdgcn_s_barrier()
; #define PG8_SCHED __builtin_amdgcn_sched_barrier(0)
; template <class Epi, class Sched, bool ALIGN_EPI = false, bool SP2 = false>
; __device__ __forceinline__ void gemm_phase(PG8_LAS unsigned char* lds, const Gemm g, const Sched& S, const Epi& E) {
;     ...
;             PG8_WAIT_V(8); PG8_WAIT_L(0); PG8_BAR; PG8_MMA(1, 0, At, B0); PG8_MMA(1, 1, At, B1); PG8_BAR; PG8_SCHED;
;             PG8_LDB(B0, 1, 0); PG8_LDB(B1, 1, 1); PG8_SCHED; PG8_LDA(At, 1, 0); PG8_STAGE(PG8_SA(0, 1), a2 + hstep, voffA);
;             PG8_WAIT_V(8); PG8_WAIT_L(0); PG8_BAR; PG8_MMA(0, 0, At, B0); PG8_MMA(0, 1, At, B1); PG8_BAR; PG8_SCHED;
.Lpw12_j:
	s_waitcnt lgkmcnt(0)
	s_setprio 1
	s_barrier
	v_mfma_f32_16x16x32_bf16 v[62:65], v[156:159], v[208:211], 0
	v_mfma_f32_16x16x32_bf16 v[58:61], v[168:171], v[208:211], 0
	v_mfma_f32_16x16x32_bf16 v[46:49], v[156:159], v[216:219], 0
	v_mfma_f32_16x16x32_bf16 v[42:45], v[168:171], v[216:219], 0
	v_mfma_f32_16x16x32_bf16 v[30:33], v[156:159], v[224:227], 0
	v_mfma_f32_16x16x32_bf16 v[26:29], v[168:171], v[224:227], 0
	v_mfma_f32_16x16x32_bf16 v[14:17], v[156:159], v[232:235], 0
	v_mfma_f32_16x16x32_bf16 v[10:13], v[168:171], v[232:235], 0
	v_mfma_f32_16x16x32_bf16 v[62:65], v[164:167], v[212:215], v[62:65]
	v_mfma_f32_16x16x32_bf16 v[58:61], v[172:175], v[212:215], v[58:61]
	v_mfma_f32_16x16x32_bf16 v[46:49], v[164:167], v[220:223], v[46:49]
	v_mfma_f32_16x16x32_bf16 v[42:45], v[172:175], v[220:223], v[42:45]
	v_mfma_f32_16x16x32_bf16 v[30:33], v[164:167], v[228:231], v[30:33]
	v_mfma_f32_16x16x32_bf16 v[26:29], v[172:175], v[228:231], v[26:29]
	v_mfma_f32_16x16x32_bf16 v[14:17], v[164:167], v[236:239], v[14:17]
	v_mfma_f32_16x16x32_bf16 v[10:13], v[172:175], v[236:239], v[10:13]
	v_mfma_f32_16x16x32_bf16 v[54:57], v[176:179], v[208:211], 0
	v_mfma_f32_16x16x32_bf16 v[50:53], v[184:187], v[208:211], 0
	v_mfma_f32_16x16x32_bf16 v[38:41], v[176:179], v[216:219], 0
	v_mfma_f32_16x16x32_bf16 v[34:37], v[184:187], v[216:219], 0
	v_mfma_f32_16x16x32_bf16 v[22:25], v[176:179], v[224:227], 0
	v_mfma_f32_16x16x32_bf16 v[18:21], v[184:187], v[224:227], 0
	v_mfma_f32_16x16x32_bf16 v[6:9], v[176:179], v[232:235], 0
	v_mfma_f32_16x16x32_bf16 v[2:5], v[184:187], v[232:235], 0
	v_mfma_f32_16x16x32_bf16 v[54:57], v[180:183], v[212:215], v[54:57]
	v_mfma_f32_16x16x32_bf16 v[50:53], v[204:207], v[212:215], v[50:53]
	v_mfma_f32_16x16x32_bf16 v[38:41], v[180:183], v[220:223], v[38:41]
	v_mfma_f32_16x16x32_bf16 v[34:37], v[204:207], v[220:223], v[34:37]
	v_mfma_f32_16x16x32_bf16 v[22:25], v[180:183], v[228:231], v[22:25]
	v_mfma_f32_16x16x32_bf16 v[18:21], v[204:207], v[228:231], v[18:21]
	v_mfma_f32_16x16x32_bf16 v[6:9], v[180:183], v[236:239], v[6:9]
	v_mfma_f32_16x16x32_bf16 v[2:5], v[204:207], v[236:239], v[2:5]
	s_setprio 0
	s_barrier
	s_add_i32 s73, 0, 0x18000
	v_add_u32_e32 v163, s73, v160
	s_add_i32 s76, 0, 0x1c000
	ds_read_b128 v[156:159], v163
	ds_read_b128 v[164:167], v163 offset:1024
	ds_read_b128 v[168:171], v163 offset:2048
	ds_read_b128 v[172:175], v163 offset:3072
	v_add_u32_e32 v163, s76, v160
	ds_read_b128 v[176:179], v163
	ds_read_b128 v[180:183], v163 offset:1024
	ds_read_b128 v[184:187], v163 offset:2048
	ds_read_b128 v[204:207], v163 offset:3072
	s_add_u32 s42, s42, 0x80000
	s_addc_u32 s43, s43, 0
	s_mov_b32 m0, s44
	v_lshl_add_u64 v[248:249], s[42:43], 0, v[148:149]
	ds_read_b128 v[208:211], v162 offset:32768
	ds_read_b128 v[212:215], v162 offset:33792
	ds_read_b128 v[216:219], v162 offset:34816
	ds_read_b128 v[220:223], v162 offset:35840
	ds_read_b128 v[224:227], v162 offset:36864
	ds_read_b128 v[228:231], v162 offset:37888
	ds_read_b128 v[232:235], v162 offset:38912
	ds_read_b128 v[236:239], v162 offset:39936
	global_load_lds_dwordx4 v[248:249], off
	v_lshl_add_u64 v[248:249], s[42:43], 0, v[144:145]
	s_mov_b32 m0, s45
	s_nop 0
	global_load_lds_dwordx4 v[248:249], off
	s_waitcnt vmcnt(8)
	s_waitcnt lgkmcnt(0)
	s_setprio 1
	s_barrier
	v_mfma_f32_16x16x32_bf16 v[126:129], v[156:159], v[208:211], v[126:129]
	v_mfma_f32_16x16x32_bf16 v[122:125], v[168:171], v[208:211], v[122:125]
	v_mfma_f32_16x16x32_bf16 v[110:113], v[156:159], v[216:219], v[110:113]
	v_mfma_f32_16x16x32_bf16 v[106:109], v[168:171], v[216:219], v[106:109]
	v_mfma_f32_16x16x32_bf16 v[94:97], v[156:159], v[224:227], v[94:97]
	v_mfma_f32_16x16x32_bf16 v[90:93], v[168:171], v[224:227], v[90:93]
	v_mfma_f32_16x16x32_bf16 v[78:81], v[156:159], v[232:235], v[78:81]
	v_mfma_f32_16x16x32_bf16 v[74:77], v[168:171], v[232:235], v[74:77]
	s_setprio 0
	s_setprio 1
	v_mfma_f32_16x16x32_bf16 v[126:129], v[164:167], v[212:215], v[126:129]
	v_mfma_f32_16x16x32_bf16 v[122:125], v[172:175], v[212:215], v[122:125]
	v_mfma_f32_16x16x32_bf16 v[110:113], v[164:167], v[220:223], v[110:113]
	v_mfma_f32_16x16x32_bf16 v[106:109], v[172:175], v[220:223], v[106:109]
	v_mfma_f32_16x16x32_bf16 v[94:97], v[164:167], v[228:231], v[94:97]
	v_mfma_f32_16x16x32_bf16 v[90:93], v[172:175], v[228:231], v[90:93]
	v_mfma_f32_16x16x32_bf16 v[78:81], v[164:167], v[236:239], v[78:81]
	v_mfma_f32_16x16x32_bf16 v[74:77], v[172:175], v[236:239], v[74:77]
	s_setprio 0
	s_setprio 1
	v_mfma_f32_16x16x32_bf16 v[118:121], v[176:179], v[208:211], v[118:121]
	v_mfma_f32_16x16x32_bf16 v[114:117], v[184:187], v[208:211], v[114:117]
	v_mfma_f32_16x16x32_bf16 v[102:105], v[176:179], v[216:219], v[102:105]
	v_mfma_f32_16x16x32_bf16 v[98:101], v[184:187], v[216:219], v[98:101]
	v_mfma_f32_16x16x32_bf16 v[86:89], v[176:179], v[224:227], v[86:89]
	v_mfma_f32_16x16x32_bf16 v[82:85], v[184:187], v[224:227], v[82:85]
	v_mfma_f32_16x16x32_bf16 v[70:73], v[176:179], v[232:235], v[70:73]
	v_mfma_f32_16x16x32_bf16 v[66:69], v[184:187], v[232:235], v[66:69]
	s_setprio 0
	s_setprio 1
	v_mfma_f32_16x16x32_bf16 v[118:121], v[180:183], v[212:215], v[118:121]
	v_mfma_f32_16x16x32_bf16 v[114:117], v[204:207], v[212:215], v[114:117]
	v_mfma_f32_16x16x32_bf16 v[102:105], v[180:183], v[220:223], v[102:105]
	v_mfma_f32_16x16x32_bf16 v[98:101], v[204:207], v[220:223], v[98:101]
	v_mfma_f32_16x16x32_bf16 v[86:89], v[180:183], v[228:231], v[86:89]
	v_mfma_f32_16x16x32_bf16 v[82:85], v[204:207], v[228:231], v[82:85]
	v_mfma_f32_16x16x32_bf16 v[70:73], v[180:183], v[236:239], v[70:73]
	v_mfma_f32_16x16x32_bf16 v[66:69], v[204:207], v[236:239], v[66:69]
	s_setprio 0
	s_barrier
; #define PG8_STAGE(bufoff, gbase, voff) do { _Pragma("unroll") for (int _i = 0; _i < 2; ++_i) \
;         __builtin_amdgcn_global_load_lds((const unsigned*)((const char*)(gbase) + (voff)[_i]), (PG8_LAS unsigned*)(lds + (bufoff) + ldsw + _i * 8192), 16, 0, 0); } while (0)
; #define PG8_LDA(dst, b, h) do { _Pragma("unroll") for (int m = 0; m < 4; ++m) _Pragma("unroll") for (int k = 0; k < 2; ++k) dst[m][k] = *(const PG8_LAS bf16x8*)(lds + PG8_SA(b, h) + aoff + m * 2048 + k * 1024); } while (0)
; #define PG8_LDB(dst, b, h) do { _Pragma("unroll") for (int n = 0; n < 2; ++n) _Pragma("unroll") for (int k = 0; k < 2; ++k) dst[n][k] = *(const PG8_LAS bf16x8*)(lds + PG8_SB(b, h) + boff + n * 2048 + k * 1024); } while (0)
; #define PG8_MMA(ai, bj, At, Bt) do { __builtin_amdgcn_s_setprio(1); _Pragma("unroll") for (int m = 0; m < 4; ++m) _Pragma("unroll") for (int n = 0; n < 2; ++n) _Pragma("unroll") for (int k = 0; k < 2; ++k) \
;         acc[ai][bj][m][n] = __builtin_amdgcn_mfma_f32_16x16x32_bf16(Bt[n][k], At[m][k], acc[ai][bj][m][n], 0, 0, 0); __builtin_amdgcn_s_setprio(0); } while (0)
; #define PG8_WAIT_V(n) asm volatile("s_waitcnt vmcnt(" #n ")" ::: "memory")
; #define PG8_BAR __builtin_amdgcn_s_barrier()
; template <class Epi, class Sched, bool ALIGN_EPI = false, bool SP2 = false>
; __device__ __forceinline__ void gemm_phase(PG8_LAS unsigned char* lds, const Gemm g, const Sched& S, const Epi& E) {
;     ...
;         for (int t = 0; t < nt; t += 2) {
;             const bool last = (t == nt - 2);
;             const char* a1 = cA + (size_t)(t + 1) * kstep;
;             const char* a2 = last ? nA : cA + (size_t)(t + 2) * kstep; const char* b2 = last ? nB : cB + (size_t)(t + 2) * kstep;
;             const char* a3 = a2 + kstep; const char* b3 = b2 + kstep;
;             if (last && has_next) S.a_ready(nxt);
;             if constexpr (SP2) {
;             PG8_LDB(B0, 0, 0); PG8_LDB(B1, 0, 1); PG8_SCHED; PG8_LDA(At, 0, 0); PG8_STAGE(PG8_SA(1, 1), a1 + hstep, voffA);
;             PG8_WAIT_V(8); PG8_WAIT_L(0); PG8_BAR; PG8_MMA(0, 0, At, B0); PG8_MMA(0, 1, At, B1); PG8_BAR; PG8_SCHED;
;     ...
;             PG8_LDA(At, 1, 1); PG8_STAGE(PG8_SB(1, 0), b3, voffB); PG8_STAGE(PG8_SB(1, 1), b3 + hstep, voffB); PG8_STAGE(PG8_SA(1, 0), a3, voffA);
;             PG8_WAIT_V(8); PG8_WAIT_L(0); PG8_BAR; PG8_MMA(1, 0, At, B0); PG8_MMA(1, 1, At, B1); PG8_BAR; PG8_SCHED;
	s_add_i32 s42, s73, s28
	v_lshl_add_u64 v[240:241], v[240:241], 0, s[68:69]
	s_mov_b32 m0, s42
	ds_read_b128 v[208:211], v162 offset:49152
	ds_read_b128 v[212:215], v162 offset:50176
	ds_read_b128 v[216:219], v162 offset:51200
	ds_read_b128 v[220:223], v162 offset:52224
	ds_read_b128 v[224:227], v162 offset:53248
	ds_read_b128 v[228:231], v162 offset:54272
	ds_read_b128 v[232:235], v162 offset:55296
	ds_read_b128 v[236:239], v162 offset:56320
	global_load_lds_dwordx4 v[240:241], off
	s_add_i32 m0, s42, 0x2000
	s_add_u32 s18, s18, 0x80080
	v_lshl_add_u64 v[240:241], v[242:243], 0, s[68:69]
	s_addc_u32 s19, s19, 0
	s_add_i32 s42, s76, s28
	global_load_lds_dwordx4 v[240:241], off
	v_lshl_add_u64 v[240:241], s[18:19], 0, v[146:147]
	s_mov_b32 m0, s42
	s_nop 0
	global_load_lds_dwordx4 v[240:241], off
	v_lshl_add_u64 v[240:241], s[18:19], 0, v[142:143]
	s_add_i32 m0, s42, 0x2000
	s_nop 0
	global_load_lds_dwordx4 v[240:241], off
	v_lshl_add_u64 v[240:241], v[244:245], 0, s[68:69]
	s_mov_b32 m0, s46
	s_nop 0
	global_load_lds_dwordx4 v[240:241], off
	v_lshl_add_u64 v[240:241], v[246:247], 0, s[68:69]
	s_mov_b32 m0, s47
	s_nop 0
	global_load_lds_dwordx4 v[240:241], off
	s_nop 0
	s_waitcnt vmcnt(8)
	s_waitcnt lgkmcnt(0)
	s_setprio 1
	s_barrier
	v_mfma_f32_16x16x32_bf16 v[62:65], v[156:159], v[208:211], v[62:65]
	v_mfma_f32_16x16x32_bf16 v[58:61], v[168:171], v[208:211], v[58:61]
	v_mfma_f32_16x16x32_bf16 v[46:49], v[156:159], v[216:219], v[46:49]
	v_mfma_f32_16x16x32_bf16 v[42:45], v[168:171], v[216:219], v[42:45]
	v_mfma_f32_16x16x32_bf16 v[30:33], v[156:159], v[224:227], v[30:33]
	v_mfma_f32_16x16x32_bf16 v[26:29], v[168:171], v[224:227], v[26:29]
	v_mfma_f32_16x16x32_bf16 v[14:17], v[156:159], v[232:235], v[14:17]
	v_mfma_f32_16x16x32_bf16 v[10:13], v[168:171], v[232:235], v[10:13]
	v_mfma_f32_16x16x32_bf16 v[62:65], v[164:167], v[212:215], v[62:65]
	v_mfma_f32_16x16x32_bf16 v[58:61], v[172:175], v[212:215], v[58:61]
	v_mfma_f32_16x16x32_bf16 v[46:49], v[164:167], v[220:223], v[46:49]
	v_mfma_f32_16x16x32_bf16 v[42:45], v[172:175], v[220:223], v[42:45]
	v_mfma_f32_16x16x32_bf16 v[30:33], v[164:167], v[228:231], v[30:33]
	v_mfma_f32_16x16x32_bf16 v[26:29], v[172:175], v[228:231], v[26:29]
	v_mfma_f32_16x16x32_bf16 v[14:17], v[164:167], v[236:239], v[14:17]
	v_mfma_f32_16x16x32_bf16 v[10:13], v[172:175], v[236:239], v[10:13]
	v_mfma_f32_16x16x32_bf16 v[54:57], v[176:179], v[208:211], v[54:57]
	v_mfma_f32_16x16x32_bf16 v[50:53], v[184:187], v[208:211], v[50:53]
	v_mfma_f32_16x16x32_bf16 v[38:41], v[176:179], v[216:219], v[38:41]
	v_mfma_f32_16x16x32_bf16 v[34:37], v[184:187], v[216:219], v[34:37]
	v_mfma_f32_16x16x32_bf16 v[22:25], v[176:179], v[224:227], v[22:25]
	v_mfma_f32_16x16x32_bf16 v[18:21], v[184:187], v[224:227], v[18:21]
	v_mfma_f32_16x16x32_bf16 v[6:9], v[176:179], v[232:235], v[6:9]
	v_mfma_f32_16x16x32_bf16 v[2:5], v[184:187], v[232:235], v[2:5]
	v_mfma_f32_16x16x32_bf16 v[54:57], v[180:183], v[212:215], v[54:57]
	v_mfma_f32_16x16x32_bf16 v[50:53], v[204:207], v[212:215], v[50:53]
	v_mfma_f32_16x16x32_bf16 v[38:41], v[180:183], v[220:223], v[38:41]
	v_mfma_f32_16x16x32_bf16 v[34:37], v[204:207], v[220:223], v[34:37]
	v_mfma_f32_16x16x32_bf16 v[22:25], v[180:183], v[228:231], v[22:25]
	v_mfma_f32_16x16x32_bf16 v[18:21], v[204:207], v[228:231], v[18:21]
	v_mfma_f32_16x16x32_bf16 v[6:9], v[180:183], v[236:239], v[6:9]
	v_mfma_f32_16x16x32_bf16 v[2:5], v[204:207], v[236:239], v[2:5]
	s_setprio 0
	s_barrier
	s_add_i32 s67, s67, 2
	s_add_u32 s36, s36, 0x100
	s_addc_u32 s37, s37, 0
	s_add_u32 s62, s62, 0x100
	s_addc_u32 s63, s63, 0
	s_cmp_gt_u32 s67, 29
.LBB0_281:
	s_add_u32 s18, s36, 0xfff80080
	s_addc_u32 s19, s37, -1
	s_add_i32 s73, 0, 0x10000
	s_cmp_eq_u32 s67, 28
	s_cselect_b32 s43, s9, s19
	s_cselect_b32 s42, s59, s18
	v_add_u32_e32 v163, s73, v160
	s_cselect_b32 s19, s7, s63
	s_cselect_b32 s18, s60, s62
	s_add_i32 s76, 0, 0x14000
	ds_read_b128 v[156:159], v163
	ds_read_b128 v[164:167], v163 offset:1024
	ds_read_b128 v[168:171], v163 offset:2048
	ds_read_b128 v[172:175], v163 offset:3072
	v_add_u32_e32 v163, s76, v160
	ds_read_b128 v[176:179], v163
	ds_read_b128 v[180:183], v163 offset:1024
	ds_read_b128 v[184:187], v163 offset:2048
	ds_read_b128 v[204:207], v163 offset:3072
	v_lshl_add_u64 v[240:241], s[36:37], 0, v[152:153]
	s_add_i32 m0, s30, 0xc000
	ds_read_b128 v[208:211], v162
	ds_read_b128 v[212:215], v162 offset:1024
	ds_read_b128 v[216:219], v162 offset:2048
	ds_read_b128 v[220:223], v162 offset:3072
	ds_read_b128 v[224:227], v162 offset:4096
	ds_read_b128 v[228:231], v162 offset:5120
	ds_read_b128 v[232:235], v162 offset:6144
	ds_read_b128 v[236:239], v162 offset:7168
	global_load_lds_dwordx4 v[240:241], off
	v_lshl_add_u64 v[240:241], s[36:37], 0, v[154:155]
	s_add_i32 m0, s30, 0xe000
	s_nop 0
	global_load_lds_dwordx4 v[240:241], off
	s_nop 0
	s_nop 0
	s_nop 0
	s_waitcnt vmcnt(8)
	s_waitcnt lgkmcnt(0)
	s_setprio 1
	s_barrier
; #define PG8_STAGE(bufoff, gbase, voff) do { _Pragma("unroll") for (int _i = 0; _i < 2; ++_i) \
;         __builtin_amdgcn_global_load_lds((const unsigned*)((const char*)(gbase) + (voff)[_i]), (PG8_LAS unsigned*)(lds + (bufoff) + ldsw + _i * 8192), 16, 0, 0); } while (0)
; #define PG8_LDA(dst, b, h) do { _Pragma("unroll") for (int m = 0; m < 4; ++m) _Pragma("unroll") for (int k = 0; k < 2; ++k) dst[m][k] = *(const PG8_LAS bf16x8*)(lds + PG8_SA(b, h) + aoff + m * 2048 + k * 1024); } while (0)
; #define PG8_MMA(ai, bj, At, Bt) do { __builtin_amdgcn_s_setprio(1); _Pragma("unroll") for (int m = 0; m < 4; ++m) _Pragma("unroll") for (int n = 0; n < 2; ++n) _Pragma("unroll") for (int k = 0; k < 2; ++k) \
;         acc[ai][bj][m][n] = __builtin_amdgcn_mfma_f32_16x16x32_bf16(Bt[n][k], At[m][k], acc[ai][bj][m][n], 0, 0, 0); __builtin_amdgcn_s_setprio(0); } while (0)
; #define PG8_WAIT_V(n) asm volatile("s_waitcnt vmcnt(" #n ")" ::: "memory")
; #define PG8_WAIT_L(n) asm volatile("s_waitcnt lgkmcnt(" #n ")" ::: "memory")
; #define PG8_BAR __builtin_amdgcn_s_barrier()
; #define PG8_SCHED __builtin_amdgcn_sched_barrier(0)
; template <class Epi, class Sched, bool ALIGN_EPI = false, bool SP2 = false>
; __device__ __forceinline__ void gemm_phase(PG8_LAS unsigned char* lds, const Gemm g, const Sched& S, const Epi& E) {
;     ...
;             PG8_WAIT_V(8); PG8_WAIT_L(0); PG8_BAR; PG8_MMA(0, 0, At, B0); PG8_MMA(0, 1, At, B1); PG8_BAR; PG8_SCHED;
;             PG8_LDA(At, 0, 1); PG8_STAGE(PG8_SB(0, 0), b2, voffB); PG8_STAGE(PG8_SB(0, 1), b2 + hstep, voffB); PG8_STAGE(PG8_SA(0, 0), a2, voffA);
;             PG8_WAIT_V(8); PG8_WAIT_L(0); PG8_BAR; PG8_MMA(1, 0, At, B0); PG8_MMA(1, 1, At, B1); PG8_BAR; PG8_SCHED;
	v_mfma_f32_16x16x32_bf16 v[126:129], v[156:159], v[208:211], v[126:129]
	v_mfma_f32_16x16x32_bf16 v[122:125], v[168:171], v[208:211], v[122:125]
	v_mfma_f32_16x16x32_bf16 v[110:113], v[156:159], v[216:219], v[110:113]
	v_mfma_f32_16x16x32_bf16 v[106:109], v[168:171], v[216:219], v[106:109]
	v_mfma_f32_16x16x32_bf16 v[94:97], v[156:159], v[224:227], v[94:97]
	v_mfma_f32_16x16x32_bf16 v[90:93], v[168:171], v[224:227], v[90:93]
	v_mfma_f32_16x16x32_bf16 v[78:81], v[156:159], v[232:235], v[78:81]
	v_mfma_f32_16x16x32_bf16 v[74:77], v[168:171], v[232:235], v[74:77]
	s_setprio 0
	s_setprio 1
	v_mfma_f32_16x16x32_bf16 v[126:129], v[164:167], v[212:215], v[126:129]
	v_mfma_f32_16x16x32_bf16 v[122:125], v[172:175], v[212:215], v[122:125]
	v_mfma_f32_16x16x32_bf16 v[110:113], v[164:167], v[220:223], v[110:113]
	v_mfma_f32_16x16x32_bf16 v[106:109], v[172:175], v[220:223], v[106:109]
	v_mfma_f32_16x16x32_bf16 v[94:97], v[164:167], v[228:231], v[94:97]
	v_mfma_f32_16x16x32_bf16 v[90:93], v[172:175], v[228:231], v[90:93]
	v_mfma_f32_16x16x32_bf16 v[78:81], v[164:167], v[236:239], v[78:81]
	v_mfma_f32_16x16x32_bf16 v[74:77], v[172:175], v[236:239], v[74:77]
	s_setprio 0
	s_setprio 1
	v_mfma_f32_16x16x32_bf16 v[118:121], v[176:179], v[208:211], v[118:121]
	v_mfma_f32_16x16x32_bf16 v[114:117], v[184:187], v[208:211], v[114:117]
	v_mfma_f32_16x16x32_bf16 v[102:105], v[176:179], v[216:219], v[102:105]
	v_mfma_f32_16x16x32_bf16 v[98:101], v[184:187], v[216:219], v[98:101]
	v_mfma_f32_16x16x32_bf16 v[86:89], v[176:179], v[224:227], v[86:89]
	v_mfma_f32_16x16x32_bf16 v[82:85], v[184:187], v[224:227], v[82:85]
	v_mfma_f32_16x16x32_bf16 v[70:73], v[176:179], v[232:235], v[70:73]
	v_mfma_f32_16x16x32_bf16 v[66:69], v[184:187], v[232:235], v[66:69]
	s_setprio 0
	s_setprio 1
	v_mfma_f32_16x16x32_bf16 v[118:121], v[180:183], v[212:215], v[118:121]
	v_mfma_f32_16x16x32_bf16 v[114:117], v[204:207], v[212:215], v[114:117]
	v_mfma_f32_16x16x32_bf16 v[102:105], v[180:183], v[220:223], v[102:105]
	v_mfma_f32_16x16x32_bf16 v[98:101], v[204:207], v[220:223], v[98:101]
	v_mfma_f32_16x16x32_bf16 v[86:89], v[180:183], v[228:231], v[86:89]
	v_mfma_f32_16x16x32_bf16 v[82:85], v[204:207], v[228:231], v[82:85]
	v_mfma_f32_16x16x32_bf16 v[70:73], v[180:183], v[236:239], v[70:73]
	v_mfma_f32_16x16x32_bf16 v[66:69], v[204:207], v[236:239], v[66:69]
	s_setprio 0
	s_barrier
	s_add_i32 s73, s73, s28
	v_lshl_add_u64 v[240:241], s[18:19], 0, v[146:147]
	s_mov_b32 m0, s73
	ds_read_b128 v[208:211], v162 offset:16384
	ds_read_b128 v[212:215], v162 offset:17408
	ds_read_b128 v[216:219], v162 offset:18432
	ds_read_b128 v[220:223], v162 offset:19456
	ds_read_b128 v[224:227], v162 offset:20480
	ds_read_b128 v[228:231], v162 offset:21504
	ds_read_b128 v[232:235], v162 offset:22528
	ds_read_b128 v[236:239], v162 offset:23552
	global_load_lds_dwordx4 v[240:241], off
	s_add_i32 m0, s73, 0x2000
	s_add_u32 s78, s18, 0x80000
	v_lshl_add_u64 v[242:243], s[18:19], 0, v[142:143]
	s_addc_u32 s79, s19, 0
	s_add_i32 s73, s76, s28
	global_load_lds_dwordx4 v[242:243], off
	v_lshl_add_u64 v[244:245], s[78:79], 0, v[146:147]
	s_mov_b32 m0, s73
	v_lshl_add_u64 v[246:247], s[42:43], 0, v[144:145]
	global_load_lds_dwordx4 v[244:245], off
	v_lshl_add_u64 v[244:245], s[78:79], 0, v[142:143]
	s_add_i32 m0, s73, 0x2000
	s_nop 0
	global_load_lds_dwordx4 v[244:245], off
	v_lshl_add_u64 v[244:245], s[42:43], 0, v[148:149]
	s_mov_b32 m0, s30
	s_nop 0
	global_load_lds_dwordx4 v[244:245], off
	s_mov_b32 m0, s34
	s_nop 0
	global_load_lds_dwordx4 v[246:247], off
	s_waitcnt vmcnt(8)
	s_waitcnt lgkmcnt(0)
	s_setprio 1
	s_barrier
	v_mfma_f32_16x16x32_bf16 v[62:65], v[156:159], v[208:211], v[62:65]
	v_mfma_f32_16x16x32_bf16 v[58:61], v[168:171], v[208:211], v[58:61]
	v_mfma_f32_16x16x32_bf16 v[46:49], v[156:159], v[216:219], v[46:49]
	v_mfma_f32_16x16x32_bf16 v[42:45], v[168:171], v[216:219], v[42:45]
	v_mfma_f32_16x16x32_bf16 v[30:33], v[156:159], v[224:227], v[30:33]
	v_mfma_f32_16x16x32_bf16 v[26:29], v[168:171], v[224:227], v[26:29]
	v_mfma_f32_16x16x32_bf16 v[14:17], v[156:159], v[232:235], v[14:17]
	v_mfma_f32_16x16x32_bf16 v[10:13], v[168:171], v[232:235], v[10:13]
	v_mfma_f32_16x16x32_bf16 v[62:65], v[164:167], v[212:215], v[62:65]
	v_mfma_f32_16x16x32_bf16 v[58:61], v[172:175], v[212:215], v[58:61]
	v_mfma_f32_16x16x32_bf16 v[46:49], v[164:167], v[220:223], v[46:49]
	v_mfma_f32_16x16x32_bf16 v[42:45], v[172:175], v[220:223], v[42:45]
	v_mfma_f32_16x16x32_bf16 v[30:33], v[164:167], v[228:231], v[30:33]
	v_mfma_f32_16x16x32_bf16 v[26:29], v[172:175], v[228:231], v[26:29]
	v_mfma_f32_16x16x32_bf16 v[14:17], v[164:167], v[236:239], v[14:17]
	v_mfma_f32_16x16x32_bf16 v[10:13], v[172:175], v[236:239], v[10:13]
	v_mfma_f32_16x16x32_bf16 v[54:57], v[176:179], v[208:211], v[54:57]
	v_mfma_f32_16x16x32_bf16 v[50:53], v[184:187], v[208:211], v[50:53]
	v_mfma_f32_16x16x32_bf16 v[38:41], v[176:179], v[216:219], v[38:41]
	v_mfma_f32_16x16x32_bf16 v[34:37], v[184:187], v[216:219], v[34:37]
	v_mfma_f32_16x16x32_bf16 v[22:25], v[176:179], v[224:227], v[22:25]
	v_mfma_f32_16x16x32_bf16 v[18:21], v[184:187], v[224:227], v[18:21]
	v_mfma_f32_16x16x32_bf16 v[6:9], v[176:179], v[232:235], v[6:9]
	v_mfma_f32_16x16x32_bf16 v[2:5], v[184:187], v[232:235], v[2:5]
	v_mfma_f32_16x16x32_bf16 v[54:57], v[180:183], v[212:215], v[54:57]
	v_mfma_f32_16x16x32_bf16 v[50:53], v[204:207], v[212:215], v[50:53]
	v_mfma_f32_16x16x32_bf16 v[38:41], v[180:183], v[220:223], v[38:41]
	v_mfma_f32_16x16x32_bf16 v[34:37], v[204:207], v[220:223], v[34:37]
	v_mfma_f32_16x16x32_bf16 v[22:25], v[180:183], v[228:231], v[22:25]
	v_mfma_f32_16x16x32_bf16 v[18:21], v[204:207], v[228:231], v[18:21]
	v_mfma_f32_16x16x32_bf16 v[6:9], v[180:183], v[236:239], v[6:9]
	v_mfma_f32_16x16x32_bf16 v[2:5], v[204:207], v[236:239], v[2:5]
	s_setprio 0
	s_barrier
; #define PG8_STAGE(bufoff, gbase, voff) do { _Pragma("unroll") for (int _i = 0; _i < 2; ++_i) \
;         __builtin_amdgcn_global_load_lds((const unsigned*)((const char*)(gbase) + (voff)[_i]), (PG8_LAS unsigned*)(lds + (bufoff) + ldsw + _i * 8192), 16, 0, 0); } while (0)
; #define PG8_LDA(dst, b, h) do { _Pragma("unroll") for (int m = 0; m < 4; ++m) _Pragma("unroll") for (int k = 0; k < 2; ++k) dst[m][k] = *(const PG8_LAS bf16x8*)(lds + PG8_SA(b, h) + aoff + m * 2048 + k * 1024); } while (0)
; #define PG8_LDB(dst, b, h) do { _Pragma("unroll") for (int n = 0; n < 2; ++n) _Pragma("unroll") for (int k = 0; k < 2; ++k) dst[n][k] = *(const PG8_LAS bf16x8*)(lds + PG8_SB(b, h) + boff + n * 2048 + k * 1024); } while (0)
; #define PG8_MMA(ai, bj, At, Bt) do { __builtin_amdgcn_s_setprio(1); _Pragma("unroll") for (int m = 0; m < 4; ++m) _Pragma("unroll") for (int n = 0; n < 2; ++n) _Pragma("unroll") for (int k = 0; k < 2; ++k) \
;         acc[ai][bj][m][n] = __builtin_amdgcn_mfma_f32_16x16x32_bf16(Bt[n][k], At[m][k], acc[ai][bj][m][n], 0, 0, 0); __builtin_amdgcn_s_setprio(0); } while (0)
; #define PG8_WAIT_V(n) asm volatile("s_waitcnt vmcnt(" #n ")" ::: "memory")
; #define PG8_WAIT_L(n) asm volatile("s_waitcnt lgkmcnt(" #n ")" ::: "memory")
; #define PG8_BAR __builtin_amdgcn_s_barrier()
; #define PG8_SCHED __builtin_amdgcn_sched_barrier(0)
; template <class Epi, class Sched, bool ALIGN_EPI = false, bool SP2 = false>
; __device__ __forceinline__ void gemm_phase(PG8_LAS unsigned char* lds, const Gemm g, const Sched& S, const Epi& E) {
;     ...
;             PG8_LDB(B0, 1, 0); PG8_LDB(B1, 1, 1); PG8_SCHED; PG8_LDA(At, 1, 0); PG8_STAGE(PG8_SA(0, 1), a2 + hstep, voffA);
;             PG8_WAIT_V(8); PG8_WAIT_L(0); PG8_BAR; PG8_MMA(0, 0, At, B0); PG8_MMA(0, 1, At, B1); PG8_BAR; PG8_SCHED;
	s_add_i32 s73, 0, 0x18000
	v_add_u32_e32 v163, s73, v160
	s_add_i32 s76, 0, 0x1c000
	ds_read_b128 v[156:159], v163
	ds_read_b128 v[164:167], v163 offset:1024
	ds_read_b128 v[168:171], v163 offset:2048
	ds_read_b128 v[172:175], v163 offset:3072
	v_add_u32_e32 v163, s76, v160
	ds_read_b128 v[176:179], v163
	ds_read_b128 v[180:183], v163 offset:1024
	ds_read_b128 v[184:187], v163 offset:2048
	ds_read_b128 v[204:207], v163 offset:3072
	s_add_u32 s42, s42, 0x80000
	s_addc_u32 s43, s43, 0
	s_mov_b32 m0, s44
	v_lshl_add_u64 v[248:249], s[42:43], 0, v[148:149]
	ds_read_b128 v[208:211], v162 offset:32768
	ds_read_b128 v[212:215], v162 offset:33792
	ds_read_b128 v[216:219], v162 offset:34816
	ds_read_b128 v[220:223], v162 offset:35840
	ds_read_b128 v[224:227], v162 offset:36864
	ds_read_b128 v[228:231], v162 offset:37888
	ds_read_b128 v[232:235], v162 offset:38912
	ds_read_b128 v[236:239], v162 offset:39936
	global_load_lds_dwordx4 v[248:249], off
	v_lshl_add_u64 v[248:249], s[42:43], 0, v[144:145]
	s_mov_b32 m0, s45
	s_nop 0
	global_load_lds_dwordx4 v[248:249], off
	s_waitcnt vmcnt(8)
	s_waitcnt lgkmcnt(0)
	s_setprio 1
	s_barrier
	v_mfma_f32_16x16x32_bf16 v[126:129], v[156:159], v[208:211], v[126:129]
	v_mfma_f32_16x16x32_bf16 v[122:125], v[168:171], v[208:211], v[122:125]
	v_mfma_f32_16x16x32_bf16 v[110:113], v[156:159], v[216:219], v[110:113]
	v_mfma_f32_16x16x32_bf16 v[106:109], v[168:171], v[216:219], v[106:109]
	v_mfma_f32_16x16x32_bf16 v[94:97], v[156:159], v[224:227], v[94:97]
	v_mfma_f32_16x16x32_bf16 v[90:93], v[168:171], v[224:227], v[90:93]
	v_mfma_f32_16x16x32_bf16 v[78:81], v[156:159], v[232:235], v[78:81]
	v_mfma_f32_16x16x32_bf16 v[74:77], v[168:171], v[232:235], v[74:77]
	s_setprio 0
	s_setprio 1
	v_mfma_f32_16x16x32_bf16 v[126:129], v[164:167], v[212:215], v[126:129]
	v_mfma_f32_16x16x32_bf16 v[122:125], v[172:175], v[212:215], v[122:125]
	v_mfma_f32_16x16x32_bf16 v[110:113], v[164:167], v[220:223], v[110:113]
	v_mfma_f32_16x16x32_bf16 v[106:109], v[172:175], v[220:223], v[106:109]
	v_mfma_f32_16x16x32_bf16 v[94:97], v[164:167], v[228:231], v[94:97]
	v_mfma_f32_16x16x32_bf16 v[90:93], v[172:175], v[228:231], v[90:93]
	v_mfma_f32_16x16x32_bf16 v[78:81], v[164:167], v[236:239], v[78:81]
	v_mfma_f32_16x16x32_bf16 v[74:77], v[172:175], v[236:239], v[74:77]
	s_setprio 0
	s_setprio 1
	v_mfma_f32_16x16x32_bf16 v[118:121], v[176:179], v[208:211], v[118:121]
	v_mfma_f32_16x16x32_bf16 v[114:117], v[184:187], v[208:211], v[114:117]
	v_mfma_f32_16x16x32_bf16 v[102:105], v[176:179], v[216:219], v[102:105]
	v_mfma_f32_16x16x32_bf16 v[98:101], v[184:187], v[216:219], v[98:101]
	v_mfma_f32_16x16x32_bf16 v[86:89], v[176:179], v[224:227], v[86:89]
	v_mfma_f32_16x16x32_bf16 v[82:85], v[184:187], v[224:227], v[82:85]
	v_mfma_f32_16x16x32_bf16 v[70:73], v[176:179], v[232:235], v[70:73]
	v_mfma_f32_16x16x32_bf16 v[66:69], v[184:187], v[232:235], v[66:69]
	s_setprio 0
	s_setprio 1
	v_mfma_f32_16x16x32_bf16 v[118:121], v[180:183], v[212:215], v[118:121]
	v_mfma_f32_16x16x32_bf16 v[114:117], v[204:207], v[212:215], v[114:117]
	v_mfma_f32_16x16x32_bf16 v[102:105], v[180:183], v[220:223], v[102:105]
	v_mfma_f32_16x16x32_bf16 v[98:101], v[204:207], v[220:223], v[98:101]
	v_mfma_f32_16x16x32_bf16 v[86:89], v[180:183], v[228:231], v[86:89]
	v_mfma_f32_16x16x32_bf16 v[82:85], v[204:207], v[228:231], v[82:85]
	v_mfma_f32_16x16x32_bf16 v[70:73], v[180:183], v[236:239], v[70:73]
	v_mfma_f32_16x16x32_bf16 v[66:69], v[204:207], v[236:239], v[66:69]
	s_setprio 0
	s_barrier
; #define PG8_STAGE(bufoff, gbase, voff) do { _Pragma("unroll") for (int _i = 0; _i < 2; ++_i) \
;         __builtin_amdgcn_global_load_lds((const unsigned*)((const char*)(gbase) + (voff)[_i]), (PG8_LAS unsigned*)(lds + (bufoff) + ldsw + _i * 8192), 16, 0, 0); } while (0)
; #define PG8_LDA(dst, b, h) do { _Pragma("unroll") for (int m = 0; m < 4; ++m) _Pragma("unroll") for (int k = 0; k < 2; ++k) dst[m][k] = *(const PG8_LAS bf16x8*)(lds + PG8_SA(b, h) + aoff + m * 2048 + k * 1024); } while (0)
; #define PG8_WAIT_V(n) asm volatile("s_waitcnt vmcnt(" #n ")" ::: "memory")
; template <class Epi, class Sched, bool ALIGN_EPI = false, bool SP2 = false>
; __device__ __forceinline__ void gemm_phase(PG8_LAS unsigned char* lds, const Gemm g, const Sched& S, const Epi& E) {
;     ...
;             PG8_LDA(At, 1, 1); PG8_STAGE(PG8_SB(1, 0), b3, voffB); PG8_STAGE(PG8_SB(1, 1), b3 + hstep, voffB); PG8_STAGE(PG8_SA(1, 0), a3, voffA);
;             PG8_WAIT_V(8); PG8_WAIT_L(0); PG8_BAR; PG8_MMA(1, 0, At, B0); PG8_MMA(1, 1, At, B1); PG8_BAR; PG8_SCHED;
;             } else {
;             PG8_LDB(B0, 0, 0); PG8_SCHED; PG8_LDA(At, 0, 0); PG8_STAGE(PG8_SA(1, 1), a1 + hstep, voffA);
;             PG8_WAIT_L(8); PG8_BAR; PG8_WAIT_L(0); PG8_MMA(0, 0, At, B0); PG8_BAR; PG8_SCHED;
;             PG8_LDB(B1, 0, 1); PG8_STAGE(PG8_SB(0, 0), b2, voffB);
;             PG8_BAR; PG8_WAIT_L(0); PG8_MMA(0, 1, At, B1); PG8_BAR;
;             PG8_LDA(At, 0, 1); PG8_STAGE(PG8_SA(0, 0), a2, voffA);
;             PG8_BAR; PG8_WAIT_L(0); PG8_MMA(1, 0, At, B0); PG8_BAR; PG8_SCHED;
;             PG8_STAGE(PG8_SB(0, 1), b2 + hstep, voffB);
;             PG8_WAIT_V(6); PG8_BAR; PG8_MMA(1, 1, At, B1); PG8_BAR;
;             PG8_LDB(B0, 1, 0); PG8_SCHED; PG8_LDA(At, 1, 0); PG8_STAGE(PG8_SA(0, 1), a2 + hstep, voffA);
;             PG8_WAIT_L(8); PG8_BAR; PG8_WAIT_L(0); PG8_MMA(0, 0, At, B0); PG8_BAR; PG8_SCHED;
;             PG8_LDB(B1, 1, 1); PG8_STAGE(PG8_SB(1, 0), b3, voffB);
;             PG8_BAR; PG8_WAIT_L(0); PG8_MMA(0, 1, At, B1); PG8_BAR;
;             PG8_LDA(At, 1, 1); PG8_STAGE(PG8_SA(1, 0), a3, voffA);
;             PG8_BAR; PG8_WAIT_L(0); PG8_MMA(1, 0, At, B0); PG8_BAR; PG8_SCHED;
;             PG8_STAGE(PG8_SB(1, 1), b3 + hstep, voffB);
;             PG8_WAIT_V(6); PG8_BAR; PG8_MMA(1, 1, At, B1); PG8_BAR;
;             }
;         }
;         if constexpr (ALIGN_EPI) { if (wr == 0) PG8_BAR; }
	s_add_i32 s42, s73, s28
	v_lshl_add_u64 v[240:241], v[240:241], 0, s[68:69]
	s_mov_b32 m0, s42
	ds_read_b128 v[208:211], v162 offset:49152
	ds_read_b128 v[212:215], v162 offset:50176
	ds_read_b128 v[216:219], v162 offset:51200
	ds_read_b128 v[220:223], v162 offset:52224
	ds_read_b128 v[224:227], v162 offset:53248
	ds_read_b128 v[228:231], v162 offset:54272
	ds_read_b128 v[232:235], v162 offset:55296
	ds_read_b128 v[236:239], v162 offset:56320
	global_load_lds_dwordx4 v[240:241], off
	s_add_i32 m0, s42, 0x2000
	s_add_u32 s18, s18, 0x80080
	v_lshl_add_u64 v[240:241], v[242:243], 0, s[68:69]
	s_addc_u32 s19, s19, 0
	s_add_i32 s42, s76, s28
	global_load_lds_dwordx4 v[240:241], off
	v_lshl_add_u64 v[240:241], s[18:19], 0, v[146:147]
	s_mov_b32 m0, s42
	s_nop 0
	global_load_lds_dwordx4 v[240:241], off
	v_lshl_add_u64 v[240:241], s[18:19], 0, v[142:143]
	s_add_i32 m0, s42, 0x2000
	s_nop 0
	global_load_lds_dwordx4 v[240:241], off
	v_lshl_add_u64 v[240:241], v[244:245], 0, s[68:69]
	s_mov_b32 m0, s46
	s_nop 0
	global_load_lds_dwordx4 v[240:241], off
	v_lshl_add_u64 v[240:241], v[246:247], 0, s[68:69]
	s_mov_b32 m0, s47
	s_nop 0
	global_load_lds_dwordx4 v[240:241], off
	s_nop 0
	s_waitcnt vmcnt(8)
	s_waitcnt lgkmcnt(0)
	s_setprio 1
	s_barrier
	v_mfma_f32_16x16x32_bf16 v[62:65], v[156:159], v[208:211], v[62:65]
	v_mfma_f32_16x16x32_bf16 v[58:61], v[168:171], v[208:211], v[58:61]
	v_mfma_f32_16x16x32_bf16 v[46:49], v[156:159], v[216:219], v[46:49]
	v_mfma_f32_16x16x32_bf16 v[42:45], v[168:171], v[216:219], v[42:45]
	v_mfma_f32_16x16x32_bf16 v[30:33], v[156:159], v[224:227], v[30:33]
	v_mfma_f32_16x16x32_bf16 v[26:29], v[168:171], v[224:227], v[26:29]
	v_mfma_f32_16x16x32_bf16 v[14:17], v[156:159], v[232:235], v[14:17]
	v_mfma_f32_16x16x32_bf16 v[10:13], v[168:171], v[232:235], v[10:13]
	v_mfma_f32_16x16x32_bf16 v[62:65], v[164:167], v[212:215], v[62:65]
	v_mfma_f32_16x16x32_bf16 v[58:61], v[172:175], v[212:215], v[58:61]
	v_mfma_f32_16x16x32_bf16 v[46:49], v[164:167], v[220:223], v[46:49]
	v_mfma_f32_16x16x32_bf16 v[42:45], v[172:175], v[220:223], v[42:45]
	v_mfma_f32_16x16x32_bf16 v[30:33], v[164:167], v[228:231], v[30:33]
	v_mfma_f32_16x16x32_bf16 v[26:29], v[172:175], v[228:231], v[26:29]
	v_mfma_f32_16x16x32_bf16 v[14:17], v[164:167], v[236:239], v[14:17]
	v_mfma_f32_16x16x32_bf16 v[10:13], v[172:175], v[236:239], v[10:13]
	v_mfma_f32_16x16x32_bf16 v[54:57], v[176:179], v[208:211], v[54:57]
	v_mfma_f32_16x16x32_bf16 v[50:53], v[184:187], v[208:211], v[50:53]
	v_mfma_f32_16x16x32_bf16 v[38:41], v[176:179], v[216:219], v[38:41]
	v_mfma_f32_16x16x32_bf16 v[34:37], v[184:187], v[216:219], v[34:37]
	v_mfma_f32_16x16x32_bf16 v[22:25], v[176:179], v[224:227], v[22:25]
	v_mfma_f32_16x16x32_bf16 v[18:21], v[184:187], v[224:227], v[18:21]
	v_mfma_f32_16x16x32_bf16 v[6:9], v[176:179], v[232:235], v[6:9]
	v_mfma_f32_16x16x32_bf16 v[2:5], v[184:187], v[232:235], v[2:5]
	v_mfma_f32_16x16x32_bf16 v[54:57], v[180:183], v[212:215], v[54:57]
	v_mfma_f32_16x16x32_bf16 v[50:53], v[204:207], v[212:215], v[50:53]
	v_mfma_f32_16x16x32_bf16 v[38:41], v[180:183], v[220:223], v[38:41]
	v_mfma_f32_16x16x32_bf16 v[34:37], v[204:207], v[220:223], v[34:37]
	v_mfma_f32_16x16x32_bf16 v[22:25], v[180:183], v[228:231], v[22:25]
	v_mfma_f32_16x16x32_bf16 v[18:21], v[204:207], v[228:231], v[18:21]
	v_mfma_f32_16x16x32_bf16 v[6:9], v[180:183], v[236:239], v[6:9]
	v_mfma_f32_16x16x32_bf16 v[2:5], v[204:207], v[236:239], v[2:5]
	s_setprio 0
	s_barrier
	s_add_i32 s67, s67, 2
	s_add_u32 s36, s36, 0x100
	s_addc_u32 s37, s37, 0
	s_add_u32 s62, s62, 0x100
	s_addc_u32 s63, s63, 0
	s_cmp_gt_u32 s67, 29
	s_cbranch_scc0 .LBB0_281
	s_mov_b32 s32, 1
	s_and_b64 vcc, exec, s[4:5]
	s_cbranch_vccnz .LBB0_286
	s_cmp_lt_i32 s57, 30
	s_mov_b64 s[18:19], -1
	s_cbranch_scc1 .LBB0_287
